# DN split-K (layer-0 context rows) K-loop on the 8-phase ping-pong LDS-DMA schedule (odd K-tile count variant); packed f32 VALU ops in residual/norm loops and IN/UP epilogues split into scalar pairs; m
# speedup vs baseline: 1.0314x; 1.0031x over previous
.LBB0_19:
	v_cmp_gt_i32_e32 vcc, s12, v18
	v_add_u32_e32 v2, 0xffffc000, v18
	v_mov_b32_e32 v4, s85
	v_mov_b32_e32 v5, s81
	v_cndmask_b32_e32 v3, 0, v19, vcc
	v_cndmask_b32_e32 v2, v2, v18, vcc
	v_cndmask_b32_e32 v5, v4, v5, vcc
	v_mov_b32_e32 v4, s84
	v_mov_b32_e32 v6, s80
	v_cndmask_b32_e32 v4, v4, v6, vcc
	v_lshlrev_b64 v[2:3], 12, v[2:3]
	v_lshl_add_u64 v[2:3], v[4:5], 0, v[2:3]
	v_lshl_add_u64 v[2:3], v[2:3], 0, v[0:1]
	global_load_dwordx4 v[14:17], v[2:3], off nt
	global_load_dwordx4 v[10:13], v[2:3], off offset:1024 nt
	global_load_dwordx4 v[6:9], v[2:3], off offset:2048 nt
	s_nop 0
	global_load_dwordx4 v[2:5], v[2:3], off offset:3072 nt
	v_min_i32_e32 v25, 0x4000, v18
	v_ashrrev_i32_e32 v25, 13, v25
	v_mul_hi_i32_i24_e32 v33, 0x6000, v25
	v_mul_i32_i24_e32 v32, 0x6000, v25
	v_lshl_add_u64 v[32:33], s[4:5], 0, v[32:33]
	v_lshl_add_u64 v[34:35], v[32:33], 0, s[10:11]
	v_lshl_add_u64 v[32:33], v[32:33], 0, v[0:1]
	v_mov_b32_e32 v29, v1
	v_lshl_add_u64 v[18:19], v[18:19], 0, s[6:7]
	s_movk_i32 s0, 0x41ff
	s_waitcnt vmcnt(3)
	v_mov_b32_e32 v44, v15
	s_waitcnt vmcnt(2)
	v_mov_b32_e32 v45, v11
	v_mov_b32_e32 v42, v14
	v_mov_b32_e32 v43, v10
	v_mul_f32_e32 v44, v44, v44
	v_mul_f32_e32 v45, v45, v45
	s_waitcnt vmcnt(1)
	v_mov_b32_e32 v46, v7
	v_fma_f32 v42, v42, v42, v44
	v_fma_f32 v43, v43, v43, v45
	v_mov_b32_e32 v44, v16
	v_mov_b32_e32 v45, v12
	v_fma_f32 v42, v44, v44, v42
	v_fma_f32 v43, v45, v45, v43
	v_mov_b32_e32 v44, v17
	v_mov_b32_e32 v45, v13
	s_waitcnt vmcnt(0)
	v_mov_b32_e32 v47, v3
	v_fma_f32 v42, v44, v44, v42
	v_fma_f32 v43, v45, v45, v43
	v_mov_b32_e32 v44, v6
	v_mov_b32_e32 v45, v2
	v_mul_f32_e32 v46, v46, v46
	v_mul_f32_e32 v47, v47, v47
	v_add_f32_e32 v25, v42, v43
	v_fma_f32 v44, v44, v44, v46
	v_fma_f32 v45, v45, v45, v47
	v_mov_b32_e32 v46, v8
	v_mov_b32_e32 v47, v4
	v_fma_f32 v44, v46, v46, v44
	v_fma_f32 v45, v47, v47, v45
	v_mov_b32_e32 v46, v9
	v_mov_b32_e32 v47, v5
	v_fma_f32 v44, v46, v46, v44
	v_fma_f32 v45, v47, v47, v45
	v_lshl_add_u64 v[46:47], v[34:35], 0, v[0:1]
	v_add_f32_e32 v25, v25, v44
	v_add_f32_e32 v25, v25, v45
	global_load_dwordx4 v[42:45], v[20:21], off
	s_nop 0
	global_load_dwordx4 v[46:49], v[46:47], off
	s_nop 0
	global_load_dwordx4 v[50:53], v[32:33], off
	ds_bpermute_b32 v27, v31, v25
	s_waitcnt lgkmcnt(0)
	v_add_f32_e32 v25, v25, v27
	ds_bpermute_b32 v27, v36, v25
	s_waitcnt lgkmcnt(0)
	v_add_f32_e32 v25, v25, v27
	ds_bpermute_b32 v27, v37, v25
	s_waitcnt lgkmcnt(0)
	v_add_f32_e32 v25, v25, v27
	ds_bpermute_b32 v27, v38, v25
	s_waitcnt lgkmcnt(0)
	v_add_f32_e32 v25, v25, v27
	ds_bpermute_b32 v27, v39, v25
	s_waitcnt lgkmcnt(0)
	v_add_f32_e32 v25, v25, v27
	ds_bpermute_b32 v27, v40, v25
	s_waitcnt lgkmcnt(0)
	v_add_f32_e32 v25, v25, v27
	v_fmamk_f32 v25, v25, 0x3a800000, v201
	v_cmp_gt_f32_e32 vcc, s42, v25
	v_mul_f32_e32 v27, 0x4b800000, v25
	s_nop 0
	v_cndmask_b32_e32 v25, v25, v27, vcc
	v_rsq_f32_e32 v25, v25
	s_nop 0
	v_mul_f32_e32 v27, 0x45800000, v25
	v_cndmask_b32_e32 v30, v25, v27, vcc
	v_mul_f32_e32 v14, v14, v30
	v_mul_f32_e32 v15, v15, v30
	v_mul_f32_e32 v16, v16, v30
	v_mul_f32_e32 v17, v17, v30
	v_mov_b32_e32 v25, v1
	v_mul_f32_e32 v10, v10, v30
	v_mul_f32_e32 v11, v11, v30
	v_mul_f32_e32 v12, v12, v30
	v_mul_f32_e32 v13, v13, v30
	v_mov_b32_e32 v27, v1
	v_mul_f32_e32 v6, v6, v30
	v_mul_f32_e32 v7, v7, v30
	v_mul_f32_e32 v8, v8, v30
	v_mul_f32_e32 v9, v9, v30
	v_mul_f32_e32 v2, v2, v30
	v_mul_f32_e32 v3, v3, v30
	v_mul_f32_e32 v4, v4, v30
	v_mul_f32_e32 v5, v5, v30
	v_cmp_lt_i32_e32 vcc, s0, v18
	s_or_b64 s[38:39], vcc, s[38:39]
	s_waitcnt vmcnt(2)
	v_mul_f32_e32 v14, v42, v14
	v_mul_f32_e32 v15, v43, v15
	s_waitcnt vmcnt(1)
	v_add_f32_e32 v42, 1.0, v46
	v_add_f32_e32 v43, 1.0, v47
	v_mul_f32_e32 v16, v44, v16
	v_mul_f32_e32 v17, v45, v17
	s_waitcnt vmcnt(0)
	v_fma_f32 v14, v42, v14, v50
	v_fma_f32 v15, v43, v15, v51
	v_add_f32_e32 v42, 1.0, v48
	v_add_f32_e32 v43, 1.0, v49
	v_cvt_pk_bf16_f32 v14, v14, v15
	v_fma_f32 v16, v42, v16, v52
	v_fma_f32 v17, v43, v17, v53
	v_lshl_add_u64 v[42:43], v[34:35], 0, v[24:25]
	v_cvt_pk_bf16_f32 v15, v16, v17
	global_store_dwordx2 v[22:23], v[14:15], off offset:-1024
	global_load_dwordx4 v[14:17], v[20:21], off offset:1024
	s_nop 0
	global_load_dwordx4 v[42:45], v[42:43], off
	s_nop 0
	global_load_dwordx4 v[46:49], v[32:33], off offset:1024
	s_waitcnt vmcnt(2)
	v_mul_f32_e32 v10, v10, v14
	v_mul_f32_e32 v11, v11, v15
	s_waitcnt vmcnt(1)
	v_add_f32_e32 v14, 1.0, v42
	v_add_f32_e32 v15, 1.0, v43
	v_mul_f32_e32 v12, v12, v16
	v_mul_f32_e32 v13, v13, v17
	s_waitcnt vmcnt(0)
	v_fma_f32 v10, v10, v14, v46
	v_fma_f32 v11, v11, v15, v47
	v_add_f32_e32 v14, 1.0, v44
	v_add_f32_e32 v15, 1.0, v45
	v_cvt_pk_bf16_f32 v10, v10, v11
	v_fma_f32 v12, v12, v14, v48
	v_fma_f32 v13, v13, v15, v49
	v_lshl_add_u64 v[14:15], v[34:35], 0, v[26:27]
	v_cvt_pk_bf16_f32 v11, v12, v13
	global_store_dwordx2 v[22:23], v[10:11], off offset:-512
	global_load_dwordx4 v[10:13], v[20:21], off offset:2048
	s_nop 0
	global_load_dwordx4 v[14:17], v[14:15], off
	s_nop 0
	global_load_dwordx4 v[42:45], v[32:33], off offset:2048
	s_waitcnt vmcnt(2)
	v_mul_f32_e32 v6, v6, v10
	v_mul_f32_e32 v7, v7, v11
	s_waitcnt vmcnt(1)
	v_add_f32_e32 v10, 1.0, v14
	v_add_f32_e32 v11, 1.0, v15
	v_mul_f32_e32 v8, v8, v12
	v_mul_f32_e32 v9, v9, v13
	s_waitcnt vmcnt(0)
	v_fma_f32 v6, v6, v10, v42
	v_fma_f32 v7, v7, v11, v43
	v_add_f32_e32 v10, 1.0, v16
	v_add_f32_e32 v11, 1.0, v17
	v_cvt_pk_bf16_f32 v6, v6, v7
	v_fma_f32 v8, v8, v10, v44
	v_fma_f32 v9, v9, v11, v45
	v_lshl_add_u64 v[10:11], v[34:35], 0, v[28:29]
	v_cvt_pk_bf16_f32 v7, v8, v9
	global_store_dwordx2 v[22:23], v[6:7], off
	global_load_dwordx4 v[6:9], v[20:21], off offset:3072
	s_nop 0
	global_load_dwordx4 v[10:13], v[10:11], off
	s_nop 0
	global_load_dwordx4 v[14:17], v[32:33], off offset:3072
	s_waitcnt vmcnt(2)
	v_mul_f32_e32 v2, v2, v6
	v_mul_f32_e32 v3, v3, v7
	s_waitcnt vmcnt(1)
	v_add_f32_e32 v6, 1.0, v10
	v_add_f32_e32 v7, 1.0, v11
	v_mul_f32_e32 v4, v4, v8
	v_mul_f32_e32 v5, v5, v9
	s_waitcnt vmcnt(0)
	v_fma_f32 v2, v2, v6, v14
	v_fma_f32 v3, v3, v7, v15
	v_add_f32_e32 v6, 1.0, v12
	v_add_f32_e32 v7, 1.0, v13
	v_cvt_pk_bf16_f32 v2, v2, v3
	v_fma_f32 v4, v4, v6, v16
	v_fma_f32 v5, v5, v7, v17
	s_nop 0
	v_cvt_pk_bf16_f32 v3, v4, v5
	global_store_dwordx2 v[22:23], v[2:3], off offset:512
	v_lshl_add_u64 v[22:23], v[22:23], 0, s[18:19]
	s_andn2_b64 exec, exec, s[38:39]
	s_cbranch_execnz .LBB0_19

.LBB0_32:
	s_andn2_saveexec_b64 s[2:3], s[2:3]
	s_cbranch_execz .LBB0_34
	v_lshlrev_b64 v[46:47], 11, v[56:57]
	v_lshl_add_u64 v[58:59], v[20:21], 0, v[46:47]
	v_add_co_u32_e32 v54, vcc, 0x100000, v58
	global_load_dwordx2 v[46:47], v[58:59], off nt
	global_load_dwordx2 v[48:49], v[58:59], off offset:512 nt
	global_load_dwordx2 v[50:51], v[58:59], off offset:1024 nt
	global_load_dwordx2 v[52:53], v[58:59], off offset:1536 nt
	v_addc_co_u32_e32 v55, vcc, 0, v59, vcc
	global_load_dwordx2 v[56:57], v[54:55], off nt
	global_load_dwordx2 v[60:61], v[54:55], off offset:512 nt
	global_load_dwordx2 v[70:71], v[54:55], off offset:1024 nt
	global_load_dwordx2 v[72:73], v[54:55], off offset:1536 nt
	s_mov_b32 s0, 0x200000
	s_waitcnt vmcnt(7)
	v_lshlrev_b32_e32 v54, 16, v46
	v_and_b32_e32 v55, 0xffff0000, v46
	v_lshlrev_b32_e32 v46, 16, v47
	s_waitcnt vmcnt(3)
	v_lshlrev_b32_e32 v62, 16, v56
	v_and_b32_e32 v63, 0xffff0000, v56
	v_add_f32_e32 v62, v54, v62
	v_add_f32_e32 v63, v55, v63
	v_and_b32_e32 v47, 0xffff0000, v47
	v_lshlrev_b32_e32 v54, 16, v57
	v_and_b32_e32 v55, 0xffff0000, v57
	v_add_f32_e32 v64, v46, v54
	v_add_f32_e32 v65, v47, v55
	v_lshlrev_b32_e32 v46, 16, v48
	v_and_b32_e32 v47, 0xffff0000, v48
	s_waitcnt vmcnt(2)
	v_lshlrev_b32_e32 v54, 16, v60
	v_and_b32_e32 v55, 0xffff0000, v60
	v_add_f32_e32 v66, v46, v54
	v_add_f32_e32 v67, v47, v55
	v_lshlrev_b32_e32 v46, 16, v49
	v_and_b32_e32 v47, 0xffff0000, v49
	v_lshlrev_b32_e32 v48, 16, v61
	v_and_b32_e32 v49, 0xffff0000, v61
	v_add_f32_e32 v68, v46, v48
	v_add_f32_e32 v69, v47, v49
	v_lshlrev_b32_e32 v46, 16, v50
	v_and_b32_e32 v47, 0xffff0000, v50
	s_waitcnt vmcnt(1)
	v_lshlrev_b32_e32 v48, 16, v70
	v_and_b32_e32 v49, 0xffff0000, v70
	v_add_f32_e32 v54, v46, v48
	v_add_f32_e32 v55, v47, v49
	v_lshlrev_b32_e32 v46, 16, v51
	v_and_b32_e32 v47, 0xffff0000, v51
	v_lshlrev_b32_e32 v48, 16, v71
	v_and_b32_e32 v49, 0xffff0000, v71
	v_add_f32_e32 v56, v46, v48
	v_add_f32_e32 v57, v47, v49
	v_lshlrev_b32_e32 v46, 16, v52
	v_and_b32_e32 v47, 0xffff0000, v52
	s_waitcnt vmcnt(0)
	v_lshlrev_b32_e32 v48, 16, v72
	v_and_b32_e32 v49, 0xffff0000, v72
	v_add_f32_e32 v46, v46, v48
	v_add_f32_e32 v47, v47, v49
	v_lshlrev_b32_e32 v48, 16, v53
	v_and_b32_e32 v49, 0xffff0000, v53
	v_lshlrev_b32_e32 v50, 16, v73
	v_and_b32_e32 v51, 0xffff0000, v73
	v_add_f32_e32 v48, v48, v50
	v_add_f32_e32 v49, v49, v51
	v_add_co_u32_e32 v50, vcc, s0, v58
	s_mov_b32 s0, 0x300000
	s_nop 0
	v_addc_co_u32_e32 v51, vcc, 0, v59, vcc
	global_load_dwordx2 v[52:53], v[50:51], off nt
	v_add_co_u32_e32 v86, vcc, s0, v58
	s_nop 1
	v_addc_co_u32_e32 v87, vcc, 0, v59, vcc
	global_load_dwordx2 v[60:61], v[86:87], off nt
	s_waitcnt vmcnt(1)
	v_lshlrev_b32_e32 v70, 16, v52
	v_and_b32_e32 v71, 0xffff0000, v52
	v_lshlrev_b32_e32 v72, 16, v53
	v_and_b32_e32 v73, 0xffff0000, v53
	global_load_dwordx2 v[52:53], v[50:51], off offset:512 nt
	v_add_f32_e32 v64, v64, v72
	v_add_f32_e32 v65, v65, v73
	global_load_dwordx2 v[72:73], v[86:87], off offset:512 nt
	s_waitcnt vmcnt(2)
	v_lshlrev_b32_e32 v58, 16, v60
	v_and_b32_e32 v59, 0xffff0000, v60
	v_lshlrev_b32_e32 v60, 16, v61
	v_and_b32_e32 v61, 0xffff0000, v61
	v_add_f32_e32 v62, v62, v70
	v_add_f32_e32 v63, v63, v71
	v_add_f32_e32 v64, v64, v60
	v_add_f32_e32 v65, v65, v61
	s_waitcnt vmcnt(1)
	v_lshlrev_b32_e32 v74, 16, v52
	v_and_b32_e32 v75, 0xffff0000, v52
	v_lshlrev_b32_e32 v76, 16, v53
	v_and_b32_e32 v77, 0xffff0000, v53
	global_load_dwordx2 v[52:53], v[50:51], off offset:1024 nt
	v_add_f32_e32 v68, v68, v76
	v_add_f32_e32 v69, v69, v77
	global_load_dwordx2 v[76:77], v[86:87], off offset:1024 nt
	s_waitcnt vmcnt(2)
	v_lshlrev_b32_e32 v70, 16, v72
	global_load_dwordx2 v[50:51], v[50:51], off offset:1536 nt
	v_and_b32_e32 v71, 0xffff0000, v72
	v_lshlrev_b32_e32 v72, 16, v73
	v_and_b32_e32 v73, 0xffff0000, v73
	v_add_f32_e32 v66, v66, v74
	v_add_f32_e32 v67, v67, v75
	s_waitcnt vmcnt(2)
	v_lshlrev_b32_e32 v78, 16, v52
	v_and_b32_e32 v79, 0xffff0000, v52
	v_add_f32_e32 v54, v54, v78
	v_add_f32_e32 v55, v55, v79
	global_load_dwordx2 v[78:79], v[86:87], off offset:1536 nt
	v_lshlrev_b32_e32 v84, 16, v53
	v_and_b32_e32 v85, 0xffff0000, v53
	s_waitcnt vmcnt(1)
	v_lshlrev_b32_e32 v52, 16, v50
	v_and_b32_e32 v53, 0xffff0000, v50
	v_lshlrev_b32_e32 v50, 16, v51
	v_and_b32_e32 v51, 0xffff0000, v51
	v_lshlrev_b32_e32 v74, 16, v76
	v_and_b32_e32 v75, 0xffff0000, v76
	v_lshlrev_b32_e32 v76, 16, v77
	v_and_b32_e32 v77, 0xffff0000, v77
	v_add_f32_e32 v56, v56, v84
	v_add_f32_e32 v57, v57, v85
	v_add_f32_e32 v52, v46, v52
	v_add_f32_e32 v53, v47, v53
	v_add_f32_e32 v86, v48, v50
	v_add_f32_e32 v87, v49, v51
	v_add_f32_e32 v50, v62, v58
	v_add_f32_e32 v51, v63, v59
	v_add_f32_e32 v48, v66, v70
	v_add_f32_e32 v49, v67, v71
	v_add_f32_e32 v62, v68, v72
	v_add_f32_e32 v63, v69, v73
	v_add_f32_e32 v46, v54, v74
	v_add_f32_e32 v47, v55, v75
	v_add_f32_e32 v58, v56, v76
	v_add_f32_e32 v59, v57, v77
	s_waitcnt vmcnt(0)
	v_lshlrev_b32_e32 v84, 16, v78
	v_and_b32_e32 v85, 0xffff0000, v78
	v_lshlrev_b32_e32 v78, 16, v79
	v_and_b32_e32 v79, 0xffff0000, v79
	v_add_f32_e32 v52, v52, v84
	v_add_f32_e32 v53, v53, v85
	v_add_f32_e32 v54, v86, v78
	v_add_f32_e32 v55, v87, v79
.LBB0_34:
	s_or_b64 exec, exec, s[2:3]
	v_min_i32_e32 v41, 0x4000, v40
	v_readlane_b32 s0, v255, 30
	v_ashrrev_i32_e32 v41, 13, v41
	v_readlane_b32 s1, v255, 31
	s_mul_i32 s0, s0, 3
	v_add_u32_e32 v60, s0, v41
	v_readlane_b32 s0, v255, 6
	v_readlane_b32 s1, v255, 7
	v_mov_b32_e32 v66, v49
	v_mov_b32_e32 v67, v51
	v_mov_b64_e32 v[56:57], s[0:1]
	s_movk_i32 s0, 0x6000
	v_mad_i64_i32 v[56:57], s[0:1], v60, s0, v[56:57]
	s_mov_b64 s[0:1], 0x5000
	s_nop 0
	v_lshl_add_u64 v[60:61], v[56:57], 0, s[0:1]
	v_mov_b32_e32 v56, v48
	v_mov_b32_e32 v57, v50
	v_mul_f32_e32 v56, v56, v56
	v_mul_f32_e32 v57, v57, v57
	v_mov_b32_e32 v68, v53
	v_fma_f32 v56, v66, v66, v56
	v_fma_f32 v57, v67, v67, v57
	v_mov_b32_e32 v66, v62
	v_mov_b32_e32 v67, v64
	v_fma_f32 v56, v66, v66, v56
	v_fma_f32 v57, v67, v67, v57
	v_mov_b32_e32 v66, v63
	v_mov_b32_e32 v67, v65
	v_fma_f32 v56, v66, v66, v56
	v_fma_f32 v57, v67, v67, v57
	v_mov_b32_e32 v66, v52
	v_mov_b32_e32 v67, v46
	v_mul_f32_e32 v66, v66, v66
	v_mul_f32_e32 v67, v67, v67
	v_mov_b32_e32 v69, v47
	v_fma_f32 v66, v68, v68, v66
	v_fma_f32 v67, v69, v69, v67
	v_mov_b32_e32 v68, v54
	v_mov_b32_e32 v69, v58
	v_fma_f32 v66, v68, v68, v66
	v_fma_f32 v67, v69, v69, v67
	v_mov_b32_e32 v68, v55
	v_mov_b32_e32 v69, v59
	v_fma_f32 v66, v68, v68, v66
	v_fma_f32 v67, v69, v69, v67
	v_add_f32_e32 v56, v56, v57
	v_add_f32_e32 v56, v67, v56
	v_lshl_add_u64 v[70:71], v[60:61], 0, v[0:1]
	v_add_f32_e32 v56, v66, v56
	global_load_dwordx4 v[66:69], v[22:23], off
	s_nop 0
	global_load_dwordx4 v[70:73], v[70:71], off
	ds_bpermute_b32 v57, v27, v56
	s_waitcnt lgkmcnt(0)
	v_add_f32_e32 v56, v56, v57
	ds_bpermute_b32 v57, v29, v56
	s_waitcnt lgkmcnt(0)
	v_add_f32_e32 v56, v56, v57
	ds_bpermute_b32 v57, v80, v56
	s_waitcnt lgkmcnt(0)
	v_add_f32_e32 v56, v56, v57
	ds_bpermute_b32 v57, v81, v56
	s_waitcnt lgkmcnt(0)
	v_add_f32_e32 v56, v56, v57
	ds_bpermute_b32 v57, v82, v56
	s_waitcnt lgkmcnt(0)
	v_add_f32_e32 v56, v56, v57
	ds_bpermute_b32 v57, v83, v56
	s_waitcnt lgkmcnt(0)
	v_add_f32_e32 v56, v56, v57
	v_fmamk_f32 v56, v56, 0x3a800000, v201
	v_cmp_gt_f32_e32 vcc, s66, v56
	v_mul_f32_e32 v57, 0x4b800000, v56
	s_nop 0
	v_cndmask_b32_e32 v56, v56, v57, vcc
	v_rsq_f32_e32 v56, v56
	s_nop 0
	v_mul_f32_e32 v57, 0x45800000, v56
	v_cndmask_b32_e32 v56, v56, v57, vcc
	v_mul_f32_e32 v50, v50, v56
	v_mul_f32_e32 v51, v51, v56
	v_mul_f32_e32 v48, v48, v56
	v_mul_f32_e32 v49, v49, v56
	v_mul_f32_e32 v46, v46, v56
	v_mul_f32_e32 v47, v47, v56
	v_mul_f32_e32 v52, v52, v56
	v_mul_f32_e32 v53, v53, v56
	s_andn2_b64 vcc, exec, s[40:41]
	s_waitcnt vmcnt(1)
	v_mul_f32_e32 v50, v66, v50
	v_mul_f32_e32 v51, v67, v51
	s_waitcnt vmcnt(0)
	v_fma_f32 v14, v70, v50, v14
	v_fma_f32 v15, v71, v51, v15
	v_mul_f32_e32 v50, v64, v56
	v_mul_f32_e32 v51, v65, v56
	s_nop 0
	v_mul_f32_e32 v50, v68, v50
	v_mul_f32_e32 v51, v69, v51
	s_nop 0
	v_fma_f32 v16, v72, v50, v16
	v_fma_f32 v17, v73, v51, v17
	v_lshlrev_b32_e32 v50, 2, v24
	v_mov_b32_e32 v51, v1
	v_lshl_add_u64 v[68:69], v[60:61], 0, v[50:51]
	global_load_dwordx4 v[64:67], v[22:23], off offset:1024
	s_nop 0
	global_load_dwordx4 v[68:71], v[68:69], off
	s_waitcnt vmcnt(1)
	v_mul_f32_e32 v48, v64, v48
	v_mul_f32_e32 v49, v65, v49
	s_waitcnt vmcnt(0)
	v_fma_f32 v10, v68, v48, v10
	v_fma_f32 v11, v69, v49, v11
	v_mul_f32_e32 v48, v62, v56
	v_mul_f32_e32 v49, v63, v56
	s_nop 0
	v_mul_f32_e32 v48, v66, v48
	v_mul_f32_e32 v49, v67, v49
	s_nop 0
	v_fma_f32 v12, v48, v70, v12
	v_fma_f32 v13, v49, v71, v13
	v_lshlrev_b32_e32 v48, 2, v26
	v_mov_b32_e32 v49, v1
	v_lshl_add_u64 v[66:67], v[60:61], 0, v[48:49]
	global_load_dwordx4 v[62:65], v[22:23], off offset:2048
	s_nop 0
	global_load_dwordx4 v[66:69], v[66:67], off
	s_waitcnt vmcnt(1)
	v_mul_f32_e32 v46, v46, v62
	v_mul_f32_e32 v47, v47, v63
	s_waitcnt vmcnt(0)
	v_fma_f32 v6, v46, v66, v6
	v_fma_f32 v7, v47, v67, v7
	v_mul_f32_e32 v46, v58, v56
	v_mul_f32_e32 v47, v59, v56
	s_nop 0
	v_mul_f32_e32 v46, v46, v64
	v_mul_f32_e32 v47, v47, v65
	s_nop 0
	v_fma_f32 v8, v46, v68, v8
	v_fma_f32 v9, v47, v69, v9
	v_lshlrev_b32_e32 v46, 2, v28
	v_mov_b32_e32 v47, v1
	v_lshl_add_u64 v[62:63], v[60:61], 0, v[46:47]
	global_load_dwordx4 v[58:61], v[22:23], off offset:3072
	s_nop 0
	global_load_dwordx4 v[62:65], v[62:63], off
	s_waitcnt vmcnt(1)
	v_mul_f32_e32 v52, v52, v58
	v_mul_f32_e32 v53, v53, v59
	s_waitcnt vmcnt(0)
	v_fma_f32 v2, v52, v62, v2
	v_fma_f32 v3, v53, v63, v3
	v_mul_f32_e32 v52, v54, v56
	v_mul_f32_e32 v53, v55, v56
	s_nop 0
	v_mul_f32_e32 v52, v52, v60
	v_mul_f32_e32 v53, v53, v61
	s_nop 0
	v_fma_f32 v4, v52, v64, v4
	v_fma_f32 v5, v53, v65, v5
	global_store_dwordx4 v[44:45], v[14:17], off
	global_store_dwordx4 v[44:45], v[10:13], off offset:1024
	global_store_dwordx4 v[44:45], v[6:9], off offset:2048
	global_store_dwordx4 v[44:45], v[2:5], off offset:3072
	s_cbranch_vccnz .LBB0_29
	v_add_u32_e32 v41, 3, v41
	v_readlane_b32 s0, v255, 6
	v_mul_hi_i32_i24_e32 v45, 0x6000, v41
	v_mul_i32_i24_e32 v44, 0x6000, v41
	v_readlane_b32 s1, v255, 7
	v_mov_b32_e32 v56, v15
	v_mov_b32_e32 v57, v11
	v_lshl_add_u64 v[52:53], s[0:1], 0, v[44:45]
	v_mov_b32_e32 v44, v14
	v_mov_b32_e32 v45, v10
	v_mul_f32_e32 v56, v56, v56
	v_mul_f32_e32 v57, v57, v57
	v_mov_b32_e32 v58, v7
	v_fma_f32 v44, v44, v44, v56
	v_fma_f32 v45, v45, v45, v57
	v_mov_b32_e32 v56, v16
	v_mov_b32_e32 v57, v12
	v_fma_f32 v44, v56, v56, v44
	v_fma_f32 v45, v57, v57, v45
	v_mov_b32_e32 v56, v17
	v_mov_b32_e32 v57, v13
	v_mov_b32_e32 v59, v3
	v_fma_f32 v44, v56, v56, v44
	v_fma_f32 v45, v57, v57, v45
	v_mov_b32_e32 v56, v6
	v_mov_b32_e32 v57, v2
	v_mul_f32_e32 v58, v58, v58
	v_mul_f32_e32 v59, v59, v59
	v_lshl_add_u64 v[54:55], v[52:53], 0, s[22:23]
	v_fma_f32 v56, v56, v56, v58
	v_fma_f32 v57, v57, v57, v59
	v_mov_b32_e32 v58, v8
	v_mov_b32_e32 v59, v4
	v_fma_f32 v56, v58, v58, v56
	v_fma_f32 v57, v59, v59, v57
	v_mov_b32_e32 v58, v9
	v_mov_b32_e32 v59, v5
	v_fma_f32 v56, v58, v58, v56
	v_fma_f32 v57, v59, v59, v57
	v_add_f32_e32 v41, v44, v45
	v_add_f32_e32 v41, v41, v56
	v_lshl_add_u64 v[60:61], v[54:55], 0, v[0:1]
	v_add_f32_e32 v41, v41, v57
	v_lshl_add_u64 v[52:53], v[52:53], 0, v[0:1]
	global_load_dwordx4 v[56:59], v[30:31], off
	s_nop 0
	global_load_dwordx4 v[60:63], v[60:61], off
	s_nop 0
	global_load_dwordx4 v[64:67], v[52:53], off
	ds_bpermute_b32 v44, v27, v41
	v_lshl_add_u64 v[42:43], v[38:39], 0, v[42:43]
	v_lshl_add_u64 v[50:51], v[54:55], 0, v[50:51]
	s_waitcnt lgkmcnt(0)
	v_add_f32_e32 v41, v41, v44
	ds_bpermute_b32 v44, v29, v41
	s_waitcnt lgkmcnt(0)
	v_add_f32_e32 v41, v41, v44
	ds_bpermute_b32 v44, v80, v41
	s_waitcnt lgkmcnt(0)
	v_add_f32_e32 v41, v41, v44
	ds_bpermute_b32 v44, v81, v41
	s_waitcnt lgkmcnt(0)
	v_add_f32_e32 v41, v41, v44
	ds_bpermute_b32 v44, v82, v41
	s_waitcnt lgkmcnt(0)
	v_add_f32_e32 v41, v41, v44
	ds_bpermute_b32 v44, v83, v41
	s_waitcnt lgkmcnt(0)
	v_add_f32_e32 v41, v41, v44
	v_fmamk_f32 v41, v41, 0x3a800000, v201
	v_cmp_gt_f32_e32 vcc, s66, v41
	v_mul_f32_e32 v44, 0x4b800000, v41
	s_nop 0
	v_cndmask_b32_e32 v41, v41, v44, vcc
	v_rsq_f32_e32 v41, v41
	s_nop 0
	v_mul_f32_e32 v44, 0x45800000, v41
	v_cndmask_b32_e32 v44, v41, v44, vcc
	v_mul_f32_e32 v14, v14, v44
	v_mul_f32_e32 v15, v15, v44
	v_mul_f32_e32 v16, v16, v44
	v_mul_f32_e32 v17, v17, v44
	v_mul_f32_e32 v10, v10, v44
	v_mul_f32_e32 v11, v11, v44
	v_mul_f32_e32 v12, v12, v44
	v_mul_f32_e32 v13, v13, v44
	v_mul_f32_e32 v6, v6, v44
	v_mul_f32_e32 v7, v7, v44
	v_mul_f32_e32 v8, v8, v44
	v_mul_f32_e32 v9, v9, v44
	v_mul_f32_e32 v2, v2, v44
	v_mul_f32_e32 v3, v3, v44
	v_mul_f32_e32 v4, v4, v44
	v_mul_f32_e32 v5, v5, v44
	s_waitcnt vmcnt(2)
	v_mul_f32_e32 v14, v56, v14
	v_mul_f32_e32 v15, v57, v15
	s_waitcnt vmcnt(1)
	v_add_f32_e32 v56, 1.0, v60
	v_add_f32_e32 v57, 1.0, v61
	v_mul_f32_e32 v16, v58, v16
	v_mul_f32_e32 v17, v59, v17
	s_waitcnt vmcnt(0)
	v_fma_f32 v14, v56, v14, v64
	v_fma_f32 v15, v57, v15, v65
	v_add_f32_e32 v56, 1.0, v62
	v_add_f32_e32 v57, 1.0, v63
	v_cvt_pk_bf16_f32 v14, v14, v15
	v_fma_f32 v16, v56, v16, v66
	v_fma_f32 v17, v57, v17, v67
	s_nop 0
	v_cvt_pk_bf16_f32 v15, v16, v17
	global_store_dwordx2 v[42:43], v[14:15], off
	global_load_dwordx4 v[14:17], v[32:33], off
	s_nop 0
	global_load_dwordx4 v[56:59], v[50:51], off
	global_load_dwordx4 v[60:63], v[52:53], off offset:1024
	s_waitcnt vmcnt(2)
	v_mul_f32_e32 v10, v10, v14
	v_mul_f32_e32 v11, v11, v15
	s_waitcnt vmcnt(1)
	v_add_f32_e32 v14, 1.0, v56
	v_add_f32_e32 v15, 1.0, v57
	v_mul_f32_e32 v12, v12, v16
	v_mul_f32_e32 v13, v13, v17
	s_waitcnt vmcnt(0)
	v_fma_f32 v10, v10, v14, v60
	v_fma_f32 v11, v11, v15, v61
	v_add_f32_e32 v14, 1.0, v58
	v_add_f32_e32 v15, 1.0, v59
	v_cvt_pk_bf16_f32 v10, v10, v11
	v_fma_f32 v12, v12, v14, v62
	v_fma_f32 v13, v13, v15, v63
	v_lshl_add_u64 v[14:15], v[54:55], 0, v[48:49]
	v_cvt_pk_bf16_f32 v11, v12, v13
	global_store_dwordx2 v[42:43], v[10:11], off offset:512
	global_load_dwordx4 v[10:13], v[34:35], off
	s_nop 0
	global_load_dwordx4 v[14:17], v[14:15], off
	s_nop 0
	global_load_dwordx4 v[48:51], v[52:53], off offset:2048
	s_waitcnt vmcnt(2)
	v_mul_f32_e32 v6, v6, v10
	v_mul_f32_e32 v7, v7, v11
	s_waitcnt vmcnt(1)
	v_add_f32_e32 v10, 1.0, v14
	v_add_f32_e32 v11, 1.0, v15
	v_mul_f32_e32 v8, v8, v12
	v_mul_f32_e32 v9, v9, v13
	s_waitcnt vmcnt(0)
	v_fma_f32 v6, v6, v10, v48
	v_fma_f32 v7, v7, v11, v49
	v_add_f32_e32 v10, 1.0, v16
	v_add_f32_e32 v11, 1.0, v17
	v_cvt_pk_bf16_f32 v6, v6, v7
	v_fma_f32 v8, v8, v10, v50
	v_fma_f32 v9, v9, v11, v51
	v_lshl_add_u64 v[10:11], v[54:55], 0, v[46:47]
	v_cvt_pk_bf16_f32 v7, v8, v9
	global_store_dwordx2 v[42:43], v[6:7], off offset:1024
	global_load_dwordx4 v[6:9], v[36:37], off
	s_nop 0
	global_load_dwordx4 v[10:13], v[10:11], off
	s_nop 0
	global_load_dwordx4 v[14:17], v[52:53], off offset:3072
	s_waitcnt vmcnt(2)
	v_mul_f32_e32 v2, v2, v6
	v_mul_f32_e32 v3, v3, v7
	s_waitcnt vmcnt(1)
	v_add_f32_e32 v6, 1.0, v10
	v_add_f32_e32 v7, 1.0, v11
	v_mul_f32_e32 v4, v4, v8
	v_mul_f32_e32 v5, v5, v9
	s_waitcnt vmcnt(0)
	v_fma_f32 v2, v2, v6, v14
	v_fma_f32 v3, v3, v7, v15
	v_add_f32_e32 v6, 1.0, v12
	v_add_f32_e32 v7, 1.0, v13
	v_cvt_pk_bf16_f32 v2, v2, v3
	v_fma_f32 v4, v4, v6, v16
	v_fma_f32 v5, v5, v7, v17
	s_nop 0
	v_cvt_pk_bf16_f32 v3, v4, v5
	global_store_dwordx2 v[42:43], v[2:3], off offset:1536
	s_branch .LBB0_29

.LBB0_45:
	s_bfe_u32 s2, s10, 0x20008
	s_and_b32 s3, s1, 3
	s_mul_i32 s2, s2, 0x160000
	s_mulk_i32 s3, 0x580
	s_or_b32 s96, s2, s3
	s_and_b32 s2, s0, 0xffffff00
	v_mov_b32_e32 v0, s3
	v_add_u32_e32 v2, s2, v182
	s_and_b32 s17, s14, 3
	v_mad_i64_i32 v[2:3], s[2:3], v2, s5, v[0:1]
	s_mul_i32 s15, s17, 0x580
	s_add_u32 s2, s40, s15
	s_addc_u32 s3, s41, 0
	s_add_u32 s18, s44, s15
	s_addc_u32 s19, s45, 0
	s_lshl_b32 s16, s14, 6
	s_lshl_b32 s15, s14, 4
	s_and_b32 s16, s16, 0x300
	v_lshl_add_u64 v[178:179], v[170:171], 0, v[2:3]
	s_and_b32 s15, s15, 0xffffff00
	v_add_u32_e32 v4, s16, v180
	v_mov_b64_e32 v[2:3], s[18:19]
	s_addk_i32 s15, 0x4000
	v_mad_i64_i32 v[2:3], s[18:19], v4, s5, v[2:3]
	v_mov_b32_e32 v175, v1
	v_add_u32_e32 v0, s15, v180
	v_lshl_add_u64 v[34:35], v[2:3], 0, v[174:175]
	v_mov_b64_e32 v[2:3], s[2:3]
	v_mad_i64_i32 v[2:3], s[2:3], v0, s5, v[2:3]
	v_lshl_add_u64 v[36:37], v[2:3], 0, v[174:175]
	s_mov_b32 s2, 0x58000
	v_add_co_u32_e32 v38, vcc, s2, v36
	s_mov_b32 s3, 0xb0000
	s_nop 0
	v_addc_co_u32_e32 v39, vcc, 0, v37, vcc
	v_add_co_u32_e32 v40, vcc, s3, v36
	s_mov_b32 s4, 0x108000
	s_nop 0
	v_addc_co_u32_e32 v41, vcc, 0, v37, vcc
	v_add_co_u32_e32 v42, vcc, s4, v36
	v_addc_co_u32_e32 v43, vcc, 0, v37, vcc
	v_add_co_u32_e32 v44, vcc, s2, v34
	v_lshl_add_u64 v[176:177], v[168:169], 0, s[96:97]
	s_nop 0
	v_addc_co_u32_e32 v45, vcc, 0, v35, vcc
	v_add_co_u32_e32 v46, vcc, s3, v34
	s_nop 0
	v_addc_co_u32_e32 v47, vcc, 0, v35, vcc
	v_add_co_u32_e32 v48, vcc, s4, v34
	s_nop 0
	v_addc_co_u32_e32 v49, vcc, 0, v35, vcc
	s_mov_b32 s18, 1
	s_mov_b64 s[2:3], 0
	s_mov_b32 s4, 0x22c5000
	s_mov_b32 s12, 0x231d000
	s_mov_b32 s13, 0x2375000
	v_mov_b32_e32 v2, 0
	v_mov_b32_e32 v3, v2
	v_mov_b32_e32 v4, v2
	v_mov_b32_e32 v5, v2
	v_mov_b32_e32 v6, v2
	v_mov_b32_e32 v7, v2
	v_mov_b32_e32 v8, v2
	v_mov_b32_e32 v9, v2
	v_mov_b32_e32 v10, v2
	v_mov_b32_e32 v11, v2
	v_mov_b32_e32 v12, v2
	v_mov_b32_e32 v13, v2
	v_mov_b32_e32 v14, v2
	v_mov_b32_e32 v15, v2
	v_mov_b32_e32 v16, v2
	v_mov_b32_e32 v17, v2
	v_mov_b32_e32 v34, v2
	v_mov_b32_e32 v35, v2
	v_mov_b32_e32 v36, v2
	v_mov_b32_e32 v37, v2
	v_mov_b32_e32 v38, v2
	v_mov_b32_e32 v39, v2
	v_mov_b32_e32 v40, v2
	v_mov_b32_e32 v41, v2
	v_mov_b32_e32 v42, v2
	v_mov_b32_e32 v43, v2
	v_mov_b32_e32 v44, v2
	v_mov_b32_e32 v45, v2
	v_mov_b32_e32 v46, v2
	v_mov_b32_e32 v47, v2
	v_mov_b32_e32 v48, v2
	v_mov_b32_e32 v49, v2
	v_mov_b32_e32 v18, v2
	v_mov_b32_e32 v19, v2
	v_mov_b32_e32 v20, v2
	v_mov_b32_e32 v21, v2
	v_mov_b32_e32 v22, v2
	v_mov_b32_e32 v23, v2
	v_mov_b32_e32 v24, v2
	v_mov_b32_e32 v25, v2
	v_mov_b32_e32 v26, v2
	v_mov_b32_e32 v27, v2
	v_mov_b32_e32 v28, v2
	v_mov_b32_e32 v29, v2
	v_mov_b32_e32 v30, v2
	v_mov_b32_e32 v31, v2
	v_mov_b32_e32 v32, v2
	v_mov_b32_e32 v33, v2
	v_mov_b32_e32 v50, v2
	v_mov_b32_e32 v51, v2
	v_mov_b32_e32 v52, v2
	v_mov_b32_e32 v53, v2
	v_mov_b32_e32 v54, v2
	v_mov_b32_e32 v55, v2
	v_mov_b32_e32 v56, v2
	v_mov_b32_e32 v57, v2
	v_mov_b32_e32 v58, v2
	v_mov_b32_e32 v59, v2
	v_mov_b32_e32 v60, v2
	v_mov_b32_e32 v61, v2
	v_mov_b32_e32 v62, v2
	v_mov_b32_e32 v63, v2
	v_mov_b32_e32 v64, v2
	v_mov_b32_e32 v65, v2
	v_mov_b32_e32 v66, v2
	v_mov_b32_e32 v67, v2
	v_mov_b32_e32 v68, v2
	v_mov_b32_e32 v69, v2
	v_mov_b32_e32 v70, v2
	v_mov_b32_e32 v71, v2
	v_mov_b32_e32 v72, v2
	v_mov_b32_e32 v73, v2
	v_mov_b32_e32 v74, v2
	v_mov_b32_e32 v75, v2
	v_mov_b32_e32 v76, v2
	v_mov_b32_e32 v77, v2
	v_mov_b32_e32 v78, v2
	v_mov_b32_e32 v79, v2
	v_mov_b32_e32 v80, v2
	v_mov_b32_e32 v81, v2
	v_mov_b32_e32 v98, v2
	v_mov_b32_e32 v99, v2
	v_mov_b32_e32 v100, v2
	v_mov_b32_e32 v101, v2
	v_mov_b32_e32 v102, v2
	v_mov_b32_e32 v103, v2
	v_mov_b32_e32 v104, v2
	v_mov_b32_e32 v105, v2
	v_mov_b32_e32 v106, v2
	v_mov_b32_e32 v107, v2
	v_mov_b32_e32 v108, v2
	v_mov_b32_e32 v109, v2
	v_mov_b32_e32 v110, v2
	v_mov_b32_e32 v111, v2
	v_mov_b32_e32 v112, v2
	v_mov_b32_e32 v113, v2
	v_mov_b32_e32 v82, v2
	v_mov_b32_e32 v83, v2
	v_mov_b32_e32 v84, v2
	v_mov_b32_e32 v85, v2
	v_mov_b32_e32 v86, v2
	v_mov_b32_e32 v87, v2
	v_mov_b32_e32 v88, v2
	v_mov_b32_e32 v89, v2
	v_mov_b32_e32 v90, v2
	v_mov_b32_e32 v91, v2
	v_mov_b32_e32 v92, v2
	v_mov_b32_e32 v93, v2
	v_mov_b32_e32 v94, v2
	v_mov_b32_e32 v95, v2
	v_mov_b32_e32 v96, v2
	v_mov_b32_e32 v97, v2
	v_mov_b32_e32 v114, v2
	v_mov_b32_e32 v115, v2
	v_mov_b32_e32 v116, v2
	v_mov_b32_e32 v117, v2
	v_mov_b32_e32 v118, v2
	v_mov_b32_e32 v119, v2
	v_mov_b32_e32 v120, v2
	v_mov_b32_e32 v121, v2
	v_mov_b32_e32 v122, v2
	v_mov_b32_e32 v123, v2
	v_mov_b32_e32 v124, v2
	v_mov_b32_e32 v125, v2
	v_mov_b32_e32 v126, v2
	v_mov_b32_e32 v127, v2
	v_mov_b32_e32 v128, v2
	v_mov_b32_e32 v129, v2
	s_waitcnt lgkmcnt(0)
	v_lshrrev_b32_e32 v130, 6, v200
	v_and_b32_e32 v131, 63, v200
	v_readfirstlane_b32 s19, v130
	s_lshr_b32 s4, s19, 2
	s_lshl_b32 s4, s4, 7
	s_and_b32 s96, s19, 3
	s_lshl_b32 s96, s96, 4
	s_add_u32 s4, s4, s96
	s_add_u32 s96, s4, s15
	s_mul_i32 s96, s96, 5632
	s_add_u32 s2, s40, s96
	s_addc_u32 s3, s41, 0
	s_mul_i32 s96, s17, 0x580
	s_add_u32 s2, s2, s96
	s_addc_u32 s3, s3, 0
	s_lshl_b32 s4, s4, 7
	s_lshr_b32 s18, s19, 1
	s_lshl_b32 s18, s18, 6
	s_and_b32 s96, s19, 1
	s_lshl_b32 s96, s96, 4
	s_add_u32 s18, s18, s96
	s_add_u32 s96, s18, s16
	s_mul_i32 s96, s96, 5632
	s_add_u32 s12, s44, s96
	s_addc_u32 s13, s45, 0
	s_mul_i32 s96, s17, 0x580
	s_add_u32 s12, s12, s96
	s_addc_u32 s13, s13, 0
	s_lshl_b32 s18, s18, 7
	s_add_u32 s18, s18, 0x10000
	v_lshrrev_b32_e32 v132, 3, v131
	v_and_b32_e32 v133, 7, v131
	v_lshrrev_b32_e32 v134, 4, v131
	v_xor_b32_e32 v133, v133, v134
	v_lshlrev_b32_e32 v133, 4, v133
	v_mul_u32_u24_e32 v134, 5632, v132
	v_or_b32_e32 v226, v134, v133
	v_add_u32_e32 v227, 45056, v226
	v_xor_b32_e32 v227, 64, v227
	v_add_u32_e32 v178, 0x58000, v226
	v_add_u32_e32 v179, 0x58000, v227
	v_mul_u32_u24_e32 v134, 5632, v132
	v_or_b32_e32 v228, v134, v133
	v_add_u32_e32 v214, 45056, v228
	v_xor_b32_e32 v214, 64, v214
	v_add_u32_e32 v203, 0x2c000, v228
	v_add_u32_e32 v204, 0x2c000, v214
	v_and_b32_e32 v132, 31, v131
	v_lshrrev_b32_e32 v133, 5, v131
	v_bfe_u32 v134, v132, 1, 3
	v_and_b32_e32 v135, 1, v134
	v_xor_b32_e32 v133, v133, v135
	v_lshlrev_b32_e32 v133, 4, v133
	v_lshl_add_u32 v133, v132, 7, v133
	v_and_b32_e32 v134, 6, v134
	s_lshr_b32 s96, s19, 2
	s_lshl_b32 s96, s96, 14
	v_xor_b32_e32 v135, 0, v134
	v_lshl_add_u32 v135, v135, 4, v133
	v_add_u32_e32 v246, s96, v135
	v_xor_b32_e32 v135, 2, v134
	v_lshl_add_u32 v135, v135, 4, v133
	v_add_u32_e32 v247, s96, v135
	v_xor_b32_e32 v135, 4, v134
	v_lshl_add_u32 v135, v135, 4, v133
	v_add_u32_e32 v248, s96, v135
	v_xor_b32_e32 v135, 6, v134
	v_lshl_add_u32 v135, v135, 4, v133
	v_add_u32_e32 v249, s96, v135
	s_and_b32 s96, s19, 3
	s_lshl_b32 s96, s96, 13
	s_add_u32 s96, s96, 0x10000
	v_xor_b32_e32 v135, 0, v134
	v_lshl_add_u32 v135, v135, 4, v133
	v_add_u32_e32 v250, s96, v135
	v_xor_b32_e32 v135, 2, v134
	v_lshl_add_u32 v135, v135, 4, v133
	v_add_u32_e32 v251, s96, v135
	v_xor_b32_e32 v135, 4, v134
	v_lshl_add_u32 v135, v135, 4, v133
	v_add_u32_e32 v252, s96, v135
	v_xor_b32_e32 v135, 6, v134
	v_lshl_add_u32 v135, v135, 4, v133
	v_add_u32_e32 v233, s96, v135
	s_add_u32 m0, s18, 0x0
	s_nop 0
	global_load_lds_dwordx4 v228, s[12:13]
	s_add_u32 m0, s18, 0x400
	s_nop 0
	global_load_lds_dwordx4 v214, s[12:13]
	s_add_u32 m0, s4, 0x0
	s_nop 0
	global_load_lds_dwordx4 v226, s[2:3]
	s_add_u32 m0, s4, 0x400
	s_nop 0
	global_load_lds_dwordx4 v227, s[2:3]
	s_add_u32 m0, s18, 0x1000
	s_nop 0
	global_load_lds_dwordx4 v203, s[12:13]
	s_add_u32 m0, s18, 0x1400
	s_nop 0
	global_load_lds_dwordx4 v204, s[12:13]
	s_add_u32 m0, s4, 0x2000
	s_nop 0
	global_load_lds_dwordx4 v178, s[2:3]
	s_add_u32 m0, s4, 0x2400
	s_nop 0
	global_load_lds_dwordx4 v179, s[2:3]
	v_readfirstlane_b32 s96, v200
	s_lshr_b32 s96, s96, 8
	s_cmp_lg_u32 s96, 0
	s_cbranch_scc0 .Lgds_nolag
	s_barrier
.Lgds_nolag:
	s_waitcnt vmcnt(4)
	s_barrier
	s_add_u32 s12, s12, 0x80
	s_addc_u32 s13, s13, 0
	s_add_u32 m0, s18, 0x8000
	s_nop 0
	global_load_lds_dwordx4 v228, s[12:13]
	s_add_u32 m0, s18, 0x8400
	s_nop 0
	global_load_lds_dwordx4 v214, s[12:13]
	s_add_u32 s2, s2, 0x80
	s_addc_u32 s3, s3, 0
	s_add_u32 m0, s4, 0x8000
	s_nop 0
	global_load_lds_dwordx4 v226, s[2:3]
	s_add_u32 m0, s4, 0x8400
	s_nop 0
	global_load_lds_dwordx4 v227, s[2:3]
	s_add_u32 m0, s18, 0x9000
	s_nop 0
	global_load_lds_dwordx4 v203, s[12:13]
	s_add_u32 m0, s18, 0x9400
	s_nop 0
	global_load_lds_dwordx4 v204, s[12:13]
	s_waitcnt vmcnt(6)
	s_barrier
	s_mov_b32 s19, 0
.Lgds_loop:
	ds_read_b128 v[192:195], v250
	ds_read_b128 v[196:199], v251
	ds_read_b128 v[208:211], v252
	ds_read_b128 v[218:221], v233
	ds_read_b128 v[130:133], v246 offset:0
	ds_read_b128 v[134:137], v247 offset:0
	ds_read_b128 v[138:141], v248 offset:0
	ds_read_b128 v[142:145], v249 offset:0
	ds_read_b128 v[146:149], v246 offset:4096
	ds_read_b128 v[150:153], v247 offset:4096
	ds_read_b128 v[154:157], v248 offset:4096
	ds_read_b128 v[158:161], v249 offset:4096
	s_add_u32 m0, s4, 0xa000
	s_nop 0
	global_load_lds_dwordx4 v178, s[2:3]
	s_add_u32 m0, s4, 0xa400
	s_nop 0
	global_load_lds_dwordx4 v179, s[2:3]
	s_waitcnt lgkmcnt(8)
	s_barrier
	s_waitcnt lgkmcnt(0)
	s_setprio 1
	v_mfma_f32_32x32x16_bf16 v[114:129], v[192:195], v[130:133], v[114:129]
	v_mfma_f32_32x32x16_bf16 v[82:97], v[192:195], v[146:149], v[82:97]
	v_mfma_f32_32x32x16_bf16 v[114:129], v[196:199], v[134:137], v[114:129]
	v_mfma_f32_32x32x16_bf16 v[82:97], v[196:199], v[150:153], v[82:97]
	v_mfma_f32_32x32x16_bf16 v[114:129], v[208:211], v[138:141], v[114:129]
	v_mfma_f32_32x32x16_bf16 v[82:97], v[208:211], v[154:157], v[82:97]
	v_mfma_f32_32x32x16_bf16 v[114:129], v[218:221], v[142:145], v[114:129]
	v_mfma_f32_32x32x16_bf16 v[82:97], v[218:221], v[158:161], v[82:97]
	s_setprio 0
	s_barrier
	ds_read_b128 v[222:225], v250 offset:4096
	ds_read_b128 v[234:237], v251 offset:4096
	ds_read_b128 v[238:241], v252 offset:4096
	ds_read_b128 v[242:245], v233 offset:4096
	s_add_u32 s12, s12, 0x80
	s_addc_u32 s13, s13, 0
	s_add_u32 m0, s18, 0x0
	s_nop 0
	global_load_lds_dwordx4 v228, s[12:13]
	s_add_u32 m0, s18, 0x400
	s_nop 0
	global_load_lds_dwordx4 v214, s[12:13]
	s_barrier
	s_waitcnt lgkmcnt(0)
	s_setprio 1
	v_mfma_f32_32x32x16_bf16 v[98:113], v[222:225], v[130:133], v[98:113]
	v_mfma_f32_32x32x16_bf16 v[66:81], v[222:225], v[146:149], v[66:81]
	v_mfma_f32_32x32x16_bf16 v[98:113], v[234:237], v[134:137], v[98:113]
	v_mfma_f32_32x32x16_bf16 v[66:81], v[234:237], v[150:153], v[66:81]
	v_mfma_f32_32x32x16_bf16 v[98:113], v[238:241], v[138:141], v[98:113]
	v_mfma_f32_32x32x16_bf16 v[66:81], v[238:241], v[154:157], v[66:81]
	v_mfma_f32_32x32x16_bf16 v[98:113], v[242:245], v[142:145], v[98:113]
	v_mfma_f32_32x32x16_bf16 v[66:81], v[242:245], v[158:161], v[66:81]
	s_setprio 0
	s_barrier
	ds_read_b128 v[130:133], v246 offset:8192
	ds_read_b128 v[134:137], v247 offset:8192
	ds_read_b128 v[138:141], v248 offset:8192
	ds_read_b128 v[142:145], v249 offset:8192
	ds_read_b128 v[146:149], v246 offset:12288
	ds_read_b128 v[150:153], v247 offset:12288
	ds_read_b128 v[154:157], v248 offset:12288
	ds_read_b128 v[158:161], v249 offset:12288
	s_add_u32 s2, s2, 0x80
	s_addc_u32 s3, s3, 0
	s_add_u32 m0, s4, 0x0
	s_nop 0
	global_load_lds_dwordx4 v226, s[2:3]
	s_add_u32 m0, s4, 0x400
	s_nop 0
	global_load_lds_dwordx4 v227, s[2:3]
	s_barrier
	s_waitcnt lgkmcnt(0)
	s_setprio 1
	v_mfma_f32_32x32x16_bf16 v[50:65], v[192:195], v[130:133], v[50:65]
	v_mfma_f32_32x32x16_bf16 v[18:33], v[192:195], v[146:149], v[18:33]
	v_mfma_f32_32x32x16_bf16 v[50:65], v[196:199], v[134:137], v[50:65]
	v_mfma_f32_32x32x16_bf16 v[18:33], v[196:199], v[150:153], v[18:33]
	v_mfma_f32_32x32x16_bf16 v[50:65], v[208:211], v[138:141], v[50:65]
	v_mfma_f32_32x32x16_bf16 v[18:33], v[208:211], v[154:157], v[18:33]
	v_mfma_f32_32x32x16_bf16 v[50:65], v[218:221], v[142:145], v[50:65]
	v_mfma_f32_32x32x16_bf16 v[18:33], v[218:221], v[158:161], v[18:33]
	s_setprio 0
	s_barrier
	s_add_u32 m0, s18, 0x1000
	s_nop 0
	global_load_lds_dwordx4 v203, s[12:13]
	s_add_u32 m0, s18, 0x1400
	s_nop 0
	global_load_lds_dwordx4 v204, s[12:13]
	s_waitcnt vmcnt(6)
	s_barrier
	s_setprio 1
	v_mfma_f32_32x32x16_bf16 v[34:49], v[222:225], v[130:133], v[34:49]
	v_mfma_f32_32x32x16_bf16 v[2:17], v[222:225], v[146:149], v[2:17]
	v_mfma_f32_32x32x16_bf16 v[34:49], v[234:237], v[134:137], v[34:49]
	v_mfma_f32_32x32x16_bf16 v[2:17], v[234:237], v[150:153], v[2:17]
	v_mfma_f32_32x32x16_bf16 v[34:49], v[238:241], v[138:141], v[34:49]
	v_mfma_f32_32x32x16_bf16 v[2:17], v[238:241], v[154:157], v[2:17]
	v_mfma_f32_32x32x16_bf16 v[34:49], v[242:245], v[142:145], v[34:49]
	v_mfma_f32_32x32x16_bf16 v[2:17], v[242:245], v[158:161], v[2:17]
	s_setprio 0
	s_barrier
	ds_read_b128 v[192:195], v250 offset:32768
	ds_read_b128 v[196:199], v251 offset:32768
	ds_read_b128 v[208:211], v252 offset:32768
	ds_read_b128 v[218:221], v233 offset:32768
	ds_read_b128 v[130:133], v246 offset:32768
	ds_read_b128 v[134:137], v247 offset:32768
	ds_read_b128 v[138:141], v248 offset:32768
	ds_read_b128 v[142:145], v249 offset:32768
	ds_read_b128 v[146:149], v246 offset:36864
	ds_read_b128 v[150:153], v247 offset:36864
	ds_read_b128 v[154:157], v248 offset:36864
	ds_read_b128 v[158:161], v249 offset:36864
	s_add_u32 m0, s4, 0x2000
	s_nop 0
	global_load_lds_dwordx4 v178, s[2:3]
	s_add_u32 m0, s4, 0x2400
	s_nop 0
	global_load_lds_dwordx4 v179, s[2:3]
	s_waitcnt lgkmcnt(8)
	s_barrier
	s_waitcnt lgkmcnt(0)
	s_setprio 1
	v_mfma_f32_32x32x16_bf16 v[114:129], v[192:195], v[130:133], v[114:129]
	v_mfma_f32_32x32x16_bf16 v[82:97], v[192:195], v[146:149], v[82:97]
	v_mfma_f32_32x32x16_bf16 v[114:129], v[196:199], v[134:137], v[114:129]
	v_mfma_f32_32x32x16_bf16 v[82:97], v[196:199], v[150:153], v[82:97]
	v_mfma_f32_32x32x16_bf16 v[114:129], v[208:211], v[138:141], v[114:129]
	v_mfma_f32_32x32x16_bf16 v[82:97], v[208:211], v[154:157], v[82:97]
	v_mfma_f32_32x32x16_bf16 v[114:129], v[218:221], v[142:145], v[114:129]
	v_mfma_f32_32x32x16_bf16 v[82:97], v[218:221], v[158:161], v[82:97]
	s_setprio 0
	s_barrier
	ds_read_b128 v[222:225], v250 offset:36864
	ds_read_b128 v[234:237], v251 offset:36864
	ds_read_b128 v[238:241], v252 offset:36864
	ds_read_b128 v[242:245], v233 offset:36864
	s_add_u32 s12, s12, 0x80
	s_addc_u32 s13, s13, 0
	s_add_u32 m0, s18, 0x8000
	s_nop 0
	global_load_lds_dwordx4 v228, s[12:13]
	s_add_u32 m0, s18, 0x8400
	s_nop 0
	global_load_lds_dwordx4 v214, s[12:13]
	s_barrier
	s_waitcnt lgkmcnt(0)
	s_setprio 1
	v_mfma_f32_32x32x16_bf16 v[98:113], v[222:225], v[130:133], v[98:113]
	v_mfma_f32_32x32x16_bf16 v[66:81], v[222:225], v[146:149], v[66:81]
	v_mfma_f32_32x32x16_bf16 v[98:113], v[234:237], v[134:137], v[98:113]
	v_mfma_f32_32x32x16_bf16 v[66:81], v[234:237], v[150:153], v[66:81]
	v_mfma_f32_32x32x16_bf16 v[98:113], v[238:241], v[138:141], v[98:113]
	v_mfma_f32_32x32x16_bf16 v[66:81], v[238:241], v[154:157], v[66:81]
	v_mfma_f32_32x32x16_bf16 v[98:113], v[242:245], v[142:145], v[98:113]
	v_mfma_f32_32x32x16_bf16 v[66:81], v[242:245], v[158:161], v[66:81]
	s_setprio 0
	s_barrier
	ds_read_b128 v[130:133], v246 offset:40960
	ds_read_b128 v[134:137], v247 offset:40960
	ds_read_b128 v[138:141], v248 offset:40960
	ds_read_b128 v[142:145], v249 offset:40960
	ds_read_b128 v[146:149], v246 offset:45056
	ds_read_b128 v[150:153], v247 offset:45056
	ds_read_b128 v[154:157], v248 offset:45056
	ds_read_b128 v[158:161], v249 offset:45056
	s_add_u32 s2, s2, 0x80
	s_addc_u32 s3, s3, 0
	s_add_u32 m0, s4, 0x8000
	s_nop 0
	global_load_lds_dwordx4 v226, s[2:3]
	s_add_u32 m0, s4, 0x8400
	s_nop 0
	global_load_lds_dwordx4 v227, s[2:3]
	s_barrier
	s_waitcnt lgkmcnt(0)
	s_setprio 1
	v_mfma_f32_32x32x16_bf16 v[50:65], v[192:195], v[130:133], v[50:65]
	v_mfma_f32_32x32x16_bf16 v[18:33], v[192:195], v[146:149], v[18:33]
	v_mfma_f32_32x32x16_bf16 v[50:65], v[196:199], v[134:137], v[50:65]
	v_mfma_f32_32x32x16_bf16 v[18:33], v[196:199], v[150:153], v[18:33]
	v_mfma_f32_32x32x16_bf16 v[50:65], v[208:211], v[138:141], v[50:65]
	v_mfma_f32_32x32x16_bf16 v[18:33], v[208:211], v[154:157], v[18:33]
	v_mfma_f32_32x32x16_bf16 v[50:65], v[218:221], v[142:145], v[50:65]
	v_mfma_f32_32x32x16_bf16 v[18:33], v[218:221], v[158:161], v[18:33]
	s_setprio 0
	s_barrier
	s_add_u32 m0, s18, 0x9000
	s_nop 0
	global_load_lds_dwordx4 v203, s[12:13]
	s_add_u32 m0, s18, 0x9400
	s_nop 0
	global_load_lds_dwordx4 v204, s[12:13]
	s_waitcnt vmcnt(6)
	s_barrier
	s_setprio 1
	v_mfma_f32_32x32x16_bf16 v[34:49], v[222:225], v[130:133], v[34:49]
	v_mfma_f32_32x32x16_bf16 v[2:17], v[222:225], v[146:149], v[2:17]
	v_mfma_f32_32x32x16_bf16 v[34:49], v[234:237], v[134:137], v[34:49]
	v_mfma_f32_32x32x16_bf16 v[2:17], v[234:237], v[150:153], v[2:17]
	v_mfma_f32_32x32x16_bf16 v[34:49], v[238:241], v[138:141], v[34:49]
	v_mfma_f32_32x32x16_bf16 v[2:17], v[238:241], v[154:157], v[2:17]
	v_mfma_f32_32x32x16_bf16 v[34:49], v[242:245], v[142:145], v[34:49]
	v_mfma_f32_32x32x16_bf16 v[2:17], v[242:245], v[158:161], v[2:17]
	s_setprio 0
	s_barrier
	s_add_i32 s19, s19, 2
	s_cmp_lt_u32 s19, 8
	s_cbranch_scc1 .Lgds_loop
	ds_read_b128 v[192:195], v250
	ds_read_b128 v[196:199], v251
	ds_read_b128 v[208:211], v252
	ds_read_b128 v[218:221], v233
	ds_read_b128 v[130:133], v246 offset:0
	ds_read_b128 v[134:137], v247 offset:0
	ds_read_b128 v[138:141], v248 offset:0
	ds_read_b128 v[142:145], v249 offset:0
	ds_read_b128 v[146:149], v246 offset:4096
	ds_read_b128 v[150:153], v247 offset:4096
	ds_read_b128 v[154:157], v248 offset:4096
	ds_read_b128 v[158:161], v249 offset:4096
	s_add_u32 m0, s4, 0xa000
	s_nop 0
	global_load_lds_dwordx4 v178, s[2:3]
	s_add_u32 m0, s4, 0xa400
	s_nop 0
	global_load_lds_dwordx4 v179, s[2:3]
	s_waitcnt lgkmcnt(8)
	s_barrier
	s_waitcnt lgkmcnt(0)
	s_setprio 1
	v_mfma_f32_32x32x16_bf16 v[114:129], v[192:195], v[130:133], v[114:129]
	v_mfma_f32_32x32x16_bf16 v[82:97], v[192:195], v[146:149], v[82:97]
	v_mfma_f32_32x32x16_bf16 v[114:129], v[196:199], v[134:137], v[114:129]
	v_mfma_f32_32x32x16_bf16 v[82:97], v[196:199], v[150:153], v[82:97]
	v_mfma_f32_32x32x16_bf16 v[114:129], v[208:211], v[138:141], v[114:129]
	v_mfma_f32_32x32x16_bf16 v[82:97], v[208:211], v[154:157], v[82:97]
	v_mfma_f32_32x32x16_bf16 v[114:129], v[218:221], v[142:145], v[114:129]
	v_mfma_f32_32x32x16_bf16 v[82:97], v[218:221], v[158:161], v[82:97]
	s_setprio 0
	s_barrier
	ds_read_b128 v[222:225], v250 offset:4096
	ds_read_b128 v[234:237], v251 offset:4096
	ds_read_b128 v[238:241], v252 offset:4096
	ds_read_b128 v[242:245], v233 offset:4096
	s_add_u32 s12, s12, 0x80
	s_addc_u32 s13, s13, 0
	s_add_u32 m0, s18, 0x0
	s_nop 0
	global_load_lds_dwordx4 v228, s[12:13]
	s_add_u32 m0, s18, 0x400
	s_nop 0
	global_load_lds_dwordx4 v214, s[12:13]
	s_barrier
	s_waitcnt lgkmcnt(0)
	s_setprio 1
	v_mfma_f32_32x32x16_bf16 v[98:113], v[222:225], v[130:133], v[98:113]
	v_mfma_f32_32x32x16_bf16 v[66:81], v[222:225], v[146:149], v[66:81]
	v_mfma_f32_32x32x16_bf16 v[98:113], v[234:237], v[134:137], v[98:113]
	v_mfma_f32_32x32x16_bf16 v[66:81], v[234:237], v[150:153], v[66:81]
	v_mfma_f32_32x32x16_bf16 v[98:113], v[238:241], v[138:141], v[98:113]
	v_mfma_f32_32x32x16_bf16 v[66:81], v[238:241], v[154:157], v[66:81]
	v_mfma_f32_32x32x16_bf16 v[98:113], v[242:245], v[142:145], v[98:113]
	v_mfma_f32_32x32x16_bf16 v[66:81], v[242:245], v[158:161], v[66:81]
	s_setprio 0
	s_barrier
	ds_read_b128 v[130:133], v246 offset:8192
	ds_read_b128 v[134:137], v247 offset:8192
	ds_read_b128 v[138:141], v248 offset:8192
	ds_read_b128 v[142:145], v249 offset:8192
	ds_read_b128 v[146:149], v246 offset:12288
	ds_read_b128 v[150:153], v247 offset:12288
	ds_read_b128 v[154:157], v248 offset:12288
	ds_read_b128 v[158:161], v249 offset:12288
	s_add_u32 s2, s2, 0x80
	s_addc_u32 s3, s3, 0
	s_add_u32 m0, s4, 0x0
	s_nop 0
	global_load_lds_dwordx4 v226, s[2:3]
	s_add_u32 m0, s4, 0x400
	s_nop 0
	global_load_lds_dwordx4 v227, s[2:3]
	s_barrier
	s_waitcnt lgkmcnt(0)
	s_setprio 1
	v_mfma_f32_32x32x16_bf16 v[50:65], v[192:195], v[130:133], v[50:65]
	v_mfma_f32_32x32x16_bf16 v[18:33], v[192:195], v[146:149], v[18:33]
	v_mfma_f32_32x32x16_bf16 v[50:65], v[196:199], v[134:137], v[50:65]
	v_mfma_f32_32x32x16_bf16 v[18:33], v[196:199], v[150:153], v[18:33]
	v_mfma_f32_32x32x16_bf16 v[50:65], v[208:211], v[138:141], v[50:65]
	v_mfma_f32_32x32x16_bf16 v[18:33], v[208:211], v[154:157], v[18:33]
	v_mfma_f32_32x32x16_bf16 v[50:65], v[218:221], v[142:145], v[50:65]
	v_mfma_f32_32x32x16_bf16 v[18:33], v[218:221], v[158:161], v[18:33]
	s_setprio 0
	s_barrier
	s_add_u32 m0, s18, 0x1000
	s_nop 0
	global_load_lds_dwordx4 v203, s[12:13]
	s_add_u32 m0, s18, 0x1400
	s_nop 0
	global_load_lds_dwordx4 v204, s[12:13]
	s_waitcnt vmcnt(6)
	s_barrier
	s_setprio 1
	v_mfma_f32_32x32x16_bf16 v[34:49], v[222:225], v[130:133], v[34:49]
	v_mfma_f32_32x32x16_bf16 v[2:17], v[222:225], v[146:149], v[2:17]
	v_mfma_f32_32x32x16_bf16 v[34:49], v[234:237], v[134:137], v[34:49]
	v_mfma_f32_32x32x16_bf16 v[2:17], v[234:237], v[150:153], v[2:17]
	v_mfma_f32_32x32x16_bf16 v[34:49], v[238:241], v[138:141], v[34:49]
	v_mfma_f32_32x32x16_bf16 v[2:17], v[238:241], v[154:157], v[2:17]
	v_mfma_f32_32x32x16_bf16 v[34:49], v[242:245], v[142:145], v[34:49]
	v_mfma_f32_32x32x16_bf16 v[2:17], v[242:245], v[158:161], v[2:17]
	s_setprio 0
	s_barrier
	ds_read_b128 v[192:195], v250 offset:32768
	ds_read_b128 v[196:199], v251 offset:32768
	ds_read_b128 v[208:211], v252 offset:32768
	ds_read_b128 v[218:221], v233 offset:32768
	ds_read_b128 v[130:133], v246 offset:32768
	ds_read_b128 v[134:137], v247 offset:32768
	ds_read_b128 v[138:141], v248 offset:32768
	ds_read_b128 v[142:145], v249 offset:32768
	ds_read_b128 v[146:149], v246 offset:36864
	ds_read_b128 v[150:153], v247 offset:36864
	ds_read_b128 v[154:157], v248 offset:36864
	ds_read_b128 v[158:161], v249 offset:36864
	s_add_u32 m0, s4, 0x2000
	s_nop 0
	global_load_lds_dwordx4 v178, s[2:3]
	s_add_u32 m0, s4, 0x2400
	s_nop 0
	global_load_lds_dwordx4 v179, s[2:3]
	s_waitcnt lgkmcnt(8)
	s_barrier
	s_waitcnt lgkmcnt(0)
	s_setprio 1
	v_mfma_f32_32x32x16_bf16 v[114:129], v[192:195], v[130:133], v[114:129]
	v_mfma_f32_32x32x16_bf16 v[82:97], v[192:195], v[146:149], v[82:97]
	v_mfma_f32_32x32x16_bf16 v[114:129], v[196:199], v[134:137], v[114:129]
	v_mfma_f32_32x32x16_bf16 v[82:97], v[196:199], v[150:153], v[82:97]
	v_mfma_f32_32x32x16_bf16 v[114:129], v[208:211], v[138:141], v[114:129]
	v_mfma_f32_32x32x16_bf16 v[82:97], v[208:211], v[154:157], v[82:97]
	v_mfma_f32_32x32x16_bf16 v[114:129], v[218:221], v[142:145], v[114:129]
	v_mfma_f32_32x32x16_bf16 v[82:97], v[218:221], v[158:161], v[82:97]
	s_setprio 0
	s_barrier
	ds_read_b128 v[222:225], v250 offset:36864
	ds_read_b128 v[234:237], v251 offset:36864
	ds_read_b128 v[238:241], v252 offset:36864
	ds_read_b128 v[242:245], v233 offset:36864
	s_barrier
	s_waitcnt lgkmcnt(0)
	s_setprio 1
	v_mfma_f32_32x32x16_bf16 v[98:113], v[222:225], v[130:133], v[98:113]
	v_mfma_f32_32x32x16_bf16 v[66:81], v[222:225], v[146:149], v[66:81]
	v_mfma_f32_32x32x16_bf16 v[98:113], v[234:237], v[134:137], v[98:113]
	v_mfma_f32_32x32x16_bf16 v[66:81], v[234:237], v[150:153], v[66:81]
	v_mfma_f32_32x32x16_bf16 v[98:113], v[238:241], v[138:141], v[98:113]
	v_mfma_f32_32x32x16_bf16 v[66:81], v[238:241], v[154:157], v[66:81]
	v_mfma_f32_32x32x16_bf16 v[98:113], v[242:245], v[142:145], v[98:113]
	v_mfma_f32_32x32x16_bf16 v[66:81], v[242:245], v[158:161], v[66:81]
	s_setprio 0
	s_barrier
	ds_read_b128 v[130:133], v246 offset:40960
	ds_read_b128 v[134:137], v247 offset:40960
	ds_read_b128 v[138:141], v248 offset:40960
	ds_read_b128 v[142:145], v249 offset:40960
	ds_read_b128 v[146:149], v246 offset:45056
	ds_read_b128 v[150:153], v247 offset:45056
	ds_read_b128 v[154:157], v248 offset:45056
	ds_read_b128 v[158:161], v249 offset:45056
	s_barrier
	s_waitcnt lgkmcnt(0)
	s_setprio 1
	v_mfma_f32_32x32x16_bf16 v[50:65], v[192:195], v[130:133], v[50:65]
	v_mfma_f32_32x32x16_bf16 v[18:33], v[192:195], v[146:149], v[18:33]
	v_mfma_f32_32x32x16_bf16 v[50:65], v[196:199], v[134:137], v[50:65]
	v_mfma_f32_32x32x16_bf16 v[18:33], v[196:199], v[150:153], v[18:33]
	v_mfma_f32_32x32x16_bf16 v[50:65], v[208:211], v[138:141], v[50:65]
	v_mfma_f32_32x32x16_bf16 v[18:33], v[208:211], v[154:157], v[18:33]
	v_mfma_f32_32x32x16_bf16 v[50:65], v[218:221], v[142:145], v[50:65]
	v_mfma_f32_32x32x16_bf16 v[18:33], v[218:221], v[158:161], v[18:33]
	s_setprio 0
	s_barrier
	s_waitcnt vmcnt(0)
	s_barrier
	s_setprio 1
	v_mfma_f32_32x32x16_bf16 v[34:49], v[222:225], v[130:133], v[34:49]
	v_mfma_f32_32x32x16_bf16 v[2:17], v[222:225], v[146:149], v[2:17]
	v_mfma_f32_32x32x16_bf16 v[34:49], v[234:237], v[134:137], v[34:49]
	v_mfma_f32_32x32x16_bf16 v[2:17], v[234:237], v[150:153], v[2:17]
	v_mfma_f32_32x32x16_bf16 v[34:49], v[238:241], v[138:141], v[34:49]
	v_mfma_f32_32x32x16_bf16 v[2:17], v[238:241], v[154:157], v[2:17]
	v_mfma_f32_32x32x16_bf16 v[34:49], v[242:245], v[142:145], v[34:49]
	v_mfma_f32_32x32x16_bf16 v[2:17], v[242:245], v[158:161], v[2:17]
	s_setprio 0
	s_barrier
	ds_read_b128 v[192:195], v250
	ds_read_b128 v[196:199], v251
	ds_read_b128 v[208:211], v252
	ds_read_b128 v[218:221], v233
	ds_read_b128 v[130:133], v246 offset:0
	ds_read_b128 v[134:137], v247 offset:0
	ds_read_b128 v[138:141], v248 offset:0
	ds_read_b128 v[142:145], v249 offset:0
	ds_read_b128 v[146:149], v246 offset:4096
	ds_read_b128 v[150:153], v247 offset:4096
	ds_read_b128 v[154:157], v248 offset:4096
	ds_read_b128 v[158:161], v249 offset:4096
	s_barrier
	s_waitcnt lgkmcnt(0)
	s_setprio 1
	v_mfma_f32_32x32x16_bf16 v[114:129], v[192:195], v[130:133], v[114:129]
	v_mfma_f32_32x32x16_bf16 v[82:97], v[192:195], v[146:149], v[82:97]
	v_mfma_f32_32x32x16_bf16 v[114:129], v[196:199], v[134:137], v[114:129]
	v_mfma_f32_32x32x16_bf16 v[82:97], v[196:199], v[150:153], v[82:97]
	v_mfma_f32_32x32x16_bf16 v[114:129], v[208:211], v[138:141], v[114:129]
	v_mfma_f32_32x32x16_bf16 v[82:97], v[208:211], v[154:157], v[82:97]
	v_mfma_f32_32x32x16_bf16 v[114:129], v[218:221], v[142:145], v[114:129]
	v_mfma_f32_32x32x16_bf16 v[82:97], v[218:221], v[158:161], v[82:97]
	s_setprio 0
	s_barrier
	ds_read_b128 v[222:225], v250 offset:4096
	ds_read_b128 v[234:237], v251 offset:4096
	ds_read_b128 v[238:241], v252 offset:4096
	ds_read_b128 v[242:245], v233 offset:4096
	s_barrier
	s_waitcnt lgkmcnt(0)
	s_setprio 1
	v_mfma_f32_32x32x16_bf16 v[98:113], v[222:225], v[130:133], v[98:113]
	v_mfma_f32_32x32x16_bf16 v[66:81], v[222:225], v[146:149], v[66:81]
	v_mfma_f32_32x32x16_bf16 v[98:113], v[234:237], v[134:137], v[98:113]
	v_mfma_f32_32x32x16_bf16 v[66:81], v[234:237], v[150:153], v[66:81]
	v_mfma_f32_32x32x16_bf16 v[98:113], v[238:241], v[138:141], v[98:113]
	v_mfma_f32_32x32x16_bf16 v[66:81], v[238:241], v[154:157], v[66:81]
	v_mfma_f32_32x32x16_bf16 v[98:113], v[242:245], v[142:145], v[98:113]
	v_mfma_f32_32x32x16_bf16 v[66:81], v[242:245], v[158:161], v[66:81]
	s_setprio 0
	s_barrier
	ds_read_b128 v[130:133], v246 offset:8192
	ds_read_b128 v[134:137], v247 offset:8192
	ds_read_b128 v[138:141], v248 offset:8192
	ds_read_b128 v[142:145], v249 offset:8192
	ds_read_b128 v[146:149], v246 offset:12288
	ds_read_b128 v[150:153], v247 offset:12288
	ds_read_b128 v[154:157], v248 offset:12288
	ds_read_b128 v[158:161], v249 offset:12288
	s_barrier
	s_waitcnt lgkmcnt(0)
	s_setprio 1
	v_mfma_f32_32x32x16_bf16 v[50:65], v[192:195], v[130:133], v[50:65]
	v_mfma_f32_32x32x16_bf16 v[18:33], v[192:195], v[146:149], v[18:33]
	v_mfma_f32_32x32x16_bf16 v[50:65], v[196:199], v[134:137], v[50:65]
	v_mfma_f32_32x32x16_bf16 v[18:33], v[196:199], v[150:153], v[18:33]
	v_mfma_f32_32x32x16_bf16 v[50:65], v[208:211], v[138:141], v[50:65]
	v_mfma_f32_32x32x16_bf16 v[18:33], v[208:211], v[154:157], v[18:33]
	v_mfma_f32_32x32x16_bf16 v[50:65], v[218:221], v[142:145], v[50:65]
	v_mfma_f32_32x32x16_bf16 v[18:33], v[218:221], v[158:161], v[18:33]
	s_setprio 0
	s_setprio 1
	v_mfma_f32_32x32x16_bf16 v[34:49], v[222:225], v[130:133], v[34:49]
	v_mfma_f32_32x32x16_bf16 v[2:17], v[222:225], v[146:149], v[2:17]
	v_mfma_f32_32x32x16_bf16 v[34:49], v[234:237], v[134:137], v[34:49]
	v_mfma_f32_32x32x16_bf16 v[2:17], v[234:237], v[150:153], v[2:17]
	v_mfma_f32_32x32x16_bf16 v[34:49], v[238:241], v[138:141], v[34:49]
	v_mfma_f32_32x32x16_bf16 v[2:17], v[238:241], v[154:157], v[2:17]
	v_mfma_f32_32x32x16_bf16 v[34:49], v[242:245], v[142:145], v[34:49]
	v_mfma_f32_32x32x16_bf16 v[2:17], v[242:245], v[158:161], v[2:17]
	s_setprio 0
	s_barrier
	v_readfirstlane_b32 s96, v200
	s_lshr_b32 s96, s96, 8
	s_cmp_lg_u32 s96, 0
	s_cbranch_scc1 .Lgds_nolag2
	s_barrier
.Lgds_nolag2:
	s_nop 15
	s_nop 15
	v_add_u32_e32 v0, 0x12000, v164
	s_lshl_b32 s2, s17, 20
	s_add_u32 s2, s36, s2
	s_addc_u32 s3, s37, 0
	s_add_u32 s2, s2, 0xbdcd800
	s_addc_u32 s3, s3, 0
	v_or_b32_e32 v0, s16, v167
	v_lshlrev_b32_e32 v0, 1, v0
	v_mov_b32_e32 v173, v1
	s_add_i32 s14, s14, s46
	s_add_i32 s1, s1, s46
	s_nop 7
	v_cvt_pk_bf16_f32 v114, v114, v115
	v_add_u32_e32 v130, s15, v181
	v_ashrrev_i32_e32 v131, 31, v130
	v_lshlrev_b64 v[132:133], 11, v[130:131]
	v_lshl_add_u64 v[132:133], s[2:3], 0, v[132:133]
	v_lshl_add_u64 v[132:133], v[132:133], 0, v[0:1]
	v_lshl_add_u64 v[132:133], v[132:133], 0, v[172:173]
	v_cvt_pk_bf16_f32 v115, v116, v117
	s_nop 4
	v_cvt_pk_bf16_f32 v98, v98, v99
	v_cvt_pk_bf16_f32 v99, v100, v101
	global_store_dwordx2 v[132:133], v[98:99], off offset:64
	v_cvt_pk_bf16_f32 v98, v102, v103
	v_cvt_pk_bf16_f32 v99, v104, v105
	global_store_dwordx2 v[132:133], v[98:99], off offset:80
	v_cvt_pk_bf16_f32 v98, v106, v107
	v_cvt_pk_bf16_f32 v99, v108, v109
	global_store_dwordx2 v[132:133], v[98:99], off offset:96
	v_cvt_pk_bf16_f32 v98, v110, v111
	v_cvt_pk_bf16_f32 v99, v112, v113
	global_store_dwordx2 v[132:133], v[98:99], off offset:112
	v_or_b32_e32 v98, 32, v130
	v_ashrrev_i32_e32 v99, 31, v98
	v_lshlrev_b64 v[98:99], 11, v[98:99]
	v_lshl_add_u64 v[98:99], s[2:3], 0, v[98:99]
	v_lshl_add_u64 v[98:99], v[98:99], 0, v[0:1]
	v_lshl_add_u64 v[98:99], v[98:99], 0, v[172:173]
	v_cvt_pk_bf16_f32 v66, v66, v67
	v_cvt_pk_bf16_f32 v67, v68, v69
	global_store_dwordx2 v[98:99], v[66:67], off offset:64
	v_cvt_pk_bf16_f32 v66, v70, v71
	v_cvt_pk_bf16_f32 v67, v72, v73
	global_store_dwordx2 v[98:99], v[66:67], off offset:80
	v_cvt_pk_bf16_f32 v66, v74, v75
	v_cvt_pk_bf16_f32 v67, v76, v77
	global_store_dwordx2 v[98:99], v[66:67], off offset:96
	v_cvt_pk_bf16_f32 v66, v78, v79
	v_cvt_pk_bf16_f32 v67, v80, v81
	global_store_dwordx2 v[98:99], v[66:67], off offset:112
	v_or_b32_e32 v66, 64, v130
	v_ashrrev_i32_e32 v67, 31, v66
	v_lshlrev_b64 v[66:67], 11, v[66:67]
	v_lshl_add_u64 v[66:67], s[2:3], 0, v[66:67]
	v_lshl_add_u64 v[66:67], v[66:67], 0, v[0:1]
	v_lshl_add_u64 v[66:67], v[66:67], 0, v[172:173]
	v_cvt_pk_bf16_f32 v34, v34, v35
	v_cvt_pk_bf16_f32 v35, v36, v37
	global_store_dwordx2 v[66:67], v[34:35], off offset:64
	v_cvt_pk_bf16_f32 v34, v38, v39
	v_cvt_pk_bf16_f32 v35, v40, v41
	global_store_dwordx2 v[66:67], v[34:35], off offset:80
	v_cvt_pk_bf16_f32 v34, v42, v43
	v_cvt_pk_bf16_f32 v35, v44, v45
	global_store_dwordx2 v[66:67], v[34:35], off offset:96
	v_cvt_pk_bf16_f32 v34, v46, v47
	v_cvt_pk_bf16_f32 v35, v48, v49
	global_store_dwordx2 v[66:67], v[34:35], off offset:112
	v_or_b32_e32 v34, 0x60, v130
	v_ashrrev_i32_e32 v35, 31, v34
	v_lshlrev_b64 v[34:35], 11, v[34:35]
	v_lshl_add_u64 v[34:35], s[2:3], 0, v[34:35]
	v_lshl_add_u64 v[34:35], v[34:35], 0, v[0:1]
	v_cvt_pk_bf16_f32 v82, v82, v83
	v_cvt_pk_bf16_f32 v83, v84, v85
	s_nop 0
	v_cvt_pk_bf16_f32 v50, v50, v51
	v_cvt_pk_bf16_f32 v51, v52, v53
	v_lshl_add_u64 v[34:35], v[34:35], 0, v[172:173]
	v_readlane_b32 s2, v255, 28
	s_nop 2
	v_cvt_pk_bf16_f32 v18, v18, v19
	v_cvt_pk_bf16_f32 v19, v20, v21
	global_store_dwordx2 v[132:133], v[114:115], off
	v_cvt_pk_bf16_f32 v114, v118, v119
	v_cvt_pk_bf16_f32 v115, v120, v121
	global_store_dwordx2 v[98:99], v[82:83], off
	v_cvt_pk_bf16_f32 v82, v86, v87
	s_nop 1
	v_cvt_pk_bf16_f32 v2, v2, v3
	v_cvt_pk_bf16_f32 v3, v4, v5
	v_cvt_pk_bf16_f32 v83, v88, v89
	global_store_dwordx2 v[66:67], v[50:51], off
	v_cvt_pk_bf16_f32 v50, v54, v55
	v_cvt_pk_bf16_f32 v51, v56, v57
	global_store_dwordx2 v[34:35], v[18:19], off
	v_cvt_pk_bf16_f32 v18, v22, v23
	v_cvt_pk_bf16_f32 v19, v24, v25
	global_store_dwordx2 v[34:35], v[2:3], off offset:64
	v_cvt_pk_bf16_f32 v2, v6, v7
	v_cvt_pk_bf16_f32 v3, v8, v9
	s_add_i32 s10, s10, s2
	v_readlane_b32 s2, v254, 47
	global_store_dwordx2 v[132:133], v[114:115], off offset:16
	v_cvt_pk_bf16_f32 v114, v122, v123
	v_cvt_pk_bf16_f32 v115, v124, v125
	global_store_dwordx2 v[98:99], v[82:83], off offset:16
	v_cvt_pk_bf16_f32 v82, v90, v91
	v_cvt_pk_bf16_f32 v83, v92, v93
	global_store_dwordx2 v[66:67], v[50:51], off offset:16
	v_cvt_pk_bf16_f32 v50, v58, v59
	v_cvt_pk_bf16_f32 v51, v60, v61
	global_store_dwordx2 v[34:35], v[18:19], off offset:16
	v_cvt_pk_bf16_f32 v18, v26, v27
	v_cvt_pk_bf16_f32 v19, v28, v29
	global_store_dwordx2 v[34:35], v[2:3], off offset:80
	v_cvt_pk_bf16_f32 v2, v10, v11
	v_cvt_pk_bf16_f32 v3, v12, v13
	s_add_i32 s0, s0, s2
	global_store_dwordx2 v[132:133], v[114:115], off offset:32
	v_cvt_pk_bf16_f32 v114, v126, v127
	v_cvt_pk_bf16_f32 v115, v128, v129
	global_store_dwordx2 v[98:99], v[82:83], off offset:32
	v_cvt_pk_bf16_f32 v82, v94, v95
	v_cvt_pk_bf16_f32 v83, v96, v97
	global_store_dwordx2 v[66:67], v[50:51], off offset:32
	v_cvt_pk_bf16_f32 v50, v62, v63
	v_cvt_pk_bf16_f32 v51, v64, v65
	global_store_dwordx2 v[34:35], v[18:19], off offset:32
	v_cvt_pk_bf16_f32 v18, v30, v31
	v_cvt_pk_bf16_f32 v19, v32, v33
	global_store_dwordx2 v[34:35], v[2:3], off offset:96
	v_cvt_pk_bf16_f32 v2, v14, v15
	v_cvt_pk_bf16_f32 v3, v16, v17
	s_cmp_gt_i32 s14, 31
	global_store_dwordx2 v[132:133], v[114:115], off offset:48
	global_store_dwordx2 v[98:99], v[82:83], off offset:48
	global_store_dwordx2 v[66:67], v[50:51], off offset:48
	global_store_dwordx2 v[34:35], v[18:19], off offset:48
	global_store_dwordx2 v[34:35], v[2:3], off offset:112
	s_cbranch_scc0 .LBB0_45

.LBB0_60:
	s_or_b64 exec, exec, s[2:3]
	v_mov_b32_e32 v62, v56
	v_mov_b32_e32 v63, v76
	v_min_i32_e32 v0, 0x4000, v30
	v_readlane_b32 s0, v255, 30
	v_mul_f32_e32 v62, v62, v62
	v_mul_f32_e32 v63, v63, v63
	v_mov_b32_e32 v64, v57
	v_mov_b32_e32 v65, v77
	v_ashrrev_i32_e32 v0, 13, v0
	v_readlane_b32 s1, v255, 31
	s_mul_i32 s0, s0, 3
	v_fma_f32 v62, v64, v64, v62
	v_fma_f32 v63, v65, v65, v63
	v_mov_b32_e32 v64, v54
	v_mov_b32_e32 v65, v74
	v_add_u32_e32 v0, s0, v0
	v_readlane_b32 s0, v255, 6
	v_fma_f32 v62, v64, v64, v62
	v_fma_f32 v63, v65, v65, v63
	v_mov_b32_e32 v64, v55
	v_mov_b32_e32 v65, v75
	v_readlane_b32 s1, v255, 7
	v_fma_f32 v62, v64, v64, v62
	v_fma_f32 v63, v65, v65, v63
	v_mov_b32_e32 v64, v44
	v_mov_b32_e32 v65, v52
	v_mov_b64_e32 v[48:49], s[0:1]
	s_movk_i32 s0, 0x6000
	v_mul_f32_e32 v64, v64, v64
	v_mul_f32_e32 v65, v65, v65
	v_mov_b32_e32 v66, v45
	v_mov_b32_e32 v67, v53
	v_mad_i64_i32 v[48:49], s[0:1], v0, s0, v[48:49]
	v_fma_f32 v64, v66, v66, v64
	v_fma_f32 v65, v67, v67, v65
	v_mov_b32_e32 v66, v46
	v_mov_b32_e32 v67, v50
	s_mov_b64 s[0:1], 0x2000
	v_fma_f32 v64, v66, v66, v64
	v_fma_f32 v65, v67, v67, v65
	v_mov_b32_e32 v66, v47
	v_mov_b32_e32 v67, v51
	v_lshl_add_u64 v[60:61], v[48:49], 0, s[0:1]
	v_fma_f32 v64, v66, v66, v64
	v_fma_f32 v65, v67, v67, v65
	v_add_f32_e32 v0, v62, v63
	v_mov_b32_e32 v39, v1
	v_add_f32_e32 v0, v65, v0
	v_lshl_add_u64 v[62:63], v[60:61], 0, v[38:39]
	v_mov_b32_e32 v33, v1
	v_mov_b32_e32 v35, v1
	v_mov_b32_e32 v37, v1
	v_add_f32_e32 v0, v64, v0
	v_lshl_add_u64 v[66:67], v[60:61], 0, v[32:33]
	v_lshl_add_u64 v[68:69], v[60:61], 0, v[34:35]
	v_lshl_add_u64 v[70:71], v[60:61], 0, v[36:37]
	v_lshl_add_u64 v[42:43], v[42:43], 0, v[58:59]
	global_load_dwordx4 v[58:61], v[24:25], off
	s_nop 0
	global_load_dwordx4 v[62:65], v[62:63], off
	ds_bpermute_b32 v31, v78, v0
	s_mov_b32 s2, 0x800000
	v_lshl_add_u64 v[42:43], v[42:43], 0, v[38:39]
	s_mov_b64 s[0:1], 0x3000
	s_mov_b32 s66, 0x800000
	s_waitcnt lgkmcnt(0)
	v_add_f32_e32 v0, v0, v31
	ds_bpermute_b32 v31, v79, v0
	s_waitcnt lgkmcnt(0)
	v_add_f32_e32 v0, v0, v31
	ds_bpermute_b32 v31, v80, v0
	s_waitcnt lgkmcnt(0)
	v_add_f32_e32 v0, v0, v31
	ds_bpermute_b32 v31, v81, v0
	s_waitcnt lgkmcnt(0)
	v_add_f32_e32 v0, v0, v31
	ds_bpermute_b32 v31, v82, v0
	s_waitcnt lgkmcnt(0)
	v_add_f32_e32 v0, v0, v31
	ds_bpermute_b32 v31, v83, v0
	s_waitcnt lgkmcnt(0)
	v_add_f32_e32 v0, v0, v31
	v_fmamk_f32 v0, v0, 0x3a800000, v201
	v_cmp_gt_f32_e32 vcc, s2, v0
	v_mul_f32_e32 v31, 0x4b800000, v0
	s_nop 0
	v_cndmask_b32_e32 v0, v0, v31, vcc
	v_rsq_f32_e32 v0, v0
	s_nop 0
	v_mul_f32_e32 v31, 0x45800000, v0
	v_cndmask_b32_e32 v0, v0, v31, vcc
	v_mul_f32_e32 v72, v76, v0
	v_mul_f32_e32 v73, v77, v0
	v_mul_f32_e32 v56, v56, v0
	v_mul_f32_e32 v57, v57, v0
	v_mul_f32_e32 v54, v54, v0
	v_mul_f32_e32 v55, v55, v0
	v_mul_f32_e32 v52, v52, v0
	v_mul_f32_e32 v53, v53, v0
	v_mul_f32_e32 v50, v50, v0
	v_mul_f32_e32 v51, v51, v0
	v_mul_f32_e32 v44, v44, v0
	v_mul_f32_e32 v45, v45, v0
	s_waitcnt vmcnt(1)
	v_mul_f32_e32 v58, v58, v72
	v_mul_f32_e32 v59, v59, v73
	s_waitcnt vmcnt(0)
	v_fma_f32 v14, v62, v58, v14
	v_fma_f32 v15, v63, v59, v15
	v_mul_f32_e32 v58, v74, v0
	v_mul_f32_e32 v59, v75, v0
	s_nop 0
	v_mul_f32_e32 v58, v60, v58
	v_mul_f32_e32 v59, v61, v59
	s_nop 0
	v_fma_f32 v16, v64, v58, v16
	v_fma_f32 v17, v65, v59, v17
	global_load_dwordx4 v[58:61], v[24:25], off offset:1024
	global_load_dwordx4 v[62:65], v[66:67], off
	s_waitcnt vmcnt(1)
	v_mul_f32_e32 v56, v58, v56
	v_mul_f32_e32 v57, v59, v57
	v_mul_f32_e32 v54, v60, v54
	v_mul_f32_e32 v55, v61, v55
	s_waitcnt vmcnt(0)
	v_fma_f32 v10, v62, v56, v10
	v_fma_f32 v11, v63, v57, v11
	v_fma_f32 v12, v54, v64, v12
	v_fma_f32 v13, v55, v65, v13
	global_load_dwordx4 v[54:57], v[24:25], off offset:2048
	global_load_dwordx4 v[58:61], v[68:69], off
	s_waitcnt vmcnt(1)
	v_mul_f32_e32 v52, v52, v54
	v_mul_f32_e32 v53, v53, v55
	v_mul_f32_e32 v50, v50, v56
	v_mul_f32_e32 v51, v51, v57
	s_waitcnt vmcnt(0)
	v_fma_f32 v6, v52, v58, v6
	v_fma_f32 v7, v53, v59, v7
	v_fma_f32 v8, v50, v60, v8
	v_fma_f32 v9, v51, v61, v9
	global_load_dwordx4 v[50:53], v[24:25], off offset:3072
	global_load_dwordx4 v[54:57], v[70:71], off
	s_waitcnt vmcnt(1)
	v_mul_f32_e32 v44, v44, v50
	v_mul_f32_e32 v45, v45, v51
	s_waitcnt vmcnt(0)
	v_fma_f32 v2, v44, v54, v2
	v_fma_f32 v3, v45, v55, v3
	v_mul_f32_e32 v44, v46, v0
	v_mul_f32_e32 v45, v47, v0
	v_mov_b32_e32 v46, v14
	v_mul_f32_e32 v44, v44, v52
	v_mul_f32_e32 v45, v45, v53
	v_mov_b32_e32 v47, v10
	v_fma_f32 v4, v44, v56, v4
	v_fma_f32 v5, v45, v57, v5
	global_store_dwordx4 v[42:43], v[14:17], off
	global_store_dwordx4 v[42:43], v[10:13], off offset:1024
	global_store_dwordx4 v[42:43], v[6:9], off offset:2048
	global_store_dwordx4 v[42:43], v[2:5], off offset:3072
	v_lshl_add_u64 v[42:43], v[48:49], 0, s[0:1]
	v_lshl_add_u64 v[44:45], v[48:49], 0, s[28:29]
	v_mov_b32_e32 v48, v15
	v_mov_b32_e32 v49, v11
	v_mul_f32_e32 v48, v48, v48
	v_mul_f32_e32 v49, v49, v49
	v_mov_b32_e32 v50, v7
	v_fma_f32 v46, v46, v46, v48
	v_fma_f32 v47, v47, v47, v49
	v_mov_b32_e32 v48, v16
	v_mov_b32_e32 v49, v12
	v_fma_f32 v46, v48, v48, v46
	v_fma_f32 v47, v49, v49, v47
	v_mov_b32_e32 v48, v17
	v_mov_b32_e32 v49, v13
	v_mov_b32_e32 v51, v3
	v_fma_f32 v46, v48, v48, v46
	v_fma_f32 v47, v49, v49, v47
	v_mov_b32_e32 v48, v6
	v_mov_b32_e32 v49, v2
	v_mul_f32_e32 v50, v50, v50
	v_mul_f32_e32 v51, v51, v51
	v_add_f32_e32 v0, v46, v47
	v_fma_f32 v48, v48, v48, v50
	v_fma_f32 v49, v49, v49, v51
	v_mov_b32_e32 v50, v8
	v_mov_b32_e32 v51, v4
	v_fma_f32 v48, v50, v50, v48
	v_fma_f32 v49, v51, v51, v49
	v_mov_b32_e32 v50, v9
	v_mov_b32_e32 v51, v5
	v_fma_f32 v48, v50, v50, v48
	v_fma_f32 v49, v51, v51, v49
	v_lshl_add_u64 v[50:51], v[44:45], 0, v[38:39]
	v_add_f32_e32 v0, v0, v48
	v_lshl_add_u64 v[54:55], v[42:43], 0, v[38:39]
	v_add_f32_e32 v0, v0, v49
	global_load_dwordx4 v[46:49], v[26:27], off
	s_nop 0
	global_load_dwordx4 v[50:53], v[50:51], off
	s_nop 0
	global_load_dwordx4 v[54:57], v[54:55], off
	ds_bpermute_b32 v31, v78, v0
	v_lshl_add_u64 v[38:39], v[28:29], 0, v[40:41]
	v_readlane_b32 s0, v255, 8
	v_readlane_b32 s1, v255, 9
	s_waitcnt lgkmcnt(0)
	v_add_f32_e32 v0, v0, v31
	ds_bpermute_b32 v31, v79, v0
	v_add_u32_e32 v19, s0, v19
	v_subrev_u32_e32 v30, s0, v30
	s_waitcnt lgkmcnt(0)
	v_add_f32_e32 v0, v0, v31
	ds_bpermute_b32 v31, v80, v0
	s_waitcnt lgkmcnt(0)
	v_add_f32_e32 v0, v0, v31
	ds_bpermute_b32 v31, v81, v0
	s_waitcnt lgkmcnt(0)
	v_add_f32_e32 v0, v0, v31
	ds_bpermute_b32 v31, v82, v0
	s_waitcnt lgkmcnt(0)
	v_add_f32_e32 v0, v0, v31
	ds_bpermute_b32 v31, v83, v0
	s_waitcnt lgkmcnt(0)
	v_add_f32_e32 v0, v0, v31
	v_fmamk_f32 v0, v0, 0x3a800000, v201
	v_cmp_gt_f32_e32 vcc, s2, v0
	v_mul_f32_e32 v31, 0x4b800000, v0
	s_waitcnt vmcnt(1)
	v_add_f32_e32 v40, 1.0, v50
	v_add_f32_e32 v41, 1.0, v51
	v_cndmask_b32_e32 v0, v0, v31, vcc
	v_rsq_f32_e32 v0, v0
	v_lshl_add_u64 v[50:51], v[42:43], 0, v[32:33]
	v_mul_f32_e32 v31, 0x45800000, v0
	v_cndmask_b32_e32 v0, v0, v31, vcc
	v_mul_f32_e32 v14, v14, v0
	v_mul_f32_e32 v15, v15, v0
	v_mul_f32_e32 v16, v16, v0
	v_mul_f32_e32 v17, v17, v0
	v_mul_f32_e32 v14, v46, v14
	v_mul_f32_e32 v15, v47, v15
	v_mul_f32_e32 v16, v48, v16
	v_mul_f32_e32 v17, v49, v17
	s_waitcnt vmcnt(0)
	v_fma_f32 v14, v40, v14, v54
	v_fma_f32 v15, v41, v15, v55
	v_add_f32_e32 v40, 1.0, v52
	v_add_f32_e32 v41, 1.0, v53
	v_cvt_pk_bf16_f32 v14, v14, v15
	v_fma_f32 v16, v40, v16, v56
	v_fma_f32 v17, v41, v17, v57
	v_lshl_add_u64 v[40:41], v[44:45], 0, v[32:33]
	v_cvt_pk_bf16_f32 v15, v16, v17
	global_store_dwordx2 v[38:39], v[14:15], off
	global_load_dwordx4 v[14:17], v[26:27], off offset:1024
	s_nop 0
	global_load_dwordx4 v[46:49], v[40:41], off
	s_nop 0
	global_load_dwordx4 v[50:53], v[50:51], off
	v_mul_f32_e32 v10, v10, v0
	v_mul_f32_e32 v11, v11, v0
	v_mul_f32_e32 v12, v12, v0
	v_mul_f32_e32 v13, v13, v0
	v_lshl_add_u64 v[40:41], v[42:43], 0, v[34:35]
	v_mul_f32_e32 v6, v6, v0
	v_mul_f32_e32 v7, v7, v0
	v_mul_f32_e32 v8, v8, v0
	v_mul_f32_e32 v9, v9, v0
	v_mul_f32_e32 v2, v2, v0
	v_mul_f32_e32 v3, v3, v0
	v_mul_f32_e32 v4, v4, v0
	v_mul_f32_e32 v5, v5, v0
	v_cmp_le_i32_e32 vcc, s24, v19
	s_or_b64 s[44:45], vcc, s[44:45]
	s_waitcnt vmcnt(2)
	v_mul_f32_e32 v10, v10, v14
	v_mul_f32_e32 v11, v11, v15
	s_waitcnt vmcnt(1)
	v_add_f32_e32 v14, 1.0, v46
	v_add_f32_e32 v15, 1.0, v47
	v_mul_f32_e32 v12, v12, v16
	v_mul_f32_e32 v13, v13, v17
	s_waitcnt vmcnt(0)
	v_fma_f32 v10, v10, v14, v50
	v_fma_f32 v11, v11, v15, v51
	v_add_f32_e32 v14, 1.0, v48
	v_add_f32_e32 v15, 1.0, v49
	v_cvt_pk_bf16_f32 v10, v10, v11
	v_fma_f32 v12, v12, v14, v52
	v_fma_f32 v13, v13, v15, v53
	v_lshl_add_u64 v[14:15], v[44:45], 0, v[34:35]
	v_cvt_pk_bf16_f32 v11, v12, v13
	global_store_dwordx2 v[38:39], v[10:11], off offset:512
	global_load_dwordx4 v[10:13], v[26:27], off offset:2048
	s_nop 0
	global_load_dwordx4 v[14:17], v[14:15], off
	s_nop 0
	global_load_dwordx4 v[46:49], v[40:41], off
	s_waitcnt vmcnt(2)
	v_mul_f32_e32 v6, v6, v10
	v_mul_f32_e32 v7, v7, v11
	s_waitcnt vmcnt(1)
	v_add_f32_e32 v10, 1.0, v14
	v_add_f32_e32 v11, 1.0, v15
	v_mul_f32_e32 v8, v8, v12
	v_mul_f32_e32 v9, v9, v13
	s_waitcnt vmcnt(0)
	v_fma_f32 v6, v6, v10, v46
	v_fma_f32 v7, v7, v11, v47
	v_add_f32_e32 v10, 1.0, v16
	v_add_f32_e32 v11, 1.0, v17
	v_cvt_pk_bf16_f32 v6, v6, v7
	v_fma_f32 v8, v8, v10, v48
	v_fma_f32 v9, v9, v11, v49
	v_lshl_add_u64 v[10:11], v[44:45], 0, v[36:37]
	v_cvt_pk_bf16_f32 v7, v8, v9
	global_store_dwordx2 v[38:39], v[6:7], off offset:1024
	v_lshl_add_u64 v[14:15], v[42:43], 0, v[36:37]
	global_load_dwordx4 v[6:9], v[26:27], off offset:3072
	s_nop 0
	global_load_dwordx4 v[10:13], v[10:11], off
	s_nop 0
	global_load_dwordx4 v[14:17], v[14:15], off
	s_waitcnt vmcnt(2)
	v_mul_f32_e32 v2, v2, v6
	v_mul_f32_e32 v3, v3, v7
	s_waitcnt vmcnt(1)
	v_add_f32_e32 v6, 1.0, v10
	v_add_f32_e32 v7, 1.0, v11
	v_mul_f32_e32 v4, v4, v8
	v_mul_f32_e32 v5, v5, v9
	s_waitcnt vmcnt(0)
	v_fma_f32 v2, v2, v6, v14
	v_fma_f32 v3, v3, v7, v15
	v_add_f32_e32 v6, 1.0, v12
	v_add_f32_e32 v7, 1.0, v13
	v_cvt_pk_bf16_f32 v2, v2, v3
	v_fma_f32 v4, v4, v6, v16
	v_fma_f32 v5, v5, v7, v17
	s_nop 0
	v_cvt_pk_bf16_f32 v3, v4, v5
	global_store_dwordx2 v[38:39], v[2:3], off offset:1536
	s_andn2_b64 exec, exec, s[44:45]
	s_cbranch_execz .LBB0_65

.LBB0_63:
	s_andn2_saveexec_b64 s[2:3], s[2:3]
	s_cbranch_execz .LBB0_60
	v_lshlrev_b64 v[44:45], 11, v[0:1]
	v_lshl_add_u64 v[50:51], v[22:23], 0, v[44:45]
	v_add_co_u32_e32 v46, vcc, 0x100000, v50
	global_load_dwordx2 v[54:55], v[50:51], off nt
	global_load_dwordx2 v[62:63], v[50:51], off offset:512 nt
	global_load_dwordx2 v[70:71], v[50:51], off offset:1024 nt
	global_load_dwordx2 v[44:45], v[50:51], off offset:1536 nt
	v_addc_co_u32_e32 v47, vcc, 0, v51, vcc
	v_add_co_u32_e32 v48, vcc, 0x200000, v50
	global_load_dwordx2 v[56:57], v[46:47], off nt
	global_load_dwordx2 v[64:65], v[46:47], off offset:512 nt
	global_load_dwordx2 v[72:73], v[46:47], off offset:1024 nt
	s_nop 0
	global_load_dwordx2 v[46:47], v[46:47], off offset:1536 nt
	v_addc_co_u32_e32 v49, vcc, 0, v51, vcc
	v_add_co_u32_e32 v74, vcc, 0x300000, v50
	global_load_dwordx2 v[58:59], v[48:49], off nt
	global_load_dwordx2 v[66:67], v[48:49], off offset:512 nt
	global_load_dwordx2 v[76:77], v[48:49], off offset:1024 nt
	s_nop 0
	global_load_dwordx2 v[48:49], v[48:49], off offset:1536 nt
	v_addc_co_u32_e32 v75, vcc, 0, v51, vcc
	global_load_dwordx2 v[60:61], v[74:75], off nt
	global_load_dwordx2 v[68:69], v[74:75], off offset:512 nt
	global_load_dwordx2 v[84:85], v[74:75], off offset:1024 nt
	s_waitcnt vmcnt(14)
	v_lshlrev_b32_e32 v50, 16, v54
	global_load_dwordx2 v[74:75], v[74:75], off offset:1536 nt
	v_and_b32_e32 v51, 0xffff0000, v54
	v_lshlrev_b32_e32 v54, 16, v55
	v_and_b32_e32 v55, 0xffff0000, v55
	s_waitcnt vmcnt(11)
	v_lshlrev_b32_e32 v52, 16, v56
	v_and_b32_e32 v53, 0xffff0000, v56
	v_lshlrev_b32_e32 v56, 16, v57
	v_and_b32_e32 v57, 0xffff0000, v57
	v_add_f32_e32 v50, v50, v52
	v_add_f32_e32 v51, v51, v53
	s_waitcnt vmcnt(7)
	v_lshlrev_b32_e32 v52, 16, v58
	v_and_b32_e32 v53, 0xffff0000, v58
	v_add_f32_e32 v54, v54, v56
	v_add_f32_e32 v55, v55, v57
	v_lshlrev_b32_e32 v56, 16, v59
	v_and_b32_e32 v57, 0xffff0000, v59
	v_add_f32_e32 v50, v50, v52
	v_add_f32_e32 v51, v51, v53
	s_waitcnt vmcnt(3)
	v_lshlrev_b32_e32 v52, 16, v60
	v_and_b32_e32 v53, 0xffff0000, v60
	v_add_f32_e32 v54, v54, v56
	v_add_f32_e32 v55, v55, v57
	v_lshlrev_b32_e32 v56, 16, v61
	v_and_b32_e32 v57, 0xffff0000, v61
	v_lshlrev_b32_e32 v58, 16, v62
	v_and_b32_e32 v59, 0xffff0000, v62
	v_lshlrev_b32_e32 v60, 16, v64
	v_and_b32_e32 v61, 0xffff0000, v64
	v_lshlrev_b32_e32 v62, 16, v63
	v_and_b32_e32 v63, 0xffff0000, v63
	v_lshlrev_b32_e32 v64, 16, v65
	v_and_b32_e32 v65, 0xffff0000, v65
	v_add_f32_e32 v58, v58, v60
	v_add_f32_e32 v59, v59, v61
	v_lshlrev_b32_e32 v60, 16, v66
	v_and_b32_e32 v61, 0xffff0000, v66
	v_add_f32_e32 v62, v62, v64
	v_add_f32_e32 v63, v63, v65
	v_lshlrev_b32_e32 v64, 16, v67
	v_and_b32_e32 v65, 0xffff0000, v67
	v_add_f32_e32 v58, v58, v60
	v_add_f32_e32 v59, v59, v61
	s_waitcnt vmcnt(2)
	v_lshlrev_b32_e32 v60, 16, v68
	v_and_b32_e32 v61, 0xffff0000, v68
	v_add_f32_e32 v62, v62, v64
	v_add_f32_e32 v63, v63, v65
	v_lshlrev_b32_e32 v64, 16, v69
	v_and_b32_e32 v65, 0xffff0000, v69
	v_lshlrev_b32_e32 v66, 16, v70
	v_and_b32_e32 v67, 0xffff0000, v70
	v_lshlrev_b32_e32 v68, 16, v72
	v_and_b32_e32 v69, 0xffff0000, v72
	v_lshlrev_b32_e32 v70, 16, v71
	v_and_b32_e32 v71, 0xffff0000, v71
	v_lshlrev_b32_e32 v72, 16, v73
	v_and_b32_e32 v73, 0xffff0000, v73
	v_add_f32_e32 v66, v66, v68
	v_add_f32_e32 v67, v67, v69
	v_lshlrev_b32_e32 v68, 16, v76
	v_and_b32_e32 v69, 0xffff0000, v76
	v_add_f32_e32 v70, v70, v72
	v_add_f32_e32 v71, v71, v73
	v_lshlrev_b32_e32 v72, 16, v77
	v_and_b32_e32 v73, 0xffff0000, v77
	v_add_f32_e32 v66, v66, v68
	v_add_f32_e32 v67, v67, v69
	s_waitcnt vmcnt(1)
	v_lshlrev_b32_e32 v68, 16, v84
	v_and_b32_e32 v69, 0xffff0000, v84
	v_add_f32_e32 v70, v70, v72
	v_add_f32_e32 v71, v71, v73
	v_lshlrev_b32_e32 v72, 16, v85
	v_and_b32_e32 v73, 0xffff0000, v85
	v_lshlrev_b32_e32 v76, 16, v44
	v_and_b32_e32 v77, 0xffff0000, v44
	v_lshlrev_b32_e32 v84, 16, v46
	v_and_b32_e32 v85, 0xffff0000, v46
	v_lshlrev_b32_e32 v44, 16, v45
	v_and_b32_e32 v45, 0xffff0000, v45
	v_lshlrev_b32_e32 v46, 16, v47
	v_and_b32_e32 v47, 0xffff0000, v47
	v_add_f32_e32 v76, v76, v84
	v_add_f32_e32 v77, v77, v85
	v_lshlrev_b32_e32 v84, 16, v48
	v_and_b32_e32 v85, 0xffff0000, v48
	v_add_f32_e32 v44, v44, v46
	v_add_f32_e32 v45, v45, v47
	v_lshlrev_b32_e32 v46, 16, v49
	v_and_b32_e32 v47, 0xffff0000, v49
	v_add_f32_e32 v84, v76, v84
	v_add_f32_e32 v85, v77, v85
	v_add_f32_e32 v46, v44, v46
	v_add_f32_e32 v47, v45, v47
	v_add_f32_e32 v76, v50, v52
	v_add_f32_e32 v77, v51, v53
	v_add_f32_e32 v52, v66, v68
	v_add_f32_e32 v53, v67, v69
	v_add_f32_e32 v50, v70, v72
	v_add_f32_e32 v51, v71, v73
	s_waitcnt vmcnt(0)
	v_lshlrev_b32_e32 v86, 16, v74
	v_and_b32_e32 v87, 0xffff0000, v74
	v_lshlrev_b32_e32 v48, 16, v75
	v_and_b32_e32 v49, 0xffff0000, v75
	v_add_f32_e32 v74, v54, v56
	v_add_f32_e32 v75, v55, v57
	v_add_f32_e32 v56, v58, v60
	v_add_f32_e32 v57, v59, v61
	v_add_f32_e32 v54, v62, v64
	v_add_f32_e32 v55, v63, v65
	v_add_f32_e32 v44, v84, v86
	v_add_f32_e32 v45, v85, v87
	v_add_f32_e32 v46, v46, v48
	v_add_f32_e32 v47, v47, v49
	v_lshlrev_b64 v[58:59], 12, v[0:1]
	s_branch .LBB0_60

.Lb2_nofirst:
	v_exp_f32_e32 v50, v50
	v_exp_f32_e32 v51, v51
	v_exp_f32_e32 v52, v52
	v_exp_f32_e32 v53, v53
	v_exp_f32_e32 v54, v54
	v_exp_f32_e32 v55, v55
	v_exp_f32_e32 v56, v56
	v_exp_f32_e32 v57, v57
	v_cvt_pk_bf16_f32 v138, v50, v51
	v_cvt_pk_bf16_f32 v139, v52, v53
	v_cvt_pk_bf16_f32 v140, v54, v55
	v_cvt_pk_bf16_f32 v141, v56, v57
	v_exp_f32_e32 v58, v58
	v_exp_f32_e32 v59, v59
	s_waitcnt lgkmcnt(0)
	v_mfma_f32_32x32x16_bf16 v[2:17], v[118:121], v[138:141], v[2:17]
	v_exp_f32_e32 v60, v60
	v_exp_f32_e32 v61, v61
	v_exp_f32_e32 v62, v62
	v_exp_f32_e32 v63, v63
	v_exp_f32_e32 v64, v64
	v_exp_f32_e32 v65, v65
	v_cvt_pk_bf16_f32 v142, v58, v59
	v_mfma_f32_32x32x16_bf16 v[18:33], v[102:105], v[138:141], v[18:33]
	v_cvt_pk_bf16_f32 v143, v60, v61
	v_cvt_pk_bf16_f32 v144, v62, v63
	v_cvt_pk_bf16_f32 v145, v64, v65
	v_exp_f32_e32 v34, v34
	v_exp_f32_e32 v35, v35
	v_exp_f32_e32 v36, v36
	v_exp_f32_e32 v37, v37
	v_mfma_f32_32x32x16_bf16 v[2:17], v[114:117], v[142:145], v[2:17]
	v_exp_f32_e32 v38, v38
	v_exp_f32_e32 v39, v39
	v_exp_f32_e32 v40, v40
	v_exp_f32_e32 v41, v41
	v_cvt_pk_bf16_f32 v150, v34, v35
	v_cvt_pk_bf16_f32 v151, v36, v37
	v_cvt_pk_bf16_f32 v152, v38, v39
	v_mfma_f32_32x32x16_bf16 v[18:33], v[98:101], v[142:145], v[18:33]
	v_cvt_pk_bf16_f32 v153, v40, v41
	v_exp_f32_e32 v42, v42
	v_exp_f32_e32 v43, v43
	v_exp_f32_e32 v44, v44
	v_exp_f32_e32 v45, v45
	v_exp_f32_e32 v46, v46
	v_exp_f32_e32 v47, v47
	v_mfma_f32_32x32x16_bf16 v[2:17], v[110:113], v[150:153], v[2:17]
	v_exp_f32_e32 v48, v48
	v_exp_f32_e32 v49, v49
	v_cvt_pk_bf16_f32 v154, v42, v43
	v_cvt_pk_bf16_f32 v155, v44, v45
	v_cvt_pk_bf16_f32 v156, v46, v47
	v_cvt_pk_bf16_f32 v157, v48, v49
	v_mfma_f32_32x32x16_bf16 v[18:33], v[90:93], v[150:153], v[18:33]
	s_waitcnt vmcnt(2)
	ds_write_b128 v123, v[82:85] offset:18432
	ds_write_b128 v122, v[86:89] offset:27648
	v_mfma_f32_32x32x16_bf16 v[2:17], v[106:109], v[154:157], v[2:17]
	v_mfma_f32_32x32x16_bf16 v[18:33], v[94:97], v[154:157], v[18:33]
	s_waitcnt lgkmcnt(0)
	s_barrier
	s_barrier
	global_load_dwordx4 v[82:85], v[240:241], off
	global_load_dwordx4 v[86:89], v[242:243], off offset:128
	ds_read_b128 v[90:93], v135 offset:18432
	ds_read_b128 v[94:97], v135 offset:18464
	ds_read_b128 v[98:101], v135 offset:23040
	ds_read_b128 v[138:141], v135 offset:23072
	s_waitcnt lgkmcnt(3)
	s_nop 0
	v_mfma_f32_32x32x16_bf16 v[158:173], v[90:93], v[70:73], v[218:233]
	v_add_f32_e32 v234, v50, v51
	v_add_f32_e32 v235, v34, v35
	v_add_f32_e32 v234, v52, v234
	v_add_f32_e32 v235, v36, v235
	v_add_f32_e32 v234, v53, v234
	v_add_f32_e32 v235, v37, v235
	v_add_f32_e32 v234, v54, v234
	v_add_f32_e32 v235, v38, v235
	s_waitcnt lgkmcnt(1)
	v_mfma_f32_32x32x16_bf16 v[174:189], v[98:101], v[70:73], v[218:233]
	v_add_f32_e32 v234, v55, v234
	v_add_f32_e32 v235, v39, v235
	v_add_f32_e32 v234, v56, v234
	v_add_f32_e32 v235, v40, v235
	v_add_f32_e32 v234, v57, v234
	v_add_f32_e32 v235, v41, v235
	v_add_f32_e32 v234, v58, v234
	v_add_f32_e32 v235, v42, v235
	v_mfma_f32_32x32x16_bf16 v[158:173], v[94:97], v[74:77], v[158:173]
	ds_read_b128 v[118:121], v190 offset:27648
	ds_read_b128 v[114:117], v190 offset:27680
	ds_read_b128 v[110:113], v190 offset:27712
	ds_read_b128 v[106:109], v190 offset:27744
	ds_read_b128 v[102:105], v190 offset:32256
	ds_read_b128 v[98:101], v190 offset:32288
	ds_read_b128 v[90:93], v190 offset:32320
	ds_read_b128 v[94:97], v190 offset:32352
	v_add_f32_e32 v234, v59, v234
	v_add_f32_e32 v235, v43, v235
	v_add_f32_e32 v234, v60, v234
	v_add_f32_e32 v235, v44, v235
	v_add_f32_e32 v234, v61, v234
	v_add_f32_e32 v235, v45, v235
	v_add_f32_e32 v234, v62, v234
	v_add_f32_e32 v235, v46, v235
	s_waitcnt lgkmcnt(8)
	v_mfma_f32_32x32x16_bf16 v[174:189], v[138:141], v[74:77], v[174:189]
	v_add_f32_e32 v234, v63, v234
	v_add_f32_e32 v235, v47, v235
	v_add_f32_e32 v234, v64, v234
	v_add_f32_e32 v235, v48, v235
	v_add_f32_e32 v234, v65, v234
	v_add_f32_e32 v235, v49, v235
	v_add_f32_e32 v234, v235, v234
	v_add_f32_e32 v136, v136, v234
	v_exp_f32_e32 v158, v158
	v_exp_f32_e32 v159, v159
	v_exp_f32_e32 v160, v160
	v_exp_f32_e32 v161, v161
	v_exp_f32_e32 v162, v162
	v_exp_f32_e32 v163, v163
	v_exp_f32_e32 v164, v164
	v_exp_f32_e32 v165, v165
	v_cvt_pk_bf16_f32 v138, v158, v159
	v_cvt_pk_bf16_f32 v139, v160, v161
	v_cvt_pk_bf16_f32 v140, v162, v163
	v_cvt_pk_bf16_f32 v141, v164, v165
	v_exp_f32_e32 v166, v166
	v_exp_f32_e32 v167, v167
	s_waitcnt lgkmcnt(0)
	v_mfma_f32_32x32x16_bf16 v[2:17], v[118:121], v[138:141], v[2:17]
	v_exp_f32_e32 v168, v168
	v_exp_f32_e32 v169, v169
	v_exp_f32_e32 v170, v170
	v_exp_f32_e32 v171, v171
	v_exp_f32_e32 v172, v172
	v_exp_f32_e32 v173, v173
	v_cvt_pk_bf16_f32 v142, v166, v167
	v_mfma_f32_32x32x16_bf16 v[18:33], v[102:105], v[138:141], v[18:33]
	v_cvt_pk_bf16_f32 v143, v168, v169
	v_cvt_pk_bf16_f32 v144, v170, v171
	v_cvt_pk_bf16_f32 v145, v172, v173
	v_exp_f32_e32 v174, v174
	v_exp_f32_e32 v175, v175
	v_exp_f32_e32 v176, v176
	v_exp_f32_e32 v177, v177
	v_mfma_f32_32x32x16_bf16 v[2:17], v[114:117], v[142:145], v[2:17]
	v_exp_f32_e32 v178, v178
	v_exp_f32_e32 v179, v179
	v_exp_f32_e32 v180, v180
	v_exp_f32_e32 v181, v181
	v_cvt_pk_bf16_f32 v150, v174, v175
	v_cvt_pk_bf16_f32 v151, v176, v177
	v_cvt_pk_bf16_f32 v152, v178, v179
	v_mfma_f32_32x32x16_bf16 v[18:33], v[98:101], v[142:145], v[18:33]
	v_cvt_pk_bf16_f32 v153, v180, v181
	v_exp_f32_e32 v182, v182
	v_exp_f32_e32 v183, v183
	v_exp_f32_e32 v184, v184
	v_exp_f32_e32 v185, v185
	v_exp_f32_e32 v186, v186
	v_exp_f32_e32 v187, v187
	v_mfma_f32_32x32x16_bf16 v[2:17], v[110:113], v[150:153], v[2:17]
	v_exp_f32_e32 v188, v188
	v_exp_f32_e32 v189, v189
	v_cvt_pk_bf16_f32 v154, v182, v183
	v_cvt_pk_bf16_f32 v155, v184, v185
	v_cvt_pk_bf16_f32 v156, v186, v187
	v_cvt_pk_bf16_f32 v157, v188, v189
	v_mfma_f32_32x32x16_bf16 v[18:33], v[90:93], v[150:153], v[18:33]
	s_waitcnt vmcnt(2)
	ds_write_b128 v123, v[66:69]
	ds_write_b128 v122, v[78:81] offset:9216
	v_mfma_f32_32x32x16_bf16 v[2:17], v[106:109], v[154:157], v[2:17]
	v_mfma_f32_32x32x16_bf16 v[18:33], v[94:97], v[154:157], v[18:33]
	s_waitcnt lgkmcnt(0)
	s_barrier
	s_barrier
	v_lshl_add_u64 v[242:243], v[242:243], 0, s[30:31]
	v_lshl_add_u64 v[238:239], v[238:239], 0, s[28:29]
	v_lshl_add_u64 v[240:241], v[240:241], 0, s[28:29]
	s_add_i32 s3, s3, 2
	s_cmp_lt_u32 s3, s2
	s_cbranch_scc1 .Lb2_loop
	v_add_f32_e32 v234, v158, v159
	v_add_f32_e32 v235, v174, v175
	v_add_f32_e32 v234, v160, v234
	v_add_f32_e32 v235, v176, v235
	v_add_f32_e32 v234, v161, v234
	v_add_f32_e32 v235, v177, v235
	v_add_f32_e32 v234, v162, v234
	v_add_f32_e32 v235, v178, v235
	v_add_f32_e32 v234, v163, v234
	v_add_f32_e32 v235, v179, v235
	v_add_f32_e32 v234, v164, v234
	v_add_f32_e32 v235, v180, v235
	v_add_f32_e32 v234, v165, v234
	v_add_f32_e32 v235, v181, v235
	v_add_f32_e32 v234, v166, v234
	v_add_f32_e32 v235, v182, v235
	v_add_f32_e32 v234, v167, v234
	v_add_f32_e32 v235, v183, v235
	v_add_f32_e32 v234, v168, v234
	v_add_f32_e32 v235, v184, v235
	v_add_f32_e32 v234, v169, v234
	v_add_f32_e32 v235, v185, v235
	v_add_f32_e32 v234, v170, v234
	v_add_f32_e32 v235, v186, v235
	v_add_f32_e32 v234, v171, v234
	v_add_f32_e32 v235, v187, v235
	v_add_f32_e32 v234, v172, v234
	v_add_f32_e32 v235, v188, v235
	v_add_f32_e32 v234, v173, v234
	v_add_f32_e32 v235, v189, v235
	v_add_f32_e32 v234, v235, v234
	v_add_f32_e32 v136, v136, v234
	s_waitcnt vmcnt(0)
	s_branch .LBB0_196
.Ltramp_677:
	s_branch .LBB0_677

.Ltramp_b676:
	s_branch .LBB0_676
.LBB0_185_sl:
	v_add_f32_e32 v50, 0, v50
	v_add_f32_e32 v34, 0, v34
	v_add_f32_e32 v50, v50, v51
	v_add_f32_e32 v34, v34, v35
	v_add_f32_e32 v35, v52, v50
	v_add_f32_e32 v34, v36, v34
	v_add_f32_e32 v35, v53, v35
	v_add_f32_e32 v34, v37, v34
	v_add_f32_e32 v35, v54, v35
	v_add_f32_e32 v34, v38, v34
	v_add_f32_e32 v35, v55, v35
	v_add_f32_e32 v34, v39, v34
	v_add_f32_e32 v35, v56, v35
	v_add_f32_e32 v34, v40, v34
	v_add_f32_e32 v35, v57, v35
	v_add_f32_e32 v34, v41, v34
	v_add_f32_e32 v35, v58, v35
	v_add_f32_e32 v34, v42, v34
	v_add_f32_e32 v35, v59, v35
	v_add_f32_e32 v34, v43, v34
	v_add_f32_e32 v35, v60, v35
	v_add_f32_e32 v34, v44, v34
	v_add_f32_e32 v35, v61, v35
	v_add_f32_e32 v34, v45, v34
	v_add_f32_e32 v35, v62, v35
	v_add_f32_e32 v34, v46, v34
	v_add_f32_e32 v35, v63, v35
	v_add_f32_e32 v34, v47, v34
	v_add_f32_e32 v35, v64, v35
	v_add_f32_e32 v34, v48, v34
	v_add_f32_e32 v35, v65, v35
	v_add_f32_e32 v34, v49, v34
	v_add_f32_e32 v34, v34, v35
	s_add_i32 s3, s3, 2
	v_add_f32_e32 v136, v128, v34
	v_lshl_add_u64 v[124:125], v[124:125], 0, s[30:31]
	s_cmp_lt_u32 s12, s2
	v_lshl_add_u64 v[126:127], v[126:127], 0, s[28:29]
	s_waitcnt lgkmcnt(0)
	s_barrier
	s_barrier
	s_cbranch_scc0 .LBB0_196

.LBB0_198:
	s_or_b64 exec, exec, s[2:3]
	v_cmp_gt_i32_e32 vcc, 4, v36
	s_waitcnt lgkmcnt(0)
	s_barrier
	s_and_saveexec_b64 s[2:3], vcc
	s_cbranch_execz .LBB0_84
	global_load_dword v66, v1, s[80:81] offset:256
	s_waitcnt vmcnt(2)
	v_and_b32_e32 v83, 31, v34
	v_lshrrev_b32_e32 v34, 3, v34
	v_and_b32_e32 v82, 4, v34
	v_lshlrev_b32_e32 v62, 2, v82
	v_lshlrev_b32_e32 v110, 5, v36
	ds_read2st64_b32 v[68:69], v35 offset1:1
	ds_read2st64_b32 v[70:71], v35 offset0:2 offset1:3
	ds_read2st64_b32 v[72:73], v35 offset0:4 offset1:5
	ds_read2st64_b32 v[74:75], v35 offset0:6 offset1:7
	ds_read2st64_b32 v[76:77], v35 offset0:8 offset1:9
	ds_read2st64_b32 v[78:79], v35 offset0:10 offset1:11
	ds_read2st64_b32 v[80:81], v35 offset0:12 offset1:13
	ds_read2st64_b32 v[84:85], v35 offset0:14 offset1:15
	s_waitcnt vmcnt(1)
	ds_read2st64_b32 v[86:87], v35 offset0:16 offset1:17
	ds_read2st64_b32 v[88:89], v35 offset0:18 offset1:19
	ds_read2st64_b32 v[90:91], v35 offset0:20 offset1:21
	ds_read2st64_b32 v[92:93], v35 offset0:22 offset1:23
	ds_read2st64_b32 v[94:95], v35 offset0:24 offset1:25
	ds_read2st64_b32 v[96:97], v35 offset0:26 offset1:27
	ds_read2st64_b32 v[98:99], v35 offset0:28 offset1:29
	ds_read2st64_b32 v[100:101], v35 offset0:30 offset1:31
	global_load_dwordx4 v[34:37], v62, s[82:83]
	global_load_dwordx4 v[38:41], v62, s[82:83] offset:32
	global_load_dwordx4 v[42:45], v62, s[82:83] offset:64
	global_load_dwordx4 v[46:49], v62, s[82:83] offset:96
	global_load_dwordx4 v[50:53], v62, s[82:83] offset:128
	global_load_dwordx4 v[58:61], v62, s[82:83] offset:160
	global_load_dwordx4 v[54:57], v62, s[82:83] offset:192
	s_nop 0
	global_load_dwordx4 v[62:65], v62, s[82:83] offset:224
	s_andn2_b64 vcc, exec, s[86:87]
	s_mov_b64 s[12:13], -1
	s_waitcnt vmcnt(8) lgkmcnt(14)
	v_mul_f32_e32 v68, v66, v68
	v_mul_f32_e32 v69, v66, v69
	v_mul_f32_e32 v70, v66, v70
	v_mul_f32_e32 v71, v66, v71
	s_waitcnt lgkmcnt(10)
	v_mul_f32_e32 v106, v66, v78
	v_mul_f32_e32 v107, v66, v79
	s_waitcnt lgkmcnt(9)
	v_mul_f32_e32 v108, v66, v80
	v_mul_f32_e32 v109, v66, v81
	s_waitcnt lgkmcnt(7)
	v_mul_f32_e32 v86, v66, v86
	v_mul_f32_e32 v87, v66, v87
	v_fma_f32 v78, v2, v0, -v68
	v_fma_f32 v79, v3, v0, -v69
	v_mul_f32_e32 v72, v66, v72
	v_mul_f32_e32 v73, v66, v73
	v_mul_f32_e32 v102, v66, v74
	v_mul_f32_e32 v103, v66, v75
	v_mul_f32_e32 v104, v66, v76
	v_mul_f32_e32 v105, v66, v77
	v_mul_f32_e32 v84, v66, v84
	v_mul_f32_e32 v85, v66, v85
	s_waitcnt lgkmcnt(6)
	v_mul_f32_e32 v88, v66, v88
	v_mul_f32_e32 v89, v66, v89
	s_waitcnt lgkmcnt(5)
	v_mul_f32_e32 v90, v66, v90
	v_mul_f32_e32 v91, v66, v91
	s_waitcnt lgkmcnt(4)
	v_mul_f32_e32 v92, v66, v92
	v_mul_f32_e32 v93, v66, v93
	s_waitcnt lgkmcnt(3)
	v_mul_f32_e32 v94, v66, v94
	v_mul_f32_e32 v95, v66, v95
	s_waitcnt lgkmcnt(2)
	v_mul_f32_e32 v96, v66, v96
	v_mul_f32_e32 v97, v66, v97
	s_waitcnt lgkmcnt(1)
	v_mul_f32_e32 v98, v66, v98
	v_mul_f32_e32 v99, v66, v99
	s_waitcnt lgkmcnt(0)
	v_mul_f32_e32 v100, v66, v100
	v_mul_f32_e32 v101, v66, v101
	v_fma_f32 v80, v4, v0, -v70
	v_fma_f32 v81, v5, v0, -v71
	v_fma_f32 v66, v14, v0, -v108
	v_fma_f32 v67, v15, v0, -v109
	v_fma_f32 v14, v18, v0, -v86
	v_fma_f32 v15, v19, v0, -v87
	v_mul_f32_e32 v18, v78, v78
	v_mul_f32_e32 v19, v79, v79
	v_fma_f32 v74, v6, v0, -v72
	v_fma_f32 v75, v7, v0, -v73
	v_fma_f32 v76, v8, v0, -v102
	v_fma_f32 v77, v9, v0, -v103
	v_fma_f32 v70, v10, v0, -v104
	v_fma_f32 v71, v11, v0, -v105
	v_fma_f32 v72, v12, v0, -v106
	v_fma_f32 v73, v13, v0, -v107
	v_fma_f32 v68, v16, v0, -v84
	v_fma_f32 v69, v17, v0, -v85
	v_fma_f32 v16, v20, v0, -v88
	v_fma_f32 v17, v21, v0, -v89
	v_fma_f32 v10, v22, v0, -v90
	v_fma_f32 v11, v23, v0, -v91
	v_fma_f32 v12, v24, v0, -v92
	v_fma_f32 v13, v25, v0, -v93
	v_fma_f32 v4, v26, v0, -v94
	v_fma_f32 v5, v27, v0, -v95
	v_fma_f32 v6, v28, v0, -v96
	v_fma_f32 v7, v29, v0, -v97
	v_fma_f32 v8, v30, v0, -v98
	v_fma_f32 v9, v31, v0, -v99
	v_fma_f32 v2, v32, v0, -v100
	v_fma_f32 v3, v33, v0, -v101
	v_mul_f32_e32 v20, v80, v80
	v_mul_f32_e32 v21, v81, v81
	v_add_f32_e32 v0, v18, v19
	v_add_f32_e32 v0, v0, v20
	v_mul_f32_e32 v22, v74, v74
	v_mul_f32_e32 v23, v75, v75
	v_add_f32_e32 v0, v0, v21
	v_add_f32_e32 v0, v0, v22
	v_mul_f32_e32 v24, v76, v76
	v_mul_f32_e32 v25, v77, v77
	v_add_f32_e32 v0, v0, v23
	v_add_f32_e32 v0, v0, v24
	v_mul_f32_e32 v26, v70, v70
	v_mul_f32_e32 v27, v71, v71
	v_add_f32_e32 v0, v0, v25
	v_add_f32_e32 v0, v0, v26
	v_mul_f32_e32 v28, v72, v72
	v_mul_f32_e32 v29, v73, v73
	v_add_f32_e32 v0, v0, v27
	v_add_f32_e32 v0, v0, v28
	v_mul_f32_e32 v30, v66, v66
	v_mul_f32_e32 v31, v67, v67
	v_add_f32_e32 v0, v0, v29
	v_add_f32_e32 v0, v0, v30
	v_mul_f32_e32 v32, v68, v68
	v_mul_f32_e32 v33, v69, v69
	v_add_f32_e32 v0, v0, v31
	v_add_f32_e32 v0, v0, v32
	v_mul_f32_e32 v84, v14, v14
	v_mul_f32_e32 v85, v15, v15
	v_add_f32_e32 v0, v0, v33
	v_add_f32_e32 v0, v0, v84
	v_mul_f32_e32 v86, v16, v16
	v_mul_f32_e32 v87, v17, v17
	v_add_f32_e32 v0, v0, v85
	v_add_f32_e32 v0, v0, v86
	v_mul_f32_e32 v88, v10, v10
	v_mul_f32_e32 v89, v11, v11
	v_add_f32_e32 v0, v0, v87
	v_add_f32_e32 v0, v0, v88
	v_mul_f32_e32 v90, v12, v12
	v_mul_f32_e32 v91, v13, v13
	v_add_f32_e32 v0, v0, v89
	v_add_f32_e32 v0, v0, v90
	v_mul_f32_e32 v92, v4, v4
	v_mul_f32_e32 v93, v5, v5
	v_add_f32_e32 v0, v0, v91
	v_add_f32_e32 v0, v0, v92
	v_mul_f32_e32 v94, v6, v6
	v_mul_f32_e32 v95, v7, v7
	v_add_f32_e32 v0, v0, v93
	v_add_f32_e32 v0, v0, v94
	v_mul_f32_e32 v96, v8, v8
	v_mul_f32_e32 v97, v9, v9
	v_add_f32_e32 v0, v0, v95
	v_add_f32_e32 v0, v0, v96
	v_mul_f32_e32 v98, v2, v2
	v_mul_f32_e32 v99, v3, v3
	v_add_f32_e32 v0, v0, v97
	v_add_f32_e32 v0, v0, v98
	v_add_f32_e32 v0, v0, v99
	ds_bpermute_b32 v19, v132, v0
	v_add3_u32 v20, v83, s65, v110
	s_cbranch_vccnz .LBB0_201
	s_lshl_b32 s12, s64, 8
	s_addk_i32 s12, 0x2000
	v_add_u32_e32 v18, s12, v20
	s_mov_b64 s[12:13], 0

.LBB0_207:
	ds_bpermute_b32 v5, v159, v0
	v_ashrrev_i32_e32 v3, 31, v2
	v_lshlrev_b64 v[2:3], 11, v[2:3]
	v_lshl_add_u64 v[2:3], s[62:63], 0, v[2:3]
	s_waitcnt lgkmcnt(0)
	v_add_f32_e32 v0, v0, v5
	v_div_scale_f32 v5, s[2:3], v0, v0, 1.0
	v_rcp_f32_e32 v6, v5
	v_div_scale_f32 v7, vcc, 1.0, v0, 1.0
	s_lshl_b32 s2, s33, 6
	v_fma_f32 v8, -v5, v6, 1.0
	v_fmac_f32_e32 v6, v8, v6
	v_mul_f32_e32 v8, v7, v6
	v_fma_f32 v9, -v5, v8, v7
	v_fmac_f32_e32 v8, v9, v6
	v_fma_f32 v5, -v5, v8, v7
	v_div_fmas_f32 v5, v5, v6, v8
	v_div_fixup_f32 v6, v5, v0, 1.0
	s_ashr_i32 s3, s2, 31
	v_lshrrev_b32_e32 v0, 2, v4
	v_lshl_add_u64 v[2:3], s[2:3], 1, v[2:3]
	v_and_b32_e32 v0, 8, v0
	v_mul_f32_e32 v4, v32, v6
	v_mul_f32_e32 v5, v33, v6
	v_mul_f32_e32 v8, v34, v6
	v_mul_f32_e32 v9, v35, v6
	v_lshl_add_u64 v[2:3], v[2:3], 0, v[0:1]
	v_cvt_pk_bf16_f32 v4, v4, v5
	v_cvt_pk_bf16_f32 v5, v8, v9
	global_store_dwordx2 v[2:3], v[4:5], off offset:1280
	v_mul_f32_e32 v4, v36, v6
	v_mul_f32_e32 v5, v37, v6
	v_mul_f32_e32 v8, v38, v6
	v_mul_f32_e32 v9, v39, v6
	v_cvt_pk_bf16_f32 v4, v4, v5
	v_cvt_pk_bf16_f32 v5, v8, v9
	global_store_dwordx2 v[2:3], v[4:5], off offset:1296
	v_mul_f32_e32 v4, v40, v6
	v_mul_f32_e32 v5, v41, v6
	v_mul_f32_e32 v8, v42, v6
	v_mul_f32_e32 v9, v43, v6
	v_cvt_pk_bf16_f32 v4, v4, v5
	v_cvt_pk_bf16_f32 v5, v8, v9
	global_store_dwordx2 v[2:3], v[4:5], off offset:1312
	v_mul_f32_e32 v4, v44, v6
	v_mul_f32_e32 v5, v45, v6
	v_mul_f32_e32 v8, v46, v6
	v_mul_f32_e32 v9, v47, v6
	v_cvt_pk_bf16_f32 v4, v4, v5
	v_cvt_pk_bf16_f32 v5, v8, v9
	global_store_dwordx2 v[2:3], v[4:5], off offset:1328
	v_mul_f32_e32 v4, v16, v6
	v_mul_f32_e32 v5, v17, v6
	v_mul_f32_e32 v8, v18, v6
	v_mul_f32_e32 v9, v19, v6
	v_cvt_pk_bf16_f32 v4, v4, v5
	v_cvt_pk_bf16_f32 v5, v8, v9
	global_store_dwordx2 v[2:3], v[4:5], off offset:1344
	v_mul_f32_e32 v4, v20, v6
	v_mul_f32_e32 v5, v21, v6
	v_mul_f32_e32 v8, v22, v6
	v_mul_f32_e32 v9, v23, v6
	v_cvt_pk_bf16_f32 v4, v4, v5
	v_cvt_pk_bf16_f32 v5, v8, v9
	global_store_dwordx2 v[2:3], v[4:5], off offset:1360
	v_mul_f32_e32 v4, v24, v6
	v_mul_f32_e32 v5, v25, v6
	v_mul_f32_e32 v8, v26, v6
	v_mul_f32_e32 v9, v27, v6
	v_cvt_pk_bf16_f32 v4, v4, v5
	v_cvt_pk_bf16_f32 v5, v8, v9
	global_store_dwordx2 v[2:3], v[4:5], off offset:1376
	v_mul_f32_e32 v4, v28, v6
	v_mul_f32_e32 v5, v29, v6
	v_mul_f32_e32 v7, v31, v6
	v_mul_f32_e32 v6, v30, v6
	v_cvt_pk_bf16_f32 v4, v4, v5
	v_cvt_pk_bf16_f32 v5, v6, v7
	global_store_dwordx2 v[2:3], v[4:5], off offset:1392
	s_cbranch_execnz .LBB0_85
	s_branch .LBB0_184

.Lgin_nolag2:
	s_nop 15
	s_nop 15
	s_waitcnt lgkmcnt(3)
	s_waitcnt lgkmcnt(2)
	s_waitcnt lgkmcnt(1)
	s_waitcnt lgkmcnt(0)
	s_waitcnt lgkmcnt(0)
	v_add_u32_e32 v0, 0x12000, v172
	v_add_u32_e32 v0, 0x14400, v172
	v_add_u32_e32 v0, 0x16800, v172
	v_add_u32_e32 v0, 0x18c00, v172
	s_waitcnt lgkmcnt(3)
	s_waitcnt lgkmcnt(2)
	s_waitcnt lgkmcnt(1)
	s_waitcnt lgkmcnt(0)
	s_waitcnt lgkmcnt(0)
	v_add_u32_e32 v0, 0x1b000, v172
	v_add_u32_e32 v0, 0x1d400, v172
	v_add_u32_e32 v0, 0x1f800, v172
	v_add_u32_e32 v0, 0x21c00, v172
	s_waitcnt lgkmcnt(3)
	s_waitcnt lgkmcnt(2)
	s_waitcnt lgkmcnt(1)
	s_waitcnt lgkmcnt(0)
	s_waitcnt lgkmcnt(0)
	v_add_u32_e32 v0, 0x12000, v170
	s_waitcnt lgkmcnt(3)
	s_waitcnt lgkmcnt(2)
	s_waitcnt lgkmcnt(1)
	s_waitcnt lgkmcnt(0)
	s_waitcnt lgkmcnt(0)
	s_waitcnt lgkmcnt(1)
	s_waitcnt lgkmcnt(0)
	s_waitcnt lgkmcnt(0)
	s_waitcnt lgkmcnt(3)
	s_waitcnt lgkmcnt(2)
	s_waitcnt lgkmcnt(1)
	s_waitcnt lgkmcnt(0)
	s_waitcnt lgkmcnt(0)
	s_waitcnt lgkmcnt(3)
	s_waitcnt lgkmcnt(2)
	s_waitcnt lgkmcnt(1)
	s_waitcnt lgkmcnt(0)
	s_waitcnt lgkmcnt(0)
	s_waitcnt lgkmcnt(4)
	v_add_u32_e32 v147, s1, v233
	s_movk_i32 s1, 0x4000
	s_waitcnt lgkmcnt(0)
	v_or_b32_e32 v132, v147, v177
	v_cmp_gt_i32_e64 s[44:45], s1, v132
	v_cmp_lt_i32_e32 vcc, s24, v132
	s_and_saveexec_b64 s[2:3], vcc
	s_xor_b64 s[2:3], exec, s[2:3]
	v_add_u32_e32 v0, 0xffffc000, v147
	v_lshrrev_b32_e32 v142, 8, v0
	v_and_b32_e32 v0, 0x9f, v132
	v_or_b32_e32 v0, 0x2000, v0
	s_or_saveexec_b64 s[2:3], s[2:3]
	v_lshrrev_b32_e32 v130, 2, v147
	v_mov_b32_e32 v131, 0
	v_ashrrev_i32_e32 v146, 13, v147
	v_and_b32_e32 v148, 0x7e0, v130
	v_mov_b32_e32 v160, 0
	s_xor_b64 exec, exec, s[2:3]
	v_ashrrev_i32_e32 v142, 13, v147
	v_and_b32_e32 v0, 0x1f9f, v132
	v_and_b32_e32 v131, 0x7e0, v130
	v_mov_b32_e32 v160, v175
	s_or_b64 exec, exec, s[2:3]
	v_lshlrev_b32_e32 v134, 1, v0
	v_lshrrev_b32_e32 v135, 1, v0
	v_and_b32_e32 v133, 0x3ff3, v0
	v_and_b32_e32 v134, 8, v134
	v_and_b32_e32 v135, 4, v135
	v_and_b32_e32 v130, 0xc0, v231
	v_or3_b32 v140, v134, v133, v135
	v_ashrrev_i32_e32 v133, 31, v132
	v_or_b32_e32 v130, s0, v130
	v_lshlrev_b64 v[134:135], 8, v[132:133]
	v_lshl_add_u64 v[138:139], s[36:37], 0, v[134:135]
	v_lshlrev_b64 v[134:135], 3, v[132:133]
	v_lshlrev_b64 v[136:137], 9, v[132:133]
	v_lshlrev_b32_e32 v144, 1, v140
	v_mov_b32_e32 v145, v1
	v_ashrrev_i32_e32 v133, 5, v130
	v_or_b32_e32 v158, v131, v174
	v_or_b32_e32 v159, v131, v173
	v_or_b32_e32 v156, v131, v234
	v_or_b32_e32 v157, v131, v235
	v_or_b32_e32 v154, v160, v174
	v_or_b32_e32 v155, v160, v173
	v_or_b32_e32 v152, v160, v234
	v_or_b32_e32 v153, v160, v235
	v_mul_lo_u32 v150, v142, 6
	v_lshl_add_u64 v[136:137], v[178:179], 0, v[136:137]
	v_lshlrev_b32_e32 v149, 2, v142
	v_lshl_add_u64 v[140:141], v[180:181], 0, v[144:145]
	v_lshlrev_b32_e32 v151, 1, v142
	v_lshl_add_u64 v[142:143], v[182:183], 0, v[144:145]
	v_cmp_lt_i32_e64 s[42:43], 15, v133
	s_and_saveexec_b64 s[0:1], s[42:43]
	s_xor_b64 s[2:3], exec, s[0:1]
	s_cbranch_execz .LBB0_257
	v_cmp_lt_u32_e32 vcc, 19, v133
	s_and_saveexec_b64 s[0:1], vcc
	s_xor_b64 s[40:41], exec, s[0:1]
	s_cbranch_execz .LBB0_254
	v_cmp_lt_u32_e32 vcc, 35, v133
	s_and_saveexec_b64 s[0:1], vcc
	s_xor_b64 s[22:23], exec, s[0:1]
	s_cbranch_execz .LBB0_245
	v_cmp_lt_u32_e32 vcc, 43, v133
	s_and_saveexec_b64 s[0:1], vcc
	s_xor_b64 s[88:89], exec, s[0:1]
	s_cbranch_execz .LBB0_242
	v_cmp_lt_u32_e32 vcc, 55, v133
	s_and_saveexec_b64 s[0:1], vcc
	s_xor_b64 s[90:91], exec, s[0:1]
	s_cbranch_execz .LBB0_231
	s_movk_i32 s0, 0x700
	v_cmp_eq_u32_e32 vcc, s0, v130
	s_and_saveexec_b64 s[92:93], vcc
	s_cbranch_execz .LBB0_230
	s_and_saveexec_b64 s[94:95], s[44:45]
	s_cbranch_execz .LBB0_229
	v_lshlrev_b32_e32 v131, 3, v158
	v_lshlrev_b32_e32 v161, 3, v159
	global_load_dwordx2 v[144:145], v131, s[80:81]
	global_load_dwordx2 v[196:197], v161, s[80:81]
	v_lshlrev_b32_e32 v131, 3, v157
	s_waitcnt vmcnt(1)
	v_mov_b32_e32 v198, v144
	s_waitcnt vmcnt(0)
	v_mov_b32_e32 v199, v196
	v_mov_b32_e32 v196, v145
	v_mul_f32_e32 v144, v122, v196
	v_mul_f32_e32 v145, v123, v197
	s_nop 0
	v_fma_f32 v144, v114, v198, -v144
	v_fma_f32 v145, v115, v199, -v145
	v_mul_f32_e32 v114, v114, v196
	v_mul_f32_e32 v115, v115, v197
	s_nop 0
	v_fma_f32 v122, v122, v198, v114
	v_fma_f32 v123, v123, v199, v115
	v_lshlrev_b32_e32 v114, 3, v156
	global_load_dwordx2 v[114:115], v114, s[80:81]
	s_nop 0
	global_load_dwordx2 v[196:197], v131, s[80:81]
	s_waitcnt vmcnt(1)
	v_mov_b32_e32 v198, v114
	s_waitcnt vmcnt(0)
	v_mov_b32_e32 v199, v196
	v_mov_b32_e32 v196, v115
	v_mul_f32_e32 v114, v124, v196
	v_mul_f32_e32 v115, v125, v197
	s_nop 0
	v_fma_f32 v208, v116, v198, -v114
	v_fma_f32 v209, v117, v199, -v115
	v_mul_f32_e32 v114, v116, v196
	v_mul_f32_e32 v115, v117, v197
	v_lshlrev_b32_e32 v116, 3, v155
	v_fma_f32 v124, v124, v198, v114
	v_fma_f32 v125, v125, v199, v115
	v_lshlrev_b32_e32 v114, 3, v154
	global_load_dwordx2 v[114:115], v114, s[80:81]
	s_nop 0
	global_load_dwordx2 v[116:117], v116, s[80:81]
	s_waitcnt vmcnt(1)
	v_mov_b32_e32 v196, v114
	s_waitcnt vmcnt(0)
	v_mov_b32_e32 v197, v116
	v_mov_b32_e32 v116, v115
	v_mul_f32_e32 v114, v126, v116
	v_mul_f32_e32 v115, v127, v117
	s_nop 0
	v_fma_f32 v198, v118, v196, -v114
	v_fma_f32 v199, v119, v197, -v115
	v_mul_f32_e32 v114, v118, v116
	v_mul_f32_e32 v115, v119, v117
	v_lshlrev_b32_e32 v116, 3, v152
	v_fma_f32 v126, v126, v196, v114
	v_fma_f32 v127, v127, v197, v115
	v_lshlrev_b32_e32 v114, 3, v153
	global_load_dwordx2 v[114:115], v114, s[80:81]
	s_nop 0
	global_load_dwordx2 v[116:117], v116, s[80:81]
	s_waitcnt vmcnt(1)
	v_mov_b32_e32 v197, v115
	s_waitcnt vmcnt(0)
	v_mov_b32_e32 v196, v117
	v_mov_b32_e32 v118, v116
	v_mov_b32_e32 v119, v114
	v_mul_f32_e32 v196, v128, v196
	v_mul_f32_e32 v197, v129, v197
	v_mul_f32_e32 v116, v128, v116
	v_fma_f32 v196, v120, v118, -v196
	v_fma_f32 v197, v121, v119, -v197
	v_mul_f32_e32 v118, v120, v117
	v_mov_b32_e32 v120, v129
	v_mul_f32_e32 v114, v120, v114
	v_mul_f32_e32 v115, v121, v115
	v_mov_b32_e32 v120, v196
	v_mov_b32_e32 v117, v114
	v_mov_b32_e32 v119, v115
	v_add_f32_e32 v128, v116, v118
	v_add_f32_e32 v129, v117, v119
	v_mov_b32_e32 v114, v144
	v_mov_b32_e32 v115, v145
	v_mov_b32_e32 v116, v208
	v_mov_b32_e32 v117, v209
	v_mov_b32_e32 v118, v198
	v_mov_b32_e32 v119, v199
	v_mov_b32_e32 v121, v197

.LBB0_245:
	s_andn2_saveexec_b64 s[22:23], s[22:23]
	s_cbranch_execz .LBB0_253
	s_and_saveexec_b64 s[88:89], s[44:45]
	s_cbranch_execz .LBB0_248
	v_lshlrev_b32_e32 v131, 3, v158
	v_lshlrev_b32_e32 v161, 3, v159
	global_load_dwordx2 v[144:145], v131, s[80:81]
	global_load_dwordx2 v[196:197], v161, s[80:81]
	v_lshlrev_b32_e32 v131, 3, v157
	s_waitcnt vmcnt(1)
	v_mov_b32_e32 v198, v144
	s_waitcnt vmcnt(0)
	v_mov_b32_e32 v199, v196
	v_mov_b32_e32 v196, v145
	v_mul_f32_e32 v144, v122, v196
	v_mul_f32_e32 v145, v123, v197
	s_nop 0
	v_fma_f32 v144, v114, v198, -v144
	v_fma_f32 v145, v115, v199, -v145
	v_mul_f32_e32 v114, v114, v196
	v_mul_f32_e32 v115, v115, v197
	s_nop 0
	v_fma_f32 v122, v122, v198, v114
	v_fma_f32 v123, v123, v199, v115
	v_lshlrev_b32_e32 v114, 3, v156
	global_load_dwordx2 v[114:115], v114, s[80:81]
	s_nop 0
	global_load_dwordx2 v[196:197], v131, s[80:81]
	s_waitcnt vmcnt(1)
	v_mov_b32_e32 v198, v114
	s_waitcnt vmcnt(0)
	v_mov_b32_e32 v199, v196
	v_mov_b32_e32 v196, v115
	v_mul_f32_e32 v114, v124, v196
	v_mul_f32_e32 v115, v125, v197
	s_nop 0
	v_fma_f32 v208, v116, v198, -v114
	v_fma_f32 v209, v117, v199, -v115
	v_mul_f32_e32 v114, v116, v196
	v_mul_f32_e32 v115, v117, v197
	v_lshlrev_b32_e32 v116, 3, v155
	v_fma_f32 v124, v124, v198, v114
	v_fma_f32 v125, v125, v199, v115
	v_lshlrev_b32_e32 v114, 3, v154
	global_load_dwordx2 v[114:115], v114, s[80:81]
	s_nop 0
	global_load_dwordx2 v[116:117], v116, s[80:81]
	s_waitcnt vmcnt(1)
	v_mov_b32_e32 v196, v114
	s_waitcnt vmcnt(0)
	v_mov_b32_e32 v197, v116
	v_mov_b32_e32 v116, v115
	v_mul_f32_e32 v114, v126, v116
	v_mul_f32_e32 v115, v127, v117
	s_nop 0
	v_fma_f32 v198, v118, v196, -v114
	v_fma_f32 v199, v119, v197, -v115
	v_mul_f32_e32 v114, v118, v116
	v_mul_f32_e32 v115, v119, v117
	v_lshlrev_b32_e32 v116, 3, v152
	v_fma_f32 v126, v126, v196, v114
	v_fma_f32 v127, v127, v197, v115
	v_lshlrev_b32_e32 v114, 3, v153
	global_load_dwordx2 v[114:115], v114, s[80:81]
	s_nop 0
	global_load_dwordx2 v[116:117], v116, s[80:81]
	s_waitcnt vmcnt(1)
	v_mov_b32_e32 v197, v115
	s_waitcnt vmcnt(0)
	v_mov_b32_e32 v196, v117
	v_mov_b32_e32 v118, v116
	v_mov_b32_e32 v119, v114
	v_mul_f32_e32 v196, v128, v196
	v_mul_f32_e32 v197, v129, v197
	v_mul_f32_e32 v116, v128, v116
	v_fma_f32 v196, v120, v118, -v196
	v_fma_f32 v197, v121, v119, -v197
	v_mul_f32_e32 v118, v120, v117
	v_mov_b32_e32 v120, v129
	v_mul_f32_e32 v114, v120, v114
	v_mul_f32_e32 v115, v121, v115
	v_mov_b32_e32 v120, v196
	v_mov_b32_e32 v117, v114
	v_mov_b32_e32 v119, v115
	v_add_f32_e32 v128, v116, v118
	v_add_f32_e32 v129, v117, v119
	v_mov_b32_e32 v114, v144
	v_mov_b32_e32 v115, v145
	v_mov_b32_e32 v116, v208
	v_mov_b32_e32 v117, v209
	v_mov_b32_e32 v118, v198
	v_mov_b32_e32 v119, v199
	v_mov_b32_e32 v121, v197

.LBB0_250:
	s_andn2_saveexec_b64 s[88:89], s[12:13]
	s_cbranch_execz .LBB0_252
	v_subrev_u32_e32 v131, 20, v133
	v_lshrrev_b32_e32 v131, 1, v131
	v_add_u32_e32 v131, v149, v131
	v_mad_i64_i32 v[144:145], s[0:1], v131, s25, v[0:1]
	s_mov_b32 s0, 0x3e8293ee
	v_lshlrev_b64 v[144:145], 7, v[144:145]
	v_mul_f32_e32 v114, s0, v114
	v_mul_f32_e32 v115, s0, v115
	v_mul_f32_e32 v116, s0, v116
	v_mul_f32_e32 v117, s0, v117
	v_lshl_add_u64 v[144:145], v[186:187], 0, v[144:145]
	v_cvt_pk_bf16_f32 v114, v114, v115
	v_cvt_pk_bf16_f32 v115, v116, v117
	global_store_dwordx2 v[144:145], v[114:115], off
	v_mul_f32_e32 v114, s0, v118
	v_mul_f32_e32 v115, s0, v119
	v_mul_f32_e32 v116, s0, v120
	v_mul_f32_e32 v117, s0, v121
	v_cvt_pk_bf16_f32 v114, v114, v115
	v_cvt_pk_bf16_f32 v115, v116, v117
	global_store_dwordx2 v[144:145], v[114:115], off offset:16
	v_mul_f32_e32 v114, s0, v122
	v_mul_f32_e32 v115, s0, v123
	v_mul_f32_e32 v116, s0, v124
	v_mul_f32_e32 v117, s0, v125
	v_cvt_pk_bf16_f32 v114, v114, v115
	v_cvt_pk_bf16_f32 v115, v116, v117
	global_store_dwordx2 v[144:145], v[114:115], off offset:32
	v_mul_f32_e32 v114, s0, v126
	v_mul_f32_e32 v115, s0, v127
	v_mul_f32_e32 v116, s0, v128
	v_mul_f32_e32 v117, s0, v129
	v_cvt_pk_bf16_f32 v114, v114, v115
	v_cvt_pk_bf16_f32 v115, v116, v117
	global_store_dwordx2 v[144:145], v[114:115], off offset:48

.LBB0_257:
	s_andn2_saveexec_b64 s[2:3], s[2:3]
	s_cbranch_execz .LBB0_265
	s_and_saveexec_b64 s[22:23], s[44:45]
	s_cbranch_execz .LBB0_260
	v_or_b32_e32 v131, v131, v176
	v_lshlrev_b32_e32 v131, 3, v131
	global_load_dwordx4 v[196:199], v131, s[80:81] offset:16
	global_load_dwordx4 v[208:211], v131, s[80:81]
	s_waitcnt vmcnt(0)
	v_mov_b32_e32 v219, v210
	v_mov_b32_e32 v210, v209
	v_mov_b32_e32 v218, v208
	v_mul_f32_e32 v144, v122, v210
	v_mul_f32_e32 v145, v123, v211
	s_nop 0
	v_fma_f32 v144, v114, v218, -v144
	v_fma_f32 v145, v115, v219, -v145
	v_mul_f32_e32 v114, v114, v210
	v_mul_f32_e32 v115, v115, v211
	s_nop 0
	v_fma_f32 v122, v122, v218, v114
	v_fma_f32 v123, v123, v219, v115
	v_mov_b32_e32 v115, v198
	v_mov_b32_e32 v198, v197
	v_mov_b32_e32 v114, v196
	v_mul_f32_e32 v196, v124, v198
	v_mul_f32_e32 v197, v125, v199
	s_nop 0
	v_fma_f32 v208, v116, v114, -v196
	v_fma_f32 v209, v117, v115, -v197
	v_mul_f32_e32 v116, v116, v198
	v_mul_f32_e32 v117, v117, v199
	s_nop 0
	v_fma_f32 v124, v124, v114, v116
	v_fma_f32 v125, v125, v115, v117
	global_load_dwordx4 v[114:117], v131, s[80:81] offset:64
	global_load_dwordx4 v[196:199], v131, s[80:81] offset:80
	s_waitcnt vmcnt(1)
	v_mov_b32_e32 v211, v116
	v_mov_b32_e32 v116, v115
	v_mov_b32_e32 v210, v114
	v_mul_f32_e32 v114, v126, v116
	v_mul_f32_e32 v115, v127, v117
	s_nop 0
	v_fma_f32 v218, v118, v210, -v114
	v_fma_f32 v219, v119, v211, -v115
	v_mul_f32_e32 v114, v118, v116
	v_mul_f32_e32 v115, v119, v117
	s_waitcnt vmcnt(0)
	v_mov_b32_e32 v116, v197
	v_mov_b32_e32 v117, v199
	v_fma_f32 v126, v126, v210, v114
	v_fma_f32 v127, v127, v211, v115
	v_mov_b32_e32 v114, v196
	v_mov_b32_e32 v115, v198
	v_mul_f32_e32 v116, v128, v116
	v_mul_f32_e32 v117, v129, v117
	s_nop 0
	v_fma_f32 v210, v120, v114, -v116
	v_fma_f32 v211, v121, v115, -v117
	v_mul_f32_e32 v116, v120, v197
	v_mov_b32_e32 v120, v129
	v_mul_f32_e32 v118, v120, v198
	v_mul_f32_e32 v119, v121, v199
	v_mul_f32_e32 v114, v128, v196
	v_mov_b32_e32 v115, v118
	v_mov_b32_e32 v117, v119
	v_add_f32_e32 v128, v114, v116
	v_add_f32_e32 v129, v115, v117
	v_mov_b32_e32 v114, v144
	v_mov_b32_e32 v115, v145
	v_mov_b32_e32 v116, v208
	v_mov_b32_e32 v117, v209
	v_mov_b32_e32 v118, v218
	v_mov_b32_e32 v119, v219
	v_mov_b32_e32 v120, v210
	v_mov_b32_e32 v121, v211

.LBB0_262:
	s_andn2_saveexec_b64 s[22:23], s[12:13]
	s_cbranch_execz .LBB0_264
	v_ashrrev_i32_e32 v131, 6, v130
	v_add_u32_e32 v131, v150, v131
	v_mad_i64_i32 v[144:145], s[0:1], v131, s25, v[0:1]
	s_mov_b32 s0, 0x3e38aa3b
	v_lshlrev_b64 v[144:145], 7, v[144:145]
	v_mul_f32_e32 v114, s0, v114
	v_mul_f32_e32 v115, s0, v115
	v_mul_f32_e32 v116, s0, v116
	v_mul_f32_e32 v117, s0, v117
	v_lshl_add_u64 v[144:145], v[190:191], 0, v[144:145]
	v_cvt_pk_bf16_f32 v114, v114, v115
	v_cvt_pk_bf16_f32 v115, v116, v117
	global_store_dwordx2 v[144:145], v[114:115], off
	v_mul_f32_e32 v114, s0, v118
	v_mul_f32_e32 v115, s0, v119
	v_mul_f32_e32 v116, s0, v120
	v_mul_f32_e32 v117, s0, v121
	v_cvt_pk_bf16_f32 v114, v114, v115
	v_cvt_pk_bf16_f32 v115, v116, v117
	global_store_dwordx2 v[144:145], v[114:115], off offset:16
	v_mul_f32_e32 v114, s0, v122
	v_mul_f32_e32 v115, s0, v123
	v_mul_f32_e32 v116, s0, v124
	v_mul_f32_e32 v117, s0, v125
	v_cvt_pk_bf16_f32 v114, v114, v115
	v_cvt_pk_bf16_f32 v115, v116, v117
	global_store_dwordx2 v[144:145], v[114:115], off offset:32
	v_mul_f32_e32 v114, s0, v126
	v_mul_f32_e32 v115, s0, v127
	v_mul_f32_e32 v116, s0, v128
	v_mul_f32_e32 v117, s0, v129
	v_cvt_pk_bf16_f32 v114, v114, v115
	v_cvt_pk_bf16_f32 v115, v116, v117
	global_store_dwordx2 v[144:145], v[114:115], off offset:48

.LBB0_281:
	s_andn2_saveexec_b64 s[22:23], s[22:23]
	s_cbranch_execz .LBB0_289
	s_and_saveexec_b64 s[90:91], s[44:45]
	s_cbranch_execz .LBB0_284
	v_lshlrev_b32_e32 v114, 3, v158
	v_lshlrev_b32_e32 v117, 3, v159
	global_load_dwordx2 v[114:115], v114, s[80:81]
	s_nop 0
	global_load_dwordx2 v[118:119], v117, s[80:81]
	v_lshlrev_b32_e32 v117, 3, v157
	s_waitcnt vmcnt(1)
	v_mov_b32_e32 v120, v114
	s_waitcnt vmcnt(0)
	v_mov_b32_e32 v121, v118
	v_mov_b32_e32 v118, v115
	v_mul_f32_e32 v114, v106, v118
	v_mul_f32_e32 v115, v107, v119
	s_nop 0
	v_fma_f32 v114, v98, v120, -v114
	v_fma_f32 v115, v99, v121, -v115
	v_mul_f32_e32 v98, v98, v118
	v_mul_f32_e32 v99, v99, v119
	s_nop 0
	v_fma_f32 v106, v106, v120, v98
	v_fma_f32 v107, v107, v121, v99
	v_lshlrev_b32_e32 v98, 3, v156
	global_load_dwordx2 v[98:99], v98, s[80:81]
	s_nop 0
	global_load_dwordx2 v[118:119], v117, s[80:81]
	s_waitcnt vmcnt(1)
	v_mov_b32_e32 v120, v98
	s_waitcnt vmcnt(0)
	v_mov_b32_e32 v121, v118
	v_mov_b32_e32 v118, v99
	v_mul_f32_e32 v98, v108, v118
	v_mul_f32_e32 v99, v109, v119
	s_nop 0
	v_fma_f32 v122, v100, v120, -v98
	v_fma_f32 v123, v101, v121, -v99
	v_mul_f32_e32 v98, v100, v118
	v_mul_f32_e32 v99, v101, v119
	v_lshlrev_b32_e32 v100, 3, v155
	v_fma_f32 v108, v108, v120, v98
	v_fma_f32 v109, v109, v121, v99
	v_lshlrev_b32_e32 v98, 3, v154
	global_load_dwordx2 v[98:99], v98, s[80:81]
	s_nop 0
	global_load_dwordx2 v[100:101], v100, s[80:81]
	s_waitcnt vmcnt(1)
	v_mov_b32_e32 v118, v98
	s_waitcnt vmcnt(0)
	v_mov_b32_e32 v119, v100
	v_mov_b32_e32 v100, v99
	v_mul_f32_e32 v98, v110, v100
	v_mul_f32_e32 v99, v111, v101
	s_nop 0
	v_fma_f32 v120, v102, v118, -v98
	v_fma_f32 v121, v103, v119, -v99
	v_mul_f32_e32 v98, v102, v100
	v_mul_f32_e32 v99, v103, v101
	v_lshlrev_b32_e32 v100, 3, v152
	v_fma_f32 v110, v110, v118, v98
	v_fma_f32 v111, v111, v119, v99
	v_lshlrev_b32_e32 v98, 3, v153
	global_load_dwordx2 v[98:99], v98, s[80:81]
	s_nop 0
	global_load_dwordx2 v[100:101], v100, s[80:81]
	s_waitcnt vmcnt(1)
	v_mov_b32_e32 v119, v99
	s_waitcnt vmcnt(0)
	v_mov_b32_e32 v118, v101
	v_mov_b32_e32 v102, v100
	v_mov_b32_e32 v103, v98
	v_mul_f32_e32 v118, v112, v118
	v_mul_f32_e32 v119, v113, v119
	v_mul_f32_e32 v100, v112, v100
	v_fma_f32 v118, v104, v102, -v118
	v_fma_f32 v119, v105, v103, -v119
	v_mul_f32_e32 v102, v104, v101
	v_mov_b32_e32 v104, v113
	v_mul_f32_e32 v98, v104, v98
	v_mul_f32_e32 v99, v105, v99
	v_mov_b32_e32 v104, v118
	v_mov_b32_e32 v101, v98
	v_mov_b32_e32 v103, v99
	v_add_f32_e32 v112, v100, v102
	v_add_f32_e32 v113, v101, v103
	v_mov_b32_e32 v98, v114
	v_mov_b32_e32 v99, v115
	v_mov_b32_e32 v100, v122
	v_mov_b32_e32 v101, v123
	v_mov_b32_e32 v102, v120
	v_mov_b32_e32 v103, v121
	v_mov_b32_e32 v105, v119

.LBB0_286:
	s_andn2_saveexec_b64 s[90:91], s[12:13]
	s_cbranch_execz .LBB0_288
	v_subrev_u32_e32 v114, 20, v116
	v_lshrrev_b32_e32 v114, 1, v114
	v_add_u32_e32 v114, v149, v114
	v_mad_i64_i32 v[114:115], s[0:1], v114, s25, v[0:1]
	s_mov_b32 s0, 0x3e8293ee
	v_lshlrev_b64 v[114:115], 7, v[114:115]
	v_mul_f32_e32 v98, s0, v98
	v_mul_f32_e32 v99, s0, v99
	v_mul_f32_e32 v100, s0, v100
	v_mul_f32_e32 v101, s0, v101
	v_lshl_add_u64 v[114:115], v[186:187], 0, v[114:115]
	v_cvt_pk_bf16_f32 v98, v98, v99
	v_cvt_pk_bf16_f32 v99, v100, v101
	global_store_dwordx2 v[114:115], v[98:99], off offset:64
	v_mul_f32_e32 v98, s0, v102
	v_mul_f32_e32 v99, s0, v103
	v_mul_f32_e32 v100, s0, v104
	v_mul_f32_e32 v101, s0, v105
	v_cvt_pk_bf16_f32 v98, v98, v99
	v_cvt_pk_bf16_f32 v99, v100, v101
	global_store_dwordx2 v[114:115], v[98:99], off offset:80
	v_mul_f32_e32 v98, s0, v106
	v_mul_f32_e32 v99, s0, v107
	v_mul_f32_e32 v100, s0, v108
	v_mul_f32_e32 v101, s0, v109
	v_cvt_pk_bf16_f32 v98, v98, v99
	v_cvt_pk_bf16_f32 v99, v100, v101
	global_store_dwordx2 v[114:115], v[98:99], off offset:96
	v_mul_f32_e32 v98, s0, v110
	v_mul_f32_e32 v99, s0, v111
	v_mul_f32_e32 v100, s0, v112
	v_mul_f32_e32 v101, s0, v113
	v_cvt_pk_bf16_f32 v98, v98, v99
	v_cvt_pk_bf16_f32 v99, v100, v101
	global_store_dwordx2 v[114:115], v[98:99], off offset:112

.LBB0_293:
	s_andn2_saveexec_b64 s[2:3], s[2:3]
	s_cbranch_execz .LBB0_301
	s_and_saveexec_b64 s[22:23], s[44:45]
	s_cbranch_execz .LBB0_296
	v_or_b32_e32 v114, v160, v176
	v_lshlrev_b32_e32 v117, 3, v114
	global_load_dwordx4 v[118:121], v117, s[80:81] offset:16
	global_load_dwordx4 v[122:125], v117, s[80:81]
	s_waitcnt vmcnt(0)
	v_mov_b32_e32 v127, v124
	v_mov_b32_e32 v124, v123
	v_mov_b32_e32 v126, v122
	v_mul_f32_e32 v114, v106, v124
	v_mul_f32_e32 v115, v107, v125
	s_nop 0
	v_fma_f32 v114, v98, v126, -v114
	v_fma_f32 v115, v99, v127, -v115
	v_mul_f32_e32 v98, v98, v124
	v_mul_f32_e32 v99, v99, v125
	s_nop 0
	v_fma_f32 v106, v106, v126, v98
	v_fma_f32 v107, v107, v127, v99
	v_mov_b32_e32 v99, v120
	v_mov_b32_e32 v120, v119
	v_mov_b32_e32 v98, v118
	v_mul_f32_e32 v118, v108, v120
	v_mul_f32_e32 v119, v109, v121
	s_nop 0
	v_fma_f32 v122, v100, v98, -v118
	v_fma_f32 v123, v101, v99, -v119
	v_mul_f32_e32 v100, v100, v120
	v_mul_f32_e32 v101, v101, v121
	s_nop 0
	v_fma_f32 v108, v108, v98, v100
	v_fma_f32 v109, v109, v99, v101
	global_load_dwordx4 v[98:101], v117, s[80:81] offset:64
	global_load_dwordx4 v[118:121], v117, s[80:81] offset:80
	s_waitcnt vmcnt(1)
	v_mov_b32_e32 v125, v100
	v_mov_b32_e32 v100, v99
	v_mov_b32_e32 v124, v98
	v_mul_f32_e32 v98, v110, v100
	v_mul_f32_e32 v99, v111, v101
	s_nop 0
	v_fma_f32 v126, v102, v124, -v98
	v_fma_f32 v127, v103, v125, -v99
	v_mul_f32_e32 v98, v102, v100
	v_mul_f32_e32 v99, v103, v101
	s_waitcnt vmcnt(0)
	v_mov_b32_e32 v100, v119
	v_mov_b32_e32 v101, v121
	v_fma_f32 v110, v110, v124, v98
	v_fma_f32 v111, v111, v125, v99
	v_mov_b32_e32 v98, v118
	v_mov_b32_e32 v99, v120
	v_mul_f32_e32 v100, v112, v100
	v_mul_f32_e32 v101, v113, v101
	s_nop 0
	v_fma_f32 v124, v104, v98, -v100
	v_fma_f32 v125, v105, v99, -v101
	v_mul_f32_e32 v100, v104, v119
	v_mov_b32_e32 v104, v113
	v_mul_f32_e32 v102, v104, v120
	v_mul_f32_e32 v103, v105, v121
	v_mul_f32_e32 v98, v112, v118
	v_mov_b32_e32 v99, v102
	v_mov_b32_e32 v101, v103
	v_add_f32_e32 v112, v98, v100
	v_add_f32_e32 v113, v99, v101
	v_mov_b32_e32 v98, v114
	v_mov_b32_e32 v99, v115
	v_mov_b32_e32 v100, v122
	v_mov_b32_e32 v101, v123
	v_mov_b32_e32 v102, v126
	v_mov_b32_e32 v103, v127
	v_mov_b32_e32 v104, v124
	v_mov_b32_e32 v105, v125

.LBB0_298:
	s_andn2_saveexec_b64 s[22:23], s[12:13]
	s_cbranch_execz .LBB0_300
	v_ashrrev_i32_e32 v114, 6, v130
	v_add_u32_e32 v114, v150, v114
	v_mad_i64_i32 v[114:115], s[0:1], v114, s25, v[0:1]
	s_mov_b32 s0, 0x3e38aa3b
	v_lshlrev_b64 v[114:115], 7, v[114:115]
	v_mul_f32_e32 v98, s0, v98
	v_mul_f32_e32 v99, s0, v99
	v_mul_f32_e32 v100, s0, v100
	v_mul_f32_e32 v101, s0, v101
	v_lshl_add_u64 v[114:115], v[190:191], 0, v[114:115]
	v_cvt_pk_bf16_f32 v98, v98, v99
	v_cvt_pk_bf16_f32 v99, v100, v101
	global_store_dwordx2 v[114:115], v[98:99], off offset:64
	v_mul_f32_e32 v98, s0, v102
	v_mul_f32_e32 v99, s0, v103
	v_mul_f32_e32 v100, s0, v104
	v_mul_f32_e32 v101, s0, v105
	v_cvt_pk_bf16_f32 v98, v98, v99
	v_cvt_pk_bf16_f32 v99, v100, v101
	global_store_dwordx2 v[114:115], v[98:99], off offset:80
	v_mul_f32_e32 v98, s0, v106
	v_mul_f32_e32 v99, s0, v107
	v_mul_f32_e32 v100, s0, v108
	v_mul_f32_e32 v101, s0, v109
	v_cvt_pk_bf16_f32 v98, v98, v99
	v_cvt_pk_bf16_f32 v99, v100, v101
	global_store_dwordx2 v[114:115], v[98:99], off offset:96
	v_mul_f32_e32 v98, s0, v110
	v_mul_f32_e32 v99, s0, v111
	v_mul_f32_e32 v100, s0, v112
	v_mul_f32_e32 v101, s0, v113
	v_cvt_pk_bf16_f32 v98, v98, v99
	v_cvt_pk_bf16_f32 v99, v100, v101
	global_store_dwordx2 v[114:115], v[98:99], off offset:112

.LBB0_309:
	v_cmp_lt_u32_e32 vcc, 19, v133
	s_and_saveexec_b64 s[0:1], vcc
	s_xor_b64 s[88:89], exec, s[0:1]
	s_cbranch_execz .LBB0_341
	v_cmp_lt_u32_e32 vcc, 35, v133
	s_and_saveexec_b64 s[0:1], vcc
	s_xor_b64 s[22:23], exec, s[0:1]
	s_cbranch_execz .LBB0_332
	v_cmp_lt_u32_e32 vcc, 43, v133
	s_and_saveexec_b64 s[0:1], vcc
	s_xor_b64 s[90:91], exec, s[0:1]
	s_cbranch_execz .LBB0_329
	v_cmp_lt_u32_e32 vcc, 55, v133
	s_and_saveexec_b64 s[0:1], vcc
	s_xor_b64 s[92:93], exec, s[0:1]
	s_cbranch_execz .LBB0_318
	s_movk_i32 s0, 0x700
	v_cmp_eq_u32_e32 vcc, s0, v130
	s_and_saveexec_b64 s[94:95], vcc
	s_cbranch_execz .LBB0_317
	s_and_saveexec_b64 vcc, s[44:45]
	s_cbranch_execz .LBB0_316
	v_lshlrev_b32_e32 v108, 3, v120
	v_lshlrev_b32_e32 v123, 3, v121
	global_load_dwordx2 v[108:109], v108, s[80:81]
	s_nop 0
	global_load_dwordx2 v[124:125], v123, s[80:81]
	v_lshlrev_b32_e32 v123, 3, v119
	s_waitcnt vmcnt(1)
	v_mov_b32_e32 v126, v108
	s_waitcnt vmcnt(0)
	v_mov_b32_e32 v127, v124
	v_mov_b32_e32 v124, v109
	v_mul_f32_e32 v108, v90, v124
	v_mul_f32_e32 v109, v91, v125
	s_nop 0
	v_fma_f32 v108, v82, v126, -v108
	v_fma_f32 v109, v83, v127, -v109
	v_mul_f32_e32 v82, v82, v124
	v_mul_f32_e32 v83, v83, v125
	s_nop 0
	v_fma_f32 v90, v90, v126, v82
	v_fma_f32 v91, v91, v127, v83
	v_lshlrev_b32_e32 v82, 3, v118
	global_load_dwordx2 v[82:83], v82, s[80:81]
	s_nop 0
	global_load_dwordx2 v[124:125], v123, s[80:81]
	s_waitcnt vmcnt(1)
	v_mov_b32_e32 v126, v82
	s_waitcnt vmcnt(0)
	v_mov_b32_e32 v127, v124
	v_mov_b32_e32 v124, v83
	v_mul_f32_e32 v82, v92, v124
	v_mul_f32_e32 v83, v93, v125
	s_nop 0
	v_fma_f32 v128, v84, v126, -v82
	v_fma_f32 v129, v85, v127, -v83
	v_mul_f32_e32 v82, v84, v124
	v_mul_f32_e32 v83, v85, v125
	v_lshlrev_b32_e32 v84, 3, v117
	v_fma_f32 v92, v92, v126, v82
	v_fma_f32 v93, v93, v127, v83
	v_lshlrev_b32_e32 v82, 3, v115
	global_load_dwordx2 v[82:83], v82, s[80:81]
	s_nop 0
	global_load_dwordx2 v[84:85], v84, s[80:81]
	s_waitcnt vmcnt(1)
	v_mov_b32_e32 v124, v82
	s_waitcnt vmcnt(0)
	v_mov_b32_e32 v125, v84
	v_mov_b32_e32 v84, v83
	v_mul_f32_e32 v82, v94, v84
	v_mul_f32_e32 v83, v95, v85
	s_nop 0
	v_fma_f32 v126, v86, v124, -v82
	v_fma_f32 v127, v87, v125, -v83
	v_mul_f32_e32 v82, v86, v84
	v_mul_f32_e32 v83, v87, v85
	v_lshlrev_b32_e32 v84, 3, v113
	v_fma_f32 v94, v94, v124, v82
	v_fma_f32 v95, v95, v125, v83
	v_lshlrev_b32_e32 v82, 3, v114
	global_load_dwordx2 v[82:83], v82, s[80:81]
	s_nop 0
	global_load_dwordx2 v[84:85], v84, s[80:81]
	s_waitcnt vmcnt(1)
	v_mov_b32_e32 v125, v83
	s_waitcnt vmcnt(0)
	v_mov_b32_e32 v124, v85
	v_mov_b32_e32 v86, v84
	v_mov_b32_e32 v87, v82
	v_mul_f32_e32 v124, v96, v124
	v_mul_f32_e32 v125, v97, v125
	v_mul_f32_e32 v84, v96, v84
	v_fma_f32 v124, v88, v86, -v124
	v_fma_f32 v125, v89, v87, -v125
	v_mul_f32_e32 v86, v88, v85
	v_mov_b32_e32 v88, v97
	v_mul_f32_e32 v82, v88, v82
	v_mul_f32_e32 v83, v89, v83
	v_mov_b32_e32 v88, v124
	v_mov_b32_e32 v85, v82
	v_mov_b32_e32 v87, v83
	v_add_f32_e32 v96, v84, v86
	v_add_f32_e32 v97, v85, v87
	v_mov_b32_e32 v82, v108
	v_mov_b32_e32 v83, v109
	v_mov_b32_e32 v84, v128
	v_mov_b32_e32 v85, v129
	v_mov_b32_e32 v86, v126
	v_mov_b32_e32 v87, v127
	v_mov_b32_e32 v89, v125

.LBB0_332:
	s_andn2_saveexec_b64 s[22:23], s[22:23]
	s_cbranch_execz .LBB0_340
	s_and_saveexec_b64 s[90:91], s[44:45]
	s_cbranch_execz .LBB0_335
	v_lshlrev_b32_e32 v108, 3, v120
	v_lshlrev_b32_e32 v123, 3, v121
	global_load_dwordx2 v[108:109], v108, s[80:81]
	s_nop 0
	global_load_dwordx2 v[124:125], v123, s[80:81]
	v_lshlrev_b32_e32 v123, 3, v119
	s_waitcnt vmcnt(1)
	v_mov_b32_e32 v126, v108
	s_waitcnt vmcnt(0)
	v_mov_b32_e32 v127, v124
	v_mov_b32_e32 v124, v109
	v_mul_f32_e32 v108, v90, v124
	v_mul_f32_e32 v109, v91, v125
	s_nop 0
	v_fma_f32 v108, v82, v126, -v108
	v_fma_f32 v109, v83, v127, -v109
	v_mul_f32_e32 v82, v82, v124
	v_mul_f32_e32 v83, v83, v125
	s_nop 0
	v_fma_f32 v90, v90, v126, v82
	v_fma_f32 v91, v91, v127, v83
	v_lshlrev_b32_e32 v82, 3, v118
	global_load_dwordx2 v[82:83], v82, s[80:81]
	s_nop 0
	global_load_dwordx2 v[124:125], v123, s[80:81]
	s_waitcnt vmcnt(1)
	v_mov_b32_e32 v126, v82
	s_waitcnt vmcnt(0)
	v_mov_b32_e32 v127, v124
	v_mov_b32_e32 v124, v83
	v_mul_f32_e32 v82, v92, v124
	v_mul_f32_e32 v83, v93, v125
	s_nop 0
	v_fma_f32 v128, v84, v126, -v82
	v_fma_f32 v129, v85, v127, -v83
	v_mul_f32_e32 v82, v84, v124
	v_mul_f32_e32 v83, v85, v125
	v_lshlrev_b32_e32 v84, 3, v117
	v_fma_f32 v92, v92, v126, v82
	v_fma_f32 v93, v93, v127, v83
	v_lshlrev_b32_e32 v82, 3, v115
	global_load_dwordx2 v[82:83], v82, s[80:81]
	s_nop 0
	global_load_dwordx2 v[84:85], v84, s[80:81]
	s_waitcnt vmcnt(1)
	v_mov_b32_e32 v124, v82
	s_waitcnt vmcnt(0)
	v_mov_b32_e32 v125, v84
	v_mov_b32_e32 v84, v83
	v_mul_f32_e32 v82, v94, v84
	v_mul_f32_e32 v83, v95, v85
	s_nop 0
	v_fma_f32 v126, v86, v124, -v82
	v_fma_f32 v127, v87, v125, -v83
	v_mul_f32_e32 v82, v86, v84
	v_mul_f32_e32 v83, v87, v85
	v_lshlrev_b32_e32 v84, 3, v113
	v_fma_f32 v94, v94, v124, v82
	v_fma_f32 v95, v95, v125, v83
	v_lshlrev_b32_e32 v82, 3, v114
	global_load_dwordx2 v[82:83], v82, s[80:81]
	s_nop 0
	global_load_dwordx2 v[84:85], v84, s[80:81]
	s_waitcnt vmcnt(1)
	v_mov_b32_e32 v125, v83
	s_waitcnt vmcnt(0)
	v_mov_b32_e32 v124, v85
	v_mov_b32_e32 v86, v84
	v_mov_b32_e32 v87, v82
	v_mul_f32_e32 v124, v96, v124
	v_mul_f32_e32 v125, v97, v125
	v_mul_f32_e32 v84, v96, v84
	v_fma_f32 v124, v88, v86, -v124
	v_fma_f32 v125, v89, v87, -v125
	v_mul_f32_e32 v86, v88, v85
	v_mov_b32_e32 v88, v97
	v_mul_f32_e32 v82, v88, v82
	v_mul_f32_e32 v83, v89, v83
	v_mov_b32_e32 v88, v124
	v_mov_b32_e32 v85, v82
	v_mov_b32_e32 v87, v83
	v_add_f32_e32 v96, v84, v86
	v_add_f32_e32 v97, v85, v87
	v_mov_b32_e32 v82, v108
	v_mov_b32_e32 v83, v109
	v_mov_b32_e32 v84, v128
	v_mov_b32_e32 v85, v129
	v_mov_b32_e32 v86, v126
	v_mov_b32_e32 v87, v127
	v_mov_b32_e32 v89, v125

.LBB0_337:
	s_andn2_saveexec_b64 s[90:91], s[12:13]
	s_cbranch_execz .LBB0_339
	v_subrev_u32_e32 v108, 20, v133
	v_lshrrev_b32_e32 v108, 1, v108
	v_add_u32_e32 v108, v110, v108
	v_mad_i64_i32 v[108:109], s[0:1], v108, s25, v[0:1]
	s_mov_b32 s0, 0x3e8293ee
	v_lshlrev_b64 v[108:109], 7, v[108:109]
	v_mul_f32_e32 v82, s0, v82
	v_mul_f32_e32 v83, s0, v83
	v_mul_f32_e32 v84, s0, v84
	v_mul_f32_e32 v85, s0, v85
	v_lshl_add_u64 v[108:109], v[186:187], 0, v[108:109]
	v_cvt_pk_bf16_f32 v82, v82, v83
	v_cvt_pk_bf16_f32 v83, v84, v85
	global_store_dwordx2 v[108:109], v[82:83], off
	v_mul_f32_e32 v82, s0, v86
	v_mul_f32_e32 v83, s0, v87
	v_mul_f32_e32 v84, s0, v88
	v_mul_f32_e32 v85, s0, v89
	v_cvt_pk_bf16_f32 v82, v82, v83
	v_cvt_pk_bf16_f32 v83, v84, v85
	global_store_dwordx2 v[108:109], v[82:83], off offset:16
	v_mul_f32_e32 v82, s0, v90
	v_mul_f32_e32 v83, s0, v91
	v_mul_f32_e32 v84, s0, v92
	v_mul_f32_e32 v85, s0, v93
	v_cvt_pk_bf16_f32 v82, v82, v83
	v_cvt_pk_bf16_f32 v83, v84, v85
	global_store_dwordx2 v[108:109], v[82:83], off offset:32
	v_mul_f32_e32 v82, s0, v94
	v_mul_f32_e32 v83, s0, v95
	v_mul_f32_e32 v84, s0, v96
	v_mul_f32_e32 v85, s0, v97
	v_cvt_pk_bf16_f32 v82, v82, v83
	v_cvt_pk_bf16_f32 v83, v84, v85
	global_store_dwordx2 v[108:109], v[82:83], off offset:48

.LBB0_344:
	s_and_saveexec_b64 s[22:23], s[44:45]
	s_cbranch_execz .LBB0_346
	v_or_b32_e32 v108, v108, v176
	v_lshlrev_b32_e32 v123, 3, v108
	global_load_dwordx4 v[124:127], v123, s[80:81] offset:16
	global_load_dwordx4 v[134:137], v123, s[80:81]
	s_waitcnt vmcnt(0)
	v_mov_b32_e32 v129, v136
	v_mov_b32_e32 v136, v135
	v_mov_b32_e32 v128, v134
	v_mul_f32_e32 v108, v90, v136
	v_mul_f32_e32 v109, v91, v137
	s_nop 0
	v_fma_f32 v108, v82, v128, -v108
	v_fma_f32 v109, v83, v129, -v109
	v_mul_f32_e32 v82, v82, v136
	v_mul_f32_e32 v83, v83, v137
	s_nop 0
	v_fma_f32 v90, v90, v128, v82
	v_fma_f32 v91, v91, v129, v83
	v_mov_b32_e32 v83, v126
	v_mov_b32_e32 v126, v125
	v_mov_b32_e32 v82, v124
	v_mul_f32_e32 v124, v92, v126
	v_mul_f32_e32 v125, v93, v127
	s_nop 0
	v_fma_f32 v128, v84, v82, -v124
	v_fma_f32 v129, v85, v83, -v125
	v_mul_f32_e32 v84, v84, v126
	v_mul_f32_e32 v85, v85, v127
	s_nop 0
	v_fma_f32 v92, v92, v82, v84
	v_fma_f32 v93, v93, v83, v85
	global_load_dwordx4 v[82:85], v123, s[80:81] offset:64
	global_load_dwordx4 v[124:127], v123, s[80:81] offset:80
	s_waitcnt vmcnt(1)
	v_mov_b32_e32 v135, v84
	v_mov_b32_e32 v84, v83
	v_mov_b32_e32 v134, v82
	v_mul_f32_e32 v82, v94, v84
	v_mul_f32_e32 v83, v95, v85
	s_nop 0
	v_fma_f32 v136, v86, v134, -v82
	v_fma_f32 v137, v87, v135, -v83
	v_mul_f32_e32 v82, v86, v84
	v_mul_f32_e32 v83, v87, v85
	s_waitcnt vmcnt(0)
	v_mov_b32_e32 v84, v125
	v_mov_b32_e32 v85, v127
	v_fma_f32 v94, v94, v134, v82
	v_fma_f32 v95, v95, v135, v83
	v_mov_b32_e32 v82, v124
	v_mov_b32_e32 v83, v126
	v_mul_f32_e32 v84, v96, v84
	v_mul_f32_e32 v85, v97, v85
	s_nop 0
	v_fma_f32 v134, v88, v82, -v84
	v_fma_f32 v135, v89, v83, -v85
	v_mul_f32_e32 v84, v88, v125
	v_mov_b32_e32 v88, v97
	v_mul_f32_e32 v86, v88, v126
	v_mul_f32_e32 v87, v89, v127
	v_mul_f32_e32 v82, v96, v124
	v_mov_b32_e32 v83, v86
	v_mov_b32_e32 v85, v87
	v_add_f32_e32 v96, v82, v84
	v_add_f32_e32 v97, v83, v85
	v_mov_b32_e32 v82, v108
	v_mov_b32_e32 v83, v109
	v_mov_b32_e32 v84, v128
	v_mov_b32_e32 v85, v129
	v_mov_b32_e32 v86, v136
	v_mov_b32_e32 v87, v137
	v_mov_b32_e32 v88, v134
	v_mov_b32_e32 v89, v135

.LBB0_348:
	s_andn2_saveexec_b64 s[22:23], s[12:13]
	s_cbranch_execz .LBB0_350
	v_ashrrev_i32_e32 v108, 6, v130
	v_add_u32_e32 v108, v111, v108
	v_mad_i64_i32 v[108:109], s[0:1], v108, s25, v[0:1]
	s_mov_b32 s0, 0x3e38aa3b
	v_lshlrev_b64 v[108:109], 7, v[108:109]
	v_mul_f32_e32 v82, s0, v82
	v_mul_f32_e32 v83, s0, v83
	v_mul_f32_e32 v84, s0, v84
	v_mul_f32_e32 v85, s0, v85
	v_lshl_add_u64 v[108:109], v[190:191], 0, v[108:109]
	v_cvt_pk_bf16_f32 v82, v82, v83
	v_cvt_pk_bf16_f32 v83, v84, v85
	global_store_dwordx2 v[108:109], v[82:83], off
	v_mul_f32_e32 v82, s0, v86
	v_mul_f32_e32 v83, s0, v87
	v_mul_f32_e32 v84, s0, v88
	v_mul_f32_e32 v85, s0, v89
	v_cvt_pk_bf16_f32 v82, v82, v83
	v_cvt_pk_bf16_f32 v83, v84, v85
	global_store_dwordx2 v[108:109], v[82:83], off offset:16
	v_mul_f32_e32 v82, s0, v90
	v_mul_f32_e32 v83, s0, v91
	v_mul_f32_e32 v84, s0, v92
	v_mul_f32_e32 v85, s0, v93
	v_cvt_pk_bf16_f32 v82, v82, v83
	v_cvt_pk_bf16_f32 v83, v84, v85
	global_store_dwordx2 v[108:109], v[82:83], off offset:32
	v_mul_f32_e32 v82, s0, v94
	v_mul_f32_e32 v83, s0, v95
	v_mul_f32_e32 v84, s0, v96
	v_mul_f32_e32 v85, s0, v97
	v_cvt_pk_bf16_f32 v82, v82, v83
	v_cvt_pk_bf16_f32 v83, v84, v85
	global_store_dwordx2 v[108:109], v[82:83], off offset:48

.LBB0_366:
	s_andn2_saveexec_b64 s[22:23], s[22:23]
	s_cbranch_execz .LBB0_374
	s_and_saveexec_b64 s[90:91], s[44:45]
	s_cbranch_execz .LBB0_369
	v_lshlrev_b32_e32 v82, 3, v120
	v_lshlrev_b32_e32 v84, 3, v121
	global_load_dwordx2 v[82:83], v82, s[80:81]
	s_nop 0
	global_load_dwordx2 v[84:85], v84, s[80:81]
	s_waitcnt vmcnt(1)
	v_mov_b32_e32 v86, v82
	s_waitcnt vmcnt(0)
	v_mov_b32_e32 v87, v84
	v_mov_b32_e32 v84, v83
	v_mul_f32_e32 v82, v74, v84
	v_mul_f32_e32 v83, v75, v85
	s_nop 0
	v_fma_f32 v82, v66, v86, -v82
	v_fma_f32 v83, v67, v87, -v83
	v_mul_f32_e32 v66, v66, v84
	v_mul_f32_e32 v67, v67, v85
	v_lshlrev_b32_e32 v84, 3, v119
	v_fma_f32 v74, v74, v86, v66
	v_fma_f32 v75, v75, v87, v67
	v_lshlrev_b32_e32 v66, 3, v118
	global_load_dwordx2 v[66:67], v66, s[80:81]
	s_nop 0
	global_load_dwordx2 v[84:85], v84, s[80:81]
	s_waitcnt vmcnt(1)
	v_mov_b32_e32 v86, v66
	s_waitcnt vmcnt(0)
	v_mov_b32_e32 v87, v84
	v_mov_b32_e32 v84, v67
	v_mul_f32_e32 v66, v76, v84
	v_mul_f32_e32 v67, v77, v85
	s_nop 0
	v_fma_f32 v88, v68, v86, -v66
	v_fma_f32 v89, v69, v87, -v67
	v_mul_f32_e32 v66, v68, v84
	v_mul_f32_e32 v67, v69, v85
	v_lshlrev_b32_e32 v68, 3, v117
	v_fma_f32 v76, v76, v86, v66
	v_fma_f32 v77, v77, v87, v67
	v_lshlrev_b32_e32 v66, 3, v115
	global_load_dwordx2 v[66:67], v66, s[80:81]
	s_nop 0
	global_load_dwordx2 v[68:69], v68, s[80:81]
	s_waitcnt vmcnt(1)
	v_mov_b32_e32 v84, v66
	s_waitcnt vmcnt(0)
	v_mov_b32_e32 v85, v68
	v_mov_b32_e32 v68, v67
	v_mul_f32_e32 v66, v78, v68
	v_mul_f32_e32 v67, v79, v69
	s_nop 0
	v_fma_f32 v86, v70, v84, -v66
	v_fma_f32 v87, v71, v85, -v67
	v_mul_f32_e32 v66, v70, v68
	v_mul_f32_e32 v67, v71, v69
	v_lshlrev_b32_e32 v68, 3, v113
	v_fma_f32 v78, v78, v84, v66
	v_fma_f32 v79, v79, v85, v67
	v_lshlrev_b32_e32 v66, 3, v114
	global_load_dwordx2 v[66:67], v66, s[80:81]
	s_nop 0
	global_load_dwordx2 v[68:69], v68, s[80:81]
	s_waitcnt vmcnt(1)
	v_mov_b32_e32 v85, v67
	s_waitcnt vmcnt(0)
	v_mov_b32_e32 v84, v69
	v_mov_b32_e32 v70, v68
	v_mov_b32_e32 v71, v66
	v_mul_f32_e32 v84, v80, v84
	v_mul_f32_e32 v85, v81, v85
	v_mul_f32_e32 v68, v80, v68
	v_fma_f32 v84, v72, v70, -v84
	v_fma_f32 v85, v73, v71, -v85
	v_mul_f32_e32 v70, v72, v69
	v_mov_b32_e32 v72, v81
	v_mul_f32_e32 v66, v72, v66
	v_mul_f32_e32 v67, v73, v67
	v_mov_b32_e32 v72, v84
	v_mov_b32_e32 v69, v66
	v_mov_b32_e32 v71, v67
	v_add_f32_e32 v80, v68, v70
	v_add_f32_e32 v81, v69, v71
	v_mov_b32_e32 v66, v82
	v_mov_b32_e32 v67, v83
	v_mov_b32_e32 v68, v88
	v_mov_b32_e32 v69, v89
	v_mov_b32_e32 v70, v86
	v_mov_b32_e32 v71, v87
	v_mov_b32_e32 v73, v85

.LBB0_371:
	s_andn2_saveexec_b64 s[90:91], s[12:13]
	s_cbranch_execz .LBB0_373
	v_subrev_u32_e32 v82, 20, v116
	v_lshrrev_b32_e32 v82, 1, v82
	v_add_u32_e32 v82, v110, v82
	v_mad_i64_i32 v[82:83], s[0:1], v82, s25, v[0:1]
	s_mov_b32 s0, 0x3e8293ee
	v_lshlrev_b64 v[82:83], 7, v[82:83]
	v_mul_f32_e32 v66, s0, v66
	v_mul_f32_e32 v67, s0, v67
	v_mul_f32_e32 v68, s0, v68
	v_mul_f32_e32 v69, s0, v69
	v_lshl_add_u64 v[82:83], v[186:187], 0, v[82:83]
	v_cvt_pk_bf16_f32 v66, v66, v67
	v_cvt_pk_bf16_f32 v67, v68, v69
	global_store_dwordx2 v[82:83], v[66:67], off offset:64
	v_mul_f32_e32 v66, s0, v70
	v_mul_f32_e32 v67, s0, v71
	v_mul_f32_e32 v68, s0, v72
	v_mul_f32_e32 v69, s0, v73
	v_cvt_pk_bf16_f32 v66, v66, v67
	v_cvt_pk_bf16_f32 v67, v68, v69
	global_store_dwordx2 v[82:83], v[66:67], off offset:80
	v_mul_f32_e32 v66, s0, v74
	v_mul_f32_e32 v67, s0, v75
	v_mul_f32_e32 v68, s0, v76
	v_mul_f32_e32 v69, s0, v77
	v_cvt_pk_bf16_f32 v66, v66, v67
	v_cvt_pk_bf16_f32 v67, v68, v69
	global_store_dwordx2 v[82:83], v[66:67], off offset:96
	v_mul_f32_e32 v66, s0, v78
	v_mul_f32_e32 v67, s0, v79
	v_mul_f32_e32 v68, s0, v80
	v_mul_f32_e32 v69, s0, v81
	v_cvt_pk_bf16_f32 v66, v66, v67
	v_cvt_pk_bf16_f32 v67, v68, v69
	global_store_dwordx2 v[82:83], v[66:67], off offset:112

.LBB0_378:
	s_and_saveexec_b64 s[22:23], s[44:45]
	s_cbranch_execz .LBB0_380
	v_or_b32_e32 v82, v122, v176
	v_lshlrev_b32_e32 v94, 3, v82
	global_load_dwordx4 v[84:87], v94, s[80:81] offset:16
	global_load_dwordx4 v[88:91], v94, s[80:81]
	s_waitcnt vmcnt(0)
	v_mov_b32_e32 v93, v90
	v_mov_b32_e32 v90, v89
	v_mov_b32_e32 v92, v88
	v_mul_f32_e32 v82, v74, v90
	v_mul_f32_e32 v83, v75, v91
	s_nop 0
	v_fma_f32 v82, v66, v92, -v82
	v_fma_f32 v83, v67, v93, -v83
	v_mul_f32_e32 v66, v66, v90
	v_mul_f32_e32 v67, v67, v91
	s_nop 0
	v_fma_f32 v74, v74, v92, v66
	v_fma_f32 v75, v75, v93, v67
	v_mov_b32_e32 v67, v86
	v_mov_b32_e32 v86, v85
	v_mov_b32_e32 v66, v84
	v_mul_f32_e32 v84, v76, v86
	v_mul_f32_e32 v85, v77, v87
	s_nop 0
	v_fma_f32 v88, v68, v66, -v84
	v_fma_f32 v89, v69, v67, -v85
	v_mul_f32_e32 v68, v68, v86
	v_mul_f32_e32 v69, v69, v87
	s_nop 0
	v_fma_f32 v76, v76, v66, v68
	v_fma_f32 v77, v77, v67, v69
	global_load_dwordx4 v[66:69], v94, s[80:81] offset:64
	global_load_dwordx4 v[84:87], v94, s[80:81] offset:80
	s_waitcnt vmcnt(1)
	v_mov_b32_e32 v91, v68
	v_mov_b32_e32 v68, v67
	v_mov_b32_e32 v90, v66
	v_mul_f32_e32 v66, v78, v68
	v_mul_f32_e32 v67, v79, v69
	s_nop 0
	v_fma_f32 v92, v70, v90, -v66
	v_fma_f32 v93, v71, v91, -v67
	v_mul_f32_e32 v66, v70, v68
	v_mul_f32_e32 v67, v71, v69
	s_waitcnt vmcnt(0)
	v_mov_b32_e32 v68, v85
	v_mov_b32_e32 v69, v87
	v_fma_f32 v78, v78, v90, v66
	v_fma_f32 v79, v79, v91, v67
	v_mov_b32_e32 v66, v84
	v_mov_b32_e32 v67, v86
	v_mul_f32_e32 v68, v80, v68
	v_mul_f32_e32 v69, v81, v69
	s_nop 0
	v_fma_f32 v90, v72, v66, -v68
	v_fma_f32 v91, v73, v67, -v69
	v_mul_f32_e32 v68, v72, v85
	v_mov_b32_e32 v72, v81
	v_mul_f32_e32 v70, v72, v86
	v_mul_f32_e32 v71, v73, v87
	v_mul_f32_e32 v66, v80, v84
	v_mov_b32_e32 v67, v70
	v_mov_b32_e32 v69, v71
	v_add_f32_e32 v80, v66, v68
	v_add_f32_e32 v81, v67, v69
	v_mov_b32_e32 v66, v82
	v_mov_b32_e32 v67, v83
	v_mov_b32_e32 v68, v88
	v_mov_b32_e32 v69, v89
	v_mov_b32_e32 v70, v92
	v_mov_b32_e32 v71, v93
	v_mov_b32_e32 v72, v90
	v_mov_b32_e32 v73, v91

.LBB0_382:
	s_andn2_saveexec_b64 s[22:23], s[12:13]
	s_cbranch_execz .LBB0_384
	v_ashrrev_i32_e32 v82, 6, v130
	v_add_u32_e32 v82, v111, v82
	v_mad_i64_i32 v[82:83], s[0:1], v82, s25, v[0:1]
	s_mov_b32 s0, 0x3e38aa3b
	v_lshlrev_b64 v[82:83], 7, v[82:83]
	v_mul_f32_e32 v66, s0, v66
	v_mul_f32_e32 v67, s0, v67
	v_mul_f32_e32 v68, s0, v68
	v_mul_f32_e32 v69, s0, v69
	v_lshl_add_u64 v[82:83], v[190:191], 0, v[82:83]
	v_cvt_pk_bf16_f32 v66, v66, v67
	v_cvt_pk_bf16_f32 v67, v68, v69
	global_store_dwordx2 v[82:83], v[66:67], off offset:64
	v_mul_f32_e32 v66, s0, v70
	v_mul_f32_e32 v67, s0, v71
	v_mul_f32_e32 v68, s0, v72
	v_mul_f32_e32 v69, s0, v73
	v_cvt_pk_bf16_f32 v66, v66, v67
	v_cvt_pk_bf16_f32 v67, v68, v69
	global_store_dwordx2 v[82:83], v[66:67], off offset:80
	v_mul_f32_e32 v66, s0, v74
	v_mul_f32_e32 v67, s0, v75
	v_mul_f32_e32 v68, s0, v76
	v_mul_f32_e32 v69, s0, v77
	v_cvt_pk_bf16_f32 v66, v66, v67
	v_cvt_pk_bf16_f32 v67, v68, v69
	global_store_dwordx2 v[82:83], v[66:67], off offset:96
	v_mul_f32_e32 v66, s0, v78
	v_mul_f32_e32 v67, s0, v79
	v_mul_f32_e32 v68, s0, v80
	v_mul_f32_e32 v69, s0, v81
	v_cvt_pk_bf16_f32 v66, v66, v67
	v_cvt_pk_bf16_f32 v67, v68, v69
	global_store_dwordx2 v[82:83], v[66:67], off offset:112

.LBB0_393:
	v_cmp_lt_u32_e32 vcc, 19, v133
	s_and_saveexec_b64 s[0:1], vcc
	s_xor_b64 s[88:89], exec, s[0:1]
	s_cbranch_execz .LBB0_425
	v_cmp_lt_u32_e32 vcc, 35, v133
	s_and_saveexec_b64 s[0:1], vcc
	s_xor_b64 s[22:23], exec, s[0:1]
	s_cbranch_execz .LBB0_416
	v_cmp_lt_u32_e32 vcc, 43, v133
	s_and_saveexec_b64 s[0:1], vcc
	s_xor_b64 s[90:91], exec, s[0:1]
	s_cbranch_execz .LBB0_413
	v_cmp_lt_u32_e32 vcc, 55, v133
	s_and_saveexec_b64 s[0:1], vcc
	s_xor_b64 s[92:93], exec, s[0:1]
	s_cbranch_execz .LBB0_402
	s_movk_i32 s0, 0x700
	v_cmp_eq_u32_e32 vcc, s0, v130
	s_and_saveexec_b64 s[94:95], vcc
	s_cbranch_execz .LBB0_401
	s_and_saveexec_b64 vcc, s[44:45]
	s_cbranch_execz .LBB0_400
	v_lshlrev_b32_e32 v76, 3, v87
	v_lshlrev_b32_e32 v90, 3, v88
	global_load_dwordx2 v[76:77], v76, s[80:81]
	s_nop 0
	global_load_dwordx2 v[90:91], v90, s[80:81]
	s_waitcnt vmcnt(1)
	v_mov_b32_e32 v92, v76
	s_waitcnt vmcnt(0)
	v_mov_b32_e32 v93, v90
	v_mov_b32_e32 v90, v77
	v_mul_f32_e32 v76, v58, v90
	v_mul_f32_e32 v77, v59, v91
	s_nop 0
	v_fma_f32 v76, v50, v92, -v76
	v_fma_f32 v77, v51, v93, -v77
	v_mul_f32_e32 v50, v50, v90
	v_mul_f32_e32 v51, v51, v91
	v_lshlrev_b32_e32 v90, 3, v86
	v_fma_f32 v58, v58, v92, v50
	v_fma_f32 v59, v59, v93, v51
	v_lshlrev_b32_e32 v50, 3, v85
	global_load_dwordx2 v[50:51], v50, s[80:81]
	s_nop 0
	global_load_dwordx2 v[90:91], v90, s[80:81]
	s_waitcnt vmcnt(1)
	v_mov_b32_e32 v92, v50
	s_waitcnt vmcnt(0)
	v_mov_b32_e32 v93, v90
	v_mov_b32_e32 v90, v51
	v_mul_f32_e32 v50, v60, v90
	v_mul_f32_e32 v51, v61, v91
	s_nop 0
	v_fma_f32 v94, v52, v92, -v50
	v_fma_f32 v95, v53, v93, -v51
	v_mul_f32_e32 v50, v52, v90
	v_mul_f32_e32 v51, v53, v91
	v_lshlrev_b32_e32 v52, 3, v84
	v_fma_f32 v60, v60, v92, v50
	v_fma_f32 v61, v61, v93, v51
	v_lshlrev_b32_e32 v50, 3, v83
	global_load_dwordx2 v[50:51], v50, s[80:81]
	s_nop 0
	global_load_dwordx2 v[52:53], v52, s[80:81]
	s_waitcnt vmcnt(1)
	v_mov_b32_e32 v90, v50
	s_waitcnt vmcnt(0)
	v_mov_b32_e32 v91, v52
	v_mov_b32_e32 v52, v51
	v_mul_f32_e32 v50, v62, v52
	v_mul_f32_e32 v51, v63, v53
	s_nop 0
	v_fma_f32 v92, v54, v90, -v50
	v_fma_f32 v93, v55, v91, -v51
	v_mul_f32_e32 v50, v54, v52
	v_mul_f32_e32 v51, v55, v53
	v_lshlrev_b32_e32 v52, 3, v81
	v_fma_f32 v62, v62, v90, v50
	v_fma_f32 v63, v63, v91, v51
	v_lshlrev_b32_e32 v50, 3, v82
	global_load_dwordx2 v[50:51], v50, s[80:81]
	s_nop 0
	global_load_dwordx2 v[52:53], v52, s[80:81]
	s_waitcnt vmcnt(1)
	v_mov_b32_e32 v91, v51
	s_waitcnt vmcnt(0)
	v_mov_b32_e32 v90, v53
	v_mov_b32_e32 v54, v52
	v_mov_b32_e32 v55, v50
	v_mul_f32_e32 v90, v64, v90
	v_mul_f32_e32 v91, v65, v91
	v_mul_f32_e32 v52, v64, v52
	v_fma_f32 v90, v56, v54, -v90
	v_fma_f32 v91, v57, v55, -v91
	v_mul_f32_e32 v54, v56, v53
	v_mov_b32_e32 v56, v65
	v_mul_f32_e32 v50, v56, v50
	v_mul_f32_e32 v51, v57, v51
	v_mov_b32_e32 v56, v90
	v_mov_b32_e32 v53, v50
	v_mov_b32_e32 v55, v51
	v_add_f32_e32 v64, v52, v54
	v_add_f32_e32 v65, v53, v55
	v_mov_b32_e32 v50, v76
	v_mov_b32_e32 v51, v77
	v_mov_b32_e32 v52, v94
	v_mov_b32_e32 v53, v95
	v_mov_b32_e32 v54, v92
	v_mov_b32_e32 v55, v93
	v_mov_b32_e32 v57, v91

.LBB0_416:
	s_andn2_saveexec_b64 s[22:23], s[22:23]
	s_cbranch_execz .LBB0_424
	s_and_saveexec_b64 s[90:91], s[44:45]
	s_cbranch_execz .LBB0_419
	v_lshlrev_b32_e32 v76, 3, v87
	v_lshlrev_b32_e32 v90, 3, v88
	global_load_dwordx2 v[76:77], v76, s[80:81]
	s_nop 0
	global_load_dwordx2 v[90:91], v90, s[80:81]
	s_waitcnt vmcnt(1)
	v_mov_b32_e32 v92, v76
	s_waitcnt vmcnt(0)
	v_mov_b32_e32 v93, v90
	v_mov_b32_e32 v90, v77
	v_mul_f32_e32 v76, v58, v90
	v_mul_f32_e32 v77, v59, v91
	s_nop 0
	v_fma_f32 v76, v50, v92, -v76
	v_fma_f32 v77, v51, v93, -v77
	v_mul_f32_e32 v50, v50, v90
	v_mul_f32_e32 v51, v51, v91
	v_lshlrev_b32_e32 v90, 3, v86
	v_fma_f32 v58, v58, v92, v50
	v_fma_f32 v59, v59, v93, v51
	v_lshlrev_b32_e32 v50, 3, v85
	global_load_dwordx2 v[50:51], v50, s[80:81]
	s_nop 0
	global_load_dwordx2 v[90:91], v90, s[80:81]
	s_waitcnt vmcnt(1)
	v_mov_b32_e32 v92, v50
	s_waitcnt vmcnt(0)
	v_mov_b32_e32 v93, v90
	v_mov_b32_e32 v90, v51
	v_mul_f32_e32 v50, v60, v90
	v_mul_f32_e32 v51, v61, v91
	s_nop 0
	v_fma_f32 v94, v52, v92, -v50
	v_fma_f32 v95, v53, v93, -v51
	v_mul_f32_e32 v50, v52, v90
	v_mul_f32_e32 v51, v53, v91
	v_lshlrev_b32_e32 v52, 3, v84
	v_fma_f32 v60, v60, v92, v50
	v_fma_f32 v61, v61, v93, v51
	v_lshlrev_b32_e32 v50, 3, v83
	global_load_dwordx2 v[50:51], v50, s[80:81]
	s_nop 0
	global_load_dwordx2 v[52:53], v52, s[80:81]
	s_waitcnt vmcnt(1)
	v_mov_b32_e32 v90, v50
	s_waitcnt vmcnt(0)
	v_mov_b32_e32 v91, v52
	v_mov_b32_e32 v52, v51
	v_mul_f32_e32 v50, v62, v52
	v_mul_f32_e32 v51, v63, v53
	s_nop 0
	v_fma_f32 v92, v54, v90, -v50
	v_fma_f32 v93, v55, v91, -v51
	v_mul_f32_e32 v50, v54, v52
	v_mul_f32_e32 v51, v55, v53
	v_lshlrev_b32_e32 v52, 3, v81
	v_fma_f32 v62, v62, v90, v50
	v_fma_f32 v63, v63, v91, v51
	v_lshlrev_b32_e32 v50, 3, v82
	global_load_dwordx2 v[50:51], v50, s[80:81]
	s_nop 0
	global_load_dwordx2 v[52:53], v52, s[80:81]
	s_waitcnt vmcnt(1)
	v_mov_b32_e32 v91, v51
	s_waitcnt vmcnt(0)
	v_mov_b32_e32 v90, v53
	v_mov_b32_e32 v54, v52
	v_mov_b32_e32 v55, v50
	v_mul_f32_e32 v90, v64, v90
	v_mul_f32_e32 v91, v65, v91
	v_mul_f32_e32 v52, v64, v52
	v_fma_f32 v90, v56, v54, -v90
	v_fma_f32 v91, v57, v55, -v91
	v_mul_f32_e32 v54, v56, v53
	v_mov_b32_e32 v56, v65
	v_mul_f32_e32 v50, v56, v50
	v_mul_f32_e32 v51, v57, v51
	v_mov_b32_e32 v56, v90
	v_mov_b32_e32 v53, v50
	v_mov_b32_e32 v55, v51
	v_add_f32_e32 v64, v52, v54
	v_add_f32_e32 v65, v53, v55
	v_mov_b32_e32 v50, v76
	v_mov_b32_e32 v51, v77
	v_mov_b32_e32 v52, v94
	v_mov_b32_e32 v53, v95
	v_mov_b32_e32 v54, v92
	v_mov_b32_e32 v55, v93
	v_mov_b32_e32 v57, v91

.LBB0_421:
	s_andn2_saveexec_b64 s[90:91], s[12:13]
	s_cbranch_execz .LBB0_423
	v_subrev_u32_e32 v76, 20, v133
	v_lshrrev_b32_e32 v76, 1, v76
	v_add_u32_e32 v76, v78, v76
	v_mad_i64_i32 v[76:77], s[0:1], v76, s25, v[0:1]
	s_mov_b32 s0, 0x3e8293ee
	v_lshlrev_b64 v[76:77], 7, v[76:77]
	v_mul_f32_e32 v50, s0, v50
	v_mul_f32_e32 v51, s0, v51
	v_mul_f32_e32 v52, s0, v52
	v_mul_f32_e32 v53, s0, v53
	v_lshl_add_u64 v[76:77], v[186:187], 0, v[76:77]
	v_cvt_pk_bf16_f32 v50, v50, v51
	v_cvt_pk_bf16_f32 v51, v52, v53
	global_store_dwordx2 v[76:77], v[50:51], off
	v_mul_f32_e32 v50, s0, v54
	v_mul_f32_e32 v51, s0, v55
	v_mul_f32_e32 v52, s0, v56
	v_mul_f32_e32 v53, s0, v57
	v_cvt_pk_bf16_f32 v50, v50, v51
	v_cvt_pk_bf16_f32 v51, v52, v53
	global_store_dwordx2 v[76:77], v[50:51], off offset:16
	v_mul_f32_e32 v50, s0, v58
	v_mul_f32_e32 v51, s0, v59
	v_mul_f32_e32 v52, s0, v60
	v_mul_f32_e32 v53, s0, v61
	v_cvt_pk_bf16_f32 v50, v50, v51
	v_cvt_pk_bf16_f32 v51, v52, v53
	global_store_dwordx2 v[76:77], v[50:51], off offset:32
	v_mul_f32_e32 v50, s0, v62
	v_mul_f32_e32 v51, s0, v63
	v_mul_f32_e32 v52, s0, v64
	v_mul_f32_e32 v53, s0, v65
	v_cvt_pk_bf16_f32 v50, v50, v51
	v_cvt_pk_bf16_f32 v51, v52, v53
	global_store_dwordx2 v[76:77], v[50:51], off offset:48

.LBB0_428:
	s_and_saveexec_b64 s[22:23], s[44:45]
	s_cbranch_execz .LBB0_430
	v_or_b32_e32 v76, v76, v176
	v_lshlrev_b32_e32 v100, 3, v76
	global_load_dwordx4 v[90:93], v100, s[80:81] offset:16
	global_load_dwordx4 v[94:97], v100, s[80:81]
	s_waitcnt vmcnt(0)
	v_mov_b32_e32 v99, v96
	v_mov_b32_e32 v96, v95
	v_mov_b32_e32 v98, v94
	v_mul_f32_e32 v76, v58, v96
	v_mul_f32_e32 v77, v59, v97
	s_nop 0
	v_fma_f32 v76, v50, v98, -v76
	v_fma_f32 v77, v51, v99, -v77
	v_mul_f32_e32 v50, v50, v96
	v_mul_f32_e32 v51, v51, v97
	s_nop 0
	v_fma_f32 v58, v58, v98, v50
	v_fma_f32 v59, v59, v99, v51
	v_mov_b32_e32 v51, v92
	v_mov_b32_e32 v92, v91
	v_mov_b32_e32 v50, v90
	v_mul_f32_e32 v90, v60, v92
	v_mul_f32_e32 v91, v61, v93
	s_nop 0
	v_fma_f32 v94, v52, v50, -v90
	v_fma_f32 v95, v53, v51, -v91
	v_mul_f32_e32 v52, v52, v92
	v_mul_f32_e32 v53, v53, v93
	s_nop 0
	v_fma_f32 v60, v60, v50, v52
	v_fma_f32 v61, v61, v51, v53
	global_load_dwordx4 v[50:53], v100, s[80:81] offset:64
	global_load_dwordx4 v[90:93], v100, s[80:81] offset:80
	s_waitcnt vmcnt(1)
	v_mov_b32_e32 v97, v52
	v_mov_b32_e32 v52, v51
	v_mov_b32_e32 v96, v50
	v_mul_f32_e32 v50, v62, v52
	v_mul_f32_e32 v51, v63, v53
	s_nop 0
	v_fma_f32 v98, v54, v96, -v50
	v_fma_f32 v99, v55, v97, -v51
	v_mul_f32_e32 v50, v54, v52
	v_mul_f32_e32 v51, v55, v53
	s_waitcnt vmcnt(0)
	v_mov_b32_e32 v52, v91
	v_mov_b32_e32 v53, v93
	v_fma_f32 v62, v62, v96, v50
	v_fma_f32 v63, v63, v97, v51
	v_mov_b32_e32 v50, v90
	v_mov_b32_e32 v51, v92
	v_mul_f32_e32 v52, v64, v52
	v_mul_f32_e32 v53, v65, v53
	s_nop 0
	v_fma_f32 v96, v56, v50, -v52
	v_fma_f32 v97, v57, v51, -v53
	v_mul_f32_e32 v52, v56, v91
	v_mov_b32_e32 v56, v65
	v_mul_f32_e32 v54, v56, v92
	v_mul_f32_e32 v55, v57, v93
	v_mul_f32_e32 v50, v64, v90
	v_mov_b32_e32 v51, v54
	v_mov_b32_e32 v53, v55
	v_add_f32_e32 v64, v50, v52
	v_add_f32_e32 v65, v51, v53
	v_mov_b32_e32 v50, v76
	v_mov_b32_e32 v51, v77
	v_mov_b32_e32 v52, v94
	v_mov_b32_e32 v53, v95
	v_mov_b32_e32 v54, v98
	v_mov_b32_e32 v55, v99
	v_mov_b32_e32 v56, v96
	v_mov_b32_e32 v57, v97

.LBB0_432:
	s_andn2_saveexec_b64 s[22:23], s[12:13]
	s_cbranch_execz .LBB0_434
	v_ashrrev_i32_e32 v76, 6, v130
	v_add_u32_e32 v76, v79, v76
	v_mad_i64_i32 v[76:77], s[0:1], v76, s25, v[0:1]
	s_mov_b32 s0, 0x3e38aa3b
	v_lshlrev_b64 v[76:77], 7, v[76:77]
	v_mul_f32_e32 v50, s0, v50
	v_mul_f32_e32 v51, s0, v51
	v_mul_f32_e32 v52, s0, v52
	v_mul_f32_e32 v53, s0, v53
	v_lshl_add_u64 v[76:77], v[190:191], 0, v[76:77]
	v_cvt_pk_bf16_f32 v50, v50, v51
	v_cvt_pk_bf16_f32 v51, v52, v53
	global_store_dwordx2 v[76:77], v[50:51], off
	v_mul_f32_e32 v50, s0, v54
	v_mul_f32_e32 v51, s0, v55
	v_mul_f32_e32 v52, s0, v56
	v_mul_f32_e32 v53, s0, v57
	v_cvt_pk_bf16_f32 v50, v50, v51
	v_cvt_pk_bf16_f32 v51, v52, v53
	global_store_dwordx2 v[76:77], v[50:51], off offset:16
	v_mul_f32_e32 v50, s0, v58
	v_mul_f32_e32 v51, s0, v59
	v_mul_f32_e32 v52, s0, v60
	v_mul_f32_e32 v53, s0, v61
	v_cvt_pk_bf16_f32 v50, v50, v51
	v_cvt_pk_bf16_f32 v51, v52, v53
	global_store_dwordx2 v[76:77], v[50:51], off offset:32
	v_mul_f32_e32 v50, s0, v62
	v_mul_f32_e32 v51, s0, v63
	v_mul_f32_e32 v52, s0, v64
	v_mul_f32_e32 v53, s0, v65
	v_cvt_pk_bf16_f32 v50, v50, v51
	v_cvt_pk_bf16_f32 v51, v52, v53
	global_store_dwordx2 v[76:77], v[50:51], off offset:48

.LBB0_450:
	s_andn2_saveexec_b64 s[22:23], s[22:23]
	s_cbranch_execz .LBB0_458
	s_and_saveexec_b64 s[90:91], s[44:45]
	s_cbranch_execz .LBB0_453
	v_lshlrev_b32_e32 v50, 3, v87
	v_lshlrev_b32_e32 v52, 3, v88
	global_load_dwordx2 v[50:51], v50, s[80:81]
	s_nop 0
	global_load_dwordx2 v[52:53], v52, s[80:81]
	s_waitcnt vmcnt(1)
	v_mov_b32_e32 v54, v50
	s_waitcnt vmcnt(0)
	v_mov_b32_e32 v55, v52
	v_mov_b32_e32 v52, v51
	v_mul_f32_e32 v50, v42, v52
	v_mul_f32_e32 v51, v43, v53
	s_nop 0
	v_fma_f32 v50, v34, v54, -v50
	v_fma_f32 v51, v35, v55, -v51
	v_mul_f32_e32 v34, v34, v52
	v_mul_f32_e32 v35, v35, v53
	v_lshlrev_b32_e32 v52, 3, v86
	v_fma_f32 v42, v42, v54, v34
	v_fma_f32 v43, v43, v55, v35
	v_lshlrev_b32_e32 v34, 3, v85
	global_load_dwordx2 v[34:35], v34, s[80:81]
	s_nop 0
	global_load_dwordx2 v[52:53], v52, s[80:81]
	s_waitcnt vmcnt(1)
	v_mov_b32_e32 v54, v34
	s_waitcnt vmcnt(0)
	v_mov_b32_e32 v55, v52
	v_mov_b32_e32 v52, v35
	v_mul_f32_e32 v34, v44, v52
	v_mul_f32_e32 v35, v45, v53
	s_nop 0
	v_fma_f32 v56, v36, v54, -v34
	v_fma_f32 v57, v37, v55, -v35
	v_mul_f32_e32 v34, v36, v52
	v_mul_f32_e32 v35, v37, v53
	v_lshlrev_b32_e32 v36, 3, v84
	v_fma_f32 v44, v44, v54, v34
	v_fma_f32 v45, v45, v55, v35
	v_lshlrev_b32_e32 v34, 3, v83
	global_load_dwordx2 v[34:35], v34, s[80:81]
	s_nop 0
	global_load_dwordx2 v[36:37], v36, s[80:81]
	s_waitcnt vmcnt(1)
	v_mov_b32_e32 v52, v34
	s_waitcnt vmcnt(0)
	v_mov_b32_e32 v53, v36
	v_mov_b32_e32 v36, v35
	v_mul_f32_e32 v34, v46, v36
	v_mul_f32_e32 v35, v47, v37
	s_nop 0
	v_fma_f32 v54, v38, v52, -v34
	v_fma_f32 v55, v39, v53, -v35
	v_mul_f32_e32 v34, v38, v36
	v_mul_f32_e32 v35, v39, v37
	v_lshlrev_b32_e32 v36, 3, v81
	v_fma_f32 v46, v46, v52, v34
	v_fma_f32 v47, v47, v53, v35
	v_lshlrev_b32_e32 v34, 3, v82
	global_load_dwordx2 v[34:35], v34, s[80:81]
	s_nop 0
	global_load_dwordx2 v[36:37], v36, s[80:81]
	s_waitcnt vmcnt(1)
	v_mov_b32_e32 v53, v35
	s_waitcnt vmcnt(0)
	v_mov_b32_e32 v52, v37
	v_mov_b32_e32 v38, v36
	v_mov_b32_e32 v39, v34
	v_mul_f32_e32 v52, v48, v52
	v_mul_f32_e32 v53, v49, v53
	v_mul_f32_e32 v36, v48, v36
	v_fma_f32 v52, v40, v38, -v52
	v_fma_f32 v53, v41, v39, -v53
	v_mul_f32_e32 v38, v40, v37
	v_mov_b32_e32 v40, v49
	v_mul_f32_e32 v34, v40, v34
	v_mul_f32_e32 v35, v41, v35
	v_mov_b32_e32 v40, v52
	v_mov_b32_e32 v37, v34
	v_mov_b32_e32 v39, v35
	v_add_f32_e32 v48, v36, v38
	v_add_f32_e32 v49, v37, v39
	v_mov_b32_e32 v34, v50
	v_mov_b32_e32 v35, v51
	v_mov_b32_e32 v36, v56
	v_mov_b32_e32 v37, v57
	v_mov_b32_e32 v38, v54
	v_mov_b32_e32 v39, v55
	v_mov_b32_e32 v41, v53

.LBB0_455:
	s_andn2_saveexec_b64 s[90:91], s[12:13]
	s_cbranch_execz .LBB0_457
	v_subrev_u32_e32 v50, 20, v116
	v_lshrrev_b32_e32 v50, 1, v50
	v_add_u32_e32 v50, v78, v50
	v_mad_i64_i32 v[50:51], s[0:1], v50, s25, v[0:1]
	s_mov_b32 s0, 0x3e8293ee
	v_lshlrev_b64 v[50:51], 7, v[50:51]
	v_mul_f32_e32 v34, s0, v34
	v_mul_f32_e32 v35, s0, v35
	v_mul_f32_e32 v36, s0, v36
	v_mul_f32_e32 v37, s0, v37
	v_lshl_add_u64 v[50:51], v[186:187], 0, v[50:51]
	v_cvt_pk_bf16_f32 v34, v34, v35
	v_cvt_pk_bf16_f32 v35, v36, v37
	global_store_dwordx2 v[50:51], v[34:35], off offset:64
	v_mul_f32_e32 v34, s0, v38
	v_mul_f32_e32 v35, s0, v39
	v_mul_f32_e32 v36, s0, v40
	v_mul_f32_e32 v37, s0, v41
	v_cvt_pk_bf16_f32 v34, v34, v35
	v_cvt_pk_bf16_f32 v35, v36, v37
	global_store_dwordx2 v[50:51], v[34:35], off offset:80
	v_mul_f32_e32 v34, s0, v42
	v_mul_f32_e32 v35, s0, v43
	v_mul_f32_e32 v36, s0, v44
	v_mul_f32_e32 v37, s0, v45
	v_cvt_pk_bf16_f32 v34, v34, v35
	v_cvt_pk_bf16_f32 v35, v36, v37
	global_store_dwordx2 v[50:51], v[34:35], off offset:96
	v_mul_f32_e32 v34, s0, v46
	v_mul_f32_e32 v35, s0, v47
	v_mul_f32_e32 v36, s0, v48
	v_mul_f32_e32 v37, s0, v49
	v_cvt_pk_bf16_f32 v34, v34, v35
	v_cvt_pk_bf16_f32 v35, v36, v37
	global_store_dwordx2 v[50:51], v[34:35], off offset:112

.LBB0_462:
	s_and_saveexec_b64 s[22:23], s[44:45]
	s_cbranch_execz .LBB0_464
	v_or_b32_e32 v50, v89, v176
	v_lshlrev_b32_e32 v62, 3, v50
	global_load_dwordx4 v[52:55], v62, s[80:81] offset:16
	global_load_dwordx4 v[56:59], v62, s[80:81]
	s_waitcnt vmcnt(0)
	v_mov_b32_e32 v61, v58
	v_mov_b32_e32 v58, v57
	v_mov_b32_e32 v60, v56
	v_mul_f32_e32 v50, v42, v58
	v_mul_f32_e32 v51, v43, v59
	s_nop 0
	v_fma_f32 v50, v34, v60, -v50
	v_fma_f32 v51, v35, v61, -v51
	v_mul_f32_e32 v34, v34, v58
	v_mul_f32_e32 v35, v35, v59
	s_nop 0
	v_fma_f32 v42, v42, v60, v34
	v_fma_f32 v43, v43, v61, v35
	v_mov_b32_e32 v35, v54
	v_mov_b32_e32 v54, v53
	v_mov_b32_e32 v34, v52
	v_mul_f32_e32 v52, v44, v54
	v_mul_f32_e32 v53, v45, v55
	s_nop 0
	v_fma_f32 v56, v36, v34, -v52
	v_fma_f32 v57, v37, v35, -v53
	v_mul_f32_e32 v36, v36, v54
	v_mul_f32_e32 v37, v37, v55
	s_nop 0
	v_fma_f32 v44, v44, v34, v36
	v_fma_f32 v45, v45, v35, v37
	global_load_dwordx4 v[34:37], v62, s[80:81] offset:64
	global_load_dwordx4 v[52:55], v62, s[80:81] offset:80
	s_waitcnt vmcnt(1)
	v_mov_b32_e32 v59, v36
	v_mov_b32_e32 v36, v35
	v_mov_b32_e32 v58, v34
	v_mul_f32_e32 v34, v46, v36
	v_mul_f32_e32 v35, v47, v37
	s_nop 0
	v_fma_f32 v60, v38, v58, -v34
	v_fma_f32 v61, v39, v59, -v35
	v_mul_f32_e32 v34, v38, v36
	v_mul_f32_e32 v35, v39, v37
	s_waitcnt vmcnt(0)
	v_mov_b32_e32 v36, v53
	v_mov_b32_e32 v37, v55
	v_fma_f32 v46, v46, v58, v34
	v_fma_f32 v47, v47, v59, v35
	v_mov_b32_e32 v34, v52
	v_mov_b32_e32 v35, v54
	v_mul_f32_e32 v36, v48, v36
	v_mul_f32_e32 v37, v49, v37
	s_nop 0
	v_fma_f32 v58, v40, v34, -v36
	v_fma_f32 v59, v41, v35, -v37
	v_mul_f32_e32 v36, v40, v53
	v_mov_b32_e32 v40, v49
	v_mul_f32_e32 v38, v40, v54
	v_mul_f32_e32 v39, v41, v55
	v_mul_f32_e32 v34, v48, v52
	v_mov_b32_e32 v35, v38
	v_mov_b32_e32 v37, v39
	v_add_f32_e32 v48, v34, v36
	v_add_f32_e32 v49, v35, v37
	v_mov_b32_e32 v34, v50
	v_mov_b32_e32 v35, v51
	v_mov_b32_e32 v36, v56
	v_mov_b32_e32 v37, v57
	v_mov_b32_e32 v38, v60
	v_mov_b32_e32 v39, v61
	v_mov_b32_e32 v40, v58
	v_mov_b32_e32 v41, v59

.LBB0_466:
	s_andn2_saveexec_b64 s[22:23], s[12:13]
	s_cbranch_execz .LBB0_468
	v_ashrrev_i32_e32 v50, 6, v130
	v_add_u32_e32 v50, v79, v50
	v_mad_i64_i32 v[50:51], s[0:1], v50, s25, v[0:1]
	s_mov_b32 s0, 0x3e38aa3b
	v_lshlrev_b64 v[50:51], 7, v[50:51]
	v_mul_f32_e32 v34, s0, v34
	v_mul_f32_e32 v35, s0, v35
	v_mul_f32_e32 v36, s0, v36
	v_mul_f32_e32 v37, s0, v37
	v_lshl_add_u64 v[50:51], v[190:191], 0, v[50:51]
	v_cvt_pk_bf16_f32 v34, v34, v35
	v_cvt_pk_bf16_f32 v35, v36, v37
	global_store_dwordx2 v[50:51], v[34:35], off offset:64
	v_mul_f32_e32 v34, s0, v38
	v_mul_f32_e32 v35, s0, v39
	v_mul_f32_e32 v36, s0, v40
	v_mul_f32_e32 v37, s0, v41
	v_cvt_pk_bf16_f32 v34, v34, v35
	v_cvt_pk_bf16_f32 v35, v36, v37
	global_store_dwordx2 v[50:51], v[34:35], off offset:80
	v_mul_f32_e32 v34, s0, v42
	v_mul_f32_e32 v35, s0, v43
	v_mul_f32_e32 v36, s0, v44
	v_mul_f32_e32 v37, s0, v45
	v_cvt_pk_bf16_f32 v34, v34, v35
	v_cvt_pk_bf16_f32 v35, v36, v37
	global_store_dwordx2 v[50:51], v[34:35], off offset:96
	v_mul_f32_e32 v34, s0, v46
	v_mul_f32_e32 v35, s0, v47
	v_mul_f32_e32 v36, s0, v48
	v_mul_f32_e32 v37, s0, v49
	v_cvt_pk_bf16_f32 v34, v34, v35
	v_cvt_pk_bf16_f32 v35, v36, v37
	global_store_dwordx2 v[50:51], v[34:35], off offset:112

.LBB0_477:
	v_cmp_lt_u32_e32 vcc, 19, v133
	s_and_saveexec_b64 s[0:1], vcc
	s_xor_b64 s[42:43], exec, s[0:1]
	s_cbranch_execz .LBB0_509
	v_cmp_lt_u32_e32 vcc, 35, v133
	s_and_saveexec_b64 s[0:1], vcc
	s_xor_b64 s[22:23], exec, s[0:1]
	s_cbranch_execz .LBB0_500
	v_cmp_lt_u32_e32 vcc, 43, v133
	s_and_saveexec_b64 s[0:1], vcc
	s_xor_b64 s[88:89], exec, s[0:1]
	s_cbranch_execz .LBB0_497
	v_cmp_lt_u32_e32 vcc, 55, v133
	s_and_saveexec_b64 s[0:1], vcc
	s_xor_b64 s[90:91], exec, s[0:1]
	s_cbranch_execz .LBB0_486
	s_movk_i32 s0, 0x700
	v_cmp_eq_u32_e32 vcc, s0, v130
	s_and_saveexec_b64 s[92:93], vcc
	s_cbranch_execz .LBB0_485
	s_and_saveexec_b64 s[94:95], s[44:45]
	s_cbranch_execz .LBB0_484
	v_lshlrev_b32_e32 v44, 3, v55
	v_lshlrev_b32_e32 v58, 3, v56
	global_load_dwordx2 v[44:45], v44, s[80:81]
	s_nop 0
	global_load_dwordx2 v[58:59], v58, s[80:81]
	s_waitcnt vmcnt(1)
	v_mov_b32_e32 v60, v44
	s_waitcnt vmcnt(0)
	v_mov_b32_e32 v61, v58
	v_mov_b32_e32 v58, v45
	v_mul_f32_e32 v44, v26, v58
	v_mul_f32_e32 v45, v27, v59
	s_nop 0
	v_fma_f32 v44, v18, v60, -v44
	v_fma_f32 v45, v19, v61, -v45
	v_mul_f32_e32 v18, v18, v58
	v_mul_f32_e32 v19, v19, v59
	v_lshlrev_b32_e32 v58, 3, v54
	v_fma_f32 v26, v26, v60, v18
	v_fma_f32 v27, v27, v61, v19
	v_lshlrev_b32_e32 v18, 3, v53
	global_load_dwordx2 v[18:19], v18, s[80:81]
	s_nop 0
	global_load_dwordx2 v[58:59], v58, s[80:81]
	s_waitcnt vmcnt(1)
	v_mov_b32_e32 v60, v18
	s_waitcnt vmcnt(0)
	v_mov_b32_e32 v61, v58
	v_mov_b32_e32 v58, v19
	v_mul_f32_e32 v18, v28, v58
	v_mul_f32_e32 v19, v29, v59
	s_nop 0
	v_fma_f32 v62, v20, v60, -v18
	v_fma_f32 v63, v21, v61, -v19
	v_mul_f32_e32 v18, v20, v58
	v_mul_f32_e32 v19, v21, v59
	v_lshlrev_b32_e32 v20, 3, v52
	v_fma_f32 v28, v28, v60, v18
	v_fma_f32 v29, v29, v61, v19
	v_lshlrev_b32_e32 v18, 3, v51
	global_load_dwordx2 v[18:19], v18, s[80:81]
	s_nop 0
	global_load_dwordx2 v[20:21], v20, s[80:81]
	s_waitcnt vmcnt(1)
	v_mov_b32_e32 v58, v18
	s_waitcnt vmcnt(0)
	v_mov_b32_e32 v59, v20
	v_mov_b32_e32 v20, v19
	v_mul_f32_e32 v18, v30, v20
	v_mul_f32_e32 v19, v31, v21
	s_nop 0
	v_fma_f32 v60, v22, v58, -v18
	v_fma_f32 v61, v23, v59, -v19
	v_mul_f32_e32 v18, v22, v20
	v_mul_f32_e32 v19, v23, v21
	v_lshlrev_b32_e32 v20, 3, v49
	v_fma_f32 v30, v30, v58, v18
	v_fma_f32 v31, v31, v59, v19
	v_lshlrev_b32_e32 v18, 3, v50
	global_load_dwordx2 v[18:19], v18, s[80:81]
	s_nop 0
	global_load_dwordx2 v[20:21], v20, s[80:81]
	s_waitcnt vmcnt(1)
	v_mov_b32_e32 v59, v19
	s_waitcnt vmcnt(0)
	v_mov_b32_e32 v58, v21
	v_mov_b32_e32 v22, v20
	v_mov_b32_e32 v23, v18
	v_mul_f32_e32 v58, v32, v58
	v_mul_f32_e32 v59, v33, v59
	v_mul_f32_e32 v20, v32, v20
	v_fma_f32 v58, v24, v22, -v58
	v_fma_f32 v59, v25, v23, -v59
	v_mul_f32_e32 v22, v24, v21
	v_mov_b32_e32 v24, v33
	v_mul_f32_e32 v18, v24, v18
	v_mul_f32_e32 v19, v25, v19
	v_mov_b32_e32 v24, v58
	v_mov_b32_e32 v21, v18
	v_mov_b32_e32 v23, v19
	v_add_f32_e32 v32, v20, v22
	v_add_f32_e32 v33, v21, v23
	v_mov_b32_e32 v18, v44
	v_mov_b32_e32 v19, v45
	v_mov_b32_e32 v20, v62
	v_mov_b32_e32 v21, v63
	v_mov_b32_e32 v22, v60
	v_mov_b32_e32 v23, v61
	v_mov_b32_e32 v25, v59

.LBB0_500:
	s_andn2_saveexec_b64 s[22:23], s[22:23]
	s_cbranch_execz .LBB0_508
	s_and_saveexec_b64 s[88:89], s[44:45]
	s_cbranch_execz .LBB0_503
	v_lshlrev_b32_e32 v44, 3, v55
	v_lshlrev_b32_e32 v58, 3, v56
	global_load_dwordx2 v[44:45], v44, s[80:81]
	s_nop 0
	global_load_dwordx2 v[58:59], v58, s[80:81]
	s_waitcnt vmcnt(1)
	v_mov_b32_e32 v60, v44
	s_waitcnt vmcnt(0)
	v_mov_b32_e32 v61, v58
	v_mov_b32_e32 v58, v45
	v_mul_f32_e32 v44, v26, v58
	v_mul_f32_e32 v45, v27, v59
	s_nop 0
	v_fma_f32 v44, v18, v60, -v44
	v_fma_f32 v45, v19, v61, -v45
	v_mul_f32_e32 v18, v18, v58
	v_mul_f32_e32 v19, v19, v59
	v_lshlrev_b32_e32 v58, 3, v54
	v_fma_f32 v26, v26, v60, v18
	v_fma_f32 v27, v27, v61, v19
	v_lshlrev_b32_e32 v18, 3, v53
	global_load_dwordx2 v[18:19], v18, s[80:81]
	s_nop 0
	global_load_dwordx2 v[58:59], v58, s[80:81]
	s_waitcnt vmcnt(1)
	v_mov_b32_e32 v60, v18
	s_waitcnt vmcnt(0)
	v_mov_b32_e32 v61, v58
	v_mov_b32_e32 v58, v19
	v_mul_f32_e32 v18, v28, v58
	v_mul_f32_e32 v19, v29, v59
	s_nop 0
	v_fma_f32 v62, v20, v60, -v18
	v_fma_f32 v63, v21, v61, -v19
	v_mul_f32_e32 v18, v20, v58
	v_mul_f32_e32 v19, v21, v59
	v_lshlrev_b32_e32 v20, 3, v52
	v_fma_f32 v28, v28, v60, v18
	v_fma_f32 v29, v29, v61, v19
	v_lshlrev_b32_e32 v18, 3, v51
	global_load_dwordx2 v[18:19], v18, s[80:81]
	s_nop 0
	global_load_dwordx2 v[20:21], v20, s[80:81]
	s_waitcnt vmcnt(1)
	v_mov_b32_e32 v58, v18
	s_waitcnt vmcnt(0)
	v_mov_b32_e32 v59, v20
	v_mov_b32_e32 v20, v19
	v_mul_f32_e32 v18, v30, v20
	v_mul_f32_e32 v19, v31, v21
	s_nop 0
	v_fma_f32 v60, v22, v58, -v18
	v_fma_f32 v61, v23, v59, -v19
	v_mul_f32_e32 v18, v22, v20
	v_mul_f32_e32 v19, v23, v21
	v_lshlrev_b32_e32 v20, 3, v49
	v_fma_f32 v30, v30, v58, v18
	v_fma_f32 v31, v31, v59, v19
	v_lshlrev_b32_e32 v18, 3, v50
	global_load_dwordx2 v[18:19], v18, s[80:81]
	s_nop 0
	global_load_dwordx2 v[20:21], v20, s[80:81]
	s_waitcnt vmcnt(1)
	v_mov_b32_e32 v59, v19
	s_waitcnt vmcnt(0)
	v_mov_b32_e32 v58, v21
	v_mov_b32_e32 v22, v20
	v_mov_b32_e32 v23, v18
	v_mul_f32_e32 v58, v32, v58
	v_mul_f32_e32 v59, v33, v59
	v_mul_f32_e32 v20, v32, v20
	v_fma_f32 v58, v24, v22, -v58
	v_fma_f32 v59, v25, v23, -v59
	v_mul_f32_e32 v22, v24, v21
	v_mov_b32_e32 v24, v33
	v_mul_f32_e32 v18, v24, v18
	v_mul_f32_e32 v19, v25, v19
	v_mov_b32_e32 v24, v58
	v_mov_b32_e32 v21, v18
	v_mov_b32_e32 v23, v19
	v_add_f32_e32 v32, v20, v22
	v_add_f32_e32 v33, v21, v23
	v_mov_b32_e32 v18, v44
	v_mov_b32_e32 v19, v45
	v_mov_b32_e32 v20, v62
	v_mov_b32_e32 v21, v63
	v_mov_b32_e32 v22, v60
	v_mov_b32_e32 v23, v61
	v_mov_b32_e32 v25, v59

.LBB0_505:
	s_andn2_saveexec_b64 s[88:89], s[12:13]
	s_cbranch_execz .LBB0_507
	v_subrev_u32_e32 v44, 20, v133
	v_lshrrev_b32_e32 v44, 1, v44
	v_add_u32_e32 v44, v46, v44
	v_mad_i64_i32 v[44:45], s[0:1], v44, s25, v[0:1]
	s_mov_b32 s0, 0x3e8293ee
	v_lshlrev_b64 v[44:45], 7, v[44:45]
	v_mul_f32_e32 v18, s0, v18
	v_mul_f32_e32 v19, s0, v19
	v_mul_f32_e32 v20, s0, v20
	v_mul_f32_e32 v21, s0, v21
	v_lshl_add_u64 v[44:45], v[186:187], 0, v[44:45]
	v_cvt_pk_bf16_f32 v18, v18, v19
	v_cvt_pk_bf16_f32 v19, v20, v21
	global_store_dwordx2 v[44:45], v[18:19], off
	v_mul_f32_e32 v18, s0, v22
	v_mul_f32_e32 v19, s0, v23
	v_mul_f32_e32 v20, s0, v24
	v_mul_f32_e32 v21, s0, v25
	v_cvt_pk_bf16_f32 v18, v18, v19
	v_cvt_pk_bf16_f32 v19, v20, v21
	global_store_dwordx2 v[44:45], v[18:19], off offset:16
	v_mul_f32_e32 v18, s0, v26
	v_mul_f32_e32 v19, s0, v27
	v_mul_f32_e32 v20, s0, v28
	v_mul_f32_e32 v21, s0, v29
	v_cvt_pk_bf16_f32 v18, v18, v19
	v_cvt_pk_bf16_f32 v19, v20, v21
	global_store_dwordx2 v[44:45], v[18:19], off offset:32
	v_mul_f32_e32 v18, s0, v30
	v_mul_f32_e32 v19, s0, v31
	v_mul_f32_e32 v20, s0, v32
	v_mul_f32_e32 v21, s0, v33
	v_cvt_pk_bf16_f32 v18, v18, v19
	v_cvt_pk_bf16_f32 v19, v20, v21
	global_store_dwordx2 v[44:45], v[18:19], off offset:48

.LBB0_512:
	s_and_saveexec_b64 s[22:23], s[44:45]
	s_cbranch_execz .LBB0_514
	v_or_b32_e32 v44, v44, v176
	v_lshlrev_b32_e32 v68, 3, v44
	global_load_dwordx4 v[58:61], v68, s[80:81] offset:16
	global_load_dwordx4 v[62:65], v68, s[80:81]
	s_waitcnt vmcnt(0)
	v_mov_b32_e32 v67, v64
	v_mov_b32_e32 v64, v63
	v_mov_b32_e32 v66, v62
	v_mul_f32_e32 v44, v26, v64
	v_mul_f32_e32 v45, v27, v65
	s_nop 0
	v_fma_f32 v44, v18, v66, -v44
	v_fma_f32 v45, v19, v67, -v45
	v_mul_f32_e32 v18, v18, v64
	v_mul_f32_e32 v19, v19, v65
	s_nop 0
	v_fma_f32 v26, v26, v66, v18
	v_fma_f32 v27, v27, v67, v19
	v_mov_b32_e32 v19, v60
	v_mov_b32_e32 v60, v59
	v_mov_b32_e32 v18, v58
	v_mul_f32_e32 v58, v28, v60
	v_mul_f32_e32 v59, v29, v61
	s_nop 0
	v_fma_f32 v62, v20, v18, -v58
	v_fma_f32 v63, v21, v19, -v59
	v_mul_f32_e32 v20, v20, v60
	v_mul_f32_e32 v21, v21, v61
	s_nop 0
	v_fma_f32 v28, v28, v18, v20
	v_fma_f32 v29, v29, v19, v21
	global_load_dwordx4 v[18:21], v68, s[80:81] offset:64
	global_load_dwordx4 v[58:61], v68, s[80:81] offset:80
	s_waitcnt vmcnt(1)
	v_mov_b32_e32 v65, v20
	v_mov_b32_e32 v20, v19
	v_mov_b32_e32 v64, v18
	v_mul_f32_e32 v18, v30, v20
	v_mul_f32_e32 v19, v31, v21
	s_nop 0
	v_fma_f32 v66, v22, v64, -v18
	v_fma_f32 v67, v23, v65, -v19
	v_mul_f32_e32 v18, v22, v20
	v_mul_f32_e32 v19, v23, v21
	s_waitcnt vmcnt(0)
	v_mov_b32_e32 v20, v59
	v_mov_b32_e32 v21, v61
	v_fma_f32 v30, v30, v64, v18
	v_fma_f32 v31, v31, v65, v19
	v_mov_b32_e32 v18, v58
	v_mov_b32_e32 v19, v60
	v_mul_f32_e32 v20, v32, v20
	v_mul_f32_e32 v21, v33, v21
	s_nop 0
	v_fma_f32 v64, v24, v18, -v20
	v_fma_f32 v65, v25, v19, -v21
	v_mul_f32_e32 v20, v24, v59
	v_mov_b32_e32 v24, v33
	v_mul_f32_e32 v22, v24, v60
	v_mul_f32_e32 v23, v25, v61
	v_mul_f32_e32 v18, v32, v58
	v_mov_b32_e32 v19, v22
	v_mov_b32_e32 v21, v23
	v_add_f32_e32 v32, v18, v20
	v_add_f32_e32 v33, v19, v21
	v_mov_b32_e32 v18, v44
	v_mov_b32_e32 v19, v45
	v_mov_b32_e32 v20, v62
	v_mov_b32_e32 v21, v63
	v_mov_b32_e32 v22, v66
	v_mov_b32_e32 v23, v67
	v_mov_b32_e32 v24, v64
	v_mov_b32_e32 v25, v65

.LBB0_516:
	s_andn2_saveexec_b64 s[22:23], s[12:13]
	s_cbranch_execz .LBB0_518
	v_ashrrev_i32_e32 v44, 6, v130
	v_add_u32_e32 v44, v47, v44
	v_mad_i64_i32 v[44:45], s[0:1], v44, s25, v[0:1]
	s_mov_b32 s0, 0x3e38aa3b
	v_lshlrev_b64 v[44:45], 7, v[44:45]
	v_mul_f32_e32 v18, s0, v18
	v_mul_f32_e32 v19, s0, v19
	v_mul_f32_e32 v20, s0, v20
	v_mul_f32_e32 v21, s0, v21
	v_lshl_add_u64 v[44:45], v[190:191], 0, v[44:45]
	v_cvt_pk_bf16_f32 v18, v18, v19
	v_cvt_pk_bf16_f32 v19, v20, v21
	global_store_dwordx2 v[44:45], v[18:19], off
	v_mul_f32_e32 v18, s0, v22
	v_mul_f32_e32 v19, s0, v23
	v_mul_f32_e32 v20, s0, v24
	v_mul_f32_e32 v21, s0, v25
	v_cvt_pk_bf16_f32 v18, v18, v19
	v_cvt_pk_bf16_f32 v19, v20, v21
	global_store_dwordx2 v[44:45], v[18:19], off offset:16
	v_mul_f32_e32 v18, s0, v26
	v_mul_f32_e32 v19, s0, v27
	v_mul_f32_e32 v20, s0, v28
	v_mul_f32_e32 v21, s0, v29
	v_cvt_pk_bf16_f32 v18, v18, v19
	v_cvt_pk_bf16_f32 v19, v20, v21
	global_store_dwordx2 v[44:45], v[18:19], off offset:32
	v_mul_f32_e32 v18, s0, v30
	v_mul_f32_e32 v19, s0, v31
	v_mul_f32_e32 v20, s0, v32
	v_mul_f32_e32 v21, s0, v33
	v_cvt_pk_bf16_f32 v18, v18, v19
	v_cvt_pk_bf16_f32 v19, v20, v21
	global_store_dwordx2 v[44:45], v[18:19], off offset:48

.LBB0_534:
	s_andn2_saveexec_b64 s[22:23], s[22:23]
	s_cbranch_execz .LBB0_542
	s_and_saveexec_b64 s[42:43], s[44:45]
	s_cbranch_execz .LBB0_537
	v_lshlrev_b32_e32 v18, 3, v55
	v_lshlrev_b32_e32 v20, 3, v56
	global_load_dwordx2 v[18:19], v18, s[80:81]
	s_nop 0
	global_load_dwordx2 v[20:21], v20, s[80:81]
	s_waitcnt vmcnt(1)
	v_mov_b32_e32 v22, v18
	s_waitcnt vmcnt(0)
	v_mov_b32_e32 v23, v20
	v_mov_b32_e32 v20, v19
	v_mul_f32_e32 v18, v10, v20
	v_mul_f32_e32 v19, v11, v21
	s_nop 0
	v_fma_f32 v18, v2, v22, -v18
	v_fma_f32 v19, v3, v23, -v19
	v_mul_f32_e32 v2, v2, v20
	v_mul_f32_e32 v3, v3, v21
	v_lshlrev_b32_e32 v20, 3, v54
	v_fma_f32 v10, v10, v22, v2
	v_fma_f32 v11, v11, v23, v3
	v_lshlrev_b32_e32 v2, 3, v53
	global_load_dwordx2 v[2:3], v2, s[80:81]
	s_nop 0
	global_load_dwordx2 v[20:21], v20, s[80:81]
	s_waitcnt vmcnt(1)
	v_mov_b32_e32 v22, v2
	s_waitcnt vmcnt(0)
	v_mov_b32_e32 v23, v20
	v_mov_b32_e32 v20, v3
	v_mul_f32_e32 v2, v12, v20
	v_mul_f32_e32 v3, v13, v21
	s_nop 0
	v_fma_f32 v24, v4, v22, -v2
	v_fma_f32 v25, v5, v23, -v3
	v_mul_f32_e32 v2, v4, v20
	v_mul_f32_e32 v3, v5, v21
	v_lshlrev_b32_e32 v4, 3, v52
	v_fma_f32 v12, v12, v22, v2
	v_fma_f32 v13, v13, v23, v3
	v_lshlrev_b32_e32 v2, 3, v51
	global_load_dwordx2 v[2:3], v2, s[80:81]
	s_nop 0
	global_load_dwordx2 v[4:5], v4, s[80:81]
	s_waitcnt vmcnt(1)
	v_mov_b32_e32 v20, v2
	s_waitcnt vmcnt(0)
	v_mov_b32_e32 v21, v4
	v_mov_b32_e32 v4, v3
	v_mul_f32_e32 v2, v14, v4
	v_mul_f32_e32 v3, v15, v5
	s_nop 0
	v_fma_f32 v22, v6, v20, -v2
	v_fma_f32 v23, v7, v21, -v3
	v_mul_f32_e32 v2, v6, v4
	v_mul_f32_e32 v3, v7, v5
	v_lshlrev_b32_e32 v4, 3, v49
	v_fma_f32 v14, v14, v20, v2
	v_fma_f32 v15, v15, v21, v3
	v_lshlrev_b32_e32 v2, 3, v50
	global_load_dwordx2 v[2:3], v2, s[80:81]
	s_nop 0
	global_load_dwordx2 v[4:5], v4, s[80:81]
	s_waitcnt vmcnt(1)
	v_mov_b32_e32 v21, v3
	s_waitcnt vmcnt(0)
	v_mov_b32_e32 v20, v5
	v_mov_b32_e32 v6, v4
	v_mov_b32_e32 v7, v2
	v_mul_f32_e32 v20, v16, v20
	v_mul_f32_e32 v21, v17, v21
	v_mul_f32_e32 v4, v16, v4
	v_fma_f32 v20, v8, v6, -v20
	v_fma_f32 v21, v9, v7, -v21
	v_mul_f32_e32 v6, v8, v5
	v_mov_b32_e32 v8, v17
	v_mul_f32_e32 v2, v8, v2
	v_mul_f32_e32 v3, v9, v3
	v_mov_b32_e32 v8, v20
	v_mov_b32_e32 v5, v2
	v_mov_b32_e32 v7, v3
	v_add_f32_e32 v16, v4, v6
	v_add_f32_e32 v17, v5, v7
	v_mov_b32_e32 v2, v18
	v_mov_b32_e32 v3, v19
	v_mov_b32_e32 v4, v24
	v_mov_b32_e32 v5, v25
	v_mov_b32_e32 v6, v22
	v_mov_b32_e32 v7, v23
	v_mov_b32_e32 v9, v21

.LBB0_539:
	s_andn2_saveexec_b64 s[42:43], s[12:13]
	s_cbranch_execz .LBB0_541
	v_subrev_u32_e32 v18, 20, v116
	v_lshrrev_b32_e32 v18, 1, v18
	v_add_u32_e32 v18, v46, v18
	v_mad_i64_i32 v[18:19], s[0:1], v18, s25, v[0:1]
	s_mov_b32 s0, 0x3e8293ee
	v_lshlrev_b64 v[18:19], 7, v[18:19]
	v_mul_f32_e32 v2, s0, v2
	v_mul_f32_e32 v3, s0, v3
	v_mul_f32_e32 v4, s0, v4
	v_mul_f32_e32 v5, s0, v5
	v_lshl_add_u64 v[18:19], v[186:187], 0, v[18:19]
	v_cvt_pk_bf16_f32 v2, v2, v3
	v_cvt_pk_bf16_f32 v3, v4, v5
	global_store_dwordx2 v[18:19], v[2:3], off offset:64
	v_mul_f32_e32 v2, s0, v6
	v_mul_f32_e32 v3, s0, v7
	v_mul_f32_e32 v4, s0, v8
	v_mul_f32_e32 v5, s0, v9
	v_cvt_pk_bf16_f32 v2, v2, v3
	v_cvt_pk_bf16_f32 v3, v4, v5
	global_store_dwordx2 v[18:19], v[2:3], off offset:80
	v_mul_f32_e32 v2, s0, v10
	v_mul_f32_e32 v3, s0, v11
	v_mul_f32_e32 v4, s0, v12
	v_mul_f32_e32 v5, s0, v13
	v_cvt_pk_bf16_f32 v2, v2, v3
	v_cvt_pk_bf16_f32 v3, v4, v5
	global_store_dwordx2 v[18:19], v[2:3], off offset:96
	v_mul_f32_e32 v2, s0, v14
	v_mul_f32_e32 v3, s0, v15
	v_mul_f32_e32 v4, s0, v16
	v_mul_f32_e32 v5, s0, v17
	v_cvt_pk_bf16_f32 v2, v2, v3
	v_cvt_pk_bf16_f32 v3, v4, v5
	global_store_dwordx2 v[18:19], v[2:3], off offset:112

.LBB0_546:
	s_and_saveexec_b64 s[22:23], s[44:45]
	s_cbranch_execz .LBB0_548
	v_or_b32_e32 v18, v57, v176
	v_lshlrev_b32_e32 v30, 3, v18
	global_load_dwordx4 v[20:23], v30, s[80:81] offset:16
	global_load_dwordx4 v[24:27], v30, s[80:81]
	s_waitcnt vmcnt(0)
	v_mov_b32_e32 v29, v26
	v_mov_b32_e32 v26, v25
	v_mov_b32_e32 v28, v24
	v_mul_f32_e32 v18, v10, v26
	v_mul_f32_e32 v19, v11, v27
	s_nop 0
	v_fma_f32 v18, v2, v28, -v18
	v_fma_f32 v19, v3, v29, -v19
	v_mul_f32_e32 v2, v2, v26
	v_mul_f32_e32 v3, v3, v27
	s_nop 0
	v_fma_f32 v10, v10, v28, v2
	v_fma_f32 v11, v11, v29, v3
	v_mov_b32_e32 v3, v22
	v_mov_b32_e32 v22, v21
	v_mov_b32_e32 v2, v20
	v_mul_f32_e32 v20, v12, v22
	v_mul_f32_e32 v21, v13, v23
	s_nop 0
	v_fma_f32 v24, v4, v2, -v20
	v_fma_f32 v25, v5, v3, -v21
	v_mul_f32_e32 v4, v4, v22
	v_mul_f32_e32 v5, v5, v23
	s_nop 0
	v_fma_f32 v12, v12, v2, v4
	v_fma_f32 v13, v13, v3, v5
	global_load_dwordx4 v[2:5], v30, s[80:81] offset:64
	global_load_dwordx4 v[20:23], v30, s[80:81] offset:80
	s_waitcnt vmcnt(1)
	v_mov_b32_e32 v27, v4
	v_mov_b32_e32 v4, v3
	v_mov_b32_e32 v26, v2
	v_mul_f32_e32 v2, v14, v4
	v_mul_f32_e32 v3, v15, v5
	s_nop 0
	v_fma_f32 v28, v6, v26, -v2
	v_fma_f32 v29, v7, v27, -v3
	v_mul_f32_e32 v2, v6, v4
	v_mul_f32_e32 v3, v7, v5
	s_waitcnt vmcnt(0)
	v_mov_b32_e32 v4, v21
	v_mov_b32_e32 v5, v23
	v_fma_f32 v14, v14, v26, v2
	v_fma_f32 v15, v15, v27, v3
	v_mov_b32_e32 v2, v20
	v_mov_b32_e32 v3, v22
	v_mul_f32_e32 v4, v16, v4
	v_mul_f32_e32 v5, v17, v5
	s_nop 0
	v_fma_f32 v26, v8, v2, -v4
	v_fma_f32 v27, v9, v3, -v5
	v_mul_f32_e32 v4, v8, v21
	v_mov_b32_e32 v8, v17
	v_mul_f32_e32 v6, v8, v22
	v_mul_f32_e32 v7, v9, v23
	v_mul_f32_e32 v2, v16, v20
	v_mov_b32_e32 v3, v6
	v_mov_b32_e32 v5, v7
	v_add_f32_e32 v16, v2, v4
	v_add_f32_e32 v17, v3, v5
	v_mov_b32_e32 v2, v18
	v_mov_b32_e32 v3, v19
	v_mov_b32_e32 v4, v24
	v_mov_b32_e32 v5, v25
	v_mov_b32_e32 v6, v28
	v_mov_b32_e32 v7, v29
	v_mov_b32_e32 v8, v26
	v_mov_b32_e32 v9, v27

.LBB0_550:
	s_andn2_saveexec_b64 s[22:23], s[12:13]
	s_cbranch_execz .LBB0_213
	v_ashrrev_i32_e32 v18, 6, v130
	v_add_u32_e32 v18, v47, v18
	v_mad_i64_i32 v[18:19], s[0:1], v18, s25, v[0:1]
	s_mov_b32 s0, 0x3e38aa3b
	v_lshlrev_b64 v[18:19], 7, v[18:19]
	v_mul_f32_e32 v2, s0, v2
	v_mul_f32_e32 v3, s0, v3
	v_mul_f32_e32 v4, s0, v4
	v_mul_f32_e32 v5, s0, v5
	v_lshl_add_u64 v[18:19], v[190:191], 0, v[18:19]
	v_cvt_pk_bf16_f32 v2, v2, v3
	v_cvt_pk_bf16_f32 v3, v4, v5
	global_store_dwordx2 v[18:19], v[2:3], off offset:64
	v_mul_f32_e32 v2, s0, v6
	v_mul_f32_e32 v3, s0, v7
	v_mul_f32_e32 v4, s0, v8
	v_mul_f32_e32 v5, s0, v9
	v_cvt_pk_bf16_f32 v2, v2, v3
	v_cvt_pk_bf16_f32 v3, v4, v5
	global_store_dwordx2 v[18:19], v[2:3], off offset:80
	v_mul_f32_e32 v2, s0, v10
	v_mul_f32_e32 v3, s0, v11
	v_mul_f32_e32 v4, s0, v12
	v_mul_f32_e32 v5, s0, v13
	v_cvt_pk_bf16_f32 v2, v2, v3
	v_cvt_pk_bf16_f32 v3, v4, v5
	global_store_dwordx2 v[18:19], v[2:3], off offset:96
	v_mul_f32_e32 v2, s0, v14
	v_mul_f32_e32 v3, s0, v15
	v_mul_f32_e32 v4, s0, v16
	v_mul_f32_e32 v5, s0, v17
	v_cvt_pk_bf16_f32 v2, v2, v3
	v_cvt_pk_bf16_f32 v3, v4, v5
	global_store_dwordx2 v[18:19], v[2:3], off offset:112
	s_branch .LBB0_213

.LBB0_556:
	v_and_b32_e32 v52, 0xff, v200
	s_movk_i32 s2, 0x4000
	v_ashrrev_i32_e32 v48, 3, v52
	v_add3_u32 v2, v51, v48, s2
	v_ashrrev_i32_e32 v3, 31, v2
	v_lshlrev_b64 v[2:3], 11, v[2:3]
	v_lshlrev_b32_e32 v0, 4, v52
	v_and_b32_e32 v0, 0x70, v0
	v_lshl_add_u64 v[2:3], s[82:83], 0, v[2:3]
	v_lshl_add_u64 v[34:35], v[2:3], 0, v[0:1]
	s_mov_b32 s0, 0x10000
	v_ashrrev_i32_e32 v49, 31, v48
	v_add_co_u32_e32 v36, vcc, s0, v34
	v_lshlrev_b64 v[4:5], 11, v[48:49]
	s_nop 0
	v_addc_co_u32_e32 v37, vcc, 0, v35, vcc
	v_lshl_add_u64 v[4:5], s[84:85], 0, v[4:5]
	v_add_co_u32_e32 v38, vcc, s7, v34
	v_lshl_add_u64 v[56:57], v[4:5], 0, v[0:1]
	s_nop 0
	v_addc_co_u32_e32 v39, vcc, 0, v35, vcc
	s_mov_b32 s0, 0x380000
	v_add_co_u32_e32 v14, vcc, s0, v56
	s_mov_b32 s0, 0x390000
	s_nop 0
	v_addc_co_u32_e32 v15, vcc, 0, v57, vcc
	v_add_co_u32_e32 v40, vcc, s0, v56
	s_mov_b32 s0, 0x3a0000
	s_nop 0
	v_addc_co_u32_e32 v41, vcc, 0, v57, vcc
	global_load_dwordx4 v[2:5], v[34:35], off
	global_load_dwordx4 v[6:9], v[36:37], off
	global_load_dwordx4 v[10:13], v[38:39], off
	s_nop 0
	global_load_dwordx4 v[14:17], v[14:15], off
	s_nop 0
	global_load_dwordx4 v[18:21], v[40:41], off
	v_add_co_u32_e32 v42, vcc, s0, v56
	s_mov_b32 s0, 0x3b0000
	s_nop 0
	v_addc_co_u32_e32 v43, vcc, 0, v57, vcc
	v_add_co_u32_e32 v44, vcc, s0, v56
	global_load_dwordx4 v[22:25], v[42:43], off
	s_nop 0
	v_addc_co_u32_e32 v45, vcc, 0, v57, vcc
	global_load_dwordx4 v[26:29], v[44:45], off
	v_add_co_u32_e32 v46, vcc, s54, v34
	v_lshrrev_b32_e32 v49, 1, v52
	s_nop 0
	v_addc_co_u32_e32 v47, vcc, 0, v35, vcc
	global_load_dwordx4 v[30:33], v[46:47], off
	v_and_b32_e32 v54, 0x5f, v52
	v_mul_lo_u32 v48, v48, s4
	v_and_b32_e32 v122, 16, v49
	v_mul_u32_u24_e32 v49, 0x90, v54
	s_mov_b64 s[0:1], 0x380000
	v_add3_u32 v54, v48, v0, v232
	v_add3_u32 v0, v49, v122, v232
	v_lshl_add_u64 v[48:49], v[56:57], 0, s[0:1]
	global_load_dwordx4 v[58:61], v[34:35], off offset:128
	global_load_dwordx4 v[62:65], v[42:43], off offset:128
	global_load_dwordx4 v[66:69], v[44:45], off offset:128
	global_load_dwordx4 v[70:73], v[44:45], off offset:256
	global_load_dwordx4 v[74:77], v[42:43], off offset:256
	global_load_dwordx4 v[78:81], v[40:41], off offset:128
	global_load_dwordx4 v[82:85], v[40:41], off offset:256
	global_load_dwordx4 v[86:89], v[48:49], off offset:128
	global_load_dwordx4 v[90:93], v[48:49], off offset:256
	global_load_dwordx4 v[94:97], v[36:37], off offset:128
	global_load_dwordx4 v[98:101], v[38:39], off offset:128
	global_load_dwordx4 v[102:105], v[46:47], off offset:128
	global_load_dwordx4 v[106:109], v[46:47], off offset:256
	global_load_dwordx4 v[110:113], v[38:39], off offset:256
	global_load_dwordx4 v[114:117], v[36:37], off offset:256
	global_load_dwordx4 v[118:121], v[34:35], off offset:256
	v_and_b32_e32 v53, 31, v52
	v_ashrrev_i32_e32 v55, 1, v52
	s_movk_i32 s0, 0xffc0
	v_and_or_b32 v55, v55, s0, v53
	v_add_u32_e32 v57, 0x9000, v54
	s_waitcnt vmcnt(23)
	ds_write_b128 v54, v[2:5]
	s_waitcnt vmcnt(20)
	ds_write_b128 v54, v[14:17] offset:18432
	s_waitcnt vmcnt(19)
	ds_write_b128 v54, v[18:21] offset:23040
	s_waitcnt vmcnt(18)
	ds_write_b128 v54, v[22:25] offset:27648
	s_waitcnt vmcnt(17)
	ds_write_b128 v54, v[26:29] offset:32256
	ds_write_b128 v54, v[6:9] offset:4608
	ds_write_b128 v54, v[10:13] offset:9216
	s_waitcnt vmcnt(16)
	ds_write_b128 v54, v[30:33] offset:13824
	s_waitcnt lgkmcnt(0)
	s_barrier
	ds_read_b128 v[2:5], v0 offset:18432
	v_mul_lo_u32 v6, v55, s4
	v_add3_u32 v56, v6, v122, v232
	ds_read_b128 v[6:9], v56
	ds_read_b128 v[122:125], v56 offset:32
	ds_read_b128 v[126:129], v0 offset:18464
	s_waitcnt lgkmcnt(2)
	v_mfma_f32_32x32x16_bf16 v[18:33], v[2:5], v[6:9], 0
	ds_read_b128 v[6:9], v56 offset:4608
	ds_read_b128 v[130:133], v56 offset:4640
	s_waitcnt lgkmcnt(1)
	v_mfma_f32_32x32x16_bf16 v[2:17], v[2:5], v[6:9], 0
	v_mfma_f32_32x32x16_bf16 v[18:33], v[126:129], v[122:125], v[18:33]
	s_waitcnt lgkmcnt(0)
	v_mfma_f32_32x32x16_bf16 v[2:17], v[126:129], v[130:133], v[2:17]
	ds_read_b128 v[122:125], v0 offset:18496
	ds_read_b128 v[126:129], v56 offset:64
	ds_read_b128 v[130:133], v56 offset:96
	ds_read_b128 v[134:137], v0 offset:18528
	s_waitcnt lgkmcnt(2)
	v_mfma_f32_32x32x16_bf16 v[18:33], v[122:125], v[126:129], v[18:33]
	ds_read_b128 v[126:129], v56 offset:4672
	ds_read_b128 v[138:141], v56 offset:4704
	s_waitcnt lgkmcnt(1)
	v_mfma_f32_32x32x16_bf16 v[2:17], v[122:125], v[126:129], v[2:17]
	global_load_dwordx4 v[122:125], v[36:37], off offset:384
	global_load_dwordx4 v[126:129], v[38:39], off offset:384
	global_load_dwordx4 v[142:145], v[34:35], off offset:384
	global_load_dwordx4 v[146:149], v[48:49], off offset:384
	v_mfma_f32_32x32x16_bf16 v[18:33], v[134:137], v[130:133], v[18:33]
	global_load_dwordx4 v[130:133], v[46:47], off offset:384
	global_load_dwordx4 v[150:153], v[40:41], off offset:384
	global_load_dwordx4 v[154:157], v[42:43], off offset:384
	global_load_dwordx4 v[158:161], v[44:45], off offset:384
	s_waitcnt vmcnt(23)
	ds_write_b128 v54, v[58:61] offset:36864
	s_waitcnt vmcnt(14)
	ds_write_b128 v54, v[94:97] offset:41472
	s_waitcnt vmcnt(13)
	ds_write_b128 v54, v[98:101] offset:46080
	s_waitcnt vmcnt(12)
	ds_write_b128 v54, v[102:105] offset:50688
	ds_write_b128 v54, v[86:89] offset:55296
	ds_write_b128 v54, v[78:81] offset:59904
	ds_write_b128 v54, v[62:65] offset:64512
	ds_write_b128 v57, v[66:69] offset:32256
	s_waitcnt lgkmcnt(0)
	s_barrier
	ds_read_b128 v[58:61], v0 offset:55296
	ds_read_b128 v[62:65], v56 offset:36864
	ds_read_b128 v[66:69], v56 offset:36896
	ds_read_b128 v[78:81], v0 offset:55328
	v_mfma_f32_32x32x16_bf16 v[2:17], v[134:137], v[138:141], v[2:17]
	s_waitcnt lgkmcnt(2)
	v_mfma_f32_32x32x16_bf16 v[18:33], v[58:61], v[62:65], v[18:33]
	ds_read_b128 v[62:65], v56 offset:41472
	ds_read_b128 v[86:89], v56 offset:41504
	s_waitcnt lgkmcnt(1)
	v_mfma_f32_32x32x16_bf16 v[2:17], v[58:61], v[62:65], v[2:17]
	v_mfma_f32_32x32x16_bf16 v[18:33], v[78:81], v[66:69], v[18:33]
	s_waitcnt lgkmcnt(0)
	v_mfma_f32_32x32x16_bf16 v[2:17], v[78:81], v[86:89], v[2:17]
	ds_read_b128 v[58:61], v0 offset:55360
	ds_read_b128 v[62:65], v56 offset:36928
	ds_read_b128 v[66:69], v56 offset:36960
	ds_read_b128 v[78:81], v0 offset:55392
	s_waitcnt lgkmcnt(2)
	v_mfma_f32_32x32x16_bf16 v[18:33], v[58:61], v[62:65], v[18:33]
	ds_read_b128 v[62:65], v56 offset:41536
	ds_read_b128 v[86:89], v56 offset:41568
	s_waitcnt lgkmcnt(1)
	v_mfma_f32_32x32x16_bf16 v[2:17], v[58:61], v[62:65], v[2:17]
	v_add_u32_e32 v58, 0x10e00, v54
	v_mfma_f32_32x32x16_bf16 v[18:33], v[78:81], v[66:69], v[18:33]
	global_load_dwordx4 v[60:63], v[36:37], off offset:512
	global_load_dwordx4 v[64:67], v[38:39], off offset:512
	global_load_dwordx4 v[94:97], v[34:35], off offset:512
	global_load_dwordx4 v[98:101], v[48:49], off offset:512
	global_load_dwordx4 v[102:105], v[46:47], off offset:512
	global_load_dwordx4 v[134:137], v[40:41], off offset:512
	global_load_dwordx4 v[138:141], v[42:43], off offset:512
	global_load_dwordx4 v[164:167], v[44:45], off offset:512
	s_waitcnt vmcnt(16)
	ds_write_b128 v54, v[118:121]
	ds_write_b128 v54, v[114:117] offset:4608
	ds_write_b128 v54, v[110:113] offset:9216
	ds_write_b128 v54, v[106:109] offset:13824
	ds_write_b128 v54, v[90:93] offset:18432
	ds_write_b128 v54, v[82:85] offset:23040
	ds_write_b128 v54, v[74:77] offset:27648
	ds_write_b128 v54, v[70:73] offset:32256
	s_waitcnt lgkmcnt(0)
	s_barrier
	v_mfma_f32_32x32x16_bf16 v[2:17], v[78:81], v[86:89], v[2:17]
	ds_read_b128 v[68:71], v0 offset:18432
	ds_read_b128 v[72:75], v56
	ds_read_b128 v[76:79], v56 offset:32
	ds_read_b128 v[80:83], v0 offset:18464
	s_waitcnt lgkmcnt(2)
	v_mfma_f32_32x32x16_bf16 v[18:33], v[68:71], v[72:75], v[18:33]
	ds_read_b128 v[72:75], v56 offset:4608
	ds_read_b128 v[84:87], v56 offset:4640
	s_waitcnt lgkmcnt(1)
	v_mfma_f32_32x32x16_bf16 v[2:17], v[68:71], v[72:75], v[2:17]
	v_mfma_f32_32x32x16_bf16 v[18:33], v[80:83], v[76:79], v[18:33]
	s_waitcnt lgkmcnt(0)
	v_mfma_f32_32x32x16_bf16 v[2:17], v[80:83], v[84:87], v[2:17]
	ds_read_b128 v[68:71], v0 offset:18496
	ds_read_b128 v[72:75], v56 offset:64
	ds_read_b128 v[76:79], v56 offset:96
	ds_read_b128 v[80:83], v0 offset:18528
	s_waitcnt lgkmcnt(2)
	v_mfma_f32_32x32x16_bf16 v[18:33], v[68:71], v[72:75], v[18:33]
	ds_read_b128 v[72:75], v56 offset:4672
	ds_read_b128 v[84:87], v56 offset:4704
	s_waitcnt lgkmcnt(1)
	v_mfma_f32_32x32x16_bf16 v[2:17], v[68:71], v[72:75], v[2:17]
	v_mfma_f32_32x32x16_bf16 v[18:33], v[80:83], v[76:79], v[18:33]
	global_load_dwordx4 v[68:71], v[36:37], off offset:640
	global_load_dwordx4 v[72:75], v[38:39], off offset:640
	global_load_dwordx4 v[76:79], v[34:35], off offset:640
	global_load_dwordx4 v[88:91], v[48:49], off offset:640
	global_load_dwordx4 v[106:109], v[46:47], off offset:640
	global_load_dwordx4 v[110:113], v[40:41], off offset:640
	global_load_dwordx4 v[114:117], v[42:43], off offset:640
	global_load_dwordx4 v[118:121], v[44:45], off offset:640
	s_waitcnt vmcnt(21)
	ds_write_b128 v54, v[142:145] offset:36864
	ds_write_b128 v54, v[122:125] offset:41472
	ds_write_b128 v54, v[126:129] offset:46080
	s_waitcnt vmcnt(19)
	ds_write_b128 v54, v[130:133] offset:50688
	ds_write_b128 v54, v[146:149] offset:55296
	s_waitcnt vmcnt(18)
	ds_write_b128 v54, v[150:153] offset:59904
	s_waitcnt vmcnt(17)
	ds_write_b128 v54, v[154:157] offset:64512
	s_waitcnt vmcnt(16)
	ds_write_b128 v58, v[158:161]
	s_waitcnt lgkmcnt(0)
	s_barrier
	v_mfma_f32_32x32x16_bf16 v[2:17], v[80:83], v[84:87], v[2:17]
	ds_read_b128 v[80:83], v0 offset:55296
	ds_read_b128 v[84:87], v56 offset:36864
	ds_read_b128 v[122:125], v56 offset:36896
	ds_read_b128 v[126:129], v0 offset:55328
	s_waitcnt lgkmcnt(2)
	v_mfma_f32_32x32x16_bf16 v[18:33], v[80:83], v[84:87], v[18:33]
	ds_read_b128 v[84:87], v56 offset:41472
	ds_read_b128 v[130:133], v56 offset:41504
	s_waitcnt lgkmcnt(1)
	v_mfma_f32_32x32x16_bf16 v[2:17], v[80:83], v[84:87], v[2:17]
	v_mfma_f32_32x32x16_bf16 v[18:33], v[126:129], v[122:125], v[18:33]
	s_waitcnt lgkmcnt(0)
	v_mfma_f32_32x32x16_bf16 v[2:17], v[126:129], v[130:133], v[2:17]
	ds_read_b128 v[80:83], v0 offset:55360
	ds_read_b128 v[84:87], v56 offset:36928
	ds_read_b128 v[122:125], v56 offset:36960
	ds_read_b128 v[126:129], v0 offset:55392
	s_waitcnt lgkmcnt(2)
	v_mfma_f32_32x32x16_bf16 v[18:33], v[80:83], v[84:87], v[18:33]
	ds_read_b128 v[84:87], v56 offset:41536
	ds_read_b128 v[130:133], v56 offset:41568
	s_waitcnt lgkmcnt(1)
	v_mfma_f32_32x32x16_bf16 v[2:17], v[80:83], v[84:87], v[2:17]
	v_mfma_f32_32x32x16_bf16 v[18:33], v[126:129], v[122:125], v[18:33]
	global_load_dwordx4 v[80:83], v[36:37], off offset:768
	global_load_dwordx4 v[84:87], v[38:39], off offset:768
	global_load_dwordx4 v[122:125], v[34:35], off offset:768
	global_load_dwordx4 v[142:145], v[48:49], off offset:768
	global_load_dwordx4 v[146:149], v[46:47], off offset:768
	global_load_dwordx4 v[150:153], v[40:41], off offset:768
	global_load_dwordx4 v[154:157], v[42:43], off offset:768
	global_load_dwordx4 v[158:161], v[44:45], off offset:768
	s_waitcnt vmcnt(21)
	ds_write_b128 v54, v[94:97]
	ds_write_b128 v54, v[60:63] offset:4608
	ds_write_b128 v54, v[64:67] offset:9216
	s_waitcnt vmcnt(19)
	ds_write_b128 v54, v[102:105] offset:13824
	ds_write_b128 v54, v[98:101] offset:18432
	s_waitcnt vmcnt(18)
	ds_write_b128 v54, v[134:137] offset:23040
	s_waitcnt vmcnt(17)
	ds_write_b128 v54, v[138:141] offset:27648
	s_waitcnt vmcnt(16)
	ds_write_b128 v54, v[164:167] offset:32256
	s_waitcnt lgkmcnt(0)
	s_barrier
	ds_read_b128 v[60:63], v0 offset:18432
	ds_read_b128 v[64:67], v56
	ds_read_b128 v[92:95], v56 offset:32
	ds_read_b128 v[96:99], v0 offset:18464
	v_mfma_f32_32x32x16_bf16 v[2:17], v[126:129], v[130:133], v[2:17]
	s_waitcnt lgkmcnt(2)
	v_mfma_f32_32x32x16_bf16 v[18:33], v[60:63], v[64:67], v[18:33]
	ds_read_b128 v[64:67], v56 offset:4608
	ds_read_b128 v[100:103], v56 offset:4640
	s_waitcnt lgkmcnt(1)
	v_mfma_f32_32x32x16_bf16 v[2:17], v[60:63], v[64:67], v[2:17]
	v_mfma_f32_32x32x16_bf16 v[18:33], v[96:99], v[92:95], v[18:33]
	s_waitcnt lgkmcnt(0)
	v_mfma_f32_32x32x16_bf16 v[2:17], v[96:99], v[100:103], v[2:17]
	ds_read_b128 v[60:63], v0 offset:18496
	ds_read_b128 v[64:67], v56 offset:64
	ds_read_b128 v[92:95], v56 offset:96
	ds_read_b128 v[96:99], v0 offset:18528
	s_waitcnt lgkmcnt(2)
	v_mfma_f32_32x32x16_bf16 v[18:33], v[60:63], v[64:67], v[18:33]
	ds_read_b128 v[64:67], v56 offset:4672
	ds_read_b128 v[100:103], v56 offset:4704
	s_waitcnt lgkmcnt(1)
	v_mfma_f32_32x32x16_bf16 v[2:17], v[60:63], v[64:67], v[2:17]
	v_mfma_f32_32x32x16_bf16 v[18:33], v[96:99], v[92:95], v[18:33]
	global_load_dwordx4 v[60:63], v[36:37], off offset:896
	global_load_dwordx4 v[64:67], v[38:39], off offset:896
	global_load_dwordx4 v[92:95], v[34:35], off offset:896
	global_load_dwordx4 v[126:129], v[48:49], off offset:896
	global_load_dwordx4 v[130:133], v[46:47], off offset:896
	global_load_dwordx4 v[134:137], v[40:41], off offset:896
	global_load_dwordx4 v[138:141], v[42:43], off offset:896
	global_load_dwordx4 v[164:167], v[44:45], off offset:896
	s_waitcnt vmcnt(21)
	ds_write_b128 v54, v[76:79] offset:36864
	ds_write_b128 v54, v[68:71] offset:41472
	ds_write_b128 v54, v[72:75] offset:46080
	s_waitcnt vmcnt(19)
	ds_write_b128 v54, v[106:109] offset:50688
	ds_write_b128 v54, v[88:91] offset:55296
	s_waitcnt vmcnt(18)
	ds_write_b128 v54, v[110:113] offset:59904
	s_waitcnt vmcnt(17)
	ds_write_b128 v54, v[114:117] offset:64512
	s_waitcnt vmcnt(16)
	ds_write_b128 v57, v[118:121] offset:32256
	s_waitcnt lgkmcnt(0)
	s_barrier
	ds_read_b128 v[68:71], v0 offset:55296
	ds_read_b128 v[72:75], v56 offset:36864
	ds_read_b128 v[76:79], v56 offset:36896
	ds_read_b128 v[88:91], v0 offset:55328
	v_mfma_f32_32x32x16_bf16 v[2:17], v[96:99], v[100:103], v[2:17]
	s_waitcnt lgkmcnt(2)
	v_mfma_f32_32x32x16_bf16 v[18:33], v[68:71], v[72:75], v[18:33]
	ds_read_b128 v[72:75], v56 offset:41472
	ds_read_b128 v[96:99], v56 offset:41504
	s_waitcnt lgkmcnt(1)
	v_mfma_f32_32x32x16_bf16 v[2:17], v[68:71], v[72:75], v[2:17]
	v_mfma_f32_32x32x16_bf16 v[18:33], v[88:91], v[76:79], v[18:33]
	s_waitcnt lgkmcnt(0)
	v_mfma_f32_32x32x16_bf16 v[2:17], v[88:91], v[96:99], v[2:17]
	ds_read_b128 v[68:71], v0 offset:55360
	ds_read_b128 v[72:75], v56 offset:36928
	ds_read_b128 v[76:79], v56 offset:36960
	ds_read_b128 v[88:91], v0 offset:55392
	s_waitcnt lgkmcnt(2)
	v_mfma_f32_32x32x16_bf16 v[18:33], v[68:71], v[72:75], v[18:33]
	ds_read_b128 v[72:75], v56 offset:41536
	ds_read_b128 v[96:99], v56 offset:41568
	s_waitcnt lgkmcnt(1)
	v_mfma_f32_32x32x16_bf16 v[2:17], v[68:71], v[72:75], v[2:17]
	v_mfma_f32_32x32x16_bf16 v[18:33], v[88:91], v[76:79], v[18:33]
	global_load_dwordx4 v[68:71], v[36:37], off offset:1024
	global_load_dwordx4 v[72:75], v[38:39], off offset:1024
	global_load_dwordx4 v[76:79], v[34:35], off offset:1024
	global_load_dwordx4 v[100:103], v[48:49], off offset:1024
	global_load_dwordx4 v[104:107], v[46:47], off offset:1024
	global_load_dwordx4 v[108:111], v[40:41], off offset:1024
	global_load_dwordx4 v[112:115], v[42:43], off offset:1024
	global_load_dwordx4 v[116:119], v[44:45], off offset:1024
	s_waitcnt vmcnt(21)
	ds_write_b128 v54, v[122:125]
	ds_write_b128 v54, v[80:83] offset:4608
	ds_write_b128 v54, v[84:87] offset:9216
	s_waitcnt vmcnt(19)
	ds_write_b128 v54, v[146:149] offset:13824
	ds_write_b128 v54, v[142:145] offset:18432
	s_waitcnt vmcnt(18)
	ds_write_b128 v54, v[150:153] offset:23040
	s_waitcnt vmcnt(17)
	ds_write_b128 v54, v[154:157] offset:27648
	s_waitcnt vmcnt(16)
	ds_write_b128 v54, v[158:161] offset:32256
	s_waitcnt lgkmcnt(0)
	s_barrier
	v_mfma_f32_32x32x16_bf16 v[2:17], v[88:91], v[96:99], v[2:17]
	ds_read_b128 v[80:83], v0 offset:18432
	ds_read_b128 v[84:87], v56
	ds_read_b128 v[88:91], v56 offset:32
	ds_read_b128 v[96:99], v0 offset:18464
	s_waitcnt lgkmcnt(2)
	v_mfma_f32_32x32x16_bf16 v[18:33], v[80:83], v[84:87], v[18:33]
	ds_read_b128 v[84:87], v56 offset:4608
	ds_read_b128 v[120:123], v56 offset:4640
	s_waitcnt lgkmcnt(1)
	v_mfma_f32_32x32x16_bf16 v[2:17], v[80:83], v[84:87], v[2:17]
	v_mfma_f32_32x32x16_bf16 v[18:33], v[96:99], v[88:91], v[18:33]
	s_waitcnt lgkmcnt(0)
	v_mfma_f32_32x32x16_bf16 v[2:17], v[96:99], v[120:123], v[2:17]
	ds_read_b128 v[80:83], v0 offset:18496
	ds_read_b128 v[84:87], v56 offset:64
	ds_read_b128 v[88:91], v56 offset:96
	ds_read_b128 v[96:99], v0 offset:18528
	s_waitcnt lgkmcnt(2)
	v_mfma_f32_32x32x16_bf16 v[18:33], v[80:83], v[84:87], v[18:33]
	ds_read_b128 v[84:87], v56 offset:4672
	ds_read_b128 v[120:123], v56 offset:4704
	s_waitcnt lgkmcnt(1)
	v_mfma_f32_32x32x16_bf16 v[2:17], v[80:83], v[84:87], v[2:17]
	v_mfma_f32_32x32x16_bf16 v[18:33], v[96:99], v[88:91], v[18:33]
	global_load_dwordx4 v[80:83], v[36:37], off offset:1152
	global_load_dwordx4 v[84:87], v[38:39], off offset:1152
	global_load_dwordx4 v[88:91], v[34:35], off offset:1152
	global_load_dwordx4 v[142:145], v[48:49], off offset:1152
	global_load_dwordx4 v[146:149], v[46:47], off offset:1152
	global_load_dwordx4 v[150:153], v[40:41], off offset:1152
	global_load_dwordx4 v[154:157], v[42:43], off offset:1152
	global_load_dwordx4 v[158:161], v[44:45], off offset:1152
	s_waitcnt vmcnt(21)
	ds_write_b128 v54, v[92:95] offset:36864
	ds_write_b128 v54, v[60:63] offset:41472
	ds_write_b128 v54, v[64:67] offset:46080
	s_waitcnt vmcnt(19)
	ds_write_b128 v54, v[130:133] offset:50688
	ds_write_b128 v54, v[126:129] offset:55296
	s_waitcnt vmcnt(18)
	ds_write_b128 v54, v[134:137] offset:59904
	s_waitcnt vmcnt(17)
	ds_write_b128 v54, v[138:141] offset:64512
	s_waitcnt vmcnt(16)
	ds_write_b128 v57, v[164:167] offset:32256
	s_waitcnt lgkmcnt(0)
	s_barrier
	v_mfma_f32_32x32x16_bf16 v[2:17], v[96:99], v[120:123], v[2:17]
	ds_read_b128 v[60:63], v0 offset:55296
	ds_read_b128 v[64:67], v56 offset:36864
	ds_read_b128 v[92:95], v56 offset:36896
	ds_read_b128 v[96:99], v0 offset:55328
	s_waitcnt lgkmcnt(2)
	v_mfma_f32_32x32x16_bf16 v[18:33], v[60:63], v[64:67], v[18:33]
	ds_read_b128 v[64:67], v56 offset:41472
	ds_read_b128 v[120:123], v56 offset:41504
	s_waitcnt lgkmcnt(1)
	v_mfma_f32_32x32x16_bf16 v[2:17], v[60:63], v[64:67], v[2:17]
	v_mfma_f32_32x32x16_bf16 v[18:33], v[96:99], v[92:95], v[18:33]
	s_waitcnt lgkmcnt(0)
	v_mfma_f32_32x32x16_bf16 v[2:17], v[96:99], v[120:123], v[2:17]
	ds_read_b128 v[60:63], v0 offset:55360
	ds_read_b128 v[64:67], v56 offset:36928
	ds_read_b128 v[92:95], v56 offset:36960
	ds_read_b128 v[96:99], v0 offset:55392
	s_waitcnt lgkmcnt(2)
	v_mfma_f32_32x32x16_bf16 v[18:33], v[60:63], v[64:67], v[18:33]
	ds_read_b128 v[64:67], v56 offset:41536
	ds_read_b128 v[120:123], v56 offset:41568
	s_waitcnt lgkmcnt(1)
	v_mfma_f32_32x32x16_bf16 v[2:17], v[60:63], v[64:67], v[2:17]
	v_mfma_f32_32x32x16_bf16 v[18:33], v[96:99], v[92:95], v[18:33]
	global_load_dwordx4 v[60:63], v[36:37], off offset:1280
	global_load_dwordx4 v[64:67], v[38:39], off offset:1280
	global_load_dwordx4 v[92:95], v[34:35], off offset:1280
	global_load_dwordx4 v[124:127], v[48:49], off offset:1280
	global_load_dwordx4 v[128:131], v[46:47], off offset:1280
	global_load_dwordx4 v[132:135], v[40:41], off offset:1280
	global_load_dwordx4 v[136:139], v[42:43], off offset:1280
	global_load_dwordx4 v[164:167], v[44:45], off offset:1280
	s_waitcnt vmcnt(21)
	ds_write_b128 v54, v[76:79]
	ds_write_b128 v54, v[68:71] offset:4608
	ds_write_b128 v54, v[72:75] offset:9216
	s_waitcnt vmcnt(19)
	ds_write_b128 v54, v[104:107] offset:13824
	ds_write_b128 v54, v[100:103] offset:18432
	s_waitcnt vmcnt(18)
	ds_write_b128 v54, v[108:111] offset:23040
	s_waitcnt vmcnt(17)
	ds_write_b128 v54, v[112:115] offset:27648
	s_waitcnt vmcnt(16)
	ds_write_b128 v54, v[116:119] offset:32256
	s_waitcnt lgkmcnt(0)
	s_barrier
	v_mfma_f32_32x32x16_bf16 v[2:17], v[96:99], v[120:123], v[2:17]
	ds_read_b128 v[68:71], v0 offset:18432
	ds_read_b128 v[72:75], v56
	ds_read_b128 v[76:79], v56 offset:32
	ds_read_b128 v[96:99], v0 offset:18464
	s_waitcnt lgkmcnt(2)
	v_mfma_f32_32x32x16_bf16 v[18:33], v[68:71], v[72:75], v[18:33]
	ds_read_b128 v[72:75], v56 offset:4608
	ds_read_b128 v[100:103], v56 offset:4640
	s_waitcnt lgkmcnt(1)
	v_mfma_f32_32x32x16_bf16 v[2:17], v[68:71], v[72:75], v[2:17]
	v_mfma_f32_32x32x16_bf16 v[18:33], v[96:99], v[76:79], v[18:33]
	s_waitcnt lgkmcnt(0)
	v_mfma_f32_32x32x16_bf16 v[2:17], v[96:99], v[100:103], v[2:17]
	ds_read_b128 v[68:71], v0 offset:18496
	ds_read_b128 v[72:75], v56 offset:64
	ds_read_b128 v[76:79], v56 offset:96
	ds_read_b128 v[96:99], v0 offset:18528
	s_waitcnt lgkmcnt(2)
	v_mfma_f32_32x32x16_bf16 v[18:33], v[68:71], v[72:75], v[18:33]
	ds_read_b128 v[72:75], v56 offset:4672
	ds_read_b128 v[100:103], v56 offset:4704
	s_waitcnt lgkmcnt(1)
	v_mfma_f32_32x32x16_bf16 v[2:17], v[68:71], v[72:75], v[2:17]
	v_mfma_f32_32x32x16_bf16 v[18:33], v[96:99], v[76:79], v[18:33]
	global_load_dwordx4 v[68:71], v[36:37], off offset:1408
	global_load_dwordx4 v[72:75], v[38:39], off offset:1408
	global_load_dwordx4 v[76:79], v[34:35], off offset:1408
	global_load_dwordx4 v[104:107], v[48:49], off offset:1408
	global_load_dwordx4 v[108:111], v[46:47], off offset:1408
	global_load_dwordx4 v[112:115], v[40:41], off offset:1408
	global_load_dwordx4 v[116:119], v[42:43], off offset:1408
	global_load_dwordx4 v[120:123], v[44:45], off offset:1408
	s_waitcnt vmcnt(21)
	ds_write_b128 v54, v[88:91] offset:36864
	ds_write_b128 v54, v[80:83] offset:41472
	ds_write_b128 v54, v[84:87] offset:46080
	s_waitcnt vmcnt(19)
	ds_write_b128 v54, v[146:149] offset:50688
	ds_write_b128 v54, v[142:145] offset:55296
	s_waitcnt vmcnt(18)
	ds_write_b128 v54, v[150:153] offset:59904
	s_waitcnt vmcnt(17)
	ds_write_b128 v54, v[154:157] offset:64512
	s_waitcnt vmcnt(16)
	ds_write_b128 v58, v[158:161]
	s_waitcnt lgkmcnt(0)
	s_barrier
	v_mfma_f32_32x32x16_bf16 v[2:17], v[96:99], v[100:103], v[2:17]
	ds_read_b128 v[80:83], v0 offset:55296
	ds_read_b128 v[84:87], v56 offset:36864
	ds_read_b128 v[88:91], v56 offset:36896
	ds_read_b128 v[96:99], v0 offset:55328
	s_waitcnt lgkmcnt(2)
	v_mfma_f32_32x32x16_bf16 v[18:33], v[80:83], v[84:87], v[18:33]
	ds_read_b128 v[84:87], v56 offset:41472
	ds_read_b128 v[100:103], v56 offset:41504
	s_waitcnt lgkmcnt(1)
	v_mfma_f32_32x32x16_bf16 v[2:17], v[80:83], v[84:87], v[2:17]
	v_mfma_f32_32x32x16_bf16 v[18:33], v[96:99], v[88:91], v[18:33]
	s_waitcnt lgkmcnt(0)
	v_mfma_f32_32x32x16_bf16 v[2:17], v[96:99], v[100:103], v[2:17]
	ds_read_b128 v[80:83], v0 offset:55360
	ds_read_b128 v[84:87], v56 offset:36928
	ds_read_b128 v[88:91], v56 offset:36960
	ds_read_b128 v[96:99], v0 offset:55392
	s_waitcnt lgkmcnt(2)
	v_mfma_f32_32x32x16_bf16 v[18:33], v[80:83], v[84:87], v[18:33]
	ds_read_b128 v[84:87], v56 offset:41536
	ds_read_b128 v[100:103], v56 offset:41568
	s_waitcnt lgkmcnt(1)
	v_mfma_f32_32x32x16_bf16 v[2:17], v[80:83], v[84:87], v[2:17]
	v_mfma_f32_32x32x16_bf16 v[18:33], v[96:99], v[88:91], v[18:33]
	global_load_dwordx4 v[80:83], v[36:37], off offset:1536
	global_load_dwordx4 v[84:87], v[38:39], off offset:1536
	global_load_dwordx4 v[88:91], v[34:35], off offset:1536
	global_load_dwordx4 v[140:143], v[48:49], off offset:1536
	global_load_dwordx4 v[144:147], v[46:47], off offset:1536
	global_load_dwordx4 v[148:151], v[40:41], off offset:1536
	global_load_dwordx4 v[152:155], v[42:43], off offset:1536
	global_load_dwordx4 v[156:159], v[44:45], off offset:1536
	s_waitcnt vmcnt(21)
	ds_write_b128 v54, v[92:95]
	ds_write_b128 v54, v[60:63] offset:4608
	ds_write_b128 v54, v[64:67] offset:9216
	s_waitcnt vmcnt(19)
	ds_write_b128 v54, v[128:131] offset:13824
	ds_write_b128 v54, v[124:127] offset:18432
	s_waitcnt vmcnt(18)
	ds_write_b128 v54, v[132:135] offset:23040
	s_waitcnt vmcnt(17)
	ds_write_b128 v54, v[136:139] offset:27648
	s_waitcnt vmcnt(16)
	ds_write_b128 v54, v[164:167] offset:32256
	s_waitcnt lgkmcnt(0)
	s_barrier
	v_mfma_f32_32x32x16_bf16 v[2:17], v[96:99], v[100:103], v[2:17]
	ds_read_b128 v[60:63], v0 offset:18432
	ds_read_b128 v[64:67], v56
	ds_read_b128 v[92:95], v56 offset:32
	ds_read_b128 v[96:99], v0 offset:18464
	s_waitcnt lgkmcnt(2)
	v_mfma_f32_32x32x16_bf16 v[18:33], v[60:63], v[64:67], v[18:33]
	ds_read_b128 v[64:67], v56 offset:4608
	ds_read_b128 v[100:103], v56 offset:4640
	s_waitcnt lgkmcnt(1)
	v_mfma_f32_32x32x16_bf16 v[2:17], v[60:63], v[64:67], v[2:17]
	v_mfma_f32_32x32x16_bf16 v[18:33], v[96:99], v[92:95], v[18:33]
	s_waitcnt lgkmcnt(0)
	v_mfma_f32_32x32x16_bf16 v[2:17], v[96:99], v[100:103], v[2:17]
	ds_read_b128 v[60:63], v0 offset:18496
	ds_read_b128 v[64:67], v56 offset:64
	ds_read_b128 v[92:95], v56 offset:96
	ds_read_b128 v[96:99], v0 offset:18528
	s_waitcnt lgkmcnt(2)
	v_mfma_f32_32x32x16_bf16 v[18:33], v[60:63], v[64:67], v[18:33]
	ds_read_b128 v[64:67], v56 offset:4672
	ds_read_b128 v[100:103], v56 offset:4704
	s_waitcnt lgkmcnt(1)
	v_mfma_f32_32x32x16_bf16 v[2:17], v[60:63], v[64:67], v[2:17]
	v_mfma_f32_32x32x16_bf16 v[18:33], v[96:99], v[92:95], v[18:33]
	global_load_dwordx4 v[60:63], v[36:37], off offset:1664
	global_load_dwordx4 v[64:67], v[38:39], off offset:1664
	global_load_dwordx4 v[92:95], v[34:35], off offset:1664
	global_load_dwordx4 v[124:127], v[48:49], off offset:1664
	global_load_dwordx4 v[128:131], v[46:47], off offset:1664
	global_load_dwordx4 v[132:135], v[40:41], off offset:1664
	global_load_dwordx4 v[136:139], v[42:43], off offset:1664
	global_load_dwordx4 v[164:167], v[44:45], off offset:1664
	s_waitcnt vmcnt(21)
	ds_write_b128 v54, v[76:79] offset:36864
	ds_write_b128 v54, v[68:71] offset:41472
	ds_write_b128 v54, v[72:75] offset:46080
	s_waitcnt vmcnt(19)
	ds_write_b128 v54, v[108:111] offset:50688
	ds_write_b128 v54, v[104:107] offset:55296
	s_waitcnt vmcnt(18)
	ds_write_b128 v54, v[112:115] offset:59904
	s_waitcnt vmcnt(17)
	ds_write_b128 v54, v[116:119] offset:64512
	s_waitcnt vmcnt(16)
	ds_write_b128 v57, v[120:123] offset:32256
	s_waitcnt lgkmcnt(0)
	s_barrier
	v_mfma_f32_32x32x16_bf16 v[2:17], v[96:99], v[100:103], v[2:17]
	ds_read_b128 v[68:71], v0 offset:55296
	ds_read_b128 v[72:75], v56 offset:36864
	ds_read_b128 v[76:79], v56 offset:36896
	ds_read_b128 v[96:99], v0 offset:55328
	s_waitcnt lgkmcnt(2)
	v_mfma_f32_32x32x16_bf16 v[18:33], v[68:71], v[72:75], v[18:33]
	ds_read_b128 v[72:75], v56 offset:41472
	ds_read_b128 v[100:103], v56 offset:41504
	s_waitcnt lgkmcnt(1)
	v_mfma_f32_32x32x16_bf16 v[2:17], v[68:71], v[72:75], v[2:17]
	v_mfma_f32_32x32x16_bf16 v[18:33], v[96:99], v[76:79], v[18:33]
	s_waitcnt lgkmcnt(0)
	v_mfma_f32_32x32x16_bf16 v[2:17], v[96:99], v[100:103], v[2:17]
	ds_read_b128 v[68:71], v0 offset:55360
	ds_read_b128 v[72:75], v56 offset:36928
	ds_read_b128 v[76:79], v56 offset:36960
	ds_read_b128 v[96:99], v0 offset:55392
	s_waitcnt lgkmcnt(2)
	v_mfma_f32_32x32x16_bf16 v[18:33], v[68:71], v[72:75], v[18:33]
	ds_read_b128 v[72:75], v56 offset:41536
	ds_read_b128 v[100:103], v56 offset:41568
	s_waitcnt lgkmcnt(1)
	v_mfma_f32_32x32x16_bf16 v[2:17], v[68:71], v[72:75], v[2:17]
	v_mfma_f32_32x32x16_bf16 v[18:33], v[96:99], v[76:79], v[18:33]
	global_load_dwordx4 v[68:71], v[36:37], off offset:1792
	global_load_dwordx4 v[72:75], v[38:39], off offset:1792
	global_load_dwordx4 v[76:79], v[34:35], off offset:1792
	global_load_dwordx4 v[104:107], v[48:49], off offset:1792
	global_load_dwordx4 v[108:111], v[46:47], off offset:1792
	global_load_dwordx4 v[112:115], v[40:41], off offset:1792
	global_load_dwordx4 v[116:119], v[42:43], off offset:1792
	global_load_dwordx4 v[120:123], v[44:45], off offset:1792
	s_waitcnt vmcnt(21)
	ds_write_b128 v54, v[88:91]
	ds_write_b128 v54, v[80:83] offset:4608
	ds_write_b128 v54, v[84:87] offset:9216
	s_waitcnt vmcnt(19)
	ds_write_b128 v54, v[144:147] offset:13824
	ds_write_b128 v54, v[140:143] offset:18432
	s_waitcnt vmcnt(18)
	ds_write_b128 v54, v[148:151] offset:23040
	s_waitcnt vmcnt(17)
	ds_write_b128 v54, v[152:155] offset:27648
	s_waitcnt vmcnt(16)
	ds_write_b128 v54, v[156:159] offset:32256
	s_waitcnt lgkmcnt(0)
	s_barrier
	v_mfma_f32_32x32x16_bf16 v[2:17], v[96:99], v[100:103], v[2:17]
	ds_read_b128 v[80:83], v0 offset:18432
	ds_read_b128 v[84:87], v56
	ds_read_b128 v[88:91], v56 offset:32
	ds_read_b128 v[96:99], v0 offset:18464
	s_waitcnt lgkmcnt(2)
	v_mfma_f32_32x32x16_bf16 v[18:33], v[80:83], v[84:87], v[18:33]
	ds_read_b128 v[84:87], v56 offset:4608
	ds_read_b128 v[100:103], v56 offset:4640
	s_waitcnt lgkmcnt(1)
	v_mfma_f32_32x32x16_bf16 v[2:17], v[80:83], v[84:87], v[2:17]
	v_mfma_f32_32x32x16_bf16 v[18:33], v[96:99], v[88:91], v[18:33]
	s_waitcnt lgkmcnt(0)
	v_mfma_f32_32x32x16_bf16 v[2:17], v[96:99], v[100:103], v[2:17]
	ds_read_b128 v[80:83], v0 offset:18496
	ds_read_b128 v[84:87], v56 offset:64
	ds_read_b128 v[88:91], v56 offset:96
	ds_read_b128 v[96:99], v0 offset:18528
	s_waitcnt lgkmcnt(2)
	v_mfma_f32_32x32x16_bf16 v[18:33], v[80:83], v[84:87], v[18:33]
	ds_read_b128 v[84:87], v56 offset:4672
	ds_read_b128 v[100:103], v56 offset:4704
	s_waitcnt lgkmcnt(1)
	v_mfma_f32_32x32x16_bf16 v[2:17], v[80:83], v[84:87], v[2:17]
	v_mfma_f32_32x32x16_bf16 v[18:33], v[96:99], v[88:91], v[18:33]
	global_load_dwordx4 v[80:83], v[36:37], off offset:1920
	s_nop 0
	global_load_dwordx4 v[36:39], v[38:39], off offset:1920
	s_nop 0
	global_load_dwordx4 v[84:87], v[34:35], off offset:1920
	global_load_dwordx4 v[88:91], v[48:49], off offset:1920
	s_nop 0
	global_load_dwordx4 v[46:49], v[46:47], off offset:1920
	s_nop 0
	global_load_dwordx4 v[140:143], v[40:41], off offset:1920
	s_nop 0
	global_load_dwordx4 v[40:43], v[42:43], off offset:1920
	s_nop 0
	global_load_dwordx4 v[144:147], v[44:45], off offset:1920
	s_waitcnt vmcnt(21)
	ds_write_b128 v54, v[92:95] offset:36864
	ds_write_b128 v54, v[60:63] offset:41472
	ds_write_b128 v54, v[64:67] offset:46080
	s_waitcnt vmcnt(19)
	ds_write_b128 v54, v[128:131] offset:50688
	ds_write_b128 v54, v[124:127] offset:55296
	s_waitcnt vmcnt(18)
	ds_write_b128 v54, v[132:135] offset:59904
	s_waitcnt vmcnt(17)
	ds_write_b128 v54, v[136:139] offset:64512
	s_waitcnt vmcnt(16)
	ds_write_b128 v57, v[164:167] offset:32256
	s_waitcnt lgkmcnt(0)
	s_barrier
	v_mfma_f32_32x32x16_bf16 v[2:17], v[96:99], v[100:103], v[2:17]
	ds_read_b128 v[60:63], v0 offset:55296
	ds_read_b128 v[64:67], v56 offset:36864
	ds_read_b128 v[92:95], v56 offset:36896
	ds_read_b128 v[96:99], v0 offset:55328
	s_waitcnt lgkmcnt(2)
	v_mfma_f32_32x32x16_bf16 v[18:33], v[60:63], v[64:67], v[18:33]
	ds_read_b128 v[64:67], v56 offset:41472
	ds_read_b128 v[100:103], v56 offset:41504
	s_waitcnt lgkmcnt(1)
	v_mfma_f32_32x32x16_bf16 v[2:17], v[60:63], v[64:67], v[2:17]
	v_mfma_f32_32x32x16_bf16 v[18:33], v[96:99], v[92:95], v[18:33]
	s_waitcnt lgkmcnt(0)
	v_mfma_f32_32x32x16_bf16 v[2:17], v[96:99], v[100:103], v[2:17]
	ds_read_b128 v[60:63], v0 offset:55360
	ds_read_b128 v[64:67], v56 offset:36928
	ds_read_b128 v[92:95], v56 offset:36960
	ds_read_b128 v[96:99], v0 offset:55392
	s_waitcnt lgkmcnt(2)
	v_mfma_f32_32x32x16_bf16 v[18:33], v[60:63], v[64:67], v[18:33]
	ds_read_b128 v[64:67], v56 offset:41536
	ds_read_b128 v[100:103], v56 offset:41568
	s_waitcnt vmcnt(13)
	ds_write_b128 v54, v[76:79]
	ds_write_b128 v54, v[68:71] offset:4608
	ds_write_b128 v54, v[72:75] offset:9216
	s_waitcnt vmcnt(11)
	ds_write_b128 v54, v[108:111] offset:13824
	ds_write_b128 v54, v[104:107] offset:18432
	s_waitcnt vmcnt(10)
	ds_write_b128 v54, v[112:115] offset:23040
	s_waitcnt vmcnt(9)
	ds_write_b128 v54, v[116:119] offset:27648
	s_waitcnt vmcnt(8)
	ds_write_b128 v54, v[120:123] offset:32256
	s_waitcnt lgkmcnt(0)
	s_barrier
	v_mfma_f32_32x32x16_bf16 v[2:17], v[60:63], v[64:67], v[2:17]
	ds_read_b128 v[60:63], v0 offset:18432
	ds_read_b128 v[64:67], v56
	ds_read_b128 v[68:71], v56 offset:32
	ds_read_b128 v[72:75], v0 offset:18464
	v_mfma_f32_32x32x16_bf16 v[18:33], v[96:99], v[92:95], v[18:33]
	v_mfma_f32_32x32x16_bf16 v[2:17], v[96:99], v[100:103], v[2:17]
	s_waitcnt lgkmcnt(2)
	v_mfma_f32_32x32x16_bf16 v[18:33], v[60:63], v[64:67], v[18:33]
	ds_read_b128 v[64:67], v56 offset:4608
	ds_read_b128 v[76:79], v56 offset:4640
	s_waitcnt lgkmcnt(1)
	v_mfma_f32_32x32x16_bf16 v[2:17], v[60:63], v[64:67], v[2:17]
	v_mfma_f32_32x32x16_bf16 v[18:33], v[72:75], v[68:71], v[18:33]
	s_waitcnt lgkmcnt(0)
	v_mfma_f32_32x32x16_bf16 v[2:17], v[72:75], v[76:79], v[2:17]
	ds_read_b128 v[60:63], v0 offset:18496
	ds_read_b128 v[64:67], v56 offset:64
	ds_read_b128 v[68:71], v56 offset:96
	ds_read_b128 v[72:75], v0 offset:18528
	s_waitcnt lgkmcnt(2)
	v_mfma_f32_32x32x16_bf16 v[18:33], v[60:63], v[64:67], v[18:33]
	ds_read_b128 v[64:67], v56 offset:4672
	ds_read_b128 v[76:79], v56 offset:4704
	s_waitcnt vmcnt(5)
	ds_write_b128 v54, v[84:87] offset:36864
	ds_write_b128 v54, v[80:83] offset:41472
	ds_write_b128 v54, v[36:39] offset:46080
	s_waitcnt vmcnt(3)
	ds_write_b128 v54, v[46:49] offset:50688
	ds_write_b128 v54, v[88:91] offset:55296
	s_waitcnt vmcnt(2)
	ds_write_b128 v54, v[140:143] offset:59904
	s_waitcnt vmcnt(1)
	ds_write_b128 v54, v[40:43] offset:64512
	s_waitcnt vmcnt(0)
	ds_write_b128 v58, v[144:147]
	s_waitcnt lgkmcnt(0)
	s_barrier
	ds_read_b128 v[34:37], v0 offset:55296
	ds_read_b128 v[38:41], v56 offset:36864
	ds_read_b128 v[42:45], v56 offset:36896
	ds_read_b128 v[46:49], v0 offset:55328
	v_mfma_f32_32x32x16_bf16 v[2:17], v[60:63], v[64:67], v[2:17]
	v_mfma_f32_32x32x16_bf16 v[18:33], v[72:75], v[68:71], v[18:33]
	v_mfma_f32_32x32x16_bf16 v[2:17], v[72:75], v[76:79], v[2:17]
	s_waitcnt lgkmcnt(2)
	v_mfma_f32_32x32x16_bf16 v[18:33], v[34:37], v[38:41], v[18:33]
	ds_read_b128 v[38:41], v56 offset:41472
	ds_read_b128 v[58:61], v56 offset:41504
	s_waitcnt lgkmcnt(1)
	v_mfma_f32_32x32x16_bf16 v[2:17], v[34:37], v[38:41], v[2:17]
	v_mfma_f32_32x32x16_bf16 v[18:33], v[46:49], v[42:45], v[18:33]
	s_waitcnt lgkmcnt(0)
	v_mfma_f32_32x32x16_bf16 v[2:17], v[46:49], v[58:61], v[2:17]
	ds_read_b128 v[34:37], v0 offset:55360
	ds_read_b128 v[38:41], v56 offset:36928
	ds_read_b128 v[42:45], v56 offset:36960
	ds_read_b128 v[46:49], v0 offset:55392
	s_waitcnt lgkmcnt(2)
	v_mfma_f32_32x32x16_bf16 v[18:33], v[34:37], v[38:41], v[18:33]
	ds_read_b128 v[38:41], v56 offset:41536
	ds_read_b128 v[56:59], v56 offset:41568
	s_waitcnt lgkmcnt(0)
	s_barrier
	v_mfma_f32_32x32x16_bf16 v[2:17], v[34:37], v[38:41], v[2:17]
	v_mfma_f32_32x32x16_bf16 v[18:33], v[46:49], v[42:45], v[18:33]
	v_add_u32_e32 v42, v51, v55
	v_add_u32_e32 v37, 0x4000, v42
	v_cmp_gt_i32_e32 vcc, s2, v37
	v_cmp_lt_i32_e64 s[38:39], s24, v37
	v_mfma_f32_32x32x16_bf16 v[2:17], v[46:49], v[56:59], v[2:17]
	s_and_saveexec_b64 s[0:1], s[38:39]
	s_xor_b64 s[2:3], exec, s[0:1]
	v_and_b32_e32 v0, 0xdf, v37
	v_lshrrev_b32_e32 v44, 8, v42
	v_or_b32_e32 v0, 0x2000, v0
	s_or_saveexec_b64 s[2:3], s[2:3]
	v_lshrrev_b32_e32 v38, 2, v37
	v_mov_b32_e32 v34, 0
	v_ashrrev_i32_e32 v36, 13, v37
	v_and_b32_e32 v43, 0x7f0, v38
	v_mov_b32_e32 v35, 0
	s_xor_b64 exec, exec, s[2:3]
	v_ashrrev_i32_e32 v44, 13, v37
	v_and_b32_e32 v0, 0x1fdf, v37
	v_and_b32_e32 v34, 0x7f0, v38
	v_lshlrev_b32_e32 v35, 4, v53
	s_or_b64 exec, exec, s[2:3]
	v_bfe_u32 v37, v52, 5, 1
	v_lshlrev_b32_e32 v38, 3, v37
	v_and_b32_e32 v45, 64, v52
	v_or_b32_e32 v39, 2, v38
	v_or_b32_e32 v40, 4, v38
	v_or_b32_e32 v41, 6, v38
	v_lshlrev_b32_e32 v37, 2, v37
	v_cmp_eq_u32_e64 s[38:39], 0, v45
	s_and_saveexec_b64 s[2:3], s[38:39]
	s_cbranch_execz .LBB0_564
	s_and_saveexec_b64 s[22:23], vcc
	s_cbranch_execz .LBB0_563
	v_or_b32_e32 v45, v34, v38
	v_or_b32_e32 v46, v34, v39
	v_or_b32_e32 v52, v34, v40
	v_or_b32_e32 v53, v34, v41
	v_lshlrev_b32_e32 v34, 3, v45
	v_or_b32_e32 v54, v35, v38
	v_or_b32_e32 v55, v35, v39
	v_or_b32_e32 v56, v35, v40
	v_or_b32_e32 v57, v35, v41
	v_lshlrev_b32_e32 v45, 3, v46
	global_load_dwordx2 v[34:35], v34, s[80:81]
	s_nop 0
	global_load_dwordx2 v[46:47], v45, s[80:81]
	v_lshlrev_b32_e32 v45, 3, v53
	s_waitcnt vmcnt(1)
	v_mov_b32_e32 v48, v34
	s_waitcnt vmcnt(0)
	v_mov_b32_e32 v49, v46
	v_mov_b32_e32 v46, v35
	v_mul_f32_e32 v34, v26, v46
	v_mul_f32_e32 v35, v27, v47
	s_nop 0
	v_fma_f32 v34, v18, v48, -v34
	v_fma_f32 v35, v19, v49, -v35
	v_mul_f32_e32 v18, v18, v46
	v_mul_f32_e32 v19, v19, v47
	s_nop 0
	v_fma_f32 v26, v26, v48, v18
	v_fma_f32 v27, v27, v49, v19
	v_lshlrev_b32_e32 v18, 3, v52
	global_load_dwordx2 v[18:19], v18, s[80:81]
	s_nop 0
	global_load_dwordx2 v[46:47], v45, s[80:81]
	s_waitcnt vmcnt(1)
	v_mov_b32_e32 v48, v18
	s_waitcnt vmcnt(0)
	v_mov_b32_e32 v49, v46
	v_mov_b32_e32 v46, v19
	v_mul_f32_e32 v18, v28, v46
	v_mul_f32_e32 v19, v29, v47
	s_nop 0
	v_fma_f32 v52, v20, v48, -v18
	v_fma_f32 v53, v21, v49, -v19
	v_mul_f32_e32 v18, v20, v46
	v_mul_f32_e32 v19, v21, v47
	v_lshlrev_b32_e32 v20, 3, v55
	v_fma_f32 v28, v28, v48, v18
	v_fma_f32 v29, v29, v49, v19
	v_lshlrev_b32_e32 v18, 3, v54
	global_load_dwordx2 v[18:19], v18, s[80:81]
	s_nop 0
	global_load_dwordx2 v[20:21], v20, s[80:81]
	s_waitcnt vmcnt(1)
	v_mov_b32_e32 v46, v18
	s_waitcnt vmcnt(0)
	v_mov_b32_e32 v47, v20
	v_mov_b32_e32 v20, v19
	v_mul_f32_e32 v18, v30, v20
	v_mul_f32_e32 v19, v31, v21
	s_nop 0
	v_fma_f32 v48, v22, v46, -v18
	v_fma_f32 v49, v23, v47, -v19
	v_mul_f32_e32 v18, v22, v20
	v_mul_f32_e32 v19, v23, v21
	v_lshlrev_b32_e32 v20, 3, v56
	v_fma_f32 v30, v30, v46, v18
	v_fma_f32 v31, v31, v47, v19
	v_lshlrev_b32_e32 v18, 3, v57
	global_load_dwordx2 v[18:19], v18, s[80:81]
	s_nop 0
	global_load_dwordx2 v[20:21], v20, s[80:81]
	s_waitcnt vmcnt(1)
	v_mov_b32_e32 v47, v19
	s_waitcnt vmcnt(0)
	v_mov_b32_e32 v46, v21
	v_mov_b32_e32 v22, v20
	v_mov_b32_e32 v23, v18
	v_mul_f32_e32 v46, v32, v46
	v_mul_f32_e32 v47, v33, v47
	v_mul_f32_e32 v20, v32, v20
	v_fma_f32 v46, v24, v22, -v46
	v_fma_f32 v47, v25, v23, -v47
	v_mul_f32_e32 v22, v24, v21
	v_mov_b32_e32 v24, v33
	v_mul_f32_e32 v18, v24, v18
	v_mul_f32_e32 v19, v25, v19
	v_mov_b32_e32 v24, v46
	v_mov_b32_e32 v21, v18
	v_mov_b32_e32 v23, v19
	v_add_f32_e32 v32, v20, v22
	v_add_f32_e32 v33, v21, v23
	v_mov_b32_e32 v18, v34
	v_mov_b32_e32 v19, v35
	v_mov_b32_e32 v20, v52
	v_mov_b32_e32 v21, v53
	v_mov_b32_e32 v22, v48
	v_mov_b32_e32 v23, v49
	v_mov_b32_e32 v25, v47

.LBB0_564:
	s_or_b64 exec, exec, s[2:3]
	v_add_u32_e32 v20, 0x4020, v42
	s_movk_i32 s0, 0x4000
	v_cmp_gt_i32_e32 vcc, s0, v20
	v_cmp_lt_i32_e64 s[40:41], s24, v20
	s_and_saveexec_b64 s[0:1], s[40:41]
	s_xor_b64 s[2:3], exec, s[0:1]
	v_add_u32_e32 v0, 32, v42
	s_movk_i32 s0, 0x2000
	v_lshrrev_b32_e32 v36, 8, v0
	v_or_b32_sdwa v0, v20, s0 dst_sel:DWORD dst_unused:UNUSED_PAD src0_sel:BYTE_0 src1_sel:DWORD
	s_or_saveexec_b64 s[2:3], s[2:3]
	v_mov_b32_e32 v19, 0
	v_mov_b32_e32 v18, 0
	s_xor_b64 exec, exec, s[2:3]
	v_lshlrev_b32_e32 v18, 4, v20
	v_and_b32_e32 v0, 0x1fff, v20
	v_and_b32_e32 v18, 0x3f0, v18
	v_mov_b32_e32 v19, v43
	s_or_b64 exec, exec, s[2:3]
	s_and_saveexec_b64 s[2:3], s[38:39]
	s_cbranch_execz .LBB0_555
	s_and_saveexec_b64 s[22:23], vcc
	s_cbranch_execz .LBB0_554
	v_or_b32_e32 v20, v19, v38
	v_or_b32_e32 v21, v19, v39
	v_or_b32_e32 v26, v18, v38
	v_or_b32_e32 v27, v18, v39
	v_or_b32_e32 v28, v18, v40
	v_or_b32_e32 v29, v18, v41
	v_lshlrev_b32_e32 v18, 3, v20
	v_lshlrev_b32_e32 v20, 3, v21
	v_or_b32_e32 v24, v19, v40
	v_or_b32_e32 v25, v19, v41
	global_load_dwordx2 v[18:19], v18, s[80:81]
	s_nop 0
	global_load_dwordx2 v[20:21], v20, s[80:81]
	s_waitcnt vmcnt(1)
	v_mov_b32_e32 v22, v18
	s_waitcnt vmcnt(0)
	v_mov_b32_e32 v23, v20
	v_mov_b32_e32 v20, v19
	v_mul_f32_e32 v18, v10, v20
	v_mul_f32_e32 v19, v11, v21
	s_nop 0
	v_fma_f32 v18, v2, v22, -v18
	v_fma_f32 v19, v3, v23, -v19
	v_mul_f32_e32 v2, v2, v20
	v_mul_f32_e32 v3, v3, v21
	v_lshlrev_b32_e32 v20, 3, v25
	v_fma_f32 v10, v10, v22, v2
	v_fma_f32 v11, v11, v23, v3
	v_lshlrev_b32_e32 v2, 3, v24
	global_load_dwordx2 v[2:3], v2, s[80:81]
	s_nop 0
	global_load_dwordx2 v[20:21], v20, s[80:81]
	s_waitcnt vmcnt(1)
	v_mov_b32_e32 v22, v2
	s_waitcnt vmcnt(0)
	v_mov_b32_e32 v23, v20
	v_mov_b32_e32 v20, v3
	v_mul_f32_e32 v2, v12, v20
	v_mul_f32_e32 v3, v13, v21
	s_nop 0
	v_fma_f32 v24, v4, v22, -v2
	v_fma_f32 v25, v5, v23, -v3
	v_mul_f32_e32 v2, v4, v20
	v_mul_f32_e32 v3, v5, v21
	v_lshlrev_b32_e32 v4, 3, v27
	v_fma_f32 v12, v12, v22, v2
	v_fma_f32 v13, v13, v23, v3
	v_lshlrev_b32_e32 v2, 3, v26
	global_load_dwordx2 v[2:3], v2, s[80:81]
	s_nop 0
	global_load_dwordx2 v[4:5], v4, s[80:81]
	s_waitcnt vmcnt(1)
	v_mov_b32_e32 v20, v2
	s_waitcnt vmcnt(0)
	v_mov_b32_e32 v21, v4
	v_mov_b32_e32 v4, v3
	v_mul_f32_e32 v2, v14, v4
	v_mul_f32_e32 v3, v15, v5
	s_nop 0
	v_fma_f32 v22, v6, v20, -v2
	v_fma_f32 v23, v7, v21, -v3
	v_mul_f32_e32 v2, v6, v4
	v_mul_f32_e32 v3, v7, v5
	v_lshlrev_b32_e32 v4, 3, v28
	v_fma_f32 v14, v14, v20, v2
	v_fma_f32 v15, v15, v21, v3
	v_lshlrev_b32_e32 v2, 3, v29
	global_load_dwordx2 v[2:3], v2, s[80:81]
	s_nop 0
	global_load_dwordx2 v[4:5], v4, s[80:81]
	s_waitcnt vmcnt(1)
	v_mov_b32_e32 v21, v3
	s_waitcnt vmcnt(0)
	v_mov_b32_e32 v20, v5
	v_mov_b32_e32 v6, v4
	v_mov_b32_e32 v7, v2
	v_mul_f32_e32 v20, v16, v20
	v_mul_f32_e32 v21, v17, v21
	v_mul_f32_e32 v4, v16, v4
	v_fma_f32 v20, v8, v6, -v20
	v_fma_f32 v21, v9, v7, -v21
	v_mul_f32_e32 v6, v8, v5
	v_mov_b32_e32 v8, v17
	v_mul_f32_e32 v2, v8, v2
	v_mul_f32_e32 v3, v9, v3
	v_mov_b32_e32 v8, v20
	v_mov_b32_e32 v5, v2
	v_mov_b32_e32 v7, v3
	v_add_f32_e32 v16, v4, v6
	v_add_f32_e32 v17, v5, v7
	v_mov_b32_e32 v2, v18
	v_mov_b32_e32 v3, v19
	v_mov_b32_e32 v4, v24
	v_mov_b32_e32 v5, v25
	v_mov_b32_e32 v6, v22
	v_mov_b32_e32 v7, v23
	v_mov_b32_e32 v9, v21
	s_branch .LBB0_554

.LBB0_575:
	s_or_b64 exec, exec, s[22:23]
	v_add_u32_e32 v19, v35, v22
	v_mad_i64_i32 v[20:21], s[0:1], v19, s9, v[0:1]
	v_mov_b64_e32 v[22:23], s[24:25]
	v_mad_u64_u32 v[22:23], s[0:1], v20, s5, v[22:23]
	v_lshlrev_b32_e32 v18, 5, v18
	v_mad_i32_i24 v23, v21, s5, v23
	v_ashrrev_i32_e32 v19, 31, v18
	v_lshl_add_u64 v[18:19], v[18:19], 1, v[22:23]
	v_lshlrev_b32_e32 v0, 1, v140
	v_mul_f32_e32 v2, v34, v2
	v_mul_f32_e32 v3, v34, v3
	v_mul_f32_e32 v4, v34, v4
	v_mul_f32_e32 v5, v34, v5
	v_lshl_add_u64 v[18:19], v[18:19], 0, v[0:1]
	v_cvt_pk_bf16_f32 v2, v2, v3
	v_cvt_pk_bf16_f32 v3, v4, v5
	global_store_dwordx2 v[18:19], v[2:3], off
	v_mul_f32_e32 v2, v34, v6
	v_mul_f32_e32 v3, v34, v7
	v_mul_f32_e32 v4, v34, v8
	v_mul_f32_e32 v5, v34, v9
	v_cvt_pk_bf16_f32 v2, v2, v3
	v_cvt_pk_bf16_f32 v3, v4, v5
	global_store_dwordx2 v[18:19], v[2:3], off offset:16
	v_mul_f32_e32 v2, v34, v10
	v_mul_f32_e32 v3, v34, v11
	v_mul_f32_e32 v4, v34, v12
	v_mul_f32_e32 v5, v34, v13
	v_cvt_pk_bf16_f32 v2, v2, v3
	v_cvt_pk_bf16_f32 v3, v4, v5
	global_store_dwordx2 v[18:19], v[2:3], off offset:32
	v_mul_f32_e32 v2, v34, v14
	v_mul_f32_e32 v3, v34, v15
	v_mul_f32_e32 v4, v34, v16
	v_mul_f32_e32 v5, v34, v17
	v_cvt_pk_bf16_f32 v2, v2, v3
	v_cvt_pk_bf16_f32 v3, v4, v5
	global_store_dwordx2 v[18:19], v[2:3], off offset:48

.LBB0_585:
	s_or_saveexec_b64 s[2:3], s[2:3]
	v_lshrrev_b32_e32 v159, 6, v161
	v_add_u32_e32 v165, v164, v159
	s_xor_b64 exec, exec, s[2:3]
	s_cbranch_execz .LBB0_587
	v_mad_i64_i32 v[130:131], s[0:1], v165, s9, v[0:1]
	v_mad_u64_u32 v[132:133], s[0:1], v130, s5, v[144:145]
	v_mul_f32_e32 v114, v114, v154
	v_mul_f32_e32 v115, v115, v154
	v_mul_f32_e32 v116, v116, v154
	v_mul_f32_e32 v117, v117, v154
	v_mad_i32_i24 v133, v131, s5, v133
	v_cvt_pk_bf16_f32 v114, v114, v115
	v_cvt_pk_bf16_f32 v115, v116, v117
	global_store_dwordx2 v[132:133], v[114:115], off
	v_mul_f32_e32 v114, v118, v154
	v_mul_f32_e32 v115, v119, v154
	v_mul_f32_e32 v116, v120, v154
	v_mul_f32_e32 v117, v121, v154
	v_cvt_pk_bf16_f32 v114, v114, v115
	v_cvt_pk_bf16_f32 v115, v116, v117
	global_store_dwordx2 v[132:133], v[114:115], off offset:16
	v_mul_f32_e32 v114, v122, v154
	v_mul_f32_e32 v115, v123, v154
	v_mul_f32_e32 v116, v124, v154
	v_mul_f32_e32 v117, v125, v154
	v_cvt_pk_bf16_f32 v114, v114, v115
	v_cvt_pk_bf16_f32 v115, v116, v117
	global_store_dwordx2 v[132:133], v[114:115], off offset:32
	v_mul_f32_e32 v114, v126, v154
	v_mul_f32_e32 v115, v127, v154
	v_mul_f32_e32 v116, v128, v154
	v_mul_f32_e32 v117, v129, v154
	v_cvt_pk_bf16_f32 v114, v114, v115
	v_cvt_pk_bf16_f32 v115, v116, v117
	global_store_dwordx2 v[132:133], v[114:115], off offset:48

.LBB0_589:
	s_andn2_saveexec_b64 s[2:3], s[2:3]
	s_cbranch_execz .LBB0_591
	v_mad_i64_i32 v[116:117], s[0:1], v165, s9, v[0:1]
	v_mad_u64_u32 v[118:119], s[0:1], v116, s5, v[144:145]
	v_mul_f32_e32 v100, v100, v154
	v_mul_f32_e32 v101, v101, v154
	v_mad_i32_i24 v119, v117, s5, v119
	v_cvt_pk_bf16_f32 v98, v98, v99
	v_cvt_pk_bf16_f32 v99, v100, v101
	global_store_dwordx2 v[118:119], v[98:99], off offset:64
	v_mul_f32_e32 v98, v102, v154
	v_mul_f32_e32 v99, v103, v154
	v_mul_f32_e32 v100, v104, v154
	v_mul_f32_e32 v101, v105, v154
	v_cvt_pk_bf16_f32 v98, v98, v99
	v_cvt_pk_bf16_f32 v99, v100, v101
	global_store_dwordx2 v[118:119], v[98:99], off offset:80
	v_mul_f32_e32 v98, v106, v154
	v_mul_f32_e32 v99, v107, v154
	v_mul_f32_e32 v100, v108, v154
	v_mul_f32_e32 v101, v109, v154
	v_cvt_pk_bf16_f32 v98, v98, v99
	v_cvt_pk_bf16_f32 v99, v100, v101
	global_store_dwordx2 v[118:119], v[98:99], off offset:96
	v_mul_f32_e32 v98, v110, v154
	v_mul_f32_e32 v99, v111, v154
	v_mul_f32_e32 v100, v112, v154
	v_mul_f32_e32 v101, v113, v154
	v_cvt_pk_bf16_f32 v98, v98, v99
	v_cvt_pk_bf16_f32 v99, v100, v101
	global_store_dwordx2 v[118:119], v[98:99], off offset:112

.LBB0_597:
	s_or_saveexec_b64 s[2:3], s[2:3]
	v_add_u32_e32 v102, v99, v159
	s_xor_b64 exec, exec, s[2:3]
	s_cbranch_execz .LBB0_599
	v_mad_i64_i32 v[104:105], s[0:1], v102, s9, v[0:1]
	v_mad_u64_u32 v[106:107], s[0:1], v104, s5, v[144:145]
	v_mul_f32_e32 v82, v82, v98
	v_mul_f32_e32 v83, v83, v98
	v_mul_f32_e32 v84, v84, v98
	v_mul_f32_e32 v85, v85, v98
	v_mad_i32_i24 v107, v105, s5, v107
	v_cvt_pk_bf16_f32 v82, v82, v83
	v_cvt_pk_bf16_f32 v83, v84, v85
	global_store_dwordx2 v[106:107], v[82:83], off
	v_mul_f32_e32 v82, v86, v98
	v_mul_f32_e32 v83, v87, v98
	v_mul_f32_e32 v84, v88, v98
	v_mul_f32_e32 v85, v89, v98
	v_cvt_pk_bf16_f32 v82, v82, v83
	v_cvt_pk_bf16_f32 v83, v84, v85
	global_store_dwordx2 v[106:107], v[82:83], off offset:16
	v_mul_f32_e32 v82, v90, v98
	v_mul_f32_e32 v83, v91, v98
	v_mul_f32_e32 v84, v92, v98
	v_mul_f32_e32 v85, v93, v98
	v_cvt_pk_bf16_f32 v82, v82, v83
	v_cvt_pk_bf16_f32 v83, v84, v85
	global_store_dwordx2 v[106:107], v[82:83], off offset:32
	v_mul_f32_e32 v82, v94, v98
	v_mul_f32_e32 v83, v95, v98
	v_mul_f32_e32 v84, v96, v98
	v_mul_f32_e32 v85, v97, v98
	v_cvt_pk_bf16_f32 v82, v82, v83
	v_cvt_pk_bf16_f32 v83, v84, v85
	global_store_dwordx2 v[106:107], v[82:83], off offset:48

.LBB0_601:
	s_andn2_saveexec_b64 s[2:3], s[2:3]
	s_cbranch_execz .LBB0_603
	v_mad_i64_i32 v[82:83], s[0:1], v102, s9, v[0:1]
	v_mad_u64_u32 v[84:85], s[0:1], v82, s5, v[144:145]
	v_mul_f32_e32 v68, v68, v98
	v_mul_f32_e32 v69, v69, v98
	v_mad_i32_i24 v85, v83, s5, v85
	v_cvt_pk_bf16_f32 v66, v66, v67
	v_cvt_pk_bf16_f32 v67, v68, v69
	global_store_dwordx2 v[84:85], v[66:67], off offset:64
	v_mul_f32_e32 v66, v70, v98
	v_mul_f32_e32 v67, v71, v98
	v_mul_f32_e32 v68, v72, v98
	v_mul_f32_e32 v69, v73, v98
	v_cvt_pk_bf16_f32 v66, v66, v67
	v_cvt_pk_bf16_f32 v67, v68, v69
	global_store_dwordx2 v[84:85], v[66:67], off offset:80
	v_mul_f32_e32 v66, v74, v98
	v_mul_f32_e32 v67, v75, v98
	v_mul_f32_e32 v68, v76, v98
	v_mul_f32_e32 v69, v77, v98
	v_cvt_pk_bf16_f32 v66, v66, v67
	v_cvt_pk_bf16_f32 v67, v68, v69
	global_store_dwordx2 v[84:85], v[66:67], off offset:96
	v_mul_f32_e32 v66, v78, v98
	v_mul_f32_e32 v67, v79, v98
	v_mul_f32_e32 v68, v80, v98
	v_mul_f32_e32 v69, v81, v98
	v_cvt_pk_bf16_f32 v66, v66, v67
	v_cvt_pk_bf16_f32 v67, v68, v69
	global_store_dwordx2 v[84:85], v[66:67], off offset:112

.LBB0_609:
	s_or_saveexec_b64 s[2:3], s[2:3]
	v_add_u32_e32 v70, v67, v159
	s_xor_b64 exec, exec, s[2:3]
	s_cbranch_execz .LBB0_611
	v_mad_i64_i32 v[72:73], s[0:1], v70, s9, v[0:1]
	v_mad_u64_u32 v[74:75], s[0:1], v72, s5, v[144:145]
	v_mul_f32_e32 v50, v50, v66
	v_mul_f32_e32 v51, v51, v66
	v_mul_f32_e32 v52, v52, v66
	v_mul_f32_e32 v53, v53, v66
	v_mad_i32_i24 v75, v73, s5, v75
	v_cvt_pk_bf16_f32 v50, v50, v51
	v_cvt_pk_bf16_f32 v51, v52, v53
	global_store_dwordx2 v[74:75], v[50:51], off
	v_mul_f32_e32 v50, v54, v66
	v_mul_f32_e32 v51, v55, v66
	v_mul_f32_e32 v52, v56, v66
	v_mul_f32_e32 v53, v57, v66
	v_cvt_pk_bf16_f32 v50, v50, v51
	v_cvt_pk_bf16_f32 v51, v52, v53
	global_store_dwordx2 v[74:75], v[50:51], off offset:16
	v_mul_f32_e32 v50, v58, v66
	v_mul_f32_e32 v51, v59, v66
	v_mul_f32_e32 v52, v60, v66
	v_mul_f32_e32 v53, v61, v66
	v_cvt_pk_bf16_f32 v50, v50, v51
	v_cvt_pk_bf16_f32 v51, v52, v53
	global_store_dwordx2 v[74:75], v[50:51], off offset:32
	v_mul_f32_e32 v50, v62, v66
	v_mul_f32_e32 v51, v63, v66
	v_mul_f32_e32 v52, v64, v66
	v_mul_f32_e32 v53, v65, v66
	v_cvt_pk_bf16_f32 v50, v50, v51
	v_cvt_pk_bf16_f32 v51, v52, v53
	global_store_dwordx2 v[74:75], v[50:51], off offset:48

.LBB0_613:
	s_andn2_saveexec_b64 s[2:3], s[2:3]
	s_cbranch_execz .LBB0_615
	v_mad_i64_i32 v[50:51], s[0:1], v70, s9, v[0:1]
	v_mad_u64_u32 v[52:53], s[0:1], v50, s5, v[144:145]
	v_mul_f32_e32 v36, v36, v66
	v_mul_f32_e32 v37, v37, v66
	v_mad_i32_i24 v53, v51, s5, v53
	v_cvt_pk_bf16_f32 v34, v34, v35
	v_cvt_pk_bf16_f32 v35, v36, v37
	global_store_dwordx2 v[52:53], v[34:35], off offset:64
	v_mul_f32_e32 v34, v38, v66
	v_mul_f32_e32 v35, v39, v66
	v_mul_f32_e32 v36, v40, v66
	v_mul_f32_e32 v37, v41, v66
	v_cvt_pk_bf16_f32 v34, v34, v35
	v_cvt_pk_bf16_f32 v35, v36, v37
	global_store_dwordx2 v[52:53], v[34:35], off offset:80
	v_mul_f32_e32 v34, v42, v66
	v_mul_f32_e32 v35, v43, v66
	v_mul_f32_e32 v36, v44, v66
	v_mul_f32_e32 v37, v45, v66
	v_cvt_pk_bf16_f32 v34, v34, v35
	v_cvt_pk_bf16_f32 v35, v36, v37
	global_store_dwordx2 v[52:53], v[34:35], off offset:96
	v_mul_f32_e32 v34, v46, v66
	v_mul_f32_e32 v35, v47, v66
	v_mul_f32_e32 v36, v48, v66
	v_mul_f32_e32 v37, v49, v66
	v_cvt_pk_bf16_f32 v34, v34, v35
	v_cvt_pk_bf16_f32 v35, v36, v37
	global_store_dwordx2 v[52:53], v[34:35], off offset:112

.LBB0_621:
	s_or_saveexec_b64 s[2:3], s[2:3]
	v_add_u32_e32 v38, v35, v159
	s_xor_b64 exec, exec, s[2:3]
	s_cbranch_execz .LBB0_623
	v_mad_i64_i32 v[40:41], s[0:1], v38, s9, v[0:1]
	v_mad_u64_u32 v[42:43], s[0:1], v40, s5, v[144:145]
	v_mul_f32_e32 v18, v18, v34
	v_mul_f32_e32 v19, v19, v34
	v_mul_f32_e32 v20, v20, v34
	v_mul_f32_e32 v21, v21, v34
	v_mad_i32_i24 v43, v41, s5, v43
	v_cvt_pk_bf16_f32 v18, v18, v19
	v_cvt_pk_bf16_f32 v19, v20, v21
	global_store_dwordx2 v[42:43], v[18:19], off
	v_mul_f32_e32 v18, v22, v34
	v_mul_f32_e32 v19, v23, v34
	v_mul_f32_e32 v20, v24, v34
	v_mul_f32_e32 v21, v25, v34
	v_cvt_pk_bf16_f32 v18, v18, v19
	v_cvt_pk_bf16_f32 v19, v20, v21
	global_store_dwordx2 v[42:43], v[18:19], off offset:16
	v_mul_f32_e32 v18, v26, v34
	v_mul_f32_e32 v19, v27, v34
	v_mul_f32_e32 v20, v28, v34
	v_mul_f32_e32 v21, v29, v34
	v_cvt_pk_bf16_f32 v18, v18, v19
	v_cvt_pk_bf16_f32 v19, v20, v21
	global_store_dwordx2 v[42:43], v[18:19], off offset:32
	v_mul_f32_e32 v18, v30, v34
	v_mul_f32_e32 v19, v31, v34
	v_mul_f32_e32 v20, v32, v34
	v_mul_f32_e32 v21, v33, v34
	v_cvt_pk_bf16_f32 v18, v18, v19
	v_cvt_pk_bf16_f32 v19, v20, v21
	global_store_dwordx2 v[42:43], v[18:19], off offset:48

.LBB0_625:
	s_andn2_saveexec_b64 s[2:3], s[2:3]
	s_cbranch_execz .LBB0_627
	v_mad_i64_i32 v[18:19], s[0:1], v38, s9, v[0:1]
	v_mad_u64_u32 v[20:21], s[0:1], v18, s5, v[144:145]
	v_mul_f32_e32 v4, v4, v34
	v_mul_f32_e32 v5, v5, v34
	v_mad_i32_i24 v21, v19, s5, v21
	v_cvt_pk_bf16_f32 v2, v2, v3
	v_cvt_pk_bf16_f32 v3, v4, v5
	global_store_dwordx2 v[20:21], v[2:3], off offset:64
	v_mul_f32_e32 v2, v6, v34
	v_mul_f32_e32 v3, v7, v34
	v_mul_f32_e32 v4, v8, v34
	v_mul_f32_e32 v5, v9, v34
	v_cvt_pk_bf16_f32 v2, v2, v3
	v_cvt_pk_bf16_f32 v3, v4, v5
	global_store_dwordx2 v[20:21], v[2:3], off offset:80
	v_mul_f32_e32 v2, v10, v34
	v_mul_f32_e32 v3, v11, v34
	v_mul_f32_e32 v4, v12, v34
	v_mul_f32_e32 v5, v13, v34
	v_cvt_pk_bf16_f32 v2, v2, v3
	v_cvt_pk_bf16_f32 v3, v4, v5
	global_store_dwordx2 v[20:21], v[2:3], off offset:96
	v_mul_f32_e32 v2, v14, v34
	v_mul_f32_e32 v3, v15, v34
	v_mul_f32_e32 v4, v16, v34
	v_mul_f32_e32 v5, v17, v34
	v_cvt_pk_bf16_f32 v2, v2, v3
	v_cvt_pk_bf16_f32 v3, v4, v5
	global_store_dwordx2 v[20:21], v[2:3], off offset:112

.LBB0_628:
	s_and_b64 vcc, exec, s[2:3]
	s_cbranch_vccz .LBB0_577
	s_mul_hi_i32 s0, s13, 0x3e0f83e1
	s_lshr_b32 s1, s0, 31
	s_ashr_i32 s0, s0, 4
	s_add_i32 s1, s0, s1
	s_lshl_b32 s0, s1, 8
	s_mulk_i32 s1, 0xbe00
	v_readlane_b32 s2, v254, 51
	s_add_i32 s1, s1, s2
	v_add_u32_e32 v2, s1, v184
	v_ashrrev_i32_e32 v3, 31, v2
	v_lshlrev_b64 v[2:3], 9, v[2:3]
	v_lshl_add_u64 v[158:159], v[148:149], 0, v[2:3]
	s_mov_b32 s2, 0x8000
	v_add_u32_e32 v4, s0, v141
	v_add_co_u32_e32 v160, vcc, s2, v158
	v_ashrrev_i32_e32 v5, 31, v4
	s_nop 0
	v_addc_co_u32_e32 v161, vcc, 0, v159, vcc
	s_mov_b32 s3, 0x10000
	v_lshlrev_b64 v[4:5], 9, v[4:5]
	v_add_co_u32_e32 v164, vcc, s3, v158
	v_lshl_add_u64 v[150:151], v[146:147], 0, v[4:5]
	s_nop 0
	v_addc_co_u32_e32 v165, vcc, 0, v159, vcc
	v_add_co_u32_e32 v152, vcc, s2, v150
	global_load_dwordx4 v[2:5], v[158:159], off
	global_load_dwordx4 v[6:9], v[160:161], off
	v_addc_co_u32_e32 v153, vcc, 0, v151, vcc
	global_load_dwordx4 v[10:13], v[164:165], off
	global_load_dwordx4 v[14:17], v[150:151], off
	v_add_co_u32_e32 v154, vcc, s3, v150
	s_mov_b32 s2, 0x18000
	s_nop 0
	v_addc_co_u32_e32 v155, vcc, 0, v151, vcc
	global_load_dwordx4 v[18:21], v[152:153], off
	global_load_dwordx4 v[22:25], v[154:155], off
	v_add_co_u32_e32 v156, vcc, s2, v150
	s_nop 1
	v_addc_co_u32_e32 v157, vcc, 0, v151, vcc
	global_load_dwordx4 v[26:29], v[156:157], off
	v_add_co_u32_e32 v166, vcc, s2, v158
	s_nop 1
	v_addc_co_u32_e32 v167, vcc, 0, v159, vcc
	global_load_dwordx4 v[30:33], v[166:167], off
	global_load_dwordx4 v[186:189], v[150:151], off offset:128
	global_load_dwordx4 v[190:193], v[156:157], off offset:128
	global_load_dwordx4 v[194:197], v[154:155], off offset:128
	global_load_dwordx4 v[208:211], v[152:153], off offset:128
	global_load_dwordx4 v[218:221], v[158:159], off offset:128
	global_load_dwordx4 v[238:241], v[166:167], off offset:128
	global_load_dwordx4 v[242:245], v[164:165], off offset:128
	global_load_dwordx4 v[246:249], v[160:161], off offset:128
	s_waitcnt vmcnt(12)
	ds_write_b128 v134, v[14:17] offset:36864
	ds_write_b128 v134, v[2:5]
	s_waitcnt vmcnt(11)
	ds_write_b128 v134, v[18:21] offset:46080
	s_waitcnt vmcnt(10)
	ds_write_b128 v134, v[22:25] offset:55296
	s_waitcnt vmcnt(9)
	ds_write_b128 v134, v[26:29] offset:64512
	ds_write_b128 v134, v[6:9] offset:9216
	ds_write_b128 v134, v[10:13] offset:18432
	s_waitcnt vmcnt(8)
	ds_write_b128 v134, v[30:33] offset:27648
	s_waitcnt lgkmcnt(0)
	s_barrier
	ds_read_b128 v[2:5], v137 offset:36864
	ds_read_b128 v[6:9], v136
	ds_read_b128 v[10:13], v136 offset:4608
	ds_read_b128 v[14:17], v137 offset:41472
	ds_read_b128 v[34:37], v136 offset:9216
	ds_read_b128 v[234:237], v136 offset:13824
	s_waitcnt lgkmcnt(4)
	v_mfma_f32_32x32x16_bf16 v[114:129], v[2:5], v[6:9], 0
	s_waitcnt lgkmcnt(3)
	v_mfma_f32_32x32x16_bf16 v[82:97], v[2:5], v[10:13], 0
	s_waitcnt lgkmcnt(1)
	v_mfma_f32_32x32x16_bf16 v[50:65], v[2:5], v[34:37], 0
	s_waitcnt lgkmcnt(0)
	v_mfma_f32_32x32x16_bf16 v[18:33], v[2:5], v[234:237], 0
	v_mfma_f32_32x32x16_bf16 v[98:113], v[14:17], v[6:9], 0
	v_mfma_f32_32x32x16_bf16 v[66:81], v[14:17], v[10:13], 0
	v_mfma_f32_32x32x16_bf16 v[34:49], v[14:17], v[34:37], 0
	v_mfma_f32_32x32x16_bf16 v[2:17], v[14:17], v[234:237], 0
	s_waitcnt vmcnt(3)
	ds_write_b128 v143, v[218:221]
	s_waitcnt vmcnt(0)
	ds_write_b128 v203, v[246:249]
	ds_write_b128 v233, v[242:245]
	ds_write_b128 v228, v[238:241]
	ds_read_b128 v[218:221], v137 offset:36896
	ds_read_b128 v[234:237], v136 offset:32
	ds_read_b128 v[238:241], v136 offset:4640
	ds_read_b128 v[242:245], v136 offset:9248
	ds_read_b128 v[246:249], v136 offset:13856
	s_waitcnt lgkmcnt(3)
	v_mfma_f32_32x32x16_bf16 v[114:129], v[218:221], v[234:237], v[114:129]
	s_waitcnt lgkmcnt(2)
	v_mfma_f32_32x32x16_bf16 v[82:97], v[218:221], v[238:241], v[82:97]
	s_waitcnt lgkmcnt(1)
	v_mfma_f32_32x32x16_bf16 v[50:65], v[218:221], v[242:245], v[50:65]
	s_waitcnt lgkmcnt(0)
	v_mfma_f32_32x32x16_bf16 v[18:33], v[218:221], v[246:249], v[18:33]
	ds_read_b128 v[218:221], v137 offset:41504
	s_waitcnt lgkmcnt(0)
	v_mfma_f32_32x32x16_bf16 v[98:113], v[218:221], v[234:237], v[98:113]
	v_mfma_f32_32x32x16_bf16 v[66:81], v[218:221], v[238:241], v[66:81]
	v_mfma_f32_32x32x16_bf16 v[34:49], v[218:221], v[242:245], v[34:49]
	v_mfma_f32_32x32x16_bf16 v[2:17], v[218:221], v[246:249], v[2:17]
	ds_write_b128 v252, v[186:189]
	ds_write_b128 v250, v[208:211]
	ds_write_b128 v251, v[194:197]
	ds_write_b128 v204, v[190:193]
	ds_read_b128 v[186:189], v137 offset:36928
	ds_read_b128 v[190:193], v136 offset:64
	ds_read_b128 v[194:197], v136 offset:4672
	ds_read_b128 v[208:211], v137 offset:41536
	ds_read_b128 v[218:221], v136 offset:9280
	ds_read_b128 v[234:237], v136 offset:13888
	s_waitcnt lgkmcnt(4)
	v_mfma_f32_32x32x16_bf16 v[114:129], v[186:189], v[190:193], v[114:129]
	s_waitcnt lgkmcnt(3)
	v_mfma_f32_32x32x16_bf16 v[82:97], v[186:189], v[194:197], v[82:97]
	s_waitcnt lgkmcnt(1)
	v_mfma_f32_32x32x16_bf16 v[50:65], v[186:189], v[218:221], v[50:65]
	s_waitcnt lgkmcnt(0)
	v_mfma_f32_32x32x16_bf16 v[18:33], v[186:189], v[234:237], v[18:33]
	v_mfma_f32_32x32x16_bf16 v[98:113], v[208:211], v[190:193], v[98:113]
	global_load_dwordx4 v[186:189], v[158:159], off offset:256
	global_load_dwordx4 v[190:193], v[160:161], off offset:256
	v_mfma_f32_32x32x16_bf16 v[66:81], v[208:211], v[194:197], v[66:81]
	v_mfma_f32_32x32x16_bf16 v[34:49], v[208:211], v[218:221], v[34:49]
	global_load_dwordx4 v[194:197], v[164:165], off offset:256
	global_load_dwordx4 v[218:221], v[166:167], off offset:256
	v_mfma_f32_32x32x16_bf16 v[2:17], v[208:211], v[234:237], v[2:17]
	ds_read_b128 v[208:211], v137 offset:36960
	ds_read_b128 v[234:237], v136 offset:96
	ds_read_b128 v[238:241], v136 offset:4704
	ds_read_b128 v[242:245], v136 offset:9312
	ds_read_b128 v[246:249], v136 offset:13920
	s_waitcnt lgkmcnt(3)
	v_mfma_f32_32x32x16_bf16 v[114:129], v[208:211], v[234:237], v[114:129]
	s_waitcnt lgkmcnt(2)
	v_mfma_f32_32x32x16_bf16 v[82:97], v[208:211], v[238:241], v[82:97]
	s_waitcnt lgkmcnt(1)
	v_mfma_f32_32x32x16_bf16 v[50:65], v[208:211], v[242:245], v[50:65]
	s_waitcnt lgkmcnt(0)
	v_mfma_f32_32x32x16_bf16 v[18:33], v[208:211], v[246:249], v[18:33]
	ds_read_b128 v[208:211], v137 offset:41568
	s_waitcnt lgkmcnt(0)
	v_mfma_f32_32x32x16_bf16 v[98:113], v[208:211], v[234:237], v[98:113]
	v_mfma_f32_32x32x16_bf16 v[66:81], v[208:211], v[238:241], v[66:81]
	v_mfma_f32_32x32x16_bf16 v[34:49], v[208:211], v[242:245], v[34:49]
	global_load_dwordx4 v[234:237], v[150:151], off offset:256
	global_load_dwordx4 v[238:241], v[152:153], off offset:256
	global_load_dwordx4 v[242:245], v[154:155], off offset:256
	global_load_dwordx4 v[222:225], v[156:157], off offset:256
	s_barrier
	v_mfma_f32_32x32x16_bf16 v[2:17], v[208:211], v[246:249], v[2:17]
	ds_read_b128 v[208:211], v183
	ds_read_b128 v[246:249], v185
	ds_read_b128 v[168:171], v185 offset:4608
	ds_read_b128 v[172:175], v185 offset:9216
	ds_read_b128 v[130:133], v185 offset:13824
	s_waitcnt lgkmcnt(3)
	v_mfma_f32_32x32x16_bf16 v[114:129], v[208:211], v[246:249], v[114:129]
	s_waitcnt lgkmcnt(2)
	v_mfma_f32_32x32x16_bf16 v[82:97], v[208:211], v[168:171], v[82:97]
	s_waitcnt lgkmcnt(1)
	v_mfma_f32_32x32x16_bf16 v[50:65], v[208:211], v[172:175], v[50:65]
	s_waitcnt lgkmcnt(0)
	v_mfma_f32_32x32x16_bf16 v[18:33], v[208:211], v[130:133], v[18:33]
	ds_read_b128 v[208:211], v183 offset:4608
	s_waitcnt lgkmcnt(0)
	v_mfma_f32_32x32x16_bf16 v[98:113], v[208:211], v[246:249], v[98:113]
	v_mfma_f32_32x32x16_bf16 v[66:81], v[208:211], v[168:171], v[66:81]
	v_mfma_f32_32x32x16_bf16 v[34:49], v[208:211], v[172:175], v[34:49]
	v_mfma_f32_32x32x16_bf16 v[2:17], v[208:211], v[130:133], v[2:17]
	s_waitcnt vmcnt(7)
	ds_write_b128 v134, v[186:189]
	s_waitcnt vmcnt(6)
	ds_write_b128 v134, v[190:193] offset:9216
	s_waitcnt vmcnt(5)
	ds_write_b128 v134, v[194:197] offset:18432
	s_waitcnt vmcnt(4)
	ds_write_b128 v134, v[218:221] offset:27648
	ds_read_b128 v[130:133], v183 offset:32
	ds_read_b128 v[168:171], v185 offset:32
	ds_read_b128 v[172:175], v185 offset:4640
	ds_read_b128 v[186:189], v185 offset:9248
	ds_read_b128 v[190:193], v185 offset:13856
	s_waitcnt lgkmcnt(3)
	v_mfma_f32_32x32x16_bf16 v[114:129], v[130:133], v[168:171], v[114:129]
	s_waitcnt lgkmcnt(2)
	v_mfma_f32_32x32x16_bf16 v[82:97], v[130:133], v[172:175], v[82:97]
	s_waitcnt lgkmcnt(1)
	v_mfma_f32_32x32x16_bf16 v[50:65], v[130:133], v[186:189], v[50:65]
	s_waitcnt lgkmcnt(0)
	v_mfma_f32_32x32x16_bf16 v[18:33], v[130:133], v[190:193], v[18:33]
	ds_read_b128 v[130:133], v183 offset:4640
	s_waitcnt lgkmcnt(0)
	v_mfma_f32_32x32x16_bf16 v[98:113], v[130:133], v[168:171], v[98:113]
	v_mfma_f32_32x32x16_bf16 v[66:81], v[130:133], v[172:175], v[66:81]
	v_mfma_f32_32x32x16_bf16 v[34:49], v[130:133], v[186:189], v[34:49]
	v_mfma_f32_32x32x16_bf16 v[2:17], v[130:133], v[190:193], v[2:17]
	s_waitcnt vmcnt(3)
	ds_write_b128 v134, v[234:237] offset:36864
	s_waitcnt vmcnt(2)
	ds_write_b128 v134, v[238:241] offset:46080
	s_waitcnt vmcnt(1)
	ds_write_b128 v134, v[242:245] offset:55296
	s_waitcnt vmcnt(0)
	ds_write_b128 v134, v[222:225] offset:64512
	ds_read_b128 v[130:133], v183 offset:64
	ds_read_b128 v[168:171], v185 offset:64
	ds_read_b128 v[172:175], v185 offset:4672
	ds_read_b128 v[186:189], v185 offset:9280
	ds_read_b128 v[190:193], v185 offset:13888
	s_waitcnt lgkmcnt(3)
	v_mfma_f32_32x32x16_bf16 v[114:129], v[130:133], v[168:171], v[114:129]
	s_waitcnt lgkmcnt(2)
	v_mfma_f32_32x32x16_bf16 v[82:97], v[130:133], v[172:175], v[82:97]
	s_waitcnt lgkmcnt(1)
	v_mfma_f32_32x32x16_bf16 v[50:65], v[130:133], v[186:189], v[50:65]
	s_waitcnt lgkmcnt(0)
	v_mfma_f32_32x32x16_bf16 v[18:33], v[130:133], v[190:193], v[18:33]
	ds_read_b128 v[130:133], v183 offset:4672
	s_waitcnt lgkmcnt(0)
	v_mfma_f32_32x32x16_bf16 v[98:113], v[130:133], v[168:171], v[98:113]
	global_load_dwordx4 v[168:171], v[158:159], off offset:384
	s_nop 0
	global_load_dwordx4 v[158:161], v[160:161], off offset:384
	v_mfma_f32_32x32x16_bf16 v[66:81], v[130:133], v[172:175], v[66:81]
	global_load_dwordx4 v[172:175], v[164:165], off offset:384
	s_nop 0
	global_load_dwordx4 v[164:167], v[166:167], off offset:384
	v_mfma_f32_32x32x16_bf16 v[34:49], v[130:133], v[186:189], v[34:49]
	v_mfma_f32_32x32x16_bf16 v[2:17], v[130:133], v[190:193], v[2:17]
	ds_read_b128 v[130:133], v183 offset:96
	ds_read_b128 v[186:189], v185 offset:96
	ds_read_b128 v[190:193], v185 offset:4704
	ds_read_b128 v[194:197], v185 offset:9312
	ds_read_b128 v[208:211], v185 offset:13920
	s_waitcnt lgkmcnt(3)
	v_mfma_f32_32x32x16_bf16 v[114:129], v[130:133], v[186:189], v[114:129]
	s_waitcnt lgkmcnt(2)
	v_mfma_f32_32x32x16_bf16 v[82:97], v[130:133], v[190:193], v[82:97]
	s_waitcnt lgkmcnt(1)
	v_mfma_f32_32x32x16_bf16 v[50:65], v[130:133], v[194:197], v[50:65]
	s_waitcnt lgkmcnt(0)
	v_mfma_f32_32x32x16_bf16 v[18:33], v[130:133], v[208:211], v[18:33]
	ds_read_b128 v[130:133], v183 offset:4704
	s_waitcnt lgkmcnt(0)
	v_mfma_f32_32x32x16_bf16 v[98:113], v[130:133], v[186:189], v[98:113]
	v_mfma_f32_32x32x16_bf16 v[66:81], v[130:133], v[190:193], v[66:81]
	global_load_dwordx4 v[186:189], v[150:151], off offset:384
	s_nop 0
	global_load_dwordx4 v[150:153], v[152:153], off offset:384
	s_nop 0
	global_load_dwordx4 v[190:193], v[154:155], off offset:384
	s_nop 0
	global_load_dwordx4 v[154:157], v[156:157], off offset:384
	s_barrier
	v_mfma_f32_32x32x16_bf16 v[34:49], v[130:133], v[194:197], v[34:49]
	v_mfma_f32_32x32x16_bf16 v[2:17], v[130:133], v[208:211], v[2:17]
	ds_read_b128 v[130:133], v137 offset:36864
	ds_read_b128 v[194:197], v136
	ds_read_b128 v[208:211], v136 offset:4608
	ds_read_b128 v[218:221], v136 offset:9216
	ds_read_b128 v[222:225], v136 offset:13824
	s_waitcnt lgkmcnt(3)
	v_mfma_f32_32x32x16_bf16 v[114:129], v[130:133], v[194:197], v[114:129]
	s_waitcnt lgkmcnt(2)
	v_mfma_f32_32x32x16_bf16 v[82:97], v[130:133], v[208:211], v[82:97]
	s_waitcnt lgkmcnt(1)
	v_mfma_f32_32x32x16_bf16 v[50:65], v[130:133], v[218:221], v[50:65]
	s_waitcnt lgkmcnt(0)
	v_mfma_f32_32x32x16_bf16 v[18:33], v[130:133], v[222:225], v[18:33]
	ds_read_b128 v[130:133], v137 offset:41472
	s_waitcnt lgkmcnt(0)
	v_mfma_f32_32x32x16_bf16 v[98:113], v[130:133], v[194:197], v[98:113]
	v_mfma_f32_32x32x16_bf16 v[66:81], v[130:133], v[208:211], v[66:81]
	v_mfma_f32_32x32x16_bf16 v[34:49], v[130:133], v[218:221], v[34:49]
	v_mfma_f32_32x32x16_bf16 v[2:17], v[130:133], v[222:225], v[2:17]
	s_waitcnt vmcnt(7)
	ds_write_b128 v143, v[168:171]
	s_waitcnt vmcnt(6)
	ds_write_b128 v203, v[158:161]
	s_waitcnt vmcnt(5)
	ds_write_b128 v233, v[172:175]
	s_waitcnt vmcnt(4)
	ds_write_b128 v228, v[164:167]
	ds_read_b128 v[130:133], v137 offset:36896
	ds_read_b128 v[158:161], v136 offset:32
	ds_read_b128 v[164:167], v136 offset:4640
	ds_read_b128 v[168:171], v136 offset:9248
	ds_read_b128 v[172:175], v136 offset:13856
	s_waitcnt lgkmcnt(3)
	v_mfma_f32_32x32x16_bf16 v[114:129], v[130:133], v[158:161], v[114:129]
	s_waitcnt lgkmcnt(2)
	v_mfma_f32_32x32x16_bf16 v[82:97], v[130:133], v[164:167], v[82:97]
	s_waitcnt lgkmcnt(1)
	v_mfma_f32_32x32x16_bf16 v[50:65], v[130:133], v[168:171], v[50:65]
	s_waitcnt lgkmcnt(0)
	v_mfma_f32_32x32x16_bf16 v[18:33], v[130:133], v[172:175], v[18:33]
	ds_read_b128 v[130:133], v137 offset:41504
	s_waitcnt lgkmcnt(0)
	v_mfma_f32_32x32x16_bf16 v[98:113], v[130:133], v[158:161], v[98:113]
	v_mfma_f32_32x32x16_bf16 v[66:81], v[130:133], v[164:167], v[66:81]
	v_mfma_f32_32x32x16_bf16 v[34:49], v[130:133], v[168:171], v[34:49]
	v_mfma_f32_32x32x16_bf16 v[2:17], v[130:133], v[172:175], v[2:17]
	s_waitcnt vmcnt(3)
	ds_write_b128 v252, v[186:189]
	s_waitcnt vmcnt(2)
	ds_write_b128 v250, v[150:153]
	s_waitcnt vmcnt(1)
	ds_write_b128 v251, v[190:193]
	s_waitcnt vmcnt(0)
	ds_write_b128 v204, v[154:157]
	ds_read_b128 v[130:133], v137 offset:36928
	ds_read_b128 v[150:153], v136 offset:64
	ds_read_b128 v[154:157], v136 offset:4672
	ds_read_b128 v[158:161], v136 offset:9280
	ds_read_b128 v[164:167], v136 offset:13888
	s_waitcnt lgkmcnt(3)
	v_mfma_f32_32x32x16_bf16 v[114:129], v[130:133], v[150:153], v[114:129]
	s_waitcnt lgkmcnt(2)
	v_mfma_f32_32x32x16_bf16 v[82:97], v[130:133], v[154:157], v[82:97]
	s_waitcnt lgkmcnt(1)
	v_mfma_f32_32x32x16_bf16 v[50:65], v[130:133], v[158:161], v[50:65]
	s_waitcnt lgkmcnt(0)
	v_mfma_f32_32x32x16_bf16 v[18:33], v[130:133], v[164:167], v[18:33]
	ds_read_b128 v[130:133], v137 offset:41536
	s_waitcnt lgkmcnt(0)
	v_mfma_f32_32x32x16_bf16 v[98:113], v[130:133], v[150:153], v[98:113]
	v_mfma_f32_32x32x16_bf16 v[66:81], v[130:133], v[154:157], v[66:81]
	v_mfma_f32_32x32x16_bf16 v[34:49], v[130:133], v[158:161], v[34:49]
	v_mfma_f32_32x32x16_bf16 v[2:17], v[130:133], v[164:167], v[2:17]
	ds_read_b128 v[130:133], v137 offset:36960
	ds_read_b128 v[150:153], v136 offset:96
	ds_read_b128 v[154:157], v136 offset:4704
	ds_read_b128 v[158:161], v136 offset:9312
	ds_read_b128 v[164:167], v136 offset:13920
	s_waitcnt lgkmcnt(3)
	v_mfma_f32_32x32x16_bf16 v[114:129], v[130:133], v[150:153], v[114:129]
	s_waitcnt lgkmcnt(2)
	v_mfma_f32_32x32x16_bf16 v[82:97], v[130:133], v[154:157], v[82:97]
	s_waitcnt lgkmcnt(1)
	v_mfma_f32_32x32x16_bf16 v[50:65], v[130:133], v[158:161], v[50:65]
	s_waitcnt lgkmcnt(0)
	v_mfma_f32_32x32x16_bf16 v[18:33], v[130:133], v[164:167], v[18:33]
	ds_read_b128 v[130:133], v137 offset:41568
	s_waitcnt lgkmcnt(0)
	s_barrier
	v_mfma_f32_32x32x16_bf16 v[98:113], v[130:133], v[150:153], v[98:113]
	v_mfma_f32_32x32x16_bf16 v[66:81], v[130:133], v[154:157], v[66:81]
	v_mfma_f32_32x32x16_bf16 v[34:49], v[130:133], v[158:161], v[34:49]
	v_mfma_f32_32x32x16_bf16 v[2:17], v[130:133], v[164:167], v[2:17]
	ds_read_b128 v[130:133], v183
	ds_read_b128 v[150:153], v185
	ds_read_b128 v[154:157], v185 offset:4608
	ds_read_b128 v[158:161], v185 offset:9216
	ds_read_b128 v[164:167], v185 offset:13824
	s_waitcnt lgkmcnt(3)
	v_mfma_f32_32x32x16_bf16 v[114:129], v[130:133], v[150:153], v[114:129]
	s_waitcnt lgkmcnt(2)
	v_mfma_f32_32x32x16_bf16 v[82:97], v[130:133], v[154:157], v[82:97]
	s_waitcnt lgkmcnt(1)
	v_mfma_f32_32x32x16_bf16 v[50:65], v[130:133], v[158:161], v[50:65]
	s_waitcnt lgkmcnt(0)
	v_mfma_f32_32x32x16_bf16 v[18:33], v[130:133], v[164:167], v[18:33]
	ds_read_b128 v[130:133], v183 offset:4608
	s_waitcnt lgkmcnt(0)
	v_mfma_f32_32x32x16_bf16 v[98:113], v[130:133], v[150:153], v[98:113]
	v_mfma_f32_32x32x16_bf16 v[66:81], v[130:133], v[154:157], v[66:81]
	v_mfma_f32_32x32x16_bf16 v[34:49], v[130:133], v[158:161], v[34:49]
	v_mfma_f32_32x32x16_bf16 v[2:17], v[130:133], v[164:167], v[2:17]
	ds_read_b128 v[130:133], v183 offset:32
	ds_read_b128 v[150:153], v185 offset:32
	ds_read_b128 v[154:157], v185 offset:4640
	ds_read_b128 v[158:161], v185 offset:9248
	ds_read_b128 v[164:167], v185 offset:13856
	s_waitcnt lgkmcnt(3)
	v_mfma_f32_32x32x16_bf16 v[114:129], v[130:133], v[150:153], v[114:129]
	s_waitcnt lgkmcnt(2)
	v_mfma_f32_32x32x16_bf16 v[82:97], v[130:133], v[154:157], v[82:97]
	s_waitcnt lgkmcnt(1)
	v_mfma_f32_32x32x16_bf16 v[50:65], v[130:133], v[158:161], v[50:65]
	s_waitcnt lgkmcnt(0)
	v_mfma_f32_32x32x16_bf16 v[18:33], v[130:133], v[164:167], v[18:33]
	ds_read_b128 v[130:133], v183 offset:4640
	s_waitcnt lgkmcnt(0)
	v_mfma_f32_32x32x16_bf16 v[98:113], v[130:133], v[150:153], v[98:113]
	v_mfma_f32_32x32x16_bf16 v[66:81], v[130:133], v[154:157], v[66:81]
	v_mfma_f32_32x32x16_bf16 v[34:49], v[130:133], v[158:161], v[34:49]
	v_mfma_f32_32x32x16_bf16 v[2:17], v[130:133], v[164:167], v[2:17]
	ds_read_b128 v[130:133], v183 offset:64
	ds_read_b128 v[150:153], v185 offset:64
	ds_read_b128 v[154:157], v185 offset:4672
	ds_read_b128 v[158:161], v185 offset:9280
	ds_read_b128 v[164:167], v185 offset:13888
	s_waitcnt lgkmcnt(3)
	v_mfma_f32_32x32x16_bf16 v[114:129], v[130:133], v[150:153], v[114:129]
	s_waitcnt lgkmcnt(2)
	v_mfma_f32_32x32x16_bf16 v[82:97], v[130:133], v[154:157], v[82:97]
	s_waitcnt lgkmcnt(1)
	v_mfma_f32_32x32x16_bf16 v[50:65], v[130:133], v[158:161], v[50:65]
	s_waitcnt lgkmcnt(0)
	v_mfma_f32_32x32x16_bf16 v[18:33], v[130:133], v[164:167], v[18:33]
	ds_read_b128 v[130:133], v183 offset:4672
	s_waitcnt lgkmcnt(0)
	v_mfma_f32_32x32x16_bf16 v[98:113], v[130:133], v[150:153], v[98:113]
	v_mfma_f32_32x32x16_bf16 v[66:81], v[130:133], v[154:157], v[66:81]
	v_mfma_f32_32x32x16_bf16 v[34:49], v[130:133], v[158:161], v[34:49]
	v_mfma_f32_32x32x16_bf16 v[2:17], v[130:133], v[164:167], v[2:17]
	ds_read_b128 v[130:133], v183 offset:96
	ds_read_b128 v[150:153], v185 offset:96
	ds_read_b128 v[154:157], v185 offset:4704
	ds_read_b128 v[158:161], v185 offset:9312
	ds_read_b128 v[164:167], v185 offset:13920
	s_waitcnt lgkmcnt(3)
	v_mfma_f32_32x32x16_bf16 v[114:129], v[130:133], v[150:153], v[114:129]
	s_waitcnt lgkmcnt(2)
	v_mfma_f32_32x32x16_bf16 v[82:97], v[130:133], v[154:157], v[82:97]
	s_waitcnt lgkmcnt(1)
	v_mfma_f32_32x32x16_bf16 v[50:65], v[130:133], v[158:161], v[50:65]
	s_waitcnt lgkmcnt(0)
	v_mfma_f32_32x32x16_bf16 v[18:33], v[130:133], v[164:167], v[18:33]
	ds_read_b128 v[130:133], v183 offset:4704
	s_waitcnt lgkmcnt(0)
	s_barrier
	v_mfma_f32_32x32x16_bf16 v[98:113], v[130:133], v[150:153], v[98:113]
	v_add_u32_e32 v152, s1, v163
	v_cmp_lt_i32_e32 vcc, s8, v152
	v_mfma_f32_32x32x16_bf16 v[66:81], v[130:133], v[154:157], v[66:81]
	v_add_u32_e32 v155, s1, v135
	s_movk_i32 s1, 0x4000
	v_cmp_gt_i32_e64 s[40:41], s1, v152
	v_mfma_f32_32x32x16_bf16 v[34:49], v[130:133], v[158:161], v[34:49]
	v_mfma_f32_32x32x16_bf16 v[2:17], v[130:133], v[164:167], v[2:17]
	s_and_saveexec_b64 s[2:3], vcc
	s_xor_b64 s[2:3], exec, s[2:3]
	v_add_u32_e32 v0, 0xffffc000, v155
	v_lshrrev_b32_e32 v150, 8, v0
	v_and_b32_e32 v0, 0x9f, v152
	v_or_b32_e32 v0, 0x2000, v0
	s_or_saveexec_b64 s[2:3], s[2:3]
	v_lshrrev_b32_e32 v153, 2, v155
	v_mov_b32_e32 v156, 0
	v_ashrrev_i32_e32 v151, 13, v155
	v_and_b32_e32 v161, 0x7e0, v153
	v_mov_b32_e32 v157, 0
	s_xor_b64 exec, exec, s[2:3]
	v_ashrrev_i32_e32 v150, 13, v155
	v_and_b32_e32 v0, 0x1f9f, v152
	v_and_b32_e32 v156, 0x7e0, v153
	v_mov_b32_e32 v157, v179
	s_or_b64 exec, exec, s[2:3]
	v_ashrrev_i32_e32 v153, 31, v152
	v_lshl_add_u64 v[130:131], v[152:153], 3, s[44:45]
	global_load_dword v130, v[130:131], off
	v_or_b32_e32 v132, s0, v214
	v_mul_lo_u32 v164, v150, 6
	v_ashrrev_i32_e32 v150, 5, v132
	s_mov_b32 s0, 0x55555556
	v_mul_hi_i32 v153, v150, s0
	v_or_b32_e32 v188, v156, v142
	v_or_b32_e32 v189, v156, v176
	v_or_b32_e32 v186, v156, v177
	v_or_b32_e32 v187, v156, v178
	v_or_b32_e32 v167, v157, v142
	v_or_b32_e32 v185, v157, v176
	v_or_b32_e32 v165, v157, v177
	v_or_b32_e32 v166, v157, v178
	v_lshrrev_b32_e32 v160, 31, v153
	s_waitcnt vmcnt(0)
	v_fmamk_f32 v130, v130, 0x3b800000, v201
	v_cmp_gt_f32_e32 vcc, s66, v130
	v_mul_f32_e32 v131, 0x4b800000, v130
	s_nop 0
	v_cndmask_b32_e32 v130, v130, v131, vcc
	v_rsq_f32_e32 v130, v130
	s_nop 0
	v_mul_f32_e32 v131, 0x45800000, v130
	v_cndmask_b32_e32 v130, v130, v131, vcc
	v_mul_f32_e32 v154, 0x3e16c740, v130
	v_cmp_gt_i32_e32 vcc, 18, v150
	s_and_saveexec_b64 s[2:3], vcc
	s_cbranch_execz .LBB0_637
	v_add_u32_e32 v190, v153, v160
	v_mad_u64_u32 v[156:157], s[0:1], v190, -3, v[150:151]
	v_cmp_eq_u32_e64 s[38:39], 2, v156
	s_and_b64 s[0:1], s[40:41], s[38:39]
	s_and_saveexec_b64 s[22:23], s[0:1]
	s_cbranch_execz .LBB0_636
	v_lshlrev_b32_e32 v130, 3, v188
	v_lshlrev_b32_e32 v132, 3, v189
	global_load_dwordx2 v[130:131], v130, s[80:81]
	s_nop 0
	global_load_dwordx2 v[132:133], v132, s[80:81]
	s_waitcnt vmcnt(1)
	v_mov_b32_e32 v168, v130
	s_waitcnt vmcnt(0)
	v_mov_b32_e32 v169, v132
	v_mov_b32_e32 v132, v131
	v_mul_f32_e32 v130, v122, v132
	v_mul_f32_e32 v131, v123, v133
	s_nop 0
	v_fma_f32 v158, v114, v168, -v130
	v_fma_f32 v159, v115, v169, -v131
	v_mul_f32_e32 v114, v114, v132
	v_mul_f32_e32 v115, v115, v133
	v_lshlrev_b32_e32 v130, 3, v187
	v_fma_f32 v122, v122, v168, v114
	v_fma_f32 v123, v123, v169, v115
	v_lshlrev_b32_e32 v114, 3, v186
	global_load_dwordx2 v[114:115], v114, s[80:81]
	s_nop 0
	global_load_dwordx2 v[130:131], v130, s[80:81]
	s_waitcnt vmcnt(1)
	v_mov_b32_e32 v132, v114
	s_waitcnt vmcnt(0)
	v_mov_b32_e32 v133, v130
	v_mov_b32_e32 v130, v115
	v_mul_f32_e32 v114, v124, v130
	v_mul_f32_e32 v115, v125, v131
	s_nop 0
	v_fma_f32 v168, v116, v132, -v114
	v_fma_f32 v169, v117, v133, -v115
	v_mul_f32_e32 v114, v116, v130
	v_mul_f32_e32 v115, v117, v131
	v_lshlrev_b32_e32 v116, 3, v185
	v_fma_f32 v124, v124, v132, v114
	v_fma_f32 v125, v125, v133, v115
	v_lshlrev_b32_e32 v114, 3, v167
	global_load_dwordx2 v[114:115], v114, s[80:81]
	s_nop 0
	global_load_dwordx2 v[116:117], v116, s[80:81]
	s_waitcnt vmcnt(1)
	v_mov_b32_e32 v130, v114
	s_waitcnt vmcnt(0)
	v_mov_b32_e32 v131, v116
	v_mov_b32_e32 v116, v115
	v_mul_f32_e32 v114, v126, v116
	v_mul_f32_e32 v115, v127, v117
	s_nop 0
	v_fma_f32 v132, v118, v130, -v114
	v_fma_f32 v133, v119, v131, -v115
	v_mul_f32_e32 v114, v118, v116
	v_mul_f32_e32 v115, v119, v117
	v_lshlrev_b32_e32 v116, 3, v165
	v_fma_f32 v126, v126, v130, v114
	v_fma_f32 v127, v127, v131, v115
	v_lshlrev_b32_e32 v114, 3, v166
	global_load_dwordx2 v[114:115], v114, s[80:81]
	s_nop 0
	global_load_dwordx2 v[116:117], v116, s[80:81]
	s_waitcnt vmcnt(1)
	v_mov_b32_e32 v131, v115
	s_waitcnt vmcnt(0)
	v_mov_b32_e32 v130, v117
	v_mov_b32_e32 v118, v116
	v_mov_b32_e32 v119, v114
	v_mul_f32_e32 v130, v128, v130
	v_mul_f32_e32 v131, v129, v131
	v_mul_f32_e32 v116, v128, v116
	v_fma_f32 v130, v120, v118, -v130
	v_fma_f32 v131, v121, v119, -v131
	v_mul_f32_e32 v118, v120, v117
	v_mov_b32_e32 v120, v129
	v_mul_f32_e32 v114, v120, v114
	v_mul_f32_e32 v115, v121, v115
	v_mov_b32_e32 v120, v130
	v_mov_b32_e32 v117, v114
	v_mov_b32_e32 v119, v115
	v_add_f32_e32 v128, v116, v118
	v_add_f32_e32 v129, v117, v119
	v_mov_b32_e32 v114, v158
	v_mov_b32_e32 v115, v159
	v_mov_b32_e32 v116, v168
	v_mov_b32_e32 v117, v169
	v_mov_b32_e32 v118, v132
	v_mov_b32_e32 v119, v133
	v_mov_b32_e32 v121, v131
.LBB0_636:
	s_or_b64 exec, exec, s[22:23]
	v_add_u32_e32 v130, v164, v190
	v_mad_i64_i32 v[130:131], s[0:1], v130, s9, v[0:1]
	v_mov_b64_e32 v[132:133], s[24:25]
	v_mad_u64_u32 v[132:133], s[0:1], v130, s5, v[132:133]
	v_lshlrev_b32_e32 v130, 5, v156
	v_mad_i32_i24 v133, v131, s5, v133
	v_ashrrev_i32_e32 v131, 31, v130
	v_lshl_add_u64 v[130:131], v[130:131], 1, v[132:133]
	v_lshlrev_b32_e32 v132, 1, v140
	v_mov_b32_e32 v133, v1
	v_mul_f32_e32 v114, v154, v114
	v_mul_f32_e32 v115, v154, v115
	v_mul_f32_e32 v116, v154, v116
	v_mul_f32_e32 v117, v154, v117
	v_lshl_add_u64 v[130:131], v[130:131], 0, v[132:133]
	v_cvt_pk_bf16_f32 v114, v114, v115
	v_cvt_pk_bf16_f32 v115, v116, v117
	global_store_dwordx2 v[130:131], v[114:115], off
	v_mul_f32_e32 v114, v154, v118
	v_mul_f32_e32 v115, v154, v119
	v_mul_f32_e32 v116, v154, v120
	v_mul_f32_e32 v117, v154, v121
	v_cvt_pk_bf16_f32 v114, v114, v115
	v_cvt_pk_bf16_f32 v115, v116, v117
	global_store_dwordx2 v[130:131], v[114:115], off offset:16
	v_mul_f32_e32 v114, v154, v122
	v_mul_f32_e32 v115, v154, v123
	v_mul_f32_e32 v116, v154, v124
	v_mul_f32_e32 v117, v154, v125
	v_cvt_pk_bf16_f32 v114, v114, v115
	v_cvt_pk_bf16_f32 v115, v116, v117
	global_store_dwordx2 v[130:131], v[114:115], off offset:32
	v_mul_f32_e32 v114, v154, v126
	v_mul_f32_e32 v115, v154, v127
	v_mul_f32_e32 v116, v154, v128
	v_mul_f32_e32 v117, v154, v129
	v_cvt_pk_bf16_f32 v114, v114, v115
	v_cvt_pk_bf16_f32 v115, v116, v117
	global_store_dwordx2 v[130:131], v[114:115], off offset:48
.LBB0_637:
	s_or_b64 exec, exec, s[2:3]
	v_or_b32_e32 v114, 1, v150
	s_mov_b32 s0, 0x55555556
	v_mul_hi_i32 v115, v114, s0
	v_cmp_gt_i32_e64 s[38:39], 17, v150
	v_lshrrev_b32_e32 v120, 31, v115
	s_and_saveexec_b64 s[2:3], s[38:39]
	s_cbranch_execz .LBB0_641
	v_add_u32_e32 v121, v115, v120
	v_mad_u64_u32 v[116:117], s[0:1], v121, -3, v[114:115]
	v_cmp_eq_u32_e64 s[42:43], 2, v116
	s_and_b64 s[0:1], s[40:41], s[42:43]
	s_and_saveexec_b64 s[22:23], s[0:1]
	s_cbranch_execz .LBB0_640
	v_lshlrev_b32_e32 v117, 3, v188
	v_lshlrev_b32_e32 v122, 3, v189
	global_load_dwordx2 v[118:119], v117, s[80:81]
	s_nop 0
	global_load_dwordx2 v[122:123], v122, s[80:81]
	v_lshlrev_b32_e32 v117, 3, v187
	s_waitcnt vmcnt(1)
	v_mov_b32_e32 v124, v118
	s_waitcnt vmcnt(0)
	v_mov_b32_e32 v125, v122
	v_mov_b32_e32 v122, v119
	v_mul_f32_e32 v118, v106, v122
	v_mul_f32_e32 v119, v107, v123
	s_nop 0
	v_fma_f32 v118, v98, v124, -v118
	v_fma_f32 v119, v99, v125, -v119
	v_mul_f32_e32 v98, v98, v122
	v_mul_f32_e32 v99, v99, v123
	s_nop 0
	v_fma_f32 v106, v106, v124, v98
	v_fma_f32 v107, v107, v125, v99
	v_lshlrev_b32_e32 v98, 3, v186
	global_load_dwordx2 v[98:99], v98, s[80:81]
	s_nop 0
	global_load_dwordx2 v[122:123], v117, s[80:81]
	s_waitcnt vmcnt(1)
	v_mov_b32_e32 v124, v98
	s_waitcnt vmcnt(0)
	v_mov_b32_e32 v125, v122
	v_mov_b32_e32 v122, v99
	v_mul_f32_e32 v98, v108, v122
	v_mul_f32_e32 v99, v109, v123
	s_nop 0
	v_fma_f32 v126, v100, v124, -v98
	v_fma_f32 v127, v101, v125, -v99
	v_mul_f32_e32 v98, v100, v122
	v_mul_f32_e32 v99, v101, v123
	v_lshlrev_b32_e32 v100, 3, v185
	v_fma_f32 v108, v108, v124, v98
	v_fma_f32 v109, v109, v125, v99
	v_lshlrev_b32_e32 v98, 3, v167
	global_load_dwordx2 v[98:99], v98, s[80:81]
	s_nop 0
	global_load_dwordx2 v[100:101], v100, s[80:81]
	s_waitcnt vmcnt(1)
	v_mov_b32_e32 v122, v98
	s_waitcnt vmcnt(0)
	v_mov_b32_e32 v123, v100
	v_mov_b32_e32 v100, v99
	v_mul_f32_e32 v98, v110, v100
	v_mul_f32_e32 v99, v111, v101
	s_nop 0
	v_fma_f32 v124, v102, v122, -v98
	v_fma_f32 v125, v103, v123, -v99
	v_mul_f32_e32 v98, v102, v100
	v_mul_f32_e32 v99, v103, v101
	v_lshlrev_b32_e32 v100, 3, v165
	v_fma_f32 v110, v110, v122, v98
	v_fma_f32 v111, v111, v123, v99
	v_lshlrev_b32_e32 v98, 3, v166
	global_load_dwordx2 v[98:99], v98, s[80:81]
	s_nop 0
	global_load_dwordx2 v[100:101], v100, s[80:81]
	s_waitcnt vmcnt(1)
	v_mov_b32_e32 v123, v99
	s_waitcnt vmcnt(0)
	v_mov_b32_e32 v122, v101
	v_mov_b32_e32 v102, v100
	v_mov_b32_e32 v103, v98
	v_mul_f32_e32 v122, v112, v122
	v_mul_f32_e32 v123, v113, v123
	v_mul_f32_e32 v100, v112, v100
	v_fma_f32 v122, v104, v102, -v122
	v_fma_f32 v123, v105, v103, -v123
	v_mul_f32_e32 v102, v104, v101
	v_mov_b32_e32 v104, v113
	v_mul_f32_e32 v98, v104, v98
	v_mul_f32_e32 v99, v105, v99
	v_mov_b32_e32 v104, v122
	v_mov_b32_e32 v101, v98
	v_mov_b32_e32 v103, v99
	v_add_f32_e32 v112, v100, v102
	v_add_f32_e32 v113, v101, v103
	v_mov_b32_e32 v98, v118
	v_mov_b32_e32 v99, v119
	v_mov_b32_e32 v100, v126
	v_mov_b32_e32 v101, v127
	v_mov_b32_e32 v102, v124
	v_mov_b32_e32 v103, v125
	v_mov_b32_e32 v105, v123
.LBB0_640:
	s_or_b64 exec, exec, s[22:23]
	v_add_u32_e32 v117, v164, v121
	v_mad_i64_i32 v[118:119], s[0:1], v117, s9, v[0:1]
	v_mov_b64_e32 v[122:123], s[24:25]
	v_mad_u64_u32 v[122:123], s[0:1], v118, s5, v[122:123]
	v_lshlrev_b32_e32 v116, 5, v116
	v_mad_i32_i24 v123, v119, s5, v123
	v_ashrrev_i32_e32 v117, 31, v116
	v_lshl_add_u64 v[116:117], v[116:117], 1, v[122:123]
	v_lshlrev_b32_e32 v0, 1, v140
	v_mul_f32_e32 v98, v154, v98
	v_mul_f32_e32 v99, v154, v99
	v_mul_f32_e32 v100, v154, v100
	v_mul_f32_e32 v101, v154, v101
	v_lshl_add_u64 v[116:117], v[116:117], 0, v[0:1]
	v_cvt_pk_bf16_f32 v98, v98, v99
	v_cvt_pk_bf16_f32 v99, v100, v101
	global_store_dwordx2 v[116:117], v[98:99], off
	v_mul_f32_e32 v98, v154, v102
	v_mul_f32_e32 v99, v154, v103
	v_mul_f32_e32 v100, v154, v104
	v_mul_f32_e32 v101, v154, v105
	v_cvt_pk_bf16_f32 v98, v98, v99
	v_cvt_pk_bf16_f32 v99, v100, v101
	global_store_dwordx2 v[116:117], v[98:99], off offset:16
	v_mul_f32_e32 v98, v154, v106
	v_mul_f32_e32 v99, v154, v107
	v_mul_f32_e32 v100, v154, v108
	v_mul_f32_e32 v101, v154, v109
	v_cvt_pk_bf16_f32 v98, v98, v99
	v_cvt_pk_bf16_f32 v99, v100, v101
	global_store_dwordx2 v[116:117], v[98:99], off offset:32
	v_mul_f32_e32 v98, v154, v110
	v_mul_f32_e32 v99, v154, v111
	v_mul_f32_e32 v100, v154, v112
	v_mul_f32_e32 v101, v154, v113
	v_cvt_pk_bf16_f32 v98, v98, v99
	v_cvt_pk_bf16_f32 v99, v100, v101
	global_store_dwordx2 v[116:117], v[98:99], off offset:48
.LBB0_641:
	s_or_b64 exec, exec, s[2:3]
	v_add_u32_e32 v98, 32, v152
	s_movk_i32 s0, 0x4000
	v_cmp_gt_i32_e64 s[40:41], s0, v98
	v_cmp_lt_i32_e64 s[42:43], s8, v98
	s_and_saveexec_b64 s[0:1], s[42:43]
	s_xor_b64 s[2:3], exec, s[0:1]
	v_add_u32_e32 v0, 0xffffc020, v155
	v_lshrrev_b32_e32 v100, 8, v0
	v_and_b32_e32 v0, 0xbf, v98
	v_or_b32_e32 v0, 0x2000, v0
	s_or_saveexec_b64 s[2:3], s[2:3]
	v_mov_b32_e32 v102, 0
	v_mov_b32_e32 v101, 0
	s_xor_b64 exec, exec, s[2:3]
	v_add_u32_e32 v99, 0x200, v182
	v_ashrrev_i32_e32 v100, 13, v155
	v_and_b32_e32 v0, 0x1fbf, v98
	v_and_b32_e32 v101, 0x3f0, v99
	v_mov_b32_e32 v102, v161
	s_or_b64 exec, exec, s[2:3]
	v_ashrrev_i32_e32 v99, 31, v98
	v_lshl_add_u64 v[98:99], v[98:99], 3, s[44:45]
	global_load_dword v98, v[98:99], off
	v_or_b32_e32 v110, v102, v142
	v_or_b32_e32 v111, v102, v176
	v_or_b32_e32 v108, v102, v177
	v_or_b32_e32 v109, v102, v178
	v_or_b32_e32 v106, v101, v142
	v_or_b32_e32 v107, v101, v176
	v_or_b32_e32 v104, v101, v177
	v_or_b32_e32 v105, v101, v178
	s_waitcnt vmcnt(0)
	v_fmamk_f32 v98, v98, 0x3b800000, v201
	v_cmp_gt_f32_e64 s[42:43], s66, v98
	v_mul_f32_e32 v99, 0x4b800000, v98
	s_nop 0
	v_cndmask_b32_e64 v98, v98, v99, s[42:43]
	v_rsq_f32_e32 v98, v98
	s_nop 0
	v_mul_f32_e32 v99, 0x45800000, v98
	v_cndmask_b32_e64 v98, v98, v99, s[42:43]
	v_mul_f32_e32 v98, 0x3e16c740, v98
	v_mul_lo_u32 v99, v100, 6
	s_and_saveexec_b64 s[2:3], vcc
	s_cbranch_execz .LBB0_649
	v_add_u32_e32 v112, v153, v160
	v_mad_u64_u32 v[100:101], s[0:1], v112, -3, v[150:151]
	v_cmp_eq_u32_e64 s[42:43], 2, v100
	s_and_b64 s[0:1], s[40:41], s[42:43]
	s_and_saveexec_b64 s[22:23], s[0:1]
	s_cbranch_execz .LBB0_648
	v_lshlrev_b32_e32 v101, 3, v110
	v_lshlrev_b32_e32 v113, 3, v111
	global_load_dwordx2 v[102:103], v101, s[80:81]
	global_load_dwordx2 v[116:117], v113, s[80:81]
	v_lshlrev_b32_e32 v101, 3, v109
	s_waitcnt vmcnt(1)
	v_mov_b32_e32 v118, v102
	s_waitcnt vmcnt(0)
	v_mov_b32_e32 v119, v116
	v_mov_b32_e32 v116, v103
	v_mul_f32_e32 v102, v90, v116
	v_mul_f32_e32 v103, v91, v117
	s_nop 0
	v_fma_f32 v102, v82, v118, -v102
	v_fma_f32 v103, v83, v119, -v103
	v_mul_f32_e32 v82, v82, v116
	v_mul_f32_e32 v83, v83, v117
	s_nop 0
	v_fma_f32 v90, v90, v118, v82
	v_fma_f32 v91, v91, v119, v83
	v_lshlrev_b32_e32 v82, 3, v108
	global_load_dwordx2 v[82:83], v82, s[80:81]
	s_nop 0
	global_load_dwordx2 v[116:117], v101, s[80:81]
	s_waitcnt vmcnt(1)
	v_mov_b32_e32 v118, v82
	s_waitcnt vmcnt(0)
	v_mov_b32_e32 v119, v116
	v_mov_b32_e32 v116, v83
	v_mul_f32_e32 v82, v92, v116
	v_mul_f32_e32 v83, v93, v117
	s_nop 0
	v_fma_f32 v122, v84, v118, -v82
	v_fma_f32 v123, v85, v119, -v83
	v_mul_f32_e32 v82, v84, v116
	v_mul_f32_e32 v83, v85, v117
	v_lshlrev_b32_e32 v84, 3, v107
	v_fma_f32 v92, v92, v118, v82
	v_fma_f32 v93, v93, v119, v83
	v_lshlrev_b32_e32 v82, 3, v106
	global_load_dwordx2 v[82:83], v82, s[80:81]
	s_nop 0
	global_load_dwordx2 v[84:85], v84, s[80:81]
	s_waitcnt vmcnt(1)
	v_mov_b32_e32 v116, v82
	s_waitcnt vmcnt(0)
	v_mov_b32_e32 v117, v84
	v_mov_b32_e32 v84, v83
	v_mul_f32_e32 v82, v94, v84
	v_mul_f32_e32 v83, v95, v85
	s_nop 0
	v_fma_f32 v118, v86, v116, -v82
	v_fma_f32 v119, v87, v117, -v83
	v_mul_f32_e32 v82, v86, v84
	v_mul_f32_e32 v83, v87, v85
	v_lshlrev_b32_e32 v84, 3, v104
	v_fma_f32 v94, v94, v116, v82
	v_fma_f32 v95, v95, v117, v83
	v_lshlrev_b32_e32 v82, 3, v105
	global_load_dwordx2 v[82:83], v82, s[80:81]
	s_nop 0
	global_load_dwordx2 v[84:85], v84, s[80:81]
	s_waitcnt vmcnt(1)
	v_mov_b32_e32 v117, v83
	s_waitcnt vmcnt(0)
	v_mov_b32_e32 v116, v85
	v_mov_b32_e32 v86, v84
	v_mov_b32_e32 v87, v82
	v_mul_f32_e32 v116, v96, v116
	v_mul_f32_e32 v117, v97, v117
	v_mul_f32_e32 v84, v96, v84
	v_fma_f32 v116, v88, v86, -v116
	v_fma_f32 v117, v89, v87, -v117
	v_mul_f32_e32 v86, v88, v85
	v_mov_b32_e32 v88, v97
	v_mul_f32_e32 v82, v88, v82
	v_mul_f32_e32 v83, v89, v83
	v_mov_b32_e32 v88, v116
	v_mov_b32_e32 v85, v82
	v_mov_b32_e32 v87, v83
	v_add_f32_e32 v96, v84, v86
	v_add_f32_e32 v97, v85, v87
	v_mov_b32_e32 v82, v102
	v_mov_b32_e32 v83, v103
	v_mov_b32_e32 v84, v122
	v_mov_b32_e32 v85, v123
	v_mov_b32_e32 v86, v118
	v_mov_b32_e32 v87, v119
	v_mov_b32_e32 v89, v117
.LBB0_648:
	s_or_b64 exec, exec, s[22:23]
	v_add_u32_e32 v101, v99, v112
	v_mad_i64_i32 v[102:103], s[0:1], v101, s9, v[0:1]
	v_mov_b64_e32 v[112:113], s[24:25]
	v_mad_u64_u32 v[112:113], s[0:1], v102, s5, v[112:113]
	v_lshlrev_b32_e32 v100, 5, v100
	v_mad_i32_i24 v113, v103, s5, v113
	v_ashrrev_i32_e32 v101, 31, v100
	v_lshl_add_u64 v[100:101], v[100:101], 1, v[112:113]
	v_lshlrev_b32_e32 v102, 1, v140
	v_mov_b32_e32 v103, v1
	v_mul_f32_e32 v82, v98, v82
	v_mul_f32_e32 v83, v98, v83
	v_mul_f32_e32 v84, v98, v84
	v_mul_f32_e32 v85, v98, v85
	v_lshl_add_u64 v[100:101], v[100:101], 0, v[102:103]
	v_cvt_pk_bf16_f32 v82, v82, v83
	v_cvt_pk_bf16_f32 v83, v84, v85
	global_store_dwordx2 v[100:101], v[82:83], off
	v_mul_f32_e32 v82, v98, v86
	v_mul_f32_e32 v83, v98, v87
	v_mul_f32_e32 v84, v98, v88
	v_mul_f32_e32 v85, v98, v89
	v_cvt_pk_bf16_f32 v82, v82, v83
	v_cvt_pk_bf16_f32 v83, v84, v85
	global_store_dwordx2 v[100:101], v[82:83], off offset:16
	v_mul_f32_e32 v82, v98, v90
	v_mul_f32_e32 v83, v98, v91
	v_mul_f32_e32 v84, v98, v92
	v_mul_f32_e32 v85, v98, v93
	v_cvt_pk_bf16_f32 v82, v82, v83
	v_cvt_pk_bf16_f32 v83, v84, v85
	global_store_dwordx2 v[100:101], v[82:83], off offset:32
	v_mul_f32_e32 v82, v98, v94
	v_mul_f32_e32 v83, v98, v95
	v_mul_f32_e32 v84, v98, v96
	v_mul_f32_e32 v85, v98, v97
	v_cvt_pk_bf16_f32 v82, v82, v83
	v_cvt_pk_bf16_f32 v83, v84, v85
	global_store_dwordx2 v[100:101], v[82:83], off offset:48
.LBB0_649:
	s_or_b64 exec, exec, s[2:3]
	s_and_saveexec_b64 s[2:3], s[38:39]
	s_cbranch_execz .LBB0_653
	v_add_u32_e32 v86, v115, v120
	v_mad_u64_u32 v[82:83], s[0:1], v86, -3, v[114:115]
	v_cmp_eq_u32_e64 s[42:43], 2, v82
	s_and_b64 s[0:1], s[40:41], s[42:43]
	s_and_saveexec_b64 s[22:23], s[0:1]
	s_cbranch_execz .LBB0_652
	v_lshlrev_b32_e32 v83, 3, v110
	v_lshlrev_b32_e32 v87, 3, v111
	global_load_dwordx2 v[84:85], v83, s[80:81]
	global_load_dwordx2 v[88:89], v87, s[80:81]
	v_lshlrev_b32_e32 v83, 3, v109
	s_waitcnt vmcnt(1)
	v_mov_b32_e32 v90, v84
	s_waitcnt vmcnt(0)
	v_mov_b32_e32 v91, v88
	v_mov_b32_e32 v88, v85
	v_mul_f32_e32 v84, v74, v88
	v_mul_f32_e32 v85, v75, v89
	s_nop 0
	v_fma_f32 v84, v66, v90, -v84
	v_fma_f32 v85, v67, v91, -v85
	v_mul_f32_e32 v66, v66, v88
	v_mul_f32_e32 v67, v67, v89
	s_nop 0
	v_fma_f32 v74, v74, v90, v66
	v_fma_f32 v75, v75, v91, v67
	v_lshlrev_b32_e32 v66, 3, v108
	global_load_dwordx2 v[66:67], v66, s[80:81]
	s_nop 0
	global_load_dwordx2 v[88:89], v83, s[80:81]
	s_waitcnt vmcnt(1)
	v_mov_b32_e32 v90, v66
	s_waitcnt vmcnt(0)
	v_mov_b32_e32 v91, v88
	v_mov_b32_e32 v88, v67
	v_mul_f32_e32 v66, v76, v88
	v_mul_f32_e32 v67, v77, v89
	s_nop 0
	v_fma_f32 v92, v68, v90, -v66
	v_fma_f32 v93, v69, v91, -v67
	v_mul_f32_e32 v66, v68, v88
	v_mul_f32_e32 v67, v69, v89
	v_lshlrev_b32_e32 v68, 3, v107
	v_fma_f32 v76, v76, v90, v66
	v_fma_f32 v77, v77, v91, v67
	v_lshlrev_b32_e32 v66, 3, v106
	global_load_dwordx2 v[66:67], v66, s[80:81]
	s_nop 0
	global_load_dwordx2 v[68:69], v68, s[80:81]
	s_waitcnt vmcnt(1)
	v_mov_b32_e32 v88, v66
	s_waitcnt vmcnt(0)
	v_mov_b32_e32 v89, v68
	v_mov_b32_e32 v68, v67
	v_mul_f32_e32 v66, v78, v68
	v_mul_f32_e32 v67, v79, v69
	s_nop 0
	v_fma_f32 v90, v70, v88, -v66
	v_fma_f32 v91, v71, v89, -v67
	v_mul_f32_e32 v66, v70, v68
	v_mul_f32_e32 v67, v71, v69
	v_lshlrev_b32_e32 v68, 3, v104
	v_fma_f32 v78, v78, v88, v66
	v_fma_f32 v79, v79, v89, v67
	v_lshlrev_b32_e32 v66, 3, v105
	global_load_dwordx2 v[66:67], v66, s[80:81]
	s_nop 0
	global_load_dwordx2 v[68:69], v68, s[80:81]
	s_waitcnt vmcnt(1)
	v_mov_b32_e32 v89, v67
	s_waitcnt vmcnt(0)
	v_mov_b32_e32 v88, v69
	v_mov_b32_e32 v70, v68
	v_mov_b32_e32 v71, v66
	v_mul_f32_e32 v88, v80, v88
	v_mul_f32_e32 v89, v81, v89
	v_mul_f32_e32 v68, v80, v68
	v_fma_f32 v88, v72, v70, -v88
	v_fma_f32 v89, v73, v71, -v89
	v_mul_f32_e32 v70, v72, v69
	v_mov_b32_e32 v72, v81
	v_mul_f32_e32 v66, v72, v66
	v_mul_f32_e32 v67, v73, v67
	v_mov_b32_e32 v72, v88
	v_mov_b32_e32 v69, v66
	v_mov_b32_e32 v71, v67
	v_add_f32_e32 v80, v68, v70
	v_add_f32_e32 v81, v69, v71
	v_mov_b32_e32 v66, v84
	v_mov_b32_e32 v67, v85
	v_mov_b32_e32 v68, v92
	v_mov_b32_e32 v69, v93
	v_mov_b32_e32 v70, v90
	v_mov_b32_e32 v71, v91
	v_mov_b32_e32 v73, v89
.LBB0_652:
	s_or_b64 exec, exec, s[22:23]
	v_add_u32_e32 v83, v99, v86
	v_mad_i64_i32 v[84:85], s[0:1], v83, s9, v[0:1]
	v_mov_b64_e32 v[86:87], s[24:25]
	v_mad_u64_u32 v[86:87], s[0:1], v84, s5, v[86:87]
	v_lshlrev_b32_e32 v82, 5, v82
	v_mad_i32_i24 v87, v85, s5, v87
	v_ashrrev_i32_e32 v83, 31, v82
	v_lshl_add_u64 v[82:83], v[82:83], 1, v[86:87]
	v_lshlrev_b32_e32 v0, 1, v140
	v_mul_f32_e32 v66, v98, v66
	v_mul_f32_e32 v67, v98, v67
	v_mul_f32_e32 v68, v98, v68
	v_mul_f32_e32 v69, v98, v69
	v_lshl_add_u64 v[82:83], v[82:83], 0, v[0:1]
	v_cvt_pk_bf16_f32 v66, v66, v67
	v_cvt_pk_bf16_f32 v67, v68, v69
	global_store_dwordx2 v[82:83], v[66:67], off
	v_mul_f32_e32 v66, v98, v70
	v_mul_f32_e32 v67, v98, v71
	v_mul_f32_e32 v68, v98, v72
	v_mul_f32_e32 v69, v98, v73
	v_cvt_pk_bf16_f32 v66, v66, v67
	v_cvt_pk_bf16_f32 v67, v68, v69
	global_store_dwordx2 v[82:83], v[66:67], off offset:16
	v_mul_f32_e32 v66, v98, v74
	v_mul_f32_e32 v67, v98, v75
	v_mul_f32_e32 v68, v98, v76
	v_mul_f32_e32 v69, v98, v77
	v_cvt_pk_bf16_f32 v66, v66, v67
	v_cvt_pk_bf16_f32 v67, v68, v69
	global_store_dwordx2 v[82:83], v[66:67], off offset:32
	v_mul_f32_e32 v66, v98, v78
	v_mul_f32_e32 v67, v98, v79
	v_mul_f32_e32 v68, v98, v80
	v_mul_f32_e32 v69, v98, v81
	v_cvt_pk_bf16_f32 v66, v66, v67
	v_cvt_pk_bf16_f32 v67, v68, v69
	global_store_dwordx2 v[82:83], v[66:67], off offset:48
.LBB0_653:
	s_or_b64 exec, exec, s[2:3]
	v_add_u32_e32 v66, 64, v152
	s_movk_i32 s0, 0x4000
	v_cmp_gt_i32_e64 s[40:41], s0, v66
	v_cmp_lt_i32_e64 s[42:43], s8, v66
	s_and_saveexec_b64 s[0:1], s[42:43]
	s_xor_b64 s[2:3], exec, s[0:1]
	v_add_u32_e32 v0, 0xffffc040, v155
	v_lshrrev_b32_e32 v68, 8, v0
	v_and_b32_e32 v0, 0xdf, v66
	v_or_b32_e32 v0, 0x2000, v0
	s_or_saveexec_b64 s[2:3], s[2:3]
	v_mov_b32_e32 v70, 0
	v_mov_b32_e32 v69, 0
	s_xor_b64 exec, exec, s[2:3]
	v_lshrrev_b32_e32 v67, 2, v66
	v_ashrrev_i32_e32 v68, 13, v155
	v_and_b32_e32 v0, 0x1fdf, v66
	v_and_b32_e32 v70, 0x7f0, v67
	v_mov_b32_e32 v69, v179
	s_or_b64 exec, exec, s[2:3]
	v_ashrrev_i32_e32 v67, 31, v66
	v_lshl_add_u64 v[66:67], v[66:67], 3, s[44:45]
	global_load_dword v66, v[66:67], off
	v_or_b32_e32 v78, v70, v142
	v_or_b32_e32 v79, v70, v176
	v_or_b32_e32 v76, v70, v177
	v_or_b32_e32 v77, v70, v178
	v_or_b32_e32 v74, v69, v142
	v_or_b32_e32 v75, v69, v176
	v_or_b32_e32 v72, v69, v177
	v_or_b32_e32 v73, v69, v178
	s_waitcnt vmcnt(0)
	v_fmamk_f32 v66, v66, 0x3b800000, v201
	v_cmp_gt_f32_e64 s[42:43], s66, v66
	v_mul_f32_e32 v67, 0x4b800000, v66
	s_nop 0
	v_cndmask_b32_e64 v66, v66, v67, s[42:43]
	v_rsq_f32_e32 v66, v66
	s_nop 0
	v_mul_f32_e32 v67, 0x45800000, v66
	v_cndmask_b32_e64 v66, v66, v67, s[42:43]
	v_mul_f32_e32 v66, 0x3e16c740, v66
	v_mul_lo_u32 v67, v68, 6
	s_and_saveexec_b64 s[2:3], vcc
	s_cbranch_execz .LBB0_661
	v_add_u32_e32 v80, v153, v160
	v_mad_u64_u32 v[68:69], s[0:1], v80, -3, v[150:151]
	v_cmp_eq_u32_e64 s[42:43], 2, v68
	s_and_b64 s[0:1], s[40:41], s[42:43]
	s_and_saveexec_b64 s[22:23], s[0:1]
	s_cbranch_execz .LBB0_660
	v_lshlrev_b32_e32 v69, 3, v78
	v_lshlrev_b32_e32 v81, 3, v79
	global_load_dwordx2 v[70:71], v69, s[80:81]
	global_load_dwordx2 v[82:83], v81, s[80:81]
	v_lshlrev_b32_e32 v69, 3, v77
	s_waitcnt vmcnt(1)
	v_mov_b32_e32 v84, v70
	s_waitcnt vmcnt(0)
	v_mov_b32_e32 v85, v82
	v_mov_b32_e32 v82, v71
	v_mul_f32_e32 v70, v58, v82
	v_mul_f32_e32 v71, v59, v83
	s_nop 0
	v_fma_f32 v70, v50, v84, -v70
	v_fma_f32 v71, v51, v85, -v71
	v_mul_f32_e32 v50, v50, v82
	v_mul_f32_e32 v51, v51, v83
	s_nop 0
	v_fma_f32 v58, v58, v84, v50
	v_fma_f32 v59, v59, v85, v51
	v_lshlrev_b32_e32 v50, 3, v76
	global_load_dwordx2 v[50:51], v50, s[80:81]
	s_nop 0
	global_load_dwordx2 v[82:83], v69, s[80:81]
	s_waitcnt vmcnt(1)
	v_mov_b32_e32 v84, v50
	s_waitcnt vmcnt(0)
	v_mov_b32_e32 v85, v82
	v_mov_b32_e32 v82, v51
	v_mul_f32_e32 v50, v60, v82
	v_mul_f32_e32 v51, v61, v83
	s_nop 0
	v_fma_f32 v86, v52, v84, -v50
	v_fma_f32 v87, v53, v85, -v51
	v_mul_f32_e32 v50, v52, v82
	v_mul_f32_e32 v51, v53, v83
	v_lshlrev_b32_e32 v52, 3, v75
	v_fma_f32 v60, v60, v84, v50
	v_fma_f32 v61, v61, v85, v51
	v_lshlrev_b32_e32 v50, 3, v74
	global_load_dwordx2 v[50:51], v50, s[80:81]
	s_nop 0
	global_load_dwordx2 v[52:53], v52, s[80:81]
	s_waitcnt vmcnt(1)
	v_mov_b32_e32 v82, v50
	s_waitcnt vmcnt(0)
	v_mov_b32_e32 v83, v52
	v_mov_b32_e32 v52, v51
	v_mul_f32_e32 v50, v62, v52
	v_mul_f32_e32 v51, v63, v53
	s_nop 0
	v_fma_f32 v84, v54, v82, -v50
	v_fma_f32 v85, v55, v83, -v51
	v_mul_f32_e32 v50, v54, v52
	v_mul_f32_e32 v51, v55, v53
	v_lshlrev_b32_e32 v52, 3, v72
	v_fma_f32 v62, v62, v82, v50
	v_fma_f32 v63, v63, v83, v51
	v_lshlrev_b32_e32 v50, 3, v73
	global_load_dwordx2 v[50:51], v50, s[80:81]
	s_nop 0
	global_load_dwordx2 v[52:53], v52, s[80:81]
	s_waitcnt vmcnt(1)
	v_mov_b32_e32 v83, v51
	s_waitcnt vmcnt(0)
	v_mov_b32_e32 v82, v53
	v_mov_b32_e32 v54, v52
	v_mov_b32_e32 v55, v50
	v_mul_f32_e32 v82, v64, v82
	v_mul_f32_e32 v83, v65, v83
	v_mul_f32_e32 v52, v64, v52
	v_fma_f32 v82, v56, v54, -v82
	v_fma_f32 v83, v57, v55, -v83
	v_mul_f32_e32 v54, v56, v53
	v_mov_b32_e32 v56, v65
	v_mul_f32_e32 v50, v56, v50
	v_mul_f32_e32 v51, v57, v51
	v_mov_b32_e32 v56, v82
	v_mov_b32_e32 v53, v50
	v_mov_b32_e32 v55, v51
	v_add_f32_e32 v64, v52, v54
	v_add_f32_e32 v65, v53, v55
	v_mov_b32_e32 v50, v70
	v_mov_b32_e32 v51, v71
	v_mov_b32_e32 v52, v86
	v_mov_b32_e32 v53, v87
	v_mov_b32_e32 v54, v84
	v_mov_b32_e32 v55, v85
	v_mov_b32_e32 v57, v83
.LBB0_660:
	s_or_b64 exec, exec, s[22:23]
	v_add_u32_e32 v69, v67, v80
	v_mad_i64_i32 v[70:71], s[0:1], v69, s9, v[0:1]
	v_mov_b64_e32 v[80:81], s[24:25]
	v_mad_u64_u32 v[80:81], s[0:1], v70, s5, v[80:81]
	v_lshlrev_b32_e32 v68, 5, v68
	v_mad_i32_i24 v81, v71, s5, v81
	v_ashrrev_i32_e32 v69, 31, v68
	v_lshl_add_u64 v[68:69], v[68:69], 1, v[80:81]
	v_lshlrev_b32_e32 v70, 1, v140
	v_mov_b32_e32 v71, v1
	v_mul_f32_e32 v50, v66, v50
	v_mul_f32_e32 v51, v66, v51
	v_mul_f32_e32 v52, v66, v52
	v_mul_f32_e32 v53, v66, v53
	v_lshl_add_u64 v[68:69], v[68:69], 0, v[70:71]
	v_cvt_pk_bf16_f32 v50, v50, v51
	v_cvt_pk_bf16_f32 v51, v52, v53
	global_store_dwordx2 v[68:69], v[50:51], off
	v_mul_f32_e32 v50, v66, v54
	v_mul_f32_e32 v51, v66, v55
	v_mul_f32_e32 v52, v66, v56
	v_mul_f32_e32 v53, v66, v57
	v_cvt_pk_bf16_f32 v50, v50, v51
	v_cvt_pk_bf16_f32 v51, v52, v53
	global_store_dwordx2 v[68:69], v[50:51], off offset:16
	v_mul_f32_e32 v50, v66, v58
	v_mul_f32_e32 v51, v66, v59
	v_mul_f32_e32 v52, v66, v60
	v_mul_f32_e32 v53, v66, v61
	v_cvt_pk_bf16_f32 v50, v50, v51
	v_cvt_pk_bf16_f32 v51, v52, v53
	global_store_dwordx2 v[68:69], v[50:51], off offset:32
	v_mul_f32_e32 v50, v66, v62
	v_mul_f32_e32 v51, v66, v63
	v_mul_f32_e32 v52, v66, v64
	v_mul_f32_e32 v53, v66, v65
	v_cvt_pk_bf16_f32 v50, v50, v51
	v_cvt_pk_bf16_f32 v51, v52, v53
	global_store_dwordx2 v[68:69], v[50:51], off offset:48
.LBB0_661:
	s_or_b64 exec, exec, s[2:3]
	s_and_saveexec_b64 s[2:3], s[38:39]
	s_cbranch_execz .LBB0_665
	v_add_u32_e32 v54, v115, v120
	v_mad_u64_u32 v[50:51], s[0:1], v54, -3, v[114:115]
	v_cmp_eq_u32_e64 s[42:43], 2, v50
	s_and_b64 s[0:1], s[40:41], s[42:43]
	s_and_saveexec_b64 s[22:23], s[0:1]
	s_cbranch_execz .LBB0_664
	v_lshlrev_b32_e32 v51, 3, v78
	v_lshlrev_b32_e32 v55, 3, v79
	global_load_dwordx2 v[52:53], v51, s[80:81]
	global_load_dwordx2 v[56:57], v55, s[80:81]
	v_lshlrev_b32_e32 v51, 3, v77
	s_waitcnt vmcnt(1)
	v_mov_b32_e32 v58, v52
	s_waitcnt vmcnt(0)
	v_mov_b32_e32 v59, v56
	v_mov_b32_e32 v56, v53
	v_mul_f32_e32 v52, v42, v56
	v_mul_f32_e32 v53, v43, v57
	s_nop 0
	v_fma_f32 v52, v34, v58, -v52
	v_fma_f32 v53, v35, v59, -v53
	v_mul_f32_e32 v34, v34, v56
	v_mul_f32_e32 v35, v35, v57
	s_nop 0
	v_fma_f32 v42, v42, v58, v34
	v_fma_f32 v43, v43, v59, v35
	v_lshlrev_b32_e32 v34, 3, v76
	global_load_dwordx2 v[34:35], v34, s[80:81]
	s_nop 0
	global_load_dwordx2 v[56:57], v51, s[80:81]
	s_waitcnt vmcnt(1)
	v_mov_b32_e32 v58, v34
	s_waitcnt vmcnt(0)
	v_mov_b32_e32 v59, v56
	v_mov_b32_e32 v56, v35
	v_mul_f32_e32 v34, v44, v56
	v_mul_f32_e32 v35, v45, v57
	s_nop 0
	v_fma_f32 v60, v36, v58, -v34
	v_fma_f32 v61, v37, v59, -v35
	v_mul_f32_e32 v34, v36, v56
	v_mul_f32_e32 v35, v37, v57
	v_lshlrev_b32_e32 v36, 3, v75
	v_fma_f32 v44, v44, v58, v34
	v_fma_f32 v45, v45, v59, v35
	v_lshlrev_b32_e32 v34, 3, v74
	global_load_dwordx2 v[34:35], v34, s[80:81]
	s_nop 0
	global_load_dwordx2 v[36:37], v36, s[80:81]
	s_waitcnt vmcnt(1)
	v_mov_b32_e32 v56, v34
	s_waitcnt vmcnt(0)
	v_mov_b32_e32 v57, v36
	v_mov_b32_e32 v36, v35
	v_mul_f32_e32 v34, v46, v36
	v_mul_f32_e32 v35, v47, v37
	s_nop 0
	v_fma_f32 v58, v38, v56, -v34
	v_fma_f32 v59, v39, v57, -v35
	v_mul_f32_e32 v34, v38, v36
	v_mul_f32_e32 v35, v39, v37
	v_lshlrev_b32_e32 v36, 3, v72
	v_fma_f32 v46, v46, v56, v34
	v_fma_f32 v47, v47, v57, v35
	v_lshlrev_b32_e32 v34, 3, v73
	global_load_dwordx2 v[34:35], v34, s[80:81]
	s_nop 0
	global_load_dwordx2 v[36:37], v36, s[80:81]
	s_waitcnt vmcnt(1)
	v_mov_b32_e32 v57, v35
	s_waitcnt vmcnt(0)
	v_mov_b32_e32 v56, v37
	v_mov_b32_e32 v38, v36
	v_mov_b32_e32 v39, v34
	v_mul_f32_e32 v56, v48, v56
	v_mul_f32_e32 v57, v49, v57
	v_mul_f32_e32 v36, v48, v36
	v_fma_f32 v56, v40, v38, -v56
	v_fma_f32 v57, v41, v39, -v57
	v_mul_f32_e32 v38, v40, v37
	v_mov_b32_e32 v40, v49
	v_mul_f32_e32 v34, v40, v34
	v_mul_f32_e32 v35, v41, v35
	v_mov_b32_e32 v40, v56
	v_mov_b32_e32 v37, v34
	v_mov_b32_e32 v39, v35
	v_add_f32_e32 v48, v36, v38
	v_add_f32_e32 v49, v37, v39
	v_mov_b32_e32 v34, v52
	v_mov_b32_e32 v35, v53
	v_mov_b32_e32 v36, v60
	v_mov_b32_e32 v37, v61
	v_mov_b32_e32 v38, v58
	v_mov_b32_e32 v39, v59
	v_mov_b32_e32 v41, v57
.LBB0_664:
	s_or_b64 exec, exec, s[22:23]
	v_add_u32_e32 v51, v67, v54
	v_mad_i64_i32 v[52:53], s[0:1], v51, s9, v[0:1]
	v_mov_b64_e32 v[54:55], s[24:25]
	v_mad_u64_u32 v[54:55], s[0:1], v52, s5, v[54:55]
	v_lshlrev_b32_e32 v50, 5, v50
	v_mad_i32_i24 v55, v53, s5, v55
	v_ashrrev_i32_e32 v51, 31, v50
	v_lshl_add_u64 v[50:51], v[50:51], 1, v[54:55]
	v_lshlrev_b32_e32 v0, 1, v140
	v_mul_f32_e32 v34, v66, v34
	v_mul_f32_e32 v35, v66, v35
	v_mul_f32_e32 v36, v66, v36
	v_mul_f32_e32 v37, v66, v37
	v_lshl_add_u64 v[50:51], v[50:51], 0, v[0:1]
	v_cvt_pk_bf16_f32 v34, v34, v35
	v_cvt_pk_bf16_f32 v35, v36, v37
	global_store_dwordx2 v[50:51], v[34:35], off
	v_mul_f32_e32 v34, v66, v38
	v_mul_f32_e32 v35, v66, v39
	v_mul_f32_e32 v36, v66, v40
	v_mul_f32_e32 v37, v66, v41
	v_cvt_pk_bf16_f32 v34, v34, v35
	v_cvt_pk_bf16_f32 v35, v36, v37
	global_store_dwordx2 v[50:51], v[34:35], off offset:16
	v_mul_f32_e32 v34, v66, v42
	v_mul_f32_e32 v35, v66, v43
	v_mul_f32_e32 v36, v66, v44
	v_mul_f32_e32 v37, v66, v45
	v_cvt_pk_bf16_f32 v34, v34, v35
	v_cvt_pk_bf16_f32 v35, v36, v37
	global_store_dwordx2 v[50:51], v[34:35], off offset:32
	v_mul_f32_e32 v34, v66, v46
	v_mul_f32_e32 v35, v66, v47
	v_mul_f32_e32 v36, v66, v48
	v_mul_f32_e32 v37, v66, v49
	v_cvt_pk_bf16_f32 v34, v34, v35
	v_cvt_pk_bf16_f32 v35, v36, v37
	global_store_dwordx2 v[50:51], v[34:35], off offset:48
.LBB0_665:
	s_or_b64 exec, exec, s[2:3]
	v_add_u32_e32 v34, 0x60, v152
	s_movk_i32 s0, 0x4000
	v_cmp_gt_i32_e64 s[40:41], s0, v34
	v_cmp_lt_i32_e64 s[42:43], s8, v34
	s_and_saveexec_b64 s[0:1], s[42:43]
	s_xor_b64 s[2:3], exec, s[0:1]
	v_add_u32_e32 v0, 0xffffc060, v155
	s_movk_i32 s0, 0x2000
	v_lshrrev_b32_e32 v151, 8, v0
	v_or_b32_sdwa v0, v34, s0 dst_sel:DWORD dst_unused:UNUSED_PAD src0_sel:BYTE_0 src1_sel:DWORD
	s_or_saveexec_b64 s[2:3], s[2:3]
	v_mov_b32_e32 v37, 0
	v_mov_b32_e32 v36, 0
	s_xor_b64 exec, exec, s[2:3]
	v_lshrrev_b32_e32 v35, 2, v34
	v_and_b32_e32 v37, 0x7f0, v35
	v_add_u32_e32 v35, 0x600, v182
	v_and_b32_e32 v0, 0x1fff, v34
	v_and_b32_e32 v36, 0x3f0, v35
	s_or_b64 exec, exec, s[2:3]
	v_ashrrev_i32_e32 v35, 31, v34
	v_lshl_add_u64 v[34:35], v[34:35], 3, s[44:45]
	global_load_dword v34, v[34:35], off
	v_or_b32_e32 v46, v37, v142
	v_or_b32_e32 v47, v37, v176
	v_or_b32_e32 v44, v37, v177
	v_or_b32_e32 v45, v37, v178
	v_or_b32_e32 v42, v36, v142
	v_or_b32_e32 v43, v36, v176
	v_or_b32_e32 v40, v36, v177
	v_or_b32_e32 v41, v36, v178
	s_waitcnt vmcnt(0)
	v_fmamk_f32 v34, v34, 0x3b800000, v201
	v_cmp_gt_f32_e64 s[42:43], s66, v34
	v_mul_f32_e32 v35, 0x4b800000, v34
	s_nop 0
	v_cndmask_b32_e64 v34, v34, v35, s[42:43]
	v_rsq_f32_e32 v34, v34
	s_nop 0
	v_mul_f32_e32 v35, 0x45800000, v34
	v_cndmask_b32_e64 v34, v34, v35, s[42:43]
	v_mul_f32_e32 v34, 0x3e16c740, v34
	v_mul_lo_u32 v35, v151, 6
	s_and_saveexec_b64 s[2:3], vcc
	s_cbranch_execz .LBB0_673
	v_add_u32_e32 v48, v153, v160
	v_mad_u64_u32 v[36:37], s[0:1], v48, -3, v[150:151]
	v_cmp_eq_u32_e32 vcc, 2, v36
	s_and_b64 s[0:1], s[40:41], vcc
	s_and_saveexec_b64 s[22:23], s[0:1]
	s_cbranch_execz .LBB0_672
	v_lshlrev_b32_e32 v37, 3, v46
	v_lshlrev_b32_e32 v49, 3, v47
	global_load_dwordx2 v[38:39], v37, s[80:81]
	global_load_dwordx2 v[50:51], v49, s[80:81]
	v_lshlrev_b32_e32 v37, 3, v45
	s_waitcnt vmcnt(1)
	v_mov_b32_e32 v52, v38
	s_waitcnt vmcnt(0)
	v_mov_b32_e32 v53, v50
	v_mov_b32_e32 v50, v39
	v_mul_f32_e32 v38, v26, v50
	v_mul_f32_e32 v39, v27, v51
	s_nop 0
	v_fma_f32 v38, v18, v52, -v38
	v_fma_f32 v39, v19, v53, -v39
	v_mul_f32_e32 v18, v18, v50
	v_mul_f32_e32 v19, v19, v51
	s_nop 0
	v_fma_f32 v26, v26, v52, v18
	v_fma_f32 v27, v27, v53, v19
	v_lshlrev_b32_e32 v18, 3, v44
	global_load_dwordx2 v[18:19], v18, s[80:81]
	s_nop 0
	global_load_dwordx2 v[50:51], v37, s[80:81]
	s_waitcnt vmcnt(1)
	v_mov_b32_e32 v52, v18
	s_waitcnt vmcnt(0)
	v_mov_b32_e32 v53, v50
	v_mov_b32_e32 v50, v19
	v_mul_f32_e32 v18, v28, v50
	v_mul_f32_e32 v19, v29, v51
	s_nop 0
	v_fma_f32 v54, v20, v52, -v18
	v_fma_f32 v55, v21, v53, -v19
	v_mul_f32_e32 v18, v20, v50
	v_mul_f32_e32 v19, v21, v51
	v_lshlrev_b32_e32 v20, 3, v43
	v_fma_f32 v28, v28, v52, v18
	v_fma_f32 v29, v29, v53, v19
	v_lshlrev_b32_e32 v18, 3, v42
	global_load_dwordx2 v[18:19], v18, s[80:81]
	s_nop 0
	global_load_dwordx2 v[20:21], v20, s[80:81]
	s_waitcnt vmcnt(1)
	v_mov_b32_e32 v50, v18
	s_waitcnt vmcnt(0)
	v_mov_b32_e32 v51, v20
	v_mov_b32_e32 v20, v19
	v_mul_f32_e32 v18, v30, v20
	v_mul_f32_e32 v19, v31, v21
	s_nop 0
	v_fma_f32 v52, v22, v50, -v18
	v_fma_f32 v53, v23, v51, -v19
	v_mul_f32_e32 v18, v22, v20
	v_mul_f32_e32 v19, v23, v21
	v_lshlrev_b32_e32 v20, 3, v40
	v_fma_f32 v30, v30, v50, v18
	v_fma_f32 v31, v31, v51, v19
	v_lshlrev_b32_e32 v18, 3, v41
	global_load_dwordx2 v[18:19], v18, s[80:81]
	s_nop 0
	global_load_dwordx2 v[20:21], v20, s[80:81]
	s_waitcnt vmcnt(1)
	v_mov_b32_e32 v51, v19
	s_waitcnt vmcnt(0)
	v_mov_b32_e32 v50, v21
	v_mov_b32_e32 v22, v20
	v_mov_b32_e32 v23, v18
	v_mul_f32_e32 v50, v32, v50
	v_mul_f32_e32 v51, v33, v51
	v_mul_f32_e32 v20, v32, v20
	v_fma_f32 v50, v24, v22, -v50
	v_fma_f32 v51, v25, v23, -v51
	v_mul_f32_e32 v22, v24, v21
	v_mov_b32_e32 v24, v33
	v_mul_f32_e32 v18, v24, v18
	v_mul_f32_e32 v19, v25, v19
	v_mov_b32_e32 v24, v50
	v_mov_b32_e32 v21, v18
	v_mov_b32_e32 v23, v19
	v_add_f32_e32 v32, v20, v22
	v_add_f32_e32 v33, v21, v23
	v_mov_b32_e32 v18, v38
	v_mov_b32_e32 v19, v39
	v_mov_b32_e32 v20, v54
	v_mov_b32_e32 v21, v55
	v_mov_b32_e32 v22, v52
	v_mov_b32_e32 v23, v53
	v_mov_b32_e32 v25, v51
.LBB0_672:
	s_or_b64 exec, exec, s[22:23]
	v_add_u32_e32 v37, v35, v48
	v_mad_i64_i32 v[38:39], s[0:1], v37, s9, v[0:1]
	v_mov_b64_e32 v[48:49], s[24:25]
	v_mad_u64_u32 v[48:49], s[0:1], v38, s5, v[48:49]
	v_lshlrev_b32_e32 v36, 5, v36
	v_mad_i32_i24 v49, v39, s5, v49
	v_ashrrev_i32_e32 v37, 31, v36
	v_lshl_add_u64 v[36:37], v[36:37], 1, v[48:49]
	v_lshlrev_b32_e32 v38, 1, v140
	v_mov_b32_e32 v39, v1
	v_mul_f32_e32 v18, v34, v18
	v_mul_f32_e32 v19, v34, v19
	v_mul_f32_e32 v20, v34, v20
	v_mul_f32_e32 v21, v34, v21
	v_lshl_add_u64 v[36:37], v[36:37], 0, v[38:39]
	v_cvt_pk_bf16_f32 v18, v18, v19
	v_cvt_pk_bf16_f32 v19, v20, v21
	global_store_dwordx2 v[36:37], v[18:19], off
	v_mul_f32_e32 v18, v34, v22
	v_mul_f32_e32 v19, v34, v23
	v_mul_f32_e32 v20, v34, v24
	v_mul_f32_e32 v21, v34, v25
	v_cvt_pk_bf16_f32 v18, v18, v19
	v_cvt_pk_bf16_f32 v19, v20, v21
	global_store_dwordx2 v[36:37], v[18:19], off offset:16
	v_mul_f32_e32 v18, v34, v26
	v_mul_f32_e32 v19, v34, v27
	v_mul_f32_e32 v20, v34, v28
	v_mul_f32_e32 v21, v34, v29
	v_cvt_pk_bf16_f32 v18, v18, v19
	v_cvt_pk_bf16_f32 v19, v20, v21
	global_store_dwordx2 v[36:37], v[18:19], off offset:32
	v_mul_f32_e32 v18, v34, v30
	v_mul_f32_e32 v19, v34, v31
	v_mul_f32_e32 v20, v34, v32
	v_mul_f32_e32 v21, v34, v33
	v_cvt_pk_bf16_f32 v18, v18, v19
	v_cvt_pk_bf16_f32 v19, v20, v21
	global_store_dwordx2 v[36:37], v[18:19], off offset:48
.LBB0_673:
	s_or_b64 exec, exec, s[2:3]
	s_and_saveexec_b64 s[2:3], s[38:39]
	s_cbranch_execz .LBB0_576
	v_add_u32_e32 v22, v115, v120
	v_mad_u64_u32 v[18:19], s[0:1], v22, -3, v[114:115]
	v_cmp_eq_u32_e32 vcc, 2, v18
	s_and_b64 s[0:1], s[40:41], vcc
	s_and_saveexec_b64 s[22:23], s[0:1]
	s_cbranch_execz .LBB0_575
	v_lshlrev_b32_e32 v19, 3, v46
	v_lshlrev_b32_e32 v23, 3, v47
	global_load_dwordx2 v[20:21], v19, s[80:81]
	global_load_dwordx2 v[24:25], v23, s[80:81]
	v_lshlrev_b32_e32 v19, 3, v45
	s_waitcnt vmcnt(1)
	v_mov_b32_e32 v26, v20
	s_waitcnt vmcnt(0)
	v_mov_b32_e32 v27, v24
	v_mov_b32_e32 v24, v21
	v_mul_f32_e32 v20, v10, v24
	v_mul_f32_e32 v21, v11, v25
	s_nop 0
	v_fma_f32 v20, v2, v26, -v20
	v_fma_f32 v21, v3, v27, -v21
	v_mul_f32_e32 v2, v2, v24
	v_mul_f32_e32 v3, v3, v25
	s_nop 0
	v_fma_f32 v10, v10, v26, v2
	v_fma_f32 v11, v11, v27, v3
	v_lshlrev_b32_e32 v2, 3, v44
	global_load_dwordx2 v[2:3], v2, s[80:81]
	s_nop 0
	global_load_dwordx2 v[24:25], v19, s[80:81]
	s_waitcnt vmcnt(1)
	v_mov_b32_e32 v26, v2
	s_waitcnt vmcnt(0)
	v_mov_b32_e32 v27, v24
	v_mov_b32_e32 v24, v3
	v_mul_f32_e32 v2, v12, v24
	v_mul_f32_e32 v3, v13, v25
	s_nop 0
	v_fma_f32 v28, v4, v26, -v2
	v_fma_f32 v29, v5, v27, -v3
	v_mul_f32_e32 v2, v4, v24
	v_mul_f32_e32 v3, v5, v25
	v_lshlrev_b32_e32 v4, 3, v43
	v_fma_f32 v12, v12, v26, v2
	v_fma_f32 v13, v13, v27, v3
	v_lshlrev_b32_e32 v2, 3, v42
	global_load_dwordx2 v[2:3], v2, s[80:81]
	s_nop 0
	global_load_dwordx2 v[4:5], v4, s[80:81]
	s_waitcnt vmcnt(1)
	v_mov_b32_e32 v24, v2
	s_waitcnt vmcnt(0)
	v_mov_b32_e32 v25, v4
	v_mov_b32_e32 v4, v3
	v_mul_f32_e32 v2, v14, v4
	v_mul_f32_e32 v3, v15, v5
	s_nop 0
	v_fma_f32 v26, v6, v24, -v2
	v_fma_f32 v27, v7, v25, -v3
	v_mul_f32_e32 v2, v6, v4
	v_mul_f32_e32 v3, v7, v5
	v_lshlrev_b32_e32 v4, 3, v40
	v_fma_f32 v14, v14, v24, v2
	v_fma_f32 v15, v15, v25, v3
	v_lshlrev_b32_e32 v2, 3, v41
	global_load_dwordx2 v[2:3], v2, s[80:81]
	s_nop 0
	global_load_dwordx2 v[4:5], v4, s[80:81]
	s_waitcnt vmcnt(1)
	v_mov_b32_e32 v25, v3
	s_waitcnt vmcnt(0)
	v_mov_b32_e32 v24, v5
	v_mov_b32_e32 v6, v4
	v_mov_b32_e32 v7, v2
	v_mul_f32_e32 v24, v16, v24
	v_mul_f32_e32 v25, v17, v25
	v_mul_f32_e32 v4, v16, v4
	v_fma_f32 v24, v8, v6, -v24
	v_fma_f32 v25, v9, v7, -v25
	v_mul_f32_e32 v6, v8, v5
	v_mov_b32_e32 v8, v17
	v_mul_f32_e32 v2, v8, v2
	v_mul_f32_e32 v3, v9, v3
	v_mov_b32_e32 v8, v24
	v_mov_b32_e32 v5, v2
	v_mov_b32_e32 v7, v3
	v_add_f32_e32 v16, v4, v6
	v_add_f32_e32 v17, v5, v7
	v_mov_b32_e32 v2, v20
	v_mov_b32_e32 v3, v21
	v_mov_b32_e32 v4, v28
	v_mov_b32_e32 v5, v29
	v_mov_b32_e32 v6, v26
	v_mov_b32_e32 v7, v27
	v_mov_b32_e32 v9, v25
	s_branch .LBB0_575
